# v33 + sumsq xor-1/2/4 reductions in the residual epilogues via DPP v_mov (quad_perm / row_half_mirror) instead of ds_bpermute
# baseline (speedup 1.0000x reference)
; #define LAS __attribute__((address_space(3)))
; #define ERN_EOFF(q, m) (eb + (unsigned)((((q) & 1) * HALF + (m) * 16) * DM + ERN_COL((q) >> 1)))
;     __device__ __forceinline__ void operator()(const f32x4 (&acc)[2][2][4][2], const Unit& u, int wr, int wc, int fr, int fq) const {
;         const int s = u.pm >> 5, lane = fq * 16 + fr, rr = lane >> 3, pc = lane & 7;
;         const float* __restrict__ xi = xin + (size_t)u.pm * BM * DM; float* __restrict__ xo = xout + (size_t)u.pm * BM * DM; bf16_t* __restrict__ ho = Hn + (size_t)u.pm * BM * DM;
;         LAS unsigned char* st = lds_epi + (wr * 4 + wc) * 2304;
;         LAS float* sst = (LAS float*)(lds_epi + 18432 + (wr * 4 + wc) * 512);
;         const int colr = u.pn * BM + wc * 64 + 4 * pc;
;         const unsigned eb = (unsigned)((wr * 64 + rr) * DM + colr);
;         f32x4 gv[2], gsn[2];
; #pragma unroll
;         for (int bj = 0; bj < 2; ++bj) { gv[bj] = *(const f32x4*)(gate + (size_t)s * MODW + colr + bj * 32) * (0.5f * GS2);
;             if (!PLAIN) gsn[bj] = *(const f32x4*)(gnext + colr + bj * 32) * (*(const f32x4*)(scnext + (size_t)s * MODW + colr + bj * 32) + 1.0f); else gsn[bj] = gv[bj]; }
;         const unsigned wr_off = (unsigned)(fr * 144 + 16 * fq), rd_off = (unsigned)(rr * 144 + pc * 16);
;         const bool odd = (rr & 1) != 0;
;         f32x4 xb[2][2][2];
;     ...
;         ERN_LOADX(0);
; #pragma unroll
;         for (int g = 0; g < 8; ++g) { const int ai = g >> 2, m = g & 3;
;             if (g + 1 < 8) ERN_LOADX(g + 1);
;             float sq0 = 0.f, sq1 = 0.f; u32x2 hw[2][2];
; #pragma unroll
;             for (int bj = 0; bj < 2; ++bj) {
;                 *(LAS f32x4*)(st + wr_off) = acc[ai][bj][m][0]; *(LAS f32x4*)(st + wr_off + 64) = acc[ai][bj][m][1];
;                 const f32x4 a0 = *(const LAS f32x4*)(st + rd_off), a1 = *(const LAS f32x4*)(st + rd_off + 8 * 144);
;                 { const f32x4 xv = xb[g & 1][bj][0] + gv[bj] * a0; __builtin_nontemporal_store(xv, (f32x4*)((char*)xo + 4u * ERN_EOFF(g, bj, 0)));
;                   sq0 += (xv.x * xv.x + xv.y * xv.y) + (xv.z * xv.z + xv.w * xv.w);
;                   const f32x4 hv = xv * gsn[bj]; hw[bj][0].x = cvt_pk_bf16(hv.x, hv.y); hw[bj][0].y = cvt_pk_bf16(hv.z, hv.w); }
;                 { const f32x4 xv = xb[g & 1][bj][1] + gv[bj] * a1; __builtin_nontemporal_store(xv, (f32x4*)((char*)xo + 4u * ERN_EOFF(g, bj, 1)));
.LBB0_320:
	s_ashr_i32 s12, s4, 5
	s_ashr_i32 s5, s4, 31
	v_lshl_or_b32 v130, s0, 8, v192
	s_mul_i32 s14, s12, 0x12000
	s_mul_hi_i32 s0, s12, 0x12000
	s_add_u32 s12, s35, s14
	v_ashrrev_i32_e32 v131, 31, v130
	s_addc_u32 s13, s36, s0
	v_lshlrev_b64 v[132:133], 2, v[130:131]
	v_lshl_add_u64 v[134:135], s[12:13], 0, v[132:133]
	s_add_u32 s12, s37, s14
	s_addc_u32 s13, s60, s0
	v_lshl_add_u64 v[136:137], s[46:47], 0, v[132:133]
	v_lshl_add_u64 v[132:133], s[12:13], 0, v[132:133]
	s_lshl_b64 s[54:55], s[4:5], 21
	v_readlane_b32 s12, v253, 2
	v_readlane_b32 s13, v253, 3
	s_add_u32 s58, s12, s54
	v_add_u32_e32 v202, v130, v193
	s_addc_u32 s59, s13, s55
	v_lshlrev_b32_e32 v207, 2, v202
	global_load_dwordx4 v[170:173], v[136:137], off
	global_load_dwordx4 v[166:169], v[134:135], off
	global_load_dwordx4 v[174:177], v[134:135], off offset:128
	global_load_dwordx4 v[186:189], v[132:133], off
	global_load_dwordx4 v[208:211], v[132:133], off offset:128
	global_load_dwordx4 v[212:215], v207, s[58:59]
	v_add_u32_e32 v130, 0x10000, v207
	global_load_dwordx4 v[216:219], v130, s[58:59]
	global_load_dwordx4 v[220:223], v[136:137], off offset:128
	global_load_dwordx4 v[224:227], v207, s[58:59] offset:128
	v_add_u32_e32 v206, 0x10080, v207
	v_add_u32_e32 v130, 0x20000, v207
	global_load_dwordx4 v[228:231], v206, s[58:59]
	v_add_u32_e32 v154, 0x30000, v207
	v_add_u32_e32 v184, 0x20080, v207
	v_add_u32_e32 v182, 0x30080, v207
	global_load_dwordx4 v[142:145], v130, s[58:59]
	global_load_dwordx4 v[138:141], v154, s[58:59]
	global_load_dwordx4 v[134:137], v184, s[58:59]
	s_nop 0
	global_load_dwordx4 v[130:133], v182, s[58:59]
	ds_write_b128 v200, v[126:129]
	ds_write_b128 v200, v[122:125] offset:64
	v_and_b32_e32 v127, 64, v199
	ds_read_b128 v[122:125], v201
	ds_read_b128 v[232:235], v201 offset:1152
	v_xor_b32_e32 v126, 8, v199
	v_add_u32_e32 v183, 64, v127
	v_cmp_lt_i32_e32 vcc, v126, v183
	v_add_u32_e32 v185, 0x4000, v202
	s_add_u32 s56, s90, s54
	v_cndmask_b32_e32 v126, v199, v126, vcc
	v_lshlrev_b32_e32 v203, 2, v126
	v_lshlrev_b32_e32 v236, 2, v185
	s_addc_u32 s57, s91, s55
	s_lshl_b64 s[12:13], s[4:5], 20
	s_add_u32 s54, s93, s12
	v_readlane_b32 s16, v253, 6
	v_readlane_b32 s17, v253, 7
	s_addc_u32 s55, s92, s13
	v_readlane_b32 s14, v253, 4
	v_readlane_b32 s15, v253, 5
	v_readlane_b32 s18, v253, 8
	v_readlane_b32 s19, v253, 9
	v_readlane_b32 s20, v253, 10
	v_readlane_b32 s21, v253, 11
	v_readlane_b32 s22, v253, 12
	v_readlane_b32 s23, v253, 13
	v_readlane_b32 s24, v253, 14
	v_readlane_b32 s25, v253, 15
	v_readlane_b32 s26, v253, 16
	v_readlane_b32 s27, v253, 17
	s_waitcnt vmcnt(0)
	v_pk_mul_f32 v[180:181], v[166:167], 0.5 op_sel_hi:[1,0]
	v_pk_mul_f32 v[178:179], v[168:169], 0.5 op_sel_hi:[1,0]
	v_pk_add_f32 v[126:127], v[188:189], 1.0 op_sel_hi:[1,0]
	v_pk_add_f32 v[128:129], v[186:187], 1.0 op_sel_hi:[1,0]
	v_pk_mul_f32 v[166:167], v[176:177], 0.5 op_sel_hi:[1,0]
	v_pk_mul_f32 v[168:169], v[174:175], 0.5 op_sel_hi:[1,0]
	v_pk_mul_f32 v[174:175], v[172:173], v[126:127]
	v_pk_mul_f32 v[176:177], v[170:171], v[128:129]
	s_waitcnt lgkmcnt(1)
	v_pk_fma_f32 v[126:127], v[180:181], v[122:123], v[212:213]
	s_waitcnt lgkmcnt(0)
	v_pk_fma_f32 v[122:123], v[180:181], v[232:233], v[216:217]
	v_pk_fma_f32 v[128:129], v[178:179], v[124:125], v[214:215]
	v_pk_fma_f32 v[124:125], v[178:179], v[234:235], v[218:219]
	v_pk_mul_f32 v[186:187], v[176:177], v[122:123]
	global_store_dwordx4 v207, v[126:129], s[56:57] nt
	v_pk_mul_f32 v[170:171], v[174:175], v[128:129]
	v_pk_mul_f32 v[172:173], v[176:177], v[126:127]
	v_pk_mul_f32 v[204:205], v[174:175], v[124:125]
	v_cvt_pk_bf16_f32 v188, v172, v173
	v_cvt_pk_bf16_f32 v189, v170, v171
	global_store_dwordx4 v236, v[122:125], s[56:57] nt
	v_cvt_pk_bf16_f32 v186, v186, v187
	v_cvt_pk_bf16_f32 v187, v204, v205
	ds_write_b128 v200, v[118:121]
	ds_write_b128 v200, v[114:117] offset:64
	ds_read_b128 v[114:117], v201
	v_pk_add_f32 v[190:191], v[210:211], 1.0 op_sel_hi:[1,0]
	v_pk_add_f32 v[118:119], v[208:209], 1.0 op_sel_hi:[1,0]
	ds_read_b128 v[208:211], v201 offset:1152
	v_pk_mul_f32 v[170:171], v[222:223], v[190:191]
	v_pk_mul_f32 v[172:173], v[220:221], v[118:119]
	s_waitcnt lgkmcnt(1)
	v_pk_fma_f32 v[120:121], v[166:167], v[116:117], v[226:227]
	v_pk_fma_f32 v[118:119], v[168:169], v[114:115], v[224:225]
	v_pk_mul_f32 v[190:191], v[170:171], v[120:121]
	v_pk_mul_f32 v[204:205], v[172:173], v[118:119]
	global_store_dwordx4 v207, v[118:121], s[56:57] offset:128 nt
	v_cvt_pk_bf16_f32 v204, v204, v205
	v_cvt_pk_bf16_f32 v191, v190, v191
	ds_bpermute_b32 v190, v203, v204
	ds_bpermute_b32 v191, v203, v191
	s_waitcnt lgkmcnt(2)
	v_pk_fma_f32 v[116:117], v[166:167], v[210:211], v[230:231]
	v_pk_fma_f32 v[114:115], v[168:169], v[208:209], v[228:229]
	global_store_dwordx4 v206, v[114:117], s[56:57] nt
	v_pk_mul_f32 v[204:205], v[172:173], v[114:115]
	v_lshlrev_b32_e32 v206, 1, v202
	v_pk_mul_f32 v[208:209], v[170:171], v[116:117]
	v_cvt_pk_bf16_f32 v204, v204, v205
	s_nop 0
	v_cvt_pk_bf16_f32 v205, v208, v209
	s_waitcnt lgkmcnt(0)
	v_add_u32_e32 v250, 0xfffff040, v206
	v_cndmask_b32_e64 v250, v206, v250, s[40:41]
	v_cndmask_b32_e64 v248, v188, v190, s[40:41]
	v_cndmask_b32_e64 v249, v189, v191, s[40:41]
	global_store_dwordx2 v250, v[248:249], s[54:55]
	v_cndmask_b32_e64 v246, v190, v188, s[40:41]
	v_cndmask_b32_e64 v247, v191, v189, s[40:41]
	s_waitcnt lgkmcnt(1)
	v_add_u32_e32 v190, 0x1040, v206
	v_cndmask_b32_e64 v190, v206, v190, s[38:39]
	global_store_dwordx2 v190, v[246:247], s[54:55]
	ds_bpermute_b32 v188, v203, v204
	ds_bpermute_b32 v189, v203, v205
	v_lshlrev_b32_e32 v190, 1, v185
	s_waitcnt lgkmcnt(0)
; #define LAS __attribute__((address_space(3)))
; __device__ __forceinline__ unsigned cvt_pk_bf16(float lo, float hi) { unsigned r; asm volatile("v_cvt_pk_bf16_f32 %0, %1, %2" : "=v"(r) : "v"(lo), "v"(hi)); return r; }
; #define ERN_EOFF(q, m) (eb + (unsigned)((((q) & 1) * HALF + (m) * 16) * DM + ERN_COL((q) >> 1)))
;     __device__ __forceinline__ void operator()(const f32x4 (&acc)[2][2][4][2], const Unit& u, int wr, int wc, int fr, int fq) const {
;     ...
;             float sq0 = 0.f, sq1 = 0.f; u32x2 hw[2][2];
; #pragma unroll
;             for (int bj = 0; bj < 2; ++bj) {
;                 *(LAS f32x4*)(st + wr_off) = acc[ai][bj][m][0]; *(LAS f32x4*)(st + wr_off + 64) = acc[ai][bj][m][1];
;                 const f32x4 a0 = *(const LAS f32x4*)(st + rd_off), a1 = *(const LAS f32x4*)(st + rd_off + 8 * 144);
;                 { const f32x4 xv = xb[g & 1][bj][0] + gv[bj] * a0; __builtin_nontemporal_store(xv, (f32x4*)((char*)xo + 4u * ERN_EOFF(g, bj, 0)));
;                   sq0 += (xv.x * xv.x + xv.y * xv.y) + (xv.z * xv.z + xv.w * xv.w);
;                   const f32x4 hv = xv * gsn[bj]; hw[bj][0].x = cvt_pk_bf16(hv.x, hv.y); hw[bj][0].y = cvt_pk_bf16(hv.z, hv.w); }
;                 { const f32x4 xv = xb[g & 1][bj][1] + gv[bj] * a1; __builtin_nontemporal_store(xv, (f32x4*)((char*)xo + 4u * ERN_EOFF(g, bj, 1)));
;                   sq1 += (xv.x * xv.x + xv.y * xv.y) + (xv.z * xv.z + xv.w * xv.w);
;                   const f32x4 hv = xv * gsn[bj]; hw[bj][1].x = cvt_pk_bf16(hv.x, hv.y); hw[bj][1].y = cvt_pk_bf16(hv.z, hv.w); }
;             }
;             if (!NOH && !PLAIN) {
; #pragma unroll
;                 for (int rh = 0; rh < 2; ++rh) { u32x2 rv; rv.x = __shfl_xor(hw[1][rh].x, 8); rv.y = __shfl_xor(hw[1][rh].y, 8);
;                     const unsigned e0 = ERN_EOFF(g, 0, rh);
;                     const unsigned ee = odd ? (e0 - DM + 32) : e0, eo2 = odd ? e0 : (e0 + DM + 32);
;                     *(u32x2*)((char*)ho + 2u * ee) = odd ? rv : hw[0][rh];
;                     *(u32x2*)((char*)ho + 2u * eo2) = odd ? hw[0][rh] : rv; }
;             }
;             if (!PLAIN) { sq0 += __shfl_xor(sq0, 1); sq0 += __shfl_xor(sq0, 2); sq0 += __shfl_xor(sq0, 4);
;             sq1 += __shfl_xor(sq1, 1); sq1 += __shfl_xor(sq1, 2); sq1 += __shfl_xor(sq1, 4); }
;             if (!PLAIN && pc == 0) { sst[g * 16 + rr] = sq0; sst[g * 16 + 8 + rr] = sq1; }
	v_add_u32_e32 v250, 0xfffff040, v190
	v_cndmask_b32_e64 v250, v190, v250, s[40:41]
	v_cndmask_b32_e64 v248, v186, v188, s[40:41]
	v_cndmask_b32_e64 v249, v187, v189, s[40:41]
	global_store_dwordx2 v250, v[248:249], s[54:55]
	v_cndmask_b32_e64 v246, v188, v186, s[40:41]
	v_cndmask_b32_e64 v247, v189, v187, s[40:41]
	v_mul_f32_e32 v119, v119, v119
	v_mul_f32_e32 v127, v127, v127
	v_mul_f32_e32 v129, v129, v129
	v_fmac_f32_e32 v119, v118, v118
	v_mul_f32_e32 v118, v121, v121
	v_fmac_f32_e32 v129, v128, v128
	v_fmac_f32_e32 v118, v120, v120
	v_mul_f32_e32 v115, v115, v115
	v_fmac_f32_e32 v127, v126, v126
	v_add_f32_e32 v118, v119, v118
	v_fmac_f32_e32 v115, v114, v114
	v_mul_f32_e32 v114, v117, v117
	v_add_f32_e32 v117, v127, v129
	v_add_f32_e32 v117, v117, v118
	v_xor_b32_e32 v118, 1, v199
	v_cmp_lt_i32_e32 vcc, v118, v183
	v_mul_f32_e32 v123, v123, v123
	v_mul_f32_e32 v125, v125, v125
	v_cndmask_b32_e32 v118, v199, v118, vcc
	v_lshlrev_b32_e32 v204, 2, v118
	s_nop 1
	v_mov_b32_dpp v118, v117 quad_perm:[1,0,3,2] row_mask:0xf bank_mask:0xf
	v_fmac_f32_e32 v114, v116, v116
	v_fmac_f32_e32 v125, v124, v124
	v_fmac_f32_e32 v123, v122, v122
	v_add_f32_e32 v114, v115, v114
	s_waitcnt lgkmcnt(0)
	v_add_f32_e32 v116, v117, v118
	v_xor_b32_e32 v117, 2, v199
	v_cmp_lt_i32_e32 vcc, v117, v183
	v_add_f32_e32 v115, v123, v125
	v_add_f32_e32 v115, v115, v114
	v_cndmask_b32_e32 v117, v199, v117, vcc
	v_lshlrev_b32_e32 v205, 2, v117
	s_nop 1
	v_mov_b32_dpp v117, v116 quad_perm:[2,3,0,1] row_mask:0xf bank_mask:0xf
	s_nop 1
	v_mov_b32_dpp v118, v115 quad_perm:[1,0,3,2] row_mask:0xf bank_mask:0xf
	s_waitcnt lgkmcnt(1)
	v_add_f32_e32 v114, v116, v117
	s_waitcnt lgkmcnt(0)
	v_add_f32_e32 v117, v115, v118
	s_nop 1
	v_mov_b32_dpp v118, v117 quad_perm:[2,3,0,1] row_mask:0xf bank_mask:0xf
	v_xor_b32_e32 v116, 4, v199
	v_cmp_lt_i32_e32 vcc, v116, v183
	s_nop 1
	v_cndmask_b32_e32 v115, v199, v116, vcc
	v_lshlrev_b32_e32 v206, 2, v115
	s_waitcnt lgkmcnt(0)
	v_add_f32_e32 v116, v117, v118
	s_nop 1
	v_mov_b32_dpp v115, v114 row_half_mirror row_mask:0xf bank_mask:0xf
	s_nop 1
	v_mov_b32_dpp v117, v116 row_half_mirror row_mask:0xf bank_mask:0xf
	v_add_u32_e32 v118, 0x1040, v190
	v_cndmask_b32_e64 v118, v190, v118, s[38:39]
	global_store_dwordx2 v118, v[246:247], s[54:55]
	s_and_saveexec_b64 s[16:17], s[42:43]
	s_cbranch_execz .LBB0_330
	s_waitcnt lgkmcnt(1)
	v_add_f32_e32 v114, v114, v115
	s_waitcnt lgkmcnt(0)
	v_add_f32_e32 v115, v116, v117
	ds_write2_b32 v194, v114, v115 offset1:8
.LBB0_330:
	s_or_b64 exec, exec, s[16:17]
	v_add_u32_e32 v114, 0x40000, v207
	v_add_u32_e32 v190, 0x50000, v207
	v_add_u32_e32 v188, 0x40080, v207
	global_load_dwordx4 v[122:125], v190, s[58:59]
	global_load_dwordx4 v[118:121], v188, s[58:59]
	v_add_u32_e32 v186, 0x50080, v207
	global_load_dwordx4 v[126:129], v114, s[58:59]
	s_waitcnt lgkmcnt(0)
	global_load_dwordx4 v[114:117], v186, s[58:59]
	ds_write_b128 v200, v[110:113]
	ds_write_b128 v200, v[106:109] offset:64
	ds_read_b128 v[106:109], v201
	ds_read_b128 v[110:113], v201 offset:1152
	v_mov_b32_e32 v185, v155
	v_mov_b32_e32 v183, v155
	s_waitcnt lgkmcnt(1)
	v_pk_fma_f32 v[108:109], v[178:179], v[108:109], v[144:145]
	v_add_u32_e32 v144, 0x8000, v202
	v_pk_fma_f32 v[106:107], v[180:181], v[106:107], v[142:143]
	v_lshlrev_b32_e32 v142, 2, v144
	global_store_dwordx4 v142, v[106:109], s[56:57] nt
	v_pk_mul_f32 v[142:143], v[176:177], v[106:107]
	s_waitcnt lgkmcnt(0)
	v_pk_fma_f32 v[112:113], v[178:179], v[112:113], v[140:141]
	v_pk_fma_f32 v[110:111], v[180:181], v[110:111], v[138:139]
	v_lshl_add_u64 v[138:139], s[56:57], 0, v[154:155]
	v_pk_mul_f32 v[208:209], v[174:175], v[108:109]
	v_cvt_pk_bf16_f32 v142, v142, v143
	v_pk_mul_f32 v[140:141], v[174:175], v[112:113]
	v_cvt_pk_bf16_f32 v143, v208, v209
	global_store_dwordx4 v[138:139], v[110:113], off nt
	v_pk_mul_f32 v[138:139], v[176:177], v[110:111]
	s_nop 0
	v_cvt_pk_bf16_f32 v138, v138, v139
	v_cvt_pk_bf16_f32 v139, v140, v141
	ds_write_b128 v200, v[102:105]
	ds_write_b128 v200, v[98:101] offset:64
	ds_read_b128 v[98:101], v201
	ds_read_b128 v[102:105], v201 offset:1152
	s_waitcnt lgkmcnt(1)
	v_pk_fma_f32 v[98:99], v[168:169], v[98:99], v[134:135]
	v_pk_fma_f32 v[100:101], v[166:167], v[100:101], v[136:137]
	v_lshl_add_u64 v[134:135], s[56:57], 0, v[184:185]
	v_pk_mul_f32 v[136:137], v[172:173], v[98:99]
	s_waitcnt lgkmcnt(0)
	v_pk_fma_f32 v[104:105], v[166:167], v[104:105], v[132:133]
	v_pk_fma_f32 v[102:103], v[168:169], v[102:103], v[130:131]
	v_lshl_add_u64 v[130:131], s[56:57], 0, v[182:183]
	global_store_dwordx4 v[134:135], v[98:101], off nt
	v_pk_mul_f32 v[134:135], v[170:171], v[100:101]
	v_cvt_pk_bf16_f32 v136, v136, v137
	v_pk_mul_f32 v[132:133], v[172:173], v[102:103]
	v_cvt_pk_bf16_f32 v137, v134, v135
	global_store_dwordx4 v[130:131], v[102:105], off nt
	ds_bpermute_b32 v130, v203, v136
	ds_bpermute_b32 v131, v203, v137
	v_pk_mul_f32 v[134:135], v[170:171], v[104:105]
	v_cvt_pk_bf16_f32 v132, v132, v133
	s_nop 0
	v_cvt_pk_bf16_f32 v133, v134, v135
	v_lshlrev_b32_e32 v134, 1, v144
	s_waitcnt lgkmcnt(0)
	v_add_u32_e32 v250, 0xfffff040, v134
	v_cndmask_b32_e64 v250, v134, v250, s[40:41]
	v_cndmask_b32_e64 v248, v142, v130, s[40:41]
	v_cndmask_b32_e64 v249, v143, v131, s[40:41]
	global_store_dwordx2 v250, v[248:249], s[54:55]
	v_cndmask_b32_e64 v246, v130, v142, s[40:41]
	v_cndmask_b32_e64 v247, v131, v143, s[40:41]
	s_waitcnt lgkmcnt(1)
	v_add_u32_e32 v130, 0x1040, v134
	v_cndmask_b32_e64 v130, v134, v130, s[38:39]
	global_store_dwordx2 v130, v[246:247], s[54:55]
	ds_bpermute_b32 v130, v203, v132
	s_waitcnt lgkmcnt(1)
; #define LAS __attribute__((address_space(3)))
; __device__ __forceinline__ unsigned cvt_pk_bf16(float lo, float hi) { unsigned r; asm volatile("v_cvt_pk_bf16_f32 %0, %1, %2" : "=v"(r) : "v"(lo), "v"(hi)); return r; }
; #define ERN_EOFF(q, m) (eb + (unsigned)((((q) & 1) * HALF + (m) * 16) * DM + ERN_COL((q) >> 1)))
;     __device__ __forceinline__ void operator()(const f32x4 (&acc)[2][2][4][2], const Unit& u, int wr, int wc, int fr, int fq) const {
;     ...
;             float sq0 = 0.f, sq1 = 0.f; u32x2 hw[2][2];
; #pragma unroll
;             for (int bj = 0; bj < 2; ++bj) {
;                 *(LAS f32x4*)(st + wr_off) = acc[ai][bj][m][0]; *(LAS f32x4*)(st + wr_off + 64) = acc[ai][bj][m][1];
;                 const f32x4 a0 = *(const LAS f32x4*)(st + rd_off), a1 = *(const LAS f32x4*)(st + rd_off + 8 * 144);
;                 { const f32x4 xv = xb[g & 1][bj][0] + gv[bj] * a0; __builtin_nontemporal_store(xv, (f32x4*)((char*)xo + 4u * ERN_EOFF(g, bj, 0)));
;                   sq0 += (xv.x * xv.x + xv.y * xv.y) + (xv.z * xv.z + xv.w * xv.w);
;                   const f32x4 hv = xv * gsn[bj]; hw[bj][0].x = cvt_pk_bf16(hv.x, hv.y); hw[bj][0].y = cvt_pk_bf16(hv.z, hv.w); }
;                 { const f32x4 xv = xb[g & 1][bj][1] + gv[bj] * a1; __builtin_nontemporal_store(xv, (f32x4*)((char*)xo + 4u * ERN_EOFF(g, bj, 1)));
;                   sq1 += (xv.x * xv.x + xv.y * xv.y) + (xv.z * xv.z + xv.w * xv.w);
;                   const f32x4 hv = xv * gsn[bj]; hw[bj][1].x = cvt_pk_bf16(hv.x, hv.y); hw[bj][1].y = cvt_pk_bf16(hv.z, hv.w); }
;             }
;             if (!NOH && !PLAIN) {
; #pragma unroll
;                 for (int rh = 0; rh < 2; ++rh) { u32x2 rv; rv.x = __shfl_xor(hw[1][rh].x, 8); rv.y = __shfl_xor(hw[1][rh].y, 8);
;                     const unsigned e0 = ERN_EOFF(g, 0, rh);
;                     const unsigned ee = odd ? (e0 - DM + 32) : e0, eo2 = odd ? e0 : (e0 + DM + 32);
;                     *(u32x2*)((char*)ho + 2u * ee) = odd ? rv : hw[0][rh];
;                     *(u32x2*)((char*)ho + 2u * eo2) = odd ? hw[0][rh] : rv; }
;             }
;             if (!PLAIN) { sq0 += __shfl_xor(sq0, 1); sq0 += __shfl_xor(sq0, 2); sq0 += __shfl_xor(sq0, 4);
;             sq1 += __shfl_xor(sq1, 1); sq1 += __shfl_xor(sq1, 2); sq1 += __shfl_xor(sq1, 4); }
;             if (!PLAIN && pc == 0) { sst[g * 16 + rr] = sq0; sst[g * 16 + 8 + rr] = sq1; }
	ds_bpermute_b32 v131, v203, v133
	v_add_u32_e32 v133, 0xc000, v202
	v_lshlrev_b32_e32 v132, 1, v133
	s_waitcnt lgkmcnt(0)
	v_add_u32_e32 v250, 0xfffff040, v132
	v_cndmask_b32_e64 v250, v132, v250, s[40:41]
	v_cndmask_b32_e64 v248, v138, v130, s[40:41]
	v_cndmask_b32_e64 v249, v139, v131, s[40:41]
	global_store_dwordx2 v250, v[248:249], s[54:55]
	v_cndmask_b32_e64 v246, v130, v138, s[40:41]
	v_cndmask_b32_e64 v247, v131, v139, s[40:41]
	v_mul_f32_e32 v99, v99, v99
	v_fmac_f32_e32 v99, v98, v98
	v_mul_f32_e32 v98, v101, v101
	v_mul_f32_e32 v109, v109, v109
	v_fmac_f32_e32 v98, v100, v100
	v_mul_f32_e32 v107, v107, v107
	v_fmac_f32_e32 v109, v108, v108
	v_mul_f32_e32 v108, v111, v111
	v_mul_f32_e32 v111, v113, v113
	v_add_f32_e32 v98, v99, v98
	v_mul_f32_e32 v99, v103, v103
	v_mul_f32_e32 v100, v105, v105
	v_fmac_f32_e32 v111, v112, v112
	v_fmac_f32_e32 v99, v102, v102
	v_fmac_f32_e32 v100, v104, v104
	v_fmac_f32_e32 v107, v106, v106
	v_fmac_f32_e32 v108, v110, v110
	v_add_f32_e32 v99, v99, v100
	v_add_f32_e32 v100, v107, v109
	v_add_f32_e32 v101, v108, v111
	v_add_f32_e32 v98, v100, v98
	v_add_f32_e32 v99, v101, v99
	s_nop 1
	v_mov_b32_dpp v100, v98 quad_perm:[1,0,3,2] row_mask:0xf bank_mask:0xf
	s_nop 1
	v_mov_b32_dpp v101, v99 quad_perm:[1,0,3,2] row_mask:0xf bank_mask:0xf
	s_waitcnt lgkmcnt(1)
	v_add_f32_e32 v98, v98, v100
	s_waitcnt lgkmcnt(0)
	v_add_f32_e32 v101, v99, v101
	s_nop 1
	v_mov_b32_dpp v100, v98 quad_perm:[2,3,0,1] row_mask:0xf bank_mask:0xf
	s_nop 1
	v_mov_b32_dpp v102, v101 quad_perm:[2,3,0,1] row_mask:0xf bank_mask:0xf
	s_waitcnt lgkmcnt(1)
	v_add_f32_e32 v98, v98, v100
	s_waitcnt lgkmcnt(0)
	v_add_f32_e32 v100, v101, v102
	s_nop 1
	v_mov_b32_dpp v99, v98 row_half_mirror row_mask:0xf bank_mask:0xf
	s_nop 1
	v_mov_b32_dpp v101, v100 row_half_mirror row_mask:0xf bank_mask:0xf
	v_add_u32_e32 v102, 0x1040, v132
	v_cndmask_b32_e64 v102, v132, v102, s[38:39]
	global_store_dwordx2 v102, v[246:247], s[54:55]
	s_and_saveexec_b64 s[16:17], s[42:43]
	s_cbranch_execz .LBB0_340
	s_waitcnt lgkmcnt(1)
	v_add_f32_e32 v98, v98, v99
	s_waitcnt lgkmcnt(0)
	v_add_f32_e32 v99, v100, v101
	ds_write2_b32 v194, v98, v99 offset0:16 offset1:24
.LBB0_340:
	s_or_b64 exec, exec, s[16:17]
	v_add_u32_e32 v98, 0x60000, v207
	v_add_u32_e32 v154, 0x70000, v207
	v_add_u32_e32 v132, 0x60080, v207
	global_load_dwordx4 v[106:109], v154, s[58:59]
	global_load_dwordx4 v[102:105], v132, s[58:59]
	v_add_u32_e32 v130, 0x70080, v207
	global_load_dwordx4 v[110:113], v98, s[58:59]
	s_waitcnt lgkmcnt(0)
	global_load_dwordx4 v[98:101], v130, s[58:59]
	ds_write_b128 v200, v[94:97]
	ds_write_b128 v200, v[90:93] offset:64
	ds_read_b128 v[90:93], v201
	ds_read_b128 v[94:97], v201 offset:1152
	v_mov_b32_e32 v191, v155
	v_mov_b32_e32 v189, v155
	v_mov_b32_e32 v187, v155
	s_waitcnt vmcnt(11) lgkmcnt(1)
	v_pk_fma_f32 v[92:93], v[178:179], v[92:93], v[128:129]
	v_add_u32_e32 v128, 0x10000, v202
	v_pk_fma_f32 v[90:91], v[180:181], v[90:91], v[126:127]
	v_lshlrev_b32_e32 v126, 2, v128
	global_store_dwordx4 v126, v[90:93], s[56:57] nt
	v_pk_mul_f32 v[126:127], v[176:177], v[90:91]
	s_waitcnt lgkmcnt(0)
	v_pk_fma_f32 v[96:97], v[178:179], v[96:97], v[124:125]
	v_pk_fma_f32 v[94:95], v[180:181], v[94:95], v[122:123]
	v_lshl_add_u64 v[122:123], s[56:57], 0, v[190:191]
	v_pk_mul_f32 v[134:135], v[174:175], v[92:93]
	v_cvt_pk_bf16_f32 v126, v126, v127
	v_pk_mul_f32 v[124:125], v[174:175], v[96:97]
	v_cvt_pk_bf16_f32 v127, v134, v135
	global_store_dwordx4 v[122:123], v[94:97], off nt
	v_pk_mul_f32 v[122:123], v[176:177], v[94:95]
	s_nop 0
	v_cvt_pk_bf16_f32 v122, v122, v123
	v_cvt_pk_bf16_f32 v123, v124, v125
	ds_write_b128 v200, v[86:89]
	ds_write_b128 v200, v[82:85] offset:64
	ds_read_b128 v[82:85], v201
	ds_read_b128 v[86:89], v201 offset:1152
	s_waitcnt lgkmcnt(1)
	v_pk_fma_f32 v[82:83], v[168:169], v[82:83], v[118:119]
	v_pk_fma_f32 v[84:85], v[166:167], v[84:85], v[120:121]
	v_lshl_add_u64 v[118:119], s[56:57], 0, v[188:189]
	v_pk_mul_f32 v[120:121], v[172:173], v[82:83]
	s_waitcnt vmcnt(12) lgkmcnt(0)
	v_pk_fma_f32 v[88:89], v[166:167], v[88:89], v[116:117]
	v_pk_fma_f32 v[86:87], v[168:169], v[86:87], v[114:115]
	v_lshl_add_u64 v[114:115], s[56:57], 0, v[186:187]
	global_store_dwordx4 v[118:119], v[82:85], off nt
	v_pk_mul_f32 v[118:119], v[170:171], v[84:85]
	v_cvt_pk_bf16_f32 v120, v120, v121
	v_pk_mul_f32 v[116:117], v[172:173], v[86:87]
	v_cvt_pk_bf16_f32 v121, v118, v119
	global_store_dwordx4 v[114:115], v[86:89], off nt
	ds_bpermute_b32 v114, v203, v120
	ds_bpermute_b32 v115, v203, v121
	v_pk_mul_f32 v[118:119], v[170:171], v[88:89]
	v_cvt_pk_bf16_f32 v116, v116, v117
	s_nop 0
	v_cvt_pk_bf16_f32 v117, v118, v119
	v_lshlrev_b32_e32 v118, 1, v128
	s_waitcnt lgkmcnt(0)
	v_add_u32_e32 v250, 0xfffff040, v118
	v_cndmask_b32_e64 v250, v118, v250, s[40:41]
	v_cndmask_b32_e64 v248, v126, v114, s[40:41]
	v_cndmask_b32_e64 v249, v127, v115, s[40:41]
	global_store_dwordx2 v250, v[248:249], s[54:55]
	v_cndmask_b32_e64 v246, v114, v126, s[40:41]
	v_cndmask_b32_e64 v247, v115, v127, s[40:41]
	s_waitcnt lgkmcnt(1)
	v_add_u32_e32 v114, 0x1040, v118
	v_cndmask_b32_e64 v114, v118, v114, s[38:39]
	global_store_dwordx2 v114, v[246:247], s[54:55]
	ds_bpermute_b32 v114, v203, v116
	s_waitcnt lgkmcnt(1)
	ds_bpermute_b32 v115, v203, v117
	v_add_u32_e32 v117, 0x14000, v202
	v_lshlrev_b32_e32 v116, 1, v117
	s_waitcnt lgkmcnt(0)
; #define LAS __attribute__((address_space(3)))
; __device__ __forceinline__ unsigned cvt_pk_bf16(float lo, float hi) { unsigned r; asm volatile("v_cvt_pk_bf16_f32 %0, %1, %2" : "=v"(r) : "v"(lo), "v"(hi)); return r; }
; #define ERN_EOFF(q, m) (eb + (unsigned)((((q) & 1) * HALF + (m) * 16) * DM + ERN_COL((q) >> 1)))
;     __device__ __forceinline__ void operator()(const f32x4 (&acc)[2][2][4][2], const Unit& u, int wr, int wc, int fr, int fq) const {
;     ...
;             float sq0 = 0.f, sq1 = 0.f; u32x2 hw[2][2];
; #pragma unroll
;             for (int bj = 0; bj < 2; ++bj) {
;                 *(LAS f32x4*)(st + wr_off) = acc[ai][bj][m][0]; *(LAS f32x4*)(st + wr_off + 64) = acc[ai][bj][m][1];
;                 const f32x4 a0 = *(const LAS f32x4*)(st + rd_off), a1 = *(const LAS f32x4*)(st + rd_off + 8 * 144);
;                 { const f32x4 xv = xb[g & 1][bj][0] + gv[bj] * a0; __builtin_nontemporal_store(xv, (f32x4*)((char*)xo + 4u * ERN_EOFF(g, bj, 0)));
;                   sq0 += (xv.x * xv.x + xv.y * xv.y) + (xv.z * xv.z + xv.w * xv.w);
;                   const f32x4 hv = xv * gsn[bj]; hw[bj][0].x = cvt_pk_bf16(hv.x, hv.y); hw[bj][0].y = cvt_pk_bf16(hv.z, hv.w); }
;                 { const f32x4 xv = xb[g & 1][bj][1] + gv[bj] * a1; __builtin_nontemporal_store(xv, (f32x4*)((char*)xo + 4u * ERN_EOFF(g, bj, 1)));
;                   sq1 += (xv.x * xv.x + xv.y * xv.y) + (xv.z * xv.z + xv.w * xv.w);
;                   const f32x4 hv = xv * gsn[bj]; hw[bj][1].x = cvt_pk_bf16(hv.x, hv.y); hw[bj][1].y = cvt_pk_bf16(hv.z, hv.w); }
;             }
;             if (!NOH && !PLAIN) {
; #pragma unroll
;                 for (int rh = 0; rh < 2; ++rh) { u32x2 rv; rv.x = __shfl_xor(hw[1][rh].x, 8); rv.y = __shfl_xor(hw[1][rh].y, 8);
;                     const unsigned e0 = ERN_EOFF(g, 0, rh);
;                     const unsigned ee = odd ? (e0 - DM + 32) : e0, eo2 = odd ? e0 : (e0 + DM + 32);
;                     *(u32x2*)((char*)ho + 2u * ee) = odd ? rv : hw[0][rh];
;                     *(u32x2*)((char*)ho + 2u * eo2) = odd ? hw[0][rh] : rv; }
;             }
;             if (!PLAIN) { sq0 += __shfl_xor(sq0, 1); sq0 += __shfl_xor(sq0, 2); sq0 += __shfl_xor(sq0, 4);
;             sq1 += __shfl_xor(sq1, 1); sq1 += __shfl_xor(sq1, 2); sq1 += __shfl_xor(sq1, 4); }
;             if (!PLAIN && pc == 0) { sst[g * 16 + rr] = sq0; sst[g * 16 + 8 + rr] = sq1; }
	v_add_u32_e32 v250, 0xfffff040, v116
	v_cndmask_b32_e64 v250, v116, v250, s[40:41]
	v_cndmask_b32_e64 v248, v122, v114, s[40:41]
	v_cndmask_b32_e64 v249, v123, v115, s[40:41]
	global_store_dwordx2 v250, v[248:249], s[54:55]
	v_cndmask_b32_e64 v246, v114, v122, s[40:41]
	v_cndmask_b32_e64 v247, v115, v123, s[40:41]
	v_mul_f32_e32 v83, v83, v83
	v_fmac_f32_e32 v83, v82, v82
	v_mul_f32_e32 v82, v85, v85
	v_mul_f32_e32 v93, v93, v93
	v_fmac_f32_e32 v82, v84, v84
	v_mul_f32_e32 v91, v91, v91
	v_fmac_f32_e32 v93, v92, v92
	v_mul_f32_e32 v92, v95, v95
	v_mul_f32_e32 v95, v97, v97
	v_add_f32_e32 v82, v83, v82
	v_mul_f32_e32 v83, v87, v87
	v_mul_f32_e32 v84, v89, v89
	v_fmac_f32_e32 v95, v96, v96
	v_fmac_f32_e32 v83, v86, v86
	v_fmac_f32_e32 v84, v88, v88
	v_fmac_f32_e32 v91, v90, v90
	v_fmac_f32_e32 v92, v94, v94
	v_add_f32_e32 v83, v83, v84
	v_add_f32_e32 v84, v91, v93
	v_add_f32_e32 v85, v92, v95
	v_add_f32_e32 v82, v84, v82
	v_add_f32_e32 v83, v85, v83
	s_nop 1
	v_mov_b32_dpp v84, v82 quad_perm:[1,0,3,2] row_mask:0xf bank_mask:0xf
	s_nop 1
	v_mov_b32_dpp v85, v83 quad_perm:[1,0,3,2] row_mask:0xf bank_mask:0xf
	s_waitcnt lgkmcnt(1)
	v_add_f32_e32 v82, v82, v84
	s_waitcnt lgkmcnt(0)
	v_add_f32_e32 v85, v83, v85
	s_nop 1
	v_mov_b32_dpp v84, v82 quad_perm:[2,3,0,1] row_mask:0xf bank_mask:0xf
	s_nop 1
	v_mov_b32_dpp v86, v85 quad_perm:[2,3,0,1] row_mask:0xf bank_mask:0xf
	s_waitcnt lgkmcnt(1)
	v_add_f32_e32 v82, v82, v84
	s_waitcnt lgkmcnt(0)
	v_add_f32_e32 v84, v85, v86
	s_nop 1
	v_mov_b32_dpp v83, v82 row_half_mirror row_mask:0xf bank_mask:0xf
	s_nop 1
	v_mov_b32_dpp v85, v84 row_half_mirror row_mask:0xf bank_mask:0xf
	v_add_u32_e32 v86, 0x1040, v116
	v_cndmask_b32_e64 v86, v116, v86, s[38:39]
	global_store_dwordx2 v86, v[246:247], s[54:55]
	s_and_saveexec_b64 s[16:17], s[42:43]
	s_cbranch_execz .LBB0_350
	s_waitcnt lgkmcnt(1)
	v_add_f32_e32 v82, v82, v83
	s_waitcnt lgkmcnt(0)
	v_add_f32_e32 v83, v84, v85
	ds_write2_b32 v194, v82, v83 offset0:32 offset1:40
.LBB0_350:
	s_or_b64 exec, exec, s[16:17]
	v_add_u32_e32 v82, 0x100000, v207
	s_waitcnt lgkmcnt(1)
	v_add_u32_e32 v83, 0x110000, v207
	v_add_u32_e32 v116, 0x100080, v207
	global_load_dwordx4 v[94:97], v82, s[58:59]
	global_load_dwordx4 v[90:93], v83, s[58:59]
	v_add_u32_e32 v114, 0x110080, v207
	global_load_dwordx4 v[86:89], v116, s[58:59]
	s_waitcnt lgkmcnt(0)
	global_load_dwordx4 v[82:85], v114, s[58:59]
	ds_write_b128 v200, v[78:81]
	ds_write_b128 v200, v[74:77] offset:64
	ds_read_b128 v[74:77], v201
	ds_read_b128 v[78:81], v201 offset:1152
	v_mov_b32_e32 v133, v155
	v_mov_b32_e32 v131, v155
	s_waitcnt vmcnt(11) lgkmcnt(1)
	v_pk_fma_f32 v[76:77], v[178:179], v[76:77], v[112:113]
	v_add_u32_e32 v112, 0x18000, v202
	v_pk_fma_f32 v[74:75], v[180:181], v[74:75], v[110:111]
	v_lshlrev_b32_e32 v110, 2, v112
	global_store_dwordx4 v110, v[74:77], s[56:57] nt
	v_pk_mul_f32 v[110:111], v[176:177], v[74:75]
	s_waitcnt lgkmcnt(0)
	v_pk_fma_f32 v[80:81], v[178:179], v[80:81], v[108:109]
	v_pk_fma_f32 v[78:79], v[180:181], v[78:79], v[106:107]
	v_lshl_add_u64 v[106:107], s[56:57], 0, v[154:155]
	v_pk_mul_f32 v[118:119], v[174:175], v[76:77]
	v_cvt_pk_bf16_f32 v110, v110, v111
	v_pk_mul_f32 v[108:109], v[174:175], v[80:81]
	v_cvt_pk_bf16_f32 v111, v118, v119
	global_store_dwordx4 v[106:107], v[78:81], off nt
	v_pk_mul_f32 v[106:107], v[176:177], v[78:79]
	s_nop 0
	v_cvt_pk_bf16_f32 v106, v106, v107
	v_cvt_pk_bf16_f32 v107, v108, v109
	ds_write_b128 v200, v[70:73]
	ds_write_b128 v200, v[66:69] offset:64
	ds_read_b128 v[66:69], v201
	ds_read_b128 v[70:73], v201 offset:1152
	s_waitcnt lgkmcnt(1)
	v_pk_fma_f32 v[66:67], v[168:169], v[66:67], v[102:103]
	v_pk_fma_f32 v[68:69], v[166:167], v[68:69], v[104:105]
	v_lshl_add_u64 v[102:103], s[56:57], 0, v[132:133]
	v_pk_mul_f32 v[104:105], v[172:173], v[66:67]
	s_waitcnt vmcnt(12) lgkmcnt(0)
	v_pk_fma_f32 v[72:73], v[166:167], v[72:73], v[100:101]
	v_pk_fma_f32 v[70:71], v[168:169], v[70:71], v[98:99]
	v_lshl_add_u64 v[98:99], s[56:57], 0, v[130:131]
	global_store_dwordx4 v[102:103], v[66:69], off nt
	v_pk_mul_f32 v[102:103], v[170:171], v[68:69]
	v_cvt_pk_bf16_f32 v104, v104, v105
	v_pk_mul_f32 v[100:101], v[172:173], v[70:71]
	v_cvt_pk_bf16_f32 v105, v102, v103
	global_store_dwordx4 v[98:99], v[70:73], off nt
	ds_bpermute_b32 v98, v203, v104
	ds_bpermute_b32 v99, v203, v105
	v_pk_mul_f32 v[102:103], v[170:171], v[72:73]
	v_cvt_pk_bf16_f32 v100, v100, v101
	s_nop 0
	v_cvt_pk_bf16_f32 v101, v102, v103
	v_lshlrev_b32_e32 v102, 1, v112
	s_waitcnt lgkmcnt(0)
	v_add_u32_e32 v250, 0xfffff040, v102
	v_cndmask_b32_e64 v250, v102, v250, s[40:41]
	v_cndmask_b32_e64 v248, v110, v98, s[40:41]
	v_cndmask_b32_e64 v249, v111, v99, s[40:41]
	global_store_dwordx2 v250, v[248:249], s[54:55]
	v_cndmask_b32_e64 v246, v98, v110, s[40:41]
	v_cndmask_b32_e64 v247, v99, v111, s[40:41]
	s_waitcnt lgkmcnt(1)
	v_add_u32_e32 v98, 0x1040, v102
	v_cndmask_b32_e64 v98, v102, v98, s[38:39]
	global_store_dwordx2 v98, v[246:247], s[54:55]
	ds_bpermute_b32 v98, v203, v100
	s_waitcnt lgkmcnt(1)
	ds_bpermute_b32 v99, v203, v101
	v_add_u32_e32 v101, 0x1c000, v202
	v_lshlrev_b32_e32 v100, 1, v101
	s_waitcnt lgkmcnt(0)
	v_add_u32_e32 v250, 0xfffff040, v100
	v_cndmask_b32_e64 v250, v100, v250, s[40:41]
	v_cndmask_b32_e64 v248, v106, v98, s[40:41]
	v_cndmask_b32_e64 v249, v107, v99, s[40:41]
	global_store_dwordx2 v250, v[248:249], s[54:55]
	v_cndmask_b32_e64 v246, v98, v106, s[40:41]
	v_cndmask_b32_e64 v247, v99, v107, s[40:41]
	v_mul_f32_e32 v67, v67, v67
	v_fmac_f32_e32 v67, v66, v66
	v_mul_f32_e32 v66, v69, v69
	v_mul_f32_e32 v77, v77, v77
	v_fmac_f32_e32 v66, v68, v68
	v_mul_f32_e32 v75, v75, v75
	v_fmac_f32_e32 v77, v76, v76
	v_mul_f32_e32 v76, v79, v79
	v_mul_f32_e32 v79, v81, v81
	v_add_f32_e32 v66, v67, v66
	v_mul_f32_e32 v67, v71, v71
	v_mul_f32_e32 v68, v73, v73
	v_fmac_f32_e32 v79, v80, v80
	v_fmac_f32_e32 v67, v70, v70
	v_fmac_f32_e32 v68, v72, v72
	v_fmac_f32_e32 v75, v74, v74
	v_fmac_f32_e32 v76, v78, v78
	v_add_f32_e32 v67, v67, v68
	v_add_f32_e32 v68, v75, v77
	v_add_f32_e32 v69, v76, v79
	v_add_f32_e32 v66, v68, v66
	v_add_f32_e32 v67, v69, v67
	s_nop 1
	v_mov_b32_dpp v68, v66 quad_perm:[1,0,3,2] row_mask:0xf bank_mask:0xf
	s_nop 1
	v_mov_b32_dpp v69, v67 quad_perm:[1,0,3,2] row_mask:0xf bank_mask:0xf
	s_waitcnt lgkmcnt(1)
	v_add_f32_e32 v66, v66, v68
	s_waitcnt lgkmcnt(0)
	v_add_f32_e32 v69, v67, v69
	s_nop 1
	v_mov_b32_dpp v68, v66 quad_perm:[2,3,0,1] row_mask:0xf bank_mask:0xf
	s_nop 1
	v_mov_b32_dpp v70, v69 quad_perm:[2,3,0,1] row_mask:0xf bank_mask:0xf
	s_waitcnt lgkmcnt(1)
	v_add_f32_e32 v66, v66, v68
	s_waitcnt lgkmcnt(0)
	v_add_f32_e32 v68, v69, v70
	s_nop 1
	v_mov_b32_dpp v67, v66 row_half_mirror row_mask:0xf bank_mask:0xf
	s_nop 1
	v_mov_b32_dpp v69, v68 row_half_mirror row_mask:0xf bank_mask:0xf
	v_add_u32_e32 v70, 0x1040, v100
	v_cndmask_b32_e64 v70, v100, v70, s[38:39]
	global_store_dwordx2 v70, v[246:247], s[54:55]
	s_and_saveexec_b64 s[16:17], s[42:43]
	s_cbranch_execz .LBB0_360
; #define LAS __attribute__((address_space(3)))
; __device__ __forceinline__ unsigned cvt_pk_bf16(float lo, float hi) { unsigned r; asm volatile("v_cvt_pk_bf16_f32 %0, %1, %2" : "=v"(r) : "v"(lo), "v"(hi)); return r; }
; #define ERN_EOFF(q, m) (eb + (unsigned)((((q) & 1) * HALF + (m) * 16) * DM + ERN_COL((q) >> 1)))
;     __device__ __forceinline__ void operator()(const f32x4 (&acc)[2][2][4][2], const Unit& u, int wr, int wc, int fr, int fq) const {
;     ...
;             float sq0 = 0.f, sq1 = 0.f; u32x2 hw[2][2];
; #pragma unroll
;             for (int bj = 0; bj < 2; ++bj) {
;                 *(LAS f32x4*)(st + wr_off) = acc[ai][bj][m][0]; *(LAS f32x4*)(st + wr_off + 64) = acc[ai][bj][m][1];
;                 const f32x4 a0 = *(const LAS f32x4*)(st + rd_off), a1 = *(const LAS f32x4*)(st + rd_off + 8 * 144);
;                 { const f32x4 xv = xb[g & 1][bj][0] + gv[bj] * a0; __builtin_nontemporal_store(xv, (f32x4*)((char*)xo + 4u * ERN_EOFF(g, bj, 0)));
;                   sq0 += (xv.x * xv.x + xv.y * xv.y) + (xv.z * xv.z + xv.w * xv.w);
;                   const f32x4 hv = xv * gsn[bj]; hw[bj][0].x = cvt_pk_bf16(hv.x, hv.y); hw[bj][0].y = cvt_pk_bf16(hv.z, hv.w); }
;                 { const f32x4 xv = xb[g & 1][bj][1] + gv[bj] * a1; __builtin_nontemporal_store(xv, (f32x4*)((char*)xo + 4u * ERN_EOFF(g, bj, 1)));
;                   sq1 += (xv.x * xv.x + xv.y * xv.y) + (xv.z * xv.z + xv.w * xv.w);
;                   const f32x4 hv = xv * gsn[bj]; hw[bj][1].x = cvt_pk_bf16(hv.x, hv.y); hw[bj][1].y = cvt_pk_bf16(hv.z, hv.w); }
;             }
;             if (!NOH && !PLAIN) {
; #pragma unroll
;                 for (int rh = 0; rh < 2; ++rh) { u32x2 rv; rv.x = __shfl_xor(hw[1][rh].x, 8); rv.y = __shfl_xor(hw[1][rh].y, 8);
;                     const unsigned e0 = ERN_EOFF(g, 0, rh);
;                     const unsigned ee = odd ? (e0 - DM + 32) : e0, eo2 = odd ? e0 : (e0 + DM + 32);
;                     *(u32x2*)((char*)ho + 2u * ee) = odd ? rv : hw[0][rh];
;                     *(u32x2*)((char*)ho + 2u * eo2) = odd ? hw[0][rh] : rv; }
;             }
;             if (!PLAIN) { sq0 += __shfl_xor(sq0, 1); sq0 += __shfl_xor(sq0, 2); sq0 += __shfl_xor(sq0, 4);
;             sq1 += __shfl_xor(sq1, 1); sq1 += __shfl_xor(sq1, 2); sq1 += __shfl_xor(sq1, 4); }
;             if (!PLAIN && pc == 0) { sst[g * 16 + rr] = sq0; sst[g * 16 + 8 + rr] = sq1; }
	s_waitcnt lgkmcnt(1)
	v_add_f32_e32 v66, v66, v67
	s_waitcnt lgkmcnt(0)
	v_add_f32_e32 v67, v68, v69
	ds_write2_b32 v194, v66, v67 offset0:48 offset1:56
.LBB0_360:
	s_or_b64 exec, exec, s[16:17]
	v_add_u32_e32 v154, 0x120000, v207
	v_add_u32_e32 v100, 0x120080, v207
	v_add_u32_e32 v102, 0x130000, v207
	global_load_dwordx4 v[78:81], v154, s[58:59]
	global_load_dwordx4 v[74:77], v102, s[58:59]
	v_add_u32_e32 v98, 0x130080, v207
	global_load_dwordx4 v[70:73], v100, s[58:59]
	s_waitcnt lgkmcnt(0)
	global_load_dwordx4 v[66:69], v98, s[58:59]
	ds_write_b128 v200, v[62:65]
	ds_write_b128 v200, v[58:61] offset:64
	ds_read_b128 v[58:61], v201
	ds_read_b128 v[62:65], v201 offset:1152
	v_mov_b32_e32 v117, v155
	v_mov_b32_e32 v115, v155
	s_waitcnt vmcnt(13) lgkmcnt(1)
	v_pk_fma_f32 v[60:61], v[178:179], v[60:61], v[96:97]
	v_add_u32_e32 v96, 0x40000, v202
	v_pk_fma_f32 v[58:59], v[180:181], v[58:59], v[94:95]
	v_lshlrev_b32_e32 v94, 2, v96
	s_waitcnt vmcnt(12) lgkmcnt(0)
	v_pk_fma_f32 v[64:65], v[178:179], v[64:65], v[92:93]
	v_add_u32_e32 v92, 0x44000, v202
	global_store_dwordx4 v94, v[58:61], s[56:57] nt
	v_pk_mul_f32 v[94:95], v[176:177], v[58:59]
	v_pk_fma_f32 v[62:63], v[180:181], v[62:63], v[90:91]
	v_lshlrev_b32_e32 v90, 2, v92
	v_pk_mul_f32 v[104:105], v[174:175], v[60:61]
	v_cvt_pk_bf16_f32 v94, v94, v95
	s_nop 0
	v_cvt_pk_bf16_f32 v95, v104, v105
	global_store_dwordx4 v90, v[62:65], s[56:57] nt
	v_pk_mul_f32 v[90:91], v[176:177], v[62:63]
	v_pk_mul_f32 v[104:105], v[174:175], v[64:65]
	v_cvt_pk_bf16_f32 v90, v90, v91
	s_nop 0
	v_cvt_pk_bf16_f32 v91, v104, v105
	ds_write_b128 v200, v[54:57]
	ds_write_b128 v200, v[50:53] offset:64
	ds_read_b128 v[50:53], v201
	ds_read_b128 v[54:57], v201 offset:1152
	s_waitcnt vmcnt(13) lgkmcnt(1)
	v_pk_fma_f32 v[50:51], v[168:169], v[50:51], v[86:87]
	v_pk_fma_f32 v[52:53], v[166:167], v[52:53], v[88:89]
	v_lshl_add_u64 v[86:87], s[56:57], 0, v[116:117]
	v_pk_mul_f32 v[88:89], v[172:173], v[50:51]
	s_waitcnt vmcnt(12) lgkmcnt(0)
	v_pk_fma_f32 v[56:57], v[166:167], v[56:57], v[84:85]
	v_pk_fma_f32 v[54:55], v[168:169], v[54:55], v[82:83]
	v_lshl_add_u64 v[82:83], s[56:57], 0, v[114:115]
	global_store_dwordx4 v[86:87], v[50:53], off nt
	v_pk_mul_f32 v[86:87], v[170:171], v[52:53]
	v_cvt_pk_bf16_f32 v88, v88, v89
	v_pk_mul_f32 v[84:85], v[172:173], v[54:55]
	v_cvt_pk_bf16_f32 v89, v86, v87
	global_store_dwordx4 v[82:83], v[54:57], off nt
	ds_bpermute_b32 v82, v203, v88
	ds_bpermute_b32 v83, v203, v89
	v_pk_mul_f32 v[86:87], v[170:171], v[56:57]
	v_cvt_pk_bf16_f32 v84, v84, v85
	s_nop 0
	v_cvt_pk_bf16_f32 v85, v86, v87
	v_lshlrev_b32_e32 v86, 1, v96
	s_waitcnt lgkmcnt(0)
	v_add_u32_e32 v250, 0xfffff040, v86
	v_cndmask_b32_e64 v250, v86, v250, s[40:41]
	v_cndmask_b32_e64 v248, v94, v82, s[40:41]
	v_cndmask_b32_e64 v249, v95, v83, s[40:41]
	global_store_dwordx2 v250, v[248:249], s[54:55]
	v_cndmask_b32_e64 v246, v82, v94, s[40:41]
	v_cndmask_b32_e64 v247, v83, v95, s[40:41]
	s_waitcnt lgkmcnt(1)
	v_add_u32_e32 v82, 0x1040, v86
	v_cndmask_b32_e64 v82, v86, v82, s[38:39]
	global_store_dwordx2 v82, v[246:247], s[54:55]
	ds_bpermute_b32 v82, v203, v84
	s_waitcnt lgkmcnt(1)
	ds_bpermute_b32 v83, v203, v85
	v_lshlrev_b32_e32 v84, 1, v92
	s_waitcnt lgkmcnt(0)
	v_add_u32_e32 v250, 0xfffff040, v84
	v_cndmask_b32_e64 v250, v84, v250, s[40:41]
	v_cndmask_b32_e64 v248, v90, v82, s[40:41]
	v_cndmask_b32_e64 v249, v91, v83, s[40:41]
	global_store_dwordx2 v250, v[248:249], s[54:55]
	v_cndmask_b32_e64 v246, v82, v90, s[40:41]
	v_cndmask_b32_e64 v247, v83, v91, s[40:41]
	v_mul_f32_e32 v51, v51, v51
	v_fmac_f32_e32 v51, v50, v50
	v_mul_f32_e32 v50, v53, v53
	v_mul_f32_e32 v61, v61, v61
	v_fmac_f32_e32 v50, v52, v52
	v_mul_f32_e32 v59, v59, v59
	v_fmac_f32_e32 v61, v60, v60
	v_mul_f32_e32 v60, v63, v63
	v_mul_f32_e32 v63, v65, v65
	v_add_f32_e32 v50, v51, v50
	v_mul_f32_e32 v51, v55, v55
	v_mul_f32_e32 v52, v57, v57
	v_fmac_f32_e32 v63, v64, v64
	v_fmac_f32_e32 v51, v54, v54
	v_fmac_f32_e32 v52, v56, v56
	v_fmac_f32_e32 v59, v58, v58
	v_fmac_f32_e32 v60, v62, v62
	v_add_f32_e32 v51, v51, v52
	v_add_f32_e32 v52, v59, v61
	v_add_f32_e32 v53, v60, v63
	v_add_f32_e32 v50, v52, v50
	v_add_f32_e32 v51, v53, v51
	s_nop 1
	v_mov_b32_dpp v52, v50 quad_perm:[1,0,3,2] row_mask:0xf bank_mask:0xf
	s_nop 1
	v_mov_b32_dpp v53, v51 quad_perm:[1,0,3,2] row_mask:0xf bank_mask:0xf
	s_waitcnt lgkmcnt(1)
	v_add_f32_e32 v50, v50, v52
	s_waitcnt lgkmcnt(0)
	v_add_f32_e32 v53, v51, v53
	s_nop 1
	v_mov_b32_dpp v52, v50 quad_perm:[2,3,0,1] row_mask:0xf bank_mask:0xf
	s_nop 1
	v_mov_b32_dpp v54, v53 quad_perm:[2,3,0,1] row_mask:0xf bank_mask:0xf
	s_waitcnt lgkmcnt(1)
	v_add_f32_e32 v50, v50, v52
	s_waitcnt lgkmcnt(0)
	v_add_f32_e32 v52, v53, v54
	s_nop 1
	v_mov_b32_dpp v51, v50 row_half_mirror row_mask:0xf bank_mask:0xf
	s_nop 1
	v_mov_b32_dpp v53, v52 row_half_mirror row_mask:0xf bank_mask:0xf
	v_add_u32_e32 v54, 0x1040, v84
	v_cndmask_b32_e64 v54, v84, v54, s[38:39]
	global_store_dwordx2 v54, v[246:247], s[54:55]
	s_and_saveexec_b64 s[16:17], s[42:43]
	s_cbranch_execz .LBB0_370
	s_waitcnt lgkmcnt(1)
	v_add_f32_e32 v50, v50, v51
	s_waitcnt lgkmcnt(0)
	v_add_f32_e32 v51, v52, v53
	ds_write2_b32 v194, v50, v51 offset0:64 offset1:72
; #define LAS __attribute__((address_space(3)))
; __device__ __forceinline__ unsigned cvt_pk_bf16(float lo, float hi) { unsigned r; asm volatile("v_cvt_pk_bf16_f32 %0, %1, %2" : "=v"(r) : "v"(lo), "v"(hi)); return r; }
;     __device__ __forceinline__ void operator()(const f32x4 (&acc)[2][2][4][2], const Unit& u, int wr, int wc, int fr, int fq) const {
;     ...
;             if (g + 1 < 8) ERN_LOADX(g + 1);
;             float sq0 = 0.f, sq1 = 0.f; u32x2 hw[2][2];
; #pragma unroll
;             for (int bj = 0; bj < 2; ++bj) {
;                 *(LAS f32x4*)(st + wr_off) = acc[ai][bj][m][0]; *(LAS f32x4*)(st + wr_off + 64) = acc[ai][bj][m][1];
;                 const f32x4 a0 = *(const LAS f32x4*)(st + rd_off), a1 = *(const LAS f32x4*)(st + rd_off + 8 * 144);
;                 { const f32x4 xv = xb[g & 1][bj][0] + gv[bj] * a0; __builtin_nontemporal_store(xv, (f32x4*)((char*)xo + 4u * ERN_EOFF(g, bj, 0)));
;                   sq0 += (xv.x * xv.x + xv.y * xv.y) + (xv.z * xv.z + xv.w * xv.w);
;                   const f32x4 hv = xv * gsn[bj]; hw[bj][0].x = cvt_pk_bf16(hv.x, hv.y); hw[bj][0].y = cvt_pk_bf16(hv.z, hv.w); }
;                 { const f32x4 xv = xb[g & 1][bj][1] + gv[bj] * a1; __builtin_nontemporal_store(xv, (f32x4*)((char*)xo + 4u * ERN_EOFF(g, bj, 1)));
;                   sq1 += (xv.x * xv.x + xv.y * xv.y) + (xv.z * xv.z + xv.w * xv.w);
;                   const f32x4 hv = xv * gsn[bj]; hw[bj][1].x = cvt_pk_bf16(hv.x, hv.y); hw[bj][1].y = cvt_pk_bf16(hv.z, hv.w); }
;             }
;             if (!NOH && !PLAIN) {
; #pragma unroll
;                 for (int rh = 0; rh < 2; ++rh) { u32x2 rv; rv.x = __shfl_xor(hw[1][rh].x, 8); rv.y = __shfl_xor(hw[1][rh].y, 8);
;                     const unsigned e0 = ERN_EOFF(g, 0, rh);
;                     const unsigned ee = odd ? (e0 - DM + 32) : e0, eo2 = odd ? e0 : (e0 + DM + 32);
;                     *(u32x2*)((char*)ho + 2u * ee) = odd ? rv : hw[0][rh];
;                     *(u32x2*)((char*)ho + 2u * eo2) = odd ? hw[0][rh] : rv; }
;             }
;             if (!PLAIN) { sq0 += __shfl_xor(sq0, 1); sq0 += __shfl_xor(sq0, 2); sq0 += __shfl_xor(sq0, 4);
;             sq1 += __shfl_xor(sq1, 1); sq1 += __shfl_xor(sq1, 2); sq1 += __shfl_xor(sq1, 4); }
;             if (!PLAIN && pc == 0) { sst[g * 16 + rr] = sq0; sst[g * 16 + 8 + rr] = sq1; }
.LBB0_370:
	s_or_b64 exec, exec, s[16:17]
	v_add_u32_e32 v88, 0x140000, v207
	v_add_u32_e32 v84, 0x140080, v207
	v_add_u32_e32 v86, 0x150000, v207
	global_load_dwordx4 v[62:65], v88, s[58:59]
	global_load_dwordx4 v[58:61], v86, s[58:59]
	v_add_u32_e32 v82, 0x150080, v207
	global_load_dwordx4 v[54:57], v84, s[58:59]
	s_waitcnt lgkmcnt(0)
	global_load_dwordx4 v[50:53], v82, s[58:59]
	ds_write_b128 v200, v[46:49]
	ds_write_b128 v200, v[42:45] offset:64
	ds_read_b128 v[42:45], v201
	ds_read_b128 v[46:49], v201 offset:1152
	v_mov_b32_e32 v103, v155
	v_mov_b32_e32 v101, v155
	v_mov_b32_e32 v99, v155
	s_waitcnt vmcnt(13) lgkmcnt(1)
	v_pk_fma_f32 v[44:45], v[178:179], v[44:45], v[80:81]
	v_pk_fma_f32 v[42:43], v[180:181], v[42:43], v[78:79]
	v_lshl_add_u64 v[78:79], s[56:57], 0, v[154:155]
	global_store_dwordx4 v[78:79], v[42:45], off nt
	v_pk_mul_f32 v[78:79], v[176:177], v[42:43]
	s_waitcnt vmcnt(13) lgkmcnt(0)
	v_pk_fma_f32 v[48:49], v[178:179], v[48:49], v[76:77]
	v_pk_fma_f32 v[46:47], v[180:181], v[46:47], v[74:75]
	v_lshl_add_u64 v[74:75], s[56:57], 0, v[102:103]
	v_pk_mul_f32 v[80:81], v[174:175], v[44:45]
	v_cvt_pk_bf16_f32 v78, v78, v79
	v_pk_mul_f32 v[76:77], v[174:175], v[48:49]
	v_cvt_pk_bf16_f32 v79, v80, v81
	global_store_dwordx4 v[74:75], v[46:49], off nt
	v_pk_mul_f32 v[74:75], v[176:177], v[46:47]
	s_nop 0
	v_cvt_pk_bf16_f32 v74, v74, v75
	v_cvt_pk_bf16_f32 v75, v76, v77
	ds_write_b128 v200, v[38:41]
	ds_write_b128 v200, v[34:37] offset:64
	ds_read_b128 v[34:37], v201
	ds_read_b128 v[38:41], v201 offset:1152
	s_waitcnt vmcnt(13) lgkmcnt(1)
	v_pk_fma_f32 v[34:35], v[168:169], v[34:35], v[70:71]
	v_pk_fma_f32 v[36:37], v[166:167], v[36:37], v[72:73]
	v_lshl_add_u64 v[70:71], s[56:57], 0, v[100:101]
	v_pk_mul_f32 v[72:73], v[172:173], v[34:35]
	s_waitcnt vmcnt(12) lgkmcnt(0)
	v_pk_fma_f32 v[40:41], v[166:167], v[40:41], v[68:69]
	v_pk_fma_f32 v[38:39], v[168:169], v[38:39], v[66:67]
	v_lshl_add_u64 v[66:67], s[56:57], 0, v[98:99]
	global_store_dwordx4 v[70:71], v[34:37], off nt
	v_pk_mul_f32 v[70:71], v[170:171], v[36:37]
	v_cvt_pk_bf16_f32 v72, v72, v73
	v_pk_mul_f32 v[68:69], v[172:173], v[38:39]
	v_cvt_pk_bf16_f32 v73, v70, v71
	global_store_dwordx4 v[66:67], v[38:41], off nt
	ds_bpermute_b32 v66, v203, v72
	ds_bpermute_b32 v67, v203, v73
	v_pk_mul_f32 v[70:71], v[170:171], v[40:41]
	v_cvt_pk_bf16_f32 v68, v68, v69
	s_nop 0
	v_cvt_pk_bf16_f32 v69, v70, v71
	v_add_u32_e32 v71, 0x48000, v202
	v_lshlrev_b32_e32 v70, 1, v71
	s_waitcnt lgkmcnt(0)
	v_add_u32_e32 v250, 0xfffff040, v70
	v_cndmask_b32_e64 v250, v70, v250, s[40:41]
	v_cndmask_b32_e64 v248, v78, v66, s[40:41]
	v_cndmask_b32_e64 v249, v79, v67, s[40:41]
	global_store_dwordx2 v250, v[248:249], s[54:55]
	v_cndmask_b32_e64 v246, v66, v78, s[40:41]
	v_cndmask_b32_e64 v247, v67, v79, s[40:41]
	s_waitcnt lgkmcnt(1)
	v_add_u32_e32 v66, 0x1040, v70
	v_cndmask_b32_e64 v66, v70, v66, s[38:39]
	global_store_dwordx2 v66, v[246:247], s[54:55]
	ds_bpermute_b32 v66, v203, v68
	s_waitcnt lgkmcnt(1)
	ds_bpermute_b32 v67, v203, v69
	v_add_u32_e32 v69, 0x4c000, v202
	v_lshlrev_b32_e32 v68, 1, v69
	s_waitcnt lgkmcnt(0)
	v_add_u32_e32 v250, 0xfffff040, v68
	v_cndmask_b32_e64 v250, v68, v250, s[40:41]
	v_cndmask_b32_e64 v248, v74, v66, s[40:41]
	v_cndmask_b32_e64 v249, v75, v67, s[40:41]
	global_store_dwordx2 v250, v[248:249], s[54:55]
	v_cndmask_b32_e64 v246, v66, v74, s[40:41]
	v_cndmask_b32_e64 v247, v67, v75, s[40:41]
	v_mul_f32_e32 v35, v35, v35
	v_fmac_f32_e32 v35, v34, v34
	v_mul_f32_e32 v34, v37, v37
	v_mul_f32_e32 v45, v45, v45
	v_fmac_f32_e32 v34, v36, v36
	v_mul_f32_e32 v43, v43, v43
	v_fmac_f32_e32 v45, v44, v44
	v_mul_f32_e32 v44, v47, v47
	v_mul_f32_e32 v47, v49, v49
	v_add_f32_e32 v34, v35, v34
	v_mul_f32_e32 v35, v39, v39
	v_mul_f32_e32 v36, v41, v41
	v_fmac_f32_e32 v47, v48, v48
	v_fmac_f32_e32 v35, v38, v38
	v_fmac_f32_e32 v36, v40, v40
	v_fmac_f32_e32 v43, v42, v42
	v_fmac_f32_e32 v44, v46, v46
	v_add_f32_e32 v35, v35, v36
	v_add_f32_e32 v36, v43, v45
	v_add_f32_e32 v37, v44, v47
	v_add_f32_e32 v34, v36, v34
	v_add_f32_e32 v35, v37, v35
	s_nop 1
	v_mov_b32_dpp v36, v34 quad_perm:[1,0,3,2] row_mask:0xf bank_mask:0xf
	s_nop 1
	v_mov_b32_dpp v37, v35 quad_perm:[1,0,3,2] row_mask:0xf bank_mask:0xf
	s_waitcnt lgkmcnt(1)
	v_add_f32_e32 v34, v34, v36
	s_waitcnt lgkmcnt(0)
	v_add_f32_e32 v37, v35, v37
	s_nop 1
	v_mov_b32_dpp v36, v34 quad_perm:[2,3,0,1] row_mask:0xf bank_mask:0xf
	s_nop 1
	v_mov_b32_dpp v38, v37 quad_perm:[2,3,0,1] row_mask:0xf bank_mask:0xf
	s_waitcnt lgkmcnt(1)
	v_add_f32_e32 v34, v34, v36
	s_waitcnt lgkmcnt(0)
	v_add_f32_e32 v36, v37, v38
	s_nop 1
	v_mov_b32_dpp v35, v34 row_half_mirror row_mask:0xf bank_mask:0xf
	s_nop 1
	v_mov_b32_dpp v37, v36 row_half_mirror row_mask:0xf bank_mask:0xf
	v_add_u32_e32 v38, 0x1040, v68
	v_cndmask_b32_e64 v38, v68, v38, s[38:39]
	global_store_dwordx2 v38, v[246:247], s[54:55]
	s_and_saveexec_b64 s[16:17], s[42:43]
	s_cbranch_execz .LBB0_380
	s_waitcnt lgkmcnt(1)
	v_add_f32_e32 v34, v34, v35
	s_waitcnt lgkmcnt(0)
	v_add_f32_e32 v35, v36, v37
	ds_write2_b32 v194, v34, v35 offset0:80 offset1:88
; #define LAS __attribute__((address_space(3)))
; __device__ __forceinline__ unsigned cvt_pk_bf16(float lo, float hi) { unsigned r; asm volatile("v_cvt_pk_bf16_f32 %0, %1, %2" : "=v"(r) : "v"(lo), "v"(hi)); return r; }
;     __device__ __forceinline__ void operator()(const f32x4 (&acc)[2][2][4][2], const Unit& u, int wr, int wc, int fr, int fq) const {
;     ...
;             if (g + 1 < 8) ERN_LOADX(g + 1);
;             float sq0 = 0.f, sq1 = 0.f; u32x2 hw[2][2];
; #pragma unroll
;             for (int bj = 0; bj < 2; ++bj) {
;                 *(LAS f32x4*)(st + wr_off) = acc[ai][bj][m][0]; *(LAS f32x4*)(st + wr_off + 64) = acc[ai][bj][m][1];
;                 const f32x4 a0 = *(const LAS f32x4*)(st + rd_off), a1 = *(const LAS f32x4*)(st + rd_off + 8 * 144);
;                 { const f32x4 xv = xb[g & 1][bj][0] + gv[bj] * a0; __builtin_nontemporal_store(xv, (f32x4*)((char*)xo + 4u * ERN_EOFF(g, bj, 0)));
;                   sq0 += (xv.x * xv.x + xv.y * xv.y) + (xv.z * xv.z + xv.w * xv.w);
;                   const f32x4 hv = xv * gsn[bj]; hw[bj][0].x = cvt_pk_bf16(hv.x, hv.y); hw[bj][0].y = cvt_pk_bf16(hv.z, hv.w); }
;                 { const f32x4 xv = xb[g & 1][bj][1] + gv[bj] * a1; __builtin_nontemporal_store(xv, (f32x4*)((char*)xo + 4u * ERN_EOFF(g, bj, 1)));
;                   sq1 += (xv.x * xv.x + xv.y * xv.y) + (xv.z * xv.z + xv.w * xv.w);
;                   const f32x4 hv = xv * gsn[bj]; hw[bj][1].x = cvt_pk_bf16(hv.x, hv.y); hw[bj][1].y = cvt_pk_bf16(hv.z, hv.w); }
;             }
;             if (!NOH && !PLAIN) {
; #pragma unroll
;                 for (int rh = 0; rh < 2; ++rh) { u32x2 rv; rv.x = __shfl_xor(hw[1][rh].x, 8); rv.y = __shfl_xor(hw[1][rh].y, 8);
;                     const unsigned e0 = ERN_EOFF(g, 0, rh);
;                     const unsigned ee = odd ? (e0 - DM + 32) : e0, eo2 = odd ? e0 : (e0 + DM + 32);
;                     *(u32x2*)((char*)ho + 2u * ee) = odd ? rv : hw[0][rh];
;                     *(u32x2*)((char*)ho + 2u * eo2) = odd ? hw[0][rh] : rv; }
;             }
;             if (!PLAIN) { sq0 += __shfl_xor(sq0, 1); sq0 += __shfl_xor(sq0, 2); sq0 += __shfl_xor(sq0, 4);
;             sq1 += __shfl_xor(sq1, 1); sq1 += __shfl_xor(sq1, 2); sq1 += __shfl_xor(sq1, 4); }
;             if (!PLAIN && pc == 0) { sst[g * 16 + rr] = sq0; sst[g * 16 + 8 + rr] = sq1; }
.LBB0_380:
	s_or_b64 exec, exec, s[16:17]
	v_add_u32_e32 v154, 0x160000, v207
	v_add_u32_e32 v68, 0x160080, v207
	v_add_u32_e32 v70, 0x170000, v207
	global_load_dwordx4 v[46:49], v154, s[58:59]
	global_load_dwordx4 v[42:45], v70, s[58:59]
	v_add_u32_e32 v66, 0x170080, v207
	global_load_dwordx4 v[38:41], v68, s[58:59]
	s_waitcnt lgkmcnt(0)
	global_load_dwordx4 v[34:37], v66, s[58:59]
	ds_write_b128 v200, v[30:33]
	ds_write_b128 v200, v[26:29] offset:64
	ds_read_b128 v[26:29], v201
	ds_read_b128 v[30:33], v201 offset:1152
	v_mov_b32_e32 v89, v155
	v_mov_b32_e32 v87, v155
	v_mov_b32_e32 v85, v155
	s_waitcnt vmcnt(13) lgkmcnt(1)
	v_pk_fma_f32 v[28:29], v[178:179], v[28:29], v[64:65]
	v_pk_fma_f32 v[26:27], v[180:181], v[26:27], v[62:63]
	v_lshl_add_u64 v[62:63], s[56:57], 0, v[88:89]
	global_store_dwordx4 v[62:63], v[26:29], off nt
	v_pk_mul_f32 v[62:63], v[176:177], v[26:27]
	s_waitcnt vmcnt(13) lgkmcnt(0)
	v_pk_fma_f32 v[32:33], v[178:179], v[32:33], v[60:61]
	v_pk_fma_f32 v[30:31], v[180:181], v[30:31], v[58:59]
	v_lshl_add_u64 v[58:59], s[56:57], 0, v[86:87]
	v_pk_mul_f32 v[64:65], v[174:175], v[28:29]
	v_cvt_pk_bf16_f32 v62, v62, v63
	v_pk_mul_f32 v[60:61], v[174:175], v[32:33]
	v_cvt_pk_bf16_f32 v63, v64, v65
	global_store_dwordx4 v[58:59], v[30:33], off nt
	v_pk_mul_f32 v[58:59], v[176:177], v[30:31]
	v_mov_b32_e32 v83, v155
	v_cvt_pk_bf16_f32 v58, v58, v59
	v_cvt_pk_bf16_f32 v59, v60, v61
	ds_write_b128 v200, v[22:25]
	ds_write_b128 v200, v[18:21] offset:64
	ds_read_b128 v[18:21], v201
	ds_read_b128 v[22:25], v201 offset:1152
	s_waitcnt vmcnt(13) lgkmcnt(1)
	v_pk_fma_f32 v[18:19], v[168:169], v[18:19], v[54:55]
	v_pk_fma_f32 v[20:21], v[166:167], v[20:21], v[56:57]
	v_lshl_add_u64 v[54:55], s[56:57], 0, v[84:85]
	v_pk_mul_f32 v[56:57], v[172:173], v[18:19]
	s_waitcnt vmcnt(12) lgkmcnt(0)
	v_pk_fma_f32 v[24:25], v[166:167], v[24:25], v[52:53]
	v_pk_fma_f32 v[22:23], v[168:169], v[22:23], v[50:51]
	v_lshl_add_u64 v[50:51], s[56:57], 0, v[82:83]
	global_store_dwordx4 v[54:55], v[18:21], off nt
	v_pk_mul_f32 v[54:55], v[170:171], v[20:21]
	v_cvt_pk_bf16_f32 v56, v56, v57
	v_pk_mul_f32 v[52:53], v[172:173], v[22:23]
	v_cvt_pk_bf16_f32 v57, v54, v55
	global_store_dwordx4 v[50:51], v[22:25], off nt
	ds_bpermute_b32 v50, v203, v56
	ds_bpermute_b32 v51, v203, v57
	v_pk_mul_f32 v[54:55], v[170:171], v[24:25]
	v_cvt_pk_bf16_f32 v52, v52, v53
	s_nop 0
	v_cvt_pk_bf16_f32 v53, v54, v55
	v_add_u32_e32 v55, 0x50000, v202
	v_lshlrev_b32_e32 v54, 1, v55
	s_waitcnt lgkmcnt(0)
	v_add_u32_e32 v250, 0xfffff040, v54
	v_cndmask_b32_e64 v250, v54, v250, s[40:41]
	v_cndmask_b32_e64 v248, v62, v50, s[40:41]
	v_cndmask_b32_e64 v249, v63, v51, s[40:41]
	global_store_dwordx2 v250, v[248:249], s[54:55]
	v_cndmask_b32_e64 v246, v50, v62, s[40:41]
	v_cndmask_b32_e64 v247, v51, v63, s[40:41]
	s_waitcnt lgkmcnt(1)
	v_add_u32_e32 v50, 0x1040, v54
	v_cndmask_b32_e64 v50, v54, v50, s[38:39]
	global_store_dwordx2 v50, v[246:247], s[54:55]
	ds_bpermute_b32 v50, v203, v52
	s_waitcnt lgkmcnt(1)
	ds_bpermute_b32 v51, v203, v53
	v_add_u32_e32 v53, 0x54000, v202
	v_lshlrev_b32_e32 v52, 1, v53
	s_waitcnt lgkmcnt(0)
	v_add_u32_e32 v250, 0xfffff040, v52
	v_cndmask_b32_e64 v250, v52, v250, s[40:41]
	v_cndmask_b32_e64 v248, v58, v50, s[40:41]
	v_cndmask_b32_e64 v249, v59, v51, s[40:41]
	global_store_dwordx2 v250, v[248:249], s[54:55]
	v_cndmask_b32_e64 v246, v50, v58, s[40:41]
	v_cndmask_b32_e64 v247, v51, v59, s[40:41]
	v_mul_f32_e32 v19, v19, v19
	v_fmac_f32_e32 v19, v18, v18
	v_mul_f32_e32 v18, v21, v21
	v_mul_f32_e32 v29, v29, v29
	v_fmac_f32_e32 v18, v20, v20
	v_mul_f32_e32 v27, v27, v27
	v_fmac_f32_e32 v29, v28, v28
	v_mul_f32_e32 v28, v31, v31
	v_mul_f32_e32 v31, v33, v33
	v_add_f32_e32 v18, v19, v18
	v_mul_f32_e32 v19, v23, v23
	v_mul_f32_e32 v20, v25, v25
	v_fmac_f32_e32 v31, v32, v32
	v_fmac_f32_e32 v19, v22, v22
	v_fmac_f32_e32 v20, v24, v24
	v_fmac_f32_e32 v27, v26, v26
	v_fmac_f32_e32 v28, v30, v30
	v_add_f32_e32 v19, v19, v20
	v_add_f32_e32 v20, v27, v29
	v_add_f32_e32 v21, v28, v31
	v_add_f32_e32 v18, v20, v18
	v_add_f32_e32 v19, v21, v19
	s_nop 1
	v_mov_b32_dpp v20, v18 quad_perm:[1,0,3,2] row_mask:0xf bank_mask:0xf
	s_nop 1
	v_mov_b32_dpp v21, v19 quad_perm:[1,0,3,2] row_mask:0xf bank_mask:0xf
	s_waitcnt lgkmcnt(1)
	v_add_f32_e32 v18, v18, v20
	s_waitcnt lgkmcnt(0)
	v_add_f32_e32 v21, v19, v21
	s_nop 1
	v_mov_b32_dpp v20, v18 quad_perm:[2,3,0,1] row_mask:0xf bank_mask:0xf
	s_nop 1
	v_mov_b32_dpp v22, v21 quad_perm:[2,3,0,1] row_mask:0xf bank_mask:0xf
	s_waitcnt lgkmcnt(1)
	v_add_f32_e32 v18, v18, v20
	s_waitcnt lgkmcnt(0)
	v_add_f32_e32 v20, v21, v22
	s_nop 1
	v_mov_b32_dpp v19, v18 row_half_mirror row_mask:0xf bank_mask:0xf
	s_nop 1
	v_mov_b32_dpp v21, v20 row_half_mirror row_mask:0xf bank_mask:0xf
	v_add_u32_e32 v22, 0x1040, v52
	v_cndmask_b32_e64 v22, v52, v22, s[38:39]
	global_store_dwordx2 v22, v[246:247], s[54:55]
	s_and_saveexec_b64 s[16:17], s[42:43]
	s_cbranch_execz .LBB0_390
	s_waitcnt lgkmcnt(1)
	v_add_f32_e32 v18, v18, v19
	s_waitcnt lgkmcnt(0)
	v_add_f32_e32 v19, v20, v21
	ds_write2_b32 v194, v18, v19 offset0:96 offset1:104
; #define LAS __attribute__((address_space(3)))
; __device__ __forceinline__ unsigned cvt_pk_bf16(float lo, float hi) { unsigned r; asm volatile("v_cvt_pk_bf16_f32 %0, %1, %2" : "=v"(r) : "v"(lo), "v"(hi)); return r; }
;     __device__ __forceinline__ void operator()(const f32x4 (&acc)[2][2][4][2], const Unit& u, int wr, int wc, int fr, int fq) const {
;     ...
;             if (g + 1 < 8) ERN_LOADX(g + 1);
;             float sq0 = 0.f, sq1 = 0.f; u32x2 hw[2][2];
; #pragma unroll
;             for (int bj = 0; bj < 2; ++bj) {
;                 *(LAS f32x4*)(st + wr_off) = acc[ai][bj][m][0]; *(LAS f32x4*)(st + wr_off + 64) = acc[ai][bj][m][1];
;                 const f32x4 a0 = *(const LAS f32x4*)(st + rd_off), a1 = *(const LAS f32x4*)(st + rd_off + 8 * 144);
;                 { const f32x4 xv = xb[g & 1][bj][0] + gv[bj] * a0; __builtin_nontemporal_store(xv, (f32x4*)((char*)xo + 4u * ERN_EOFF(g, bj, 0)));
;                   sq0 += (xv.x * xv.x + xv.y * xv.y) + (xv.z * xv.z + xv.w * xv.w);
;                   const f32x4 hv = xv * gsn[bj]; hw[bj][0].x = cvt_pk_bf16(hv.x, hv.y); hw[bj][0].y = cvt_pk_bf16(hv.z, hv.w); }
;                 { const f32x4 xv = xb[g & 1][bj][1] + gv[bj] * a1; __builtin_nontemporal_store(xv, (f32x4*)((char*)xo + 4u * ERN_EOFF(g, bj, 1)));
;                   sq1 += (xv.x * xv.x + xv.y * xv.y) + (xv.z * xv.z + xv.w * xv.w);
;                   const f32x4 hv = xv * gsn[bj]; hw[bj][1].x = cvt_pk_bf16(hv.x, hv.y); hw[bj][1].y = cvt_pk_bf16(hv.z, hv.w); }
;             }
;             if (!NOH && !PLAIN) {
; #pragma unroll
;                 for (int rh = 0; rh < 2; ++rh) { u32x2 rv; rv.x = __shfl_xor(hw[1][rh].x, 8); rv.y = __shfl_xor(hw[1][rh].y, 8);
;                     const unsigned e0 = ERN_EOFF(g, 0, rh);
;                     const unsigned ee = odd ? (e0 - DM + 32) : e0, eo2 = odd ? e0 : (e0 + DM + 32);
;                     *(u32x2*)((char*)ho + 2u * ee) = odd ? rv : hw[0][rh];
;                     *(u32x2*)((char*)ho + 2u * eo2) = odd ? hw[0][rh] : rv; }
;             }
;             if (!PLAIN) { sq0 += __shfl_xor(sq0, 1); sq0 += __shfl_xor(sq0, 2); sq0 += __shfl_xor(sq0, 4);
;             sq1 += __shfl_xor(sq1, 1); sq1 += __shfl_xor(sq1, 2); sq1 += __shfl_xor(sq1, 4); }
;             if (!PLAIN && pc == 0) { sst[g * 16 + rr] = sq0; sst[g * 16 + 8 + rr] = sq1; }
.LBB0_390:
	s_or_b64 exec, exec, s[16:17]
	ds_write_b128 v200, v[14:17]
	ds_write_b128 v200, v[10:13] offset:64
	ds_read_b128 v[10:13], v201
	ds_read_b128 v[14:17], v201 offset:1152
	s_waitcnt lgkmcnt(5)
	v_lshl_add_u64 v[18:19], s[56:57], 0, v[154:155]
	v_mov_b32_e32 v71, v155
	v_mov_b32_e32 v69, v155
	s_waitcnt vmcnt(9) lgkmcnt(1)
	v_pk_fma_f32 v[12:13], v[178:179], v[12:13], v[48:49]
	v_pk_fma_f32 v[10:11], v[180:181], v[10:11], v[46:47]
	global_store_dwordx4 v[18:19], v[10:13], off nt
	v_pk_mul_f32 v[18:19], v[174:175], v[12:13]
	v_pk_mul_f32 v[20:21], v[176:177], v[10:11]
	s_waitcnt vmcnt(9) lgkmcnt(0)
	v_pk_fma_f32 v[16:17], v[178:179], v[16:17], v[44:45]
	v_cvt_pk_bf16_f32 v20, v20, v21
	v_cvt_pk_bf16_f32 v21, v18, v19
	v_pk_fma_f32 v[14:15], v[180:181], v[14:15], v[42:43]
	v_lshl_add_u64 v[18:19], s[56:57], 0, v[70:71]
	global_store_dwordx4 v[18:19], v[14:17], off nt
	v_pk_mul_f32 v[18:19], v[176:177], v[14:15]
	v_pk_mul_f32 v[22:23], v[174:175], v[16:17]
	v_cvt_pk_bf16_f32 v18, v18, v19
	v_mov_b32_e32 v67, v155
	v_cvt_pk_bf16_f32 v19, v22, v23
	ds_write_b128 v200, v[6:9]
	ds_write_b128 v200, v[2:5] offset:64
	ds_read_b128 v[2:5], v201
	ds_read_b128 v[6:9], v201 offset:1152
	v_lshl_add_u64 v[22:23], s[56:57], 0, v[68:69]
	s_waitcnt vmcnt(9) lgkmcnt(1)
	v_pk_fma_f32 v[4:5], v[166:167], v[4:5], v[40:41]
	v_pk_fma_f32 v[2:3], v[168:169], v[2:3], v[38:39]
	global_store_dwordx4 v[22:23], v[2:5], off nt
	v_pk_mul_f32 v[22:23], v[170:171], v[4:5]
	v_pk_mul_f32 v[24:25], v[172:173], v[2:3]
	s_waitcnt vmcnt(9) lgkmcnt(0)
	v_pk_fma_f32 v[8:9], v[166:167], v[8:9], v[36:37]
	v_cvt_pk_bf16_f32 v28, v24, v25
	v_cvt_pk_bf16_f32 v29, v22, v23
	v_pk_fma_f32 v[6:7], v[168:169], v[6:7], v[34:35]
	v_lshl_add_u64 v[22:23], s[56:57], 0, v[66:67]
	global_store_dwordx4 v[22:23], v[6:9], off nt
	ds_bpermute_b32 v22, v203, v28
	ds_bpermute_b32 v23, v203, v29
	v_pk_mul_f32 v[26:27], v[170:171], v[8:9]
	v_pk_mul_f32 v[24:25], v[172:173], v[6:7]
	s_nop 0
	v_cvt_pk_bf16_f32 v24, v24, v25
	v_cvt_pk_bf16_f32 v25, v26, v27
	v_add_u32_e32 v27, 0x58000, v202
	v_lshlrev_b32_e32 v26, 1, v27
	s_waitcnt lgkmcnt(0)
	v_add_u32_e32 v250, 0xfffff040, v26
	v_cndmask_b32_e64 v250, v26, v250, s[40:41]
	v_cndmask_b32_e64 v248, v20, v22, s[40:41]
	v_cndmask_b32_e64 v249, v21, v23, s[40:41]
	global_store_dwordx2 v250, v[248:249], s[54:55]
	v_cndmask_b32_e64 v246, v22, v20, s[40:41]
	v_cndmask_b32_e64 v247, v23, v21, s[40:41]
	s_waitcnt lgkmcnt(1)
	v_add_u32_e32 v22, 0x1040, v26
	v_cndmask_b32_e64 v22, v26, v22, s[38:39]
	global_store_dwordx2 v22, v[246:247], s[54:55]
	ds_bpermute_b32 v20, v203, v24
	ds_bpermute_b32 v21, v203, v25
	s_waitcnt lgkmcnt(2)
	v_add_u32_e32 v23, 0x5c000, v202
	v_lshlrev_b32_e32 v22, 1, v23
	s_waitcnt lgkmcnt(0)
	v_add_u32_e32 v250, 0xfffff040, v22
	v_cndmask_b32_e64 v250, v22, v250, s[40:41]
	v_cndmask_b32_e64 v248, v18, v20, s[40:41]
	v_cndmask_b32_e64 v249, v19, v21, s[40:41]
	global_store_dwordx2 v250, v[248:249], s[54:55]
	v_cndmask_b32_e64 v246, v20, v18, s[40:41]
	v_cndmask_b32_e64 v247, v21, v19, s[40:41]
	v_mul_f32_e32 v3, v3, v3
	v_fmac_f32_e32 v3, v2, v2
	v_mul_f32_e32 v2, v5, v5
	v_mul_f32_e32 v13, v13, v13
	v_fmac_f32_e32 v2, v4, v4
	v_mul_f32_e32 v11, v11, v11
	v_fmac_f32_e32 v13, v12, v12
	v_mul_f32_e32 v12, v15, v15
	v_mul_f32_e32 v15, v17, v17
	v_add_f32_e32 v2, v3, v2
	v_mul_f32_e32 v3, v7, v7
	v_mul_f32_e32 v4, v9, v9
	v_fmac_f32_e32 v15, v16, v16
	v_fmac_f32_e32 v3, v6, v6
	v_fmac_f32_e32 v4, v8, v8
	v_fmac_f32_e32 v11, v10, v10
	v_fmac_f32_e32 v12, v14, v14
	v_add_f32_e32 v3, v3, v4
	v_add_f32_e32 v4, v11, v13
	v_add_f32_e32 v5, v12, v15
	v_add_f32_e32 v2, v4, v2
	v_add_f32_e32 v3, v5, v3
	s_nop 1
	v_mov_b32_dpp v4, v2 quad_perm:[1,0,3,2] row_mask:0xf bank_mask:0xf
	s_nop 1
	v_mov_b32_dpp v5, v3 quad_perm:[1,0,3,2] row_mask:0xf bank_mask:0xf
	s_waitcnt lgkmcnt(1)
	v_add_f32_e32 v2, v2, v4
	s_waitcnt lgkmcnt(0)
	v_add_f32_e32 v5, v3, v5
	s_nop 1
	v_mov_b32_dpp v4, v2 quad_perm:[2,3,0,1] row_mask:0xf bank_mask:0xf
	s_nop 1
	v_mov_b32_dpp v6, v5 quad_perm:[2,3,0,1] row_mask:0xf bank_mask:0xf
	s_waitcnt lgkmcnt(1)
	v_add_f32_e32 v2, v2, v4
	s_waitcnt lgkmcnt(0)
	v_add_f32_e32 v4, v5, v6
	s_nop 1
	v_mov_b32_dpp v3, v2 row_half_mirror row_mask:0xf bank_mask:0xf
	s_nop 1
	v_mov_b32_dpp v5, v4 row_half_mirror row_mask:0xf bank_mask:0xf
	v_add_u32_e32 v6, 0x1040, v22
	v_cndmask_b32_e64 v6, v22, v6, s[38:39]
	global_store_dwordx2 v6, v[246:247], s[54:55]
	s_and_saveexec_b64 s[16:17], s[42:43]
	s_cbranch_execz .LBB0_400
	s_waitcnt lgkmcnt(1)
	v_add_f32_e32 v2, v2, v3
	s_waitcnt lgkmcnt(0)
	v_add_f32_e32 v3, v4, v5
	ds_write2_b32 v194, v2, v3 offset0:112 offset1:120

; #define LAS __attribute__((address_space(3)))
; #define ERN_EOFF(q, m) (eb + (unsigned)((((q) & 1) * HALF + (m) * 16) * DM + ERN_COL((q) >> 1)))
;     __device__ __forceinline__ void operator()(const f32x4 (&acc)[2][2][4][2], const Unit& u, int wr, int wc, int fr, int fq) const {
;     ...
;         for (int g = 0; g < 8; ++g) { const int ai = g >> 2, m = g & 3;
;             if (g + 1 < 8) ERN_LOADX(g + 1);
;             float sq0 = 0.f, sq1 = 0.f; u32x2 hw[2][2];
; #pragma unroll
;             for (int bj = 0; bj < 2; ++bj) {
;                 *(LAS f32x4*)(st + wr_off) = acc[ai][bj][m][0]; *(LAS f32x4*)(st + wr_off + 64) = acc[ai][bj][m][1];
;                 const f32x4 a0 = *(const LAS f32x4*)(st + rd_off), a1 = *(const LAS f32x4*)(st + rd_off + 8 * 144);
;                 { const f32x4 xv = xb[g & 1][bj][0] + gv[bj] * a0; __builtin_nontemporal_store(xv, (f32x4*)((char*)xo + 4u * ERN_EOFF(g, bj, 0)));
;                   sq0 += (xv.x * xv.x + xv.y * xv.y) + (xv.z * xv.z + xv.w * xv.w);
;                   const f32x4 hv = xv * gsn[bj]; hw[bj][0].x = cvt_pk_bf16(hv.x, hv.y); hw[bj][0].y = cvt_pk_bf16(hv.z, hv.w); }
;                 { const f32x4 xv = xb[g & 1][bj][1] + gv[bj] * a1; __builtin_nontemporal_store(xv, (f32x4*)((char*)xo + 4u * ERN_EOFF(g, bj, 1)));
;                   sq1 += (xv.x * xv.x + xv.y * xv.y) + (xv.z * xv.z + xv.w * xv.w);
;                   const f32x4 hv = xv * gsn[bj]; hw[bj][1].x = cvt_pk_bf16(hv.x, hv.y); hw[bj][1].y = cvt_pk_bf16(hv.z, hv.w); }
;             }
;             if (!NOH && !PLAIN) {
; #pragma unroll
;                 for (int rh = 0; rh < 2; ++rh) { u32x2 rv; rv.x = __shfl_xor(hw[1][rh].x, 8); rv.y = __shfl_xor(hw[1][rh].y, 8);
;                     const unsigned e0 = ERN_EOFF(g, 0, rh);
;                     const unsigned ee = odd ? (e0 - DM + 32) : e0, eo2 = odd ? e0 : (e0 + DM + 32);
;                     *(u32x2*)((char*)ho + 2u * ee) = odd ? rv : hw[0][rh];
;                     *(u32x2*)((char*)ho + 2u * eo2) = odd ? hw[0][rh] : rv; }
;             }
;             if (!PLAIN) { sq0 += __shfl_xor(sq0, 1); sq0 += __shfl_xor(sq0, 2); sq0 += __shfl_xor(sq0, 4);
;             sq1 += __shfl_xor(sq1, 1); sq1 += __shfl_xor(sq1, 2); sq1 += __shfl_xor(sq1, 4); }
;             if (!PLAIN && pc == 0) { sst[g * 16 + rr] = sq0; sst[g * 16 + 8 + rr] = sq1; }
.LBB0_1261:
	s_or_b64 exec, exec, s[16:17]
	v_mul_f32_e32 v127, v127, v127
	v_mul_f32_e32 v135, v135, v135
	v_mul_f32_e32 v137, v137, v137
	v_fmac_f32_e32 v127, v126, v126
	v_mul_f32_e32 v126, v129, v129
	v_fmac_f32_e32 v137, v136, v136
	v_fmac_f32_e32 v126, v128, v128
	v_mul_f32_e32 v123, v123, v123
	v_fmac_f32_e32 v135, v134, v134
	v_add_f32_e32 v126, v127, v126
	v_fmac_f32_e32 v123, v122, v122
	v_mul_f32_e32 v122, v125, v125
	v_add_f32_e32 v125, v135, v137
	v_add_f32_e32 v125, v125, v126
	v_xor_b32_e32 v126, 1, v199
	v_cmp_lt_i32_e32 vcc, v126, v183
	v_mul_f32_e32 v131, v131, v131
	v_mul_f32_e32 v133, v133, v133
	v_cndmask_b32_e32 v126, v199, v126, vcc
	v_lshlrev_b32_e32 v190, 2, v126
	s_nop 1
	v_mov_b32_dpp v126, v125 quad_perm:[1,0,3,2] row_mask:0xf bank_mask:0xf
	v_fmac_f32_e32 v122, v124, v124
	v_fmac_f32_e32 v133, v132, v132
	v_fmac_f32_e32 v131, v130, v130
	v_add_f32_e32 v122, v123, v122
	s_waitcnt lgkmcnt(0)
	v_add_f32_e32 v124, v125, v126
	v_xor_b32_e32 v125, 2, v199
	v_cmp_lt_i32_e32 vcc, v125, v183
	v_add_f32_e32 v123, v131, v133
	v_add_f32_e32 v123, v123, v122
	v_cndmask_b32_e32 v125, v199, v125, vcc
	v_lshlrev_b32_e32 v191, 2, v125
	s_nop 1
	v_mov_b32_dpp v125, v124 quad_perm:[2,3,0,1] row_mask:0xf bank_mask:0xf
	s_nop 1
	v_mov_b32_dpp v126, v123 quad_perm:[1,0,3,2] row_mask:0xf bank_mask:0xf
	s_waitcnt lgkmcnt(1)
	v_add_f32_e32 v122, v124, v125
	s_waitcnt lgkmcnt(0)
	v_add_f32_e32 v125, v123, v126
	s_nop 1
	v_mov_b32_dpp v126, v125 quad_perm:[2,3,0,1] row_mask:0xf bank_mask:0xf
	v_xor_b32_e32 v124, 4, v199
	v_cmp_lt_i32_e32 vcc, v124, v183
	s_nop 1
	v_cndmask_b32_e32 v123, v199, v124, vcc
	v_lshlrev_b32_e32 v204, 2, v123
	s_waitcnt lgkmcnt(0)
	v_add_f32_e32 v124, v125, v126
	s_nop 1
	v_mov_b32_dpp v123, v122 row_half_mirror row_mask:0xf bank_mask:0xf
	s_nop 1
	v_mov_b32_dpp v125, v124 row_half_mirror row_mask:0xf bank_mask:0xf
	v_add_u32_e32 v126, 0x1040, v206
	v_cndmask_b32_e64 v126, v206, v126, s[38:39]
	global_store_dwordx2 v126, v[186:187], s[46:47]
	s_and_saveexec_b64 s[16:17], s[42:43]
	s_cbranch_execz .LBB0_1263
	s_waitcnt lgkmcnt(1)
	v_add_f32_e32 v122, v122, v123
	s_waitcnt lgkmcnt(0)
	v_add_f32_e32 v123, v124, v125
	ds_write2_b32 v194, v122, v123 offset1:8
.LBB0_1263:
	s_or_b64 exec, exec, s[16:17]
	v_lshl_add_u64 v[206:207], s[48:49], 0, v[162:163]
	v_add_u32_e32 v122, 0x40000, v205
	v_add_u32_e32 v162, 0x50000, v205
	v_add_u32_e32 v186, 0x40080, v205
	global_load_dwordx4 v[130:133], v162, s[48:49]
	global_load_dwordx4 v[126:129], v186, s[48:49]
	v_add_u32_e32 v188, 0x50080, v205
	global_load_dwordx4 v[134:137], v122, s[48:49]
	s_waitcnt lgkmcnt(0)
	global_load_dwordx4 v[122:125], v188, s[48:49]
	ds_write_b128 v200, v[118:121]
	ds_write_b128 v200, v[114:117] offset:64
	ds_read_b128 v[114:117], v201
	ds_read_b128 v[118:121], v201 offset:1152
	v_mov_b32_e32 v185, v163
	v_mov_b32_e32 v183, v163
	v_lshl_add_u64 v[182:183], s[48:49], 0, v[182:183]
	s_waitcnt lgkmcnt(1)
	v_pk_fma_f32 v[116:117], v[56:57], v[116:117], v[152:153]
	v_add_u32_e32 v152, 0x8000, v202
	v_pk_fma_f32 v[114:115], v[54:55], v[114:115], v[150:151]
	v_lshlrev_b32_e32 v150, 2, v152
	s_waitcnt lgkmcnt(0)
	v_pk_fma_f32 v[118:119], v[54:55], v[118:119], v[146:147]
	global_store_dwordx4 v150, v[114:117], s[48:49] nt
	v_pk_mul_f32 v[150:151], v[180:181], v[114:115]
	v_pk_fma_f32 v[120:121], v[56:57], v[120:121], v[148:149]
	v_pk_mul_f32 v[146:147], v[180:181], v[118:119]
	v_pk_mul_f32 v[208:209], v[178:179], v[116:117]
	v_cvt_pk_bf16_f32 v150, v150, v151
	v_pk_mul_f32 v[148:149], v[178:179], v[120:121]
	v_cvt_pk_bf16_f32 v151, v208, v209
	global_store_dwordx4 v[206:207], v[118:121], off nt
	v_cvt_pk_bf16_f32 v146, v146, v147
	v_cvt_pk_bf16_f32 v147, v148, v149
	ds_write_b128 v200, v[110:113]
	ds_write_b128 v200, v[106:109] offset:64
	ds_read_b128 v[106:109], v201
	ds_read_b128 v[110:113], v201 offset:1152
	v_lshl_add_u64 v[148:149], s[48:49], 0, v[184:185]
	s_waitcnt lgkmcnt(1)
	v_pk_fma_f32 v[106:107], v[50:51], v[106:107], v[142:143]
	v_pk_fma_f32 v[108:109], v[52:53], v[108:109], v[144:145]
	v_pk_mul_f32 v[144:145], v[176:177], v[106:107]
	global_store_dwordx4 v[148:149], v[106:109], off nt
	v_pk_mul_f32 v[142:143], v[174:175], v[108:109]
	v_cvt_pk_bf16_f32 v144, v144, v145
	s_waitcnt lgkmcnt(0)
	v_pk_fma_f32 v[110:111], v[50:51], v[110:111], v[138:139]
	v_cvt_pk_bf16_f32 v145, v142, v143
	ds_bpermute_b32 v138, v203, v144
	ds_bpermute_b32 v139, v203, v145
	v_pk_fma_f32 v[112:113], v[52:53], v[112:113], v[140:141]
	v_pk_mul_f32 v[140:141], v[176:177], v[110:111]
	v_pk_mul_f32 v[142:143], v[174:175], v[112:113]
	global_store_dwordx4 v[182:183], v[110:113], off nt
	v_cvt_pk_bf16_f32 v140, v140, v141
	v_cvt_pk_bf16_f32 v141, v142, v143
	v_lshlrev_b32_e32 v142, 1, v152
	s_waitcnt lgkmcnt(0)
	v_add_u32_e32 v250, 0xfffff040, v142
	v_cndmask_b32_e64 v250, v142, v250, s[40:41]
	v_cndmask_b32_e64 v248, v150, v138, s[40:41]
	v_cndmask_b32_e64 v249, v151, v139, s[40:41]
	global_store_dwordx2 v250, v[248:249], s[46:47]
	v_cndmask_b32_e64 v246, v138, v150, s[40:41]
	v_cndmask_b32_e64 v247, v139, v151, s[40:41]
	s_waitcnt lgkmcnt(1)
	v_add_u32_e32 v138, 0x1040, v142
	v_cndmask_b32_e64 v138, v142, v138, s[38:39]
	global_store_dwordx2 v138, v[246:247], s[46:47]
	ds_bpermute_b32 v138, v203, v140
	s_waitcnt lgkmcnt(1)
	ds_bpermute_b32 v139, v203, v141
	v_add_u32_e32 v141, 0xc000, v202
	v_lshlrev_b32_e32 v140, 1, v141
	s_waitcnt lgkmcnt(0)
; #define LAS __attribute__((address_space(3)))
; __device__ __forceinline__ unsigned cvt_pk_bf16(float lo, float hi) { unsigned r; asm volatile("v_cvt_pk_bf16_f32 %0, %1, %2" : "=v"(r) : "v"(lo), "v"(hi)); return r; }
;     __device__ __forceinline__ void operator()(const f32x4 (&acc)[2][2][4][2], const Unit& u, int wr, int wc, int fr, int fq) const {
;     ...
;             if (g + 1 < 8) ERN_LOADX(g + 1);
;             float sq0 = 0.f, sq1 = 0.f; u32x2 hw[2][2];
; #pragma unroll
;             for (int bj = 0; bj < 2; ++bj) {
;                 *(LAS f32x4*)(st + wr_off) = acc[ai][bj][m][0]; *(LAS f32x4*)(st + wr_off + 64) = acc[ai][bj][m][1];
;                 const f32x4 a0 = *(const LAS f32x4*)(st + rd_off), a1 = *(const LAS f32x4*)(st + rd_off + 8 * 144);
;                 { const f32x4 xv = xb[g & 1][bj][0] + gv[bj] * a0; __builtin_nontemporal_store(xv, (f32x4*)((char*)xo + 4u * ERN_EOFF(g, bj, 0)));
;                   sq0 += (xv.x * xv.x + xv.y * xv.y) + (xv.z * xv.z + xv.w * xv.w);
;                   const f32x4 hv = xv * gsn[bj]; hw[bj][0].x = cvt_pk_bf16(hv.x, hv.y); hw[bj][0].y = cvt_pk_bf16(hv.z, hv.w); }
;                 { const f32x4 xv = xb[g & 1][bj][1] + gv[bj] * a1; __builtin_nontemporal_store(xv, (f32x4*)((char*)xo + 4u * ERN_EOFF(g, bj, 1)));
;                   sq1 += (xv.x * xv.x + xv.y * xv.y) + (xv.z * xv.z + xv.w * xv.w);
;                   const f32x4 hv = xv * gsn[bj]; hw[bj][1].x = cvt_pk_bf16(hv.x, hv.y); hw[bj][1].y = cvt_pk_bf16(hv.z, hv.w); }
;             }
;             if (!NOH && !PLAIN) {
; #pragma unroll
;                 for (int rh = 0; rh < 2; ++rh) { u32x2 rv; rv.x = __shfl_xor(hw[1][rh].x, 8); rv.y = __shfl_xor(hw[1][rh].y, 8);
;                     const unsigned e0 = ERN_EOFF(g, 0, rh);
;                     const unsigned ee = odd ? (e0 - DM + 32) : e0, eo2 = odd ? e0 : (e0 + DM + 32);
;                     *(u32x2*)((char*)ho + 2u * ee) = odd ? rv : hw[0][rh];
;                     *(u32x2*)((char*)ho + 2u * eo2) = odd ? hw[0][rh] : rv; }
;             }
;             if (!PLAIN) { sq0 += __shfl_xor(sq0, 1); sq0 += __shfl_xor(sq0, 2); sq0 += __shfl_xor(sq0, 4);
;             sq1 += __shfl_xor(sq1, 1); sq1 += __shfl_xor(sq1, 2); sq1 += __shfl_xor(sq1, 4); }
;             if (!PLAIN && pc == 0) { sst[g * 16 + rr] = sq0; sst[g * 16 + 8 + rr] = sq1; }
	v_add_u32_e32 v250, 0xfffff040, v140
	v_cndmask_b32_e64 v250, v140, v250, s[40:41]
	v_cndmask_b32_e64 v248, v146, v138, s[40:41]
	v_cndmask_b32_e64 v249, v147, v139, s[40:41]
	global_store_dwordx2 v250, v[248:249], s[46:47]
	v_cndmask_b32_e64 v246, v138, v146, s[40:41]
	v_cndmask_b32_e64 v247, v139, v147, s[40:41]
	v_mul_f32_e32 v107, v107, v107
	v_fmac_f32_e32 v107, v106, v106
	v_mul_f32_e32 v106, v109, v109
	v_mul_f32_e32 v117, v117, v117
	v_fmac_f32_e32 v106, v108, v108
	v_mul_f32_e32 v115, v115, v115
	v_fmac_f32_e32 v117, v116, v116
	v_mul_f32_e32 v116, v119, v119
	v_mul_f32_e32 v119, v121, v121
	v_add_f32_e32 v106, v107, v106
	v_mul_f32_e32 v107, v111, v111
	v_mul_f32_e32 v108, v113, v113
	v_fmac_f32_e32 v119, v120, v120
	v_fmac_f32_e32 v107, v110, v110
	v_fmac_f32_e32 v108, v112, v112
	v_fmac_f32_e32 v115, v114, v114
	v_fmac_f32_e32 v116, v118, v118
	v_add_f32_e32 v107, v107, v108
	v_add_f32_e32 v108, v115, v117
	v_add_f32_e32 v109, v116, v119
	v_add_f32_e32 v106, v108, v106
	v_add_f32_e32 v107, v109, v107
	s_nop 1
	v_mov_b32_dpp v108, v106 quad_perm:[1,0,3,2] row_mask:0xf bank_mask:0xf
	s_nop 1
	v_mov_b32_dpp v109, v107 quad_perm:[1,0,3,2] row_mask:0xf bank_mask:0xf
	s_waitcnt lgkmcnt(1)
	v_add_f32_e32 v106, v106, v108
	s_waitcnt lgkmcnt(0)
	v_add_f32_e32 v109, v107, v109
	s_nop 1
	v_mov_b32_dpp v108, v106 quad_perm:[2,3,0,1] row_mask:0xf bank_mask:0xf
	s_nop 1
	v_mov_b32_dpp v110, v109 quad_perm:[2,3,0,1] row_mask:0xf bank_mask:0xf
	s_waitcnt lgkmcnt(1)
	v_add_f32_e32 v106, v106, v108
	s_waitcnt lgkmcnt(0)
	v_add_f32_e32 v108, v109, v110
	s_nop 1
	v_mov_b32_dpp v107, v106 row_half_mirror row_mask:0xf bank_mask:0xf
	s_nop 1
	v_mov_b32_dpp v109, v108 row_half_mirror row_mask:0xf bank_mask:0xf
	v_add_u32_e32 v110, 0x1040, v140
	v_cndmask_b32_e64 v110, v140, v110, s[38:39]
	global_store_dwordx2 v110, v[246:247], s[46:47]
	s_and_saveexec_b64 s[16:17], s[42:43]
	s_cbranch_execz .LBB0_1273
	s_waitcnt lgkmcnt(1)
	v_add_f32_e32 v106, v106, v107
	s_waitcnt lgkmcnt(0)
	v_add_f32_e32 v107, v108, v109
	ds_write2_b32 v194, v106, v107 offset0:16 offset1:24
.LBB0_1273:
	s_or_b64 exec, exec, s[16:17]
	v_lshl_add_u64 v[142:143], s[48:49], 0, v[162:163]
	v_add_u32_e32 v106, 0x60000, v205
	v_add_u32_e32 v162, 0x70000, v205
	v_add_u32_e32 v138, 0x60080, v205
	global_load_dwordx4 v[114:117], v162, s[48:49]
	global_load_dwordx4 v[110:113], v138, s[48:49]
	v_add_u32_e32 v140, 0x70080, v205
	global_load_dwordx4 v[118:121], v106, s[48:49]
	s_waitcnt lgkmcnt(0)
	global_load_dwordx4 v[106:109], v140, s[48:49]
	ds_write_b128 v200, v[102:105]
	ds_write_b128 v200, v[98:101] offset:64
	ds_read_b128 v[98:101], v201
	ds_read_b128 v[102:105], v201 offset:1152
	v_mov_b32_e32 v187, v163
	v_mov_b32_e32 v189, v163
	s_waitcnt vmcnt(11) lgkmcnt(1)
	v_pk_fma_f32 v[100:101], v[56:57], v[100:101], v[136:137]
	v_add_u32_e32 v136, 0x10000, v202
	v_pk_fma_f32 v[98:99], v[54:55], v[98:99], v[134:135]
	v_lshlrev_b32_e32 v134, 2, v136
	s_waitcnt lgkmcnt(0)
	v_pk_fma_f32 v[102:103], v[54:55], v[102:103], v[130:131]
	global_store_dwordx4 v134, v[98:101], s[48:49] nt
	v_pk_mul_f32 v[134:135], v[180:181], v[98:99]
	v_pk_fma_f32 v[104:105], v[56:57], v[104:105], v[132:133]
	v_pk_mul_f32 v[130:131], v[180:181], v[102:103]
	v_pk_mul_f32 v[144:145], v[178:179], v[100:101]
	v_cvt_pk_bf16_f32 v134, v134, v135
	v_pk_mul_f32 v[132:133], v[178:179], v[104:105]
	v_cvt_pk_bf16_f32 v135, v144, v145
	global_store_dwordx4 v[142:143], v[102:105], off nt
	v_cvt_pk_bf16_f32 v130, v130, v131
	v_cvt_pk_bf16_f32 v131, v132, v133
	ds_write_b128 v200, v[94:97]
	ds_write_b128 v200, v[90:93] offset:64
	ds_read_b128 v[90:93], v201
	ds_read_b128 v[94:97], v201 offset:1152
	v_lshl_add_u64 v[132:133], s[48:49], 0, v[186:187]
	v_lshl_add_u64 v[142:143], s[48:49], 0, v[188:189]
	s_waitcnt lgkmcnt(1)
	v_pk_fma_f32 v[90:91], v[50:51], v[90:91], v[126:127]
	v_pk_fma_f32 v[92:93], v[52:53], v[92:93], v[128:129]
	v_pk_mul_f32 v[128:129], v[176:177], v[90:91]
	global_store_dwordx4 v[132:133], v[90:93], off nt
	v_pk_mul_f32 v[126:127], v[174:175], v[92:93]
	v_cvt_pk_bf16_f32 v128, v128, v129
	s_waitcnt vmcnt(13) lgkmcnt(0)
	v_pk_fma_f32 v[94:95], v[50:51], v[94:95], v[122:123]
	v_cvt_pk_bf16_f32 v129, v126, v127
	ds_bpermute_b32 v122, v203, v128
	ds_bpermute_b32 v123, v203, v129
	v_pk_fma_f32 v[96:97], v[52:53], v[96:97], v[124:125]
	v_pk_mul_f32 v[124:125], v[176:177], v[94:95]
	v_pk_mul_f32 v[126:127], v[174:175], v[96:97]
	global_store_dwordx4 v[142:143], v[94:97], off nt
	v_cvt_pk_bf16_f32 v124, v124, v125
	v_cvt_pk_bf16_f32 v125, v126, v127
	v_lshlrev_b32_e32 v126, 1, v136
	s_waitcnt lgkmcnt(0)
	v_add_u32_e32 v250, 0xfffff040, v126
	v_cndmask_b32_e64 v250, v126, v250, s[40:41]
	v_cndmask_b32_e64 v248, v134, v122, s[40:41]
	v_cndmask_b32_e64 v249, v135, v123, s[40:41]
	global_store_dwordx2 v250, v[248:249], s[46:47]
	v_cndmask_b32_e64 v246, v122, v134, s[40:41]
	v_cndmask_b32_e64 v247, v123, v135, s[40:41]
	s_waitcnt lgkmcnt(1)
	v_add_u32_e32 v122, 0x1040, v126
	v_cndmask_b32_e64 v122, v126, v122, s[38:39]
	global_store_dwordx2 v122, v[246:247], s[46:47]
	ds_bpermute_b32 v122, v203, v124
	s_waitcnt lgkmcnt(1)
	ds_bpermute_b32 v123, v203, v125
	v_add_u32_e32 v125, 0x14000, v202
	v_lshlrev_b32_e32 v124, 1, v125
	s_waitcnt lgkmcnt(0)
; #define LAS __attribute__((address_space(3)))
; __device__ __forceinline__ unsigned cvt_pk_bf16(float lo, float hi) { unsigned r; asm volatile("v_cvt_pk_bf16_f32 %0, %1, %2" : "=v"(r) : "v"(lo), "v"(hi)); return r; }
;     __device__ __forceinline__ void operator()(const f32x4 (&acc)[2][2][4][2], const Unit& u, int wr, int wc, int fr, int fq) const {
;     ...
;             if (g + 1 < 8) ERN_LOADX(g + 1);
;             float sq0 = 0.f, sq1 = 0.f; u32x2 hw[2][2];
; #pragma unroll
;             for (int bj = 0; bj < 2; ++bj) {
;                 *(LAS f32x4*)(st + wr_off) = acc[ai][bj][m][0]; *(LAS f32x4*)(st + wr_off + 64) = acc[ai][bj][m][1];
;                 const f32x4 a0 = *(const LAS f32x4*)(st + rd_off), a1 = *(const LAS f32x4*)(st + rd_off + 8 * 144);
;                 { const f32x4 xv = xb[g & 1][bj][0] + gv[bj] * a0; __builtin_nontemporal_store(xv, (f32x4*)((char*)xo + 4u * ERN_EOFF(g, bj, 0)));
;                   sq0 += (xv.x * xv.x + xv.y * xv.y) + (xv.z * xv.z + xv.w * xv.w);
;                   const f32x4 hv = xv * gsn[bj]; hw[bj][0].x = cvt_pk_bf16(hv.x, hv.y); hw[bj][0].y = cvt_pk_bf16(hv.z, hv.w); }
;                 { const f32x4 xv = xb[g & 1][bj][1] + gv[bj] * a1; __builtin_nontemporal_store(xv, (f32x4*)((char*)xo + 4u * ERN_EOFF(g, bj, 1)));
;                   sq1 += (xv.x * xv.x + xv.y * xv.y) + (xv.z * xv.z + xv.w * xv.w);
;                   const f32x4 hv = xv * gsn[bj]; hw[bj][1].x = cvt_pk_bf16(hv.x, hv.y); hw[bj][1].y = cvt_pk_bf16(hv.z, hv.w); }
;             }
;             if (!NOH && !PLAIN) {
; #pragma unroll
;                 for (int rh = 0; rh < 2; ++rh) { u32x2 rv; rv.x = __shfl_xor(hw[1][rh].x, 8); rv.y = __shfl_xor(hw[1][rh].y, 8);
;                     const unsigned e0 = ERN_EOFF(g, 0, rh);
;                     const unsigned ee = odd ? (e0 - DM + 32) : e0, eo2 = odd ? e0 : (e0 + DM + 32);
;                     *(u32x2*)((char*)ho + 2u * ee) = odd ? rv : hw[0][rh];
;                     *(u32x2*)((char*)ho + 2u * eo2) = odd ? hw[0][rh] : rv; }
;             }
;             if (!PLAIN) { sq0 += __shfl_xor(sq0, 1); sq0 += __shfl_xor(sq0, 2); sq0 += __shfl_xor(sq0, 4);
;             sq1 += __shfl_xor(sq1, 1); sq1 += __shfl_xor(sq1, 2); sq1 += __shfl_xor(sq1, 4); }
;             if (!PLAIN && pc == 0) { sst[g * 16 + rr] = sq0; sst[g * 16 + 8 + rr] = sq1; }
	v_add_u32_e32 v250, 0xfffff040, v124
	v_cndmask_b32_e64 v250, v124, v250, s[40:41]
	v_cndmask_b32_e64 v248, v130, v122, s[40:41]
	v_cndmask_b32_e64 v249, v131, v123, s[40:41]
	global_store_dwordx2 v250, v[248:249], s[46:47]
	v_cndmask_b32_e64 v246, v122, v130, s[40:41]
	v_cndmask_b32_e64 v247, v123, v131, s[40:41]
	v_mul_f32_e32 v91, v91, v91
	v_fmac_f32_e32 v91, v90, v90
	v_mul_f32_e32 v90, v93, v93
	v_mul_f32_e32 v101, v101, v101
	v_fmac_f32_e32 v90, v92, v92
	v_mul_f32_e32 v99, v99, v99
	v_fmac_f32_e32 v101, v100, v100
	v_mul_f32_e32 v100, v103, v103
	v_mul_f32_e32 v103, v105, v105
	v_add_f32_e32 v90, v91, v90
	v_mul_f32_e32 v91, v95, v95
	v_mul_f32_e32 v92, v97, v97
	v_fmac_f32_e32 v103, v104, v104
	v_fmac_f32_e32 v91, v94, v94
	v_fmac_f32_e32 v92, v96, v96
	v_fmac_f32_e32 v99, v98, v98
	v_fmac_f32_e32 v100, v102, v102
	v_add_f32_e32 v91, v91, v92
	v_add_f32_e32 v92, v99, v101
	v_add_f32_e32 v93, v100, v103
	v_add_f32_e32 v90, v92, v90
	v_add_f32_e32 v91, v93, v91
	s_nop 1
	v_mov_b32_dpp v92, v90 quad_perm:[1,0,3,2] row_mask:0xf bank_mask:0xf
	s_nop 1
	v_mov_b32_dpp v93, v91 quad_perm:[1,0,3,2] row_mask:0xf bank_mask:0xf
	s_waitcnt lgkmcnt(1)
	v_add_f32_e32 v90, v90, v92
	s_waitcnt lgkmcnt(0)
	v_add_f32_e32 v93, v91, v93
	s_nop 1
	v_mov_b32_dpp v92, v90 quad_perm:[2,3,0,1] row_mask:0xf bank_mask:0xf
	s_nop 1
	v_mov_b32_dpp v94, v93 quad_perm:[2,3,0,1] row_mask:0xf bank_mask:0xf
	s_waitcnt lgkmcnt(1)
	v_add_f32_e32 v90, v90, v92
	s_waitcnt lgkmcnt(0)
	v_add_f32_e32 v92, v93, v94
	s_nop 1
	v_mov_b32_dpp v91, v90 row_half_mirror row_mask:0xf bank_mask:0xf
	s_nop 1
	v_mov_b32_dpp v93, v92 row_half_mirror row_mask:0xf bank_mask:0xf
	v_add_u32_e32 v94, 0x1040, v124
	v_cndmask_b32_e64 v94, v124, v94, s[38:39]
	global_store_dwordx2 v94, v[246:247], s[46:47]
	s_and_saveexec_b64 s[16:17], s[42:43]
	s_cbranch_execz .LBB0_1283
	s_waitcnt lgkmcnt(1)
	v_add_f32_e32 v90, v90, v91
	s_waitcnt lgkmcnt(0)
	v_add_f32_e32 v91, v92, v93
	ds_write2_b32 v194, v90, v91 offset0:32 offset1:40
.LBB0_1283:
	s_or_b64 exec, exec, s[16:17]
	v_lshl_add_u64 v[124:125], s[48:49], 0, v[162:163]
	v_add_u32_e32 v90, 0x100000, v205
	s_waitcnt lgkmcnt(1)
	v_add_u32_e32 v91, 0x110000, v205
	v_add_u32_e32 v162, 0x100080, v205
	global_load_dwordx4 v[102:105], v90, s[48:49]
	global_load_dwordx4 v[98:101], v91, s[48:49]
	v_add_u32_e32 v122, 0x110080, v205
	global_load_dwordx4 v[94:97], v162, s[48:49]
	s_waitcnt lgkmcnt(0)
	global_load_dwordx4 v[90:93], v122, s[48:49]
	ds_write_b128 v200, v[86:89]
	ds_write_b128 v200, v[82:85] offset:64
	ds_read_b128 v[82:85], v201
	ds_read_b128 v[86:89], v201 offset:1152
	v_mov_b32_e32 v139, v163
	v_mov_b32_e32 v141, v163
	s_waitcnt vmcnt(11) lgkmcnt(1)
	v_pk_fma_f32 v[84:85], v[56:57], v[84:85], v[120:121]
	v_add_u32_e32 v120, 0x18000, v202
	v_pk_fma_f32 v[82:83], v[54:55], v[82:83], v[118:119]
	v_lshlrev_b32_e32 v118, 2, v120
	s_waitcnt lgkmcnt(0)
	v_pk_fma_f32 v[86:87], v[54:55], v[86:87], v[114:115]
	global_store_dwordx4 v118, v[82:85], s[48:49] nt
	v_pk_mul_f32 v[118:119], v[180:181], v[82:83]
	v_pk_fma_f32 v[88:89], v[56:57], v[88:89], v[116:117]
	v_pk_mul_f32 v[114:115], v[180:181], v[86:87]
	v_pk_mul_f32 v[126:127], v[178:179], v[84:85]
	v_cvt_pk_bf16_f32 v118, v118, v119
	v_pk_mul_f32 v[116:117], v[178:179], v[88:89]
	v_cvt_pk_bf16_f32 v119, v126, v127
	global_store_dwordx4 v[124:125], v[86:89], off nt
	v_cvt_pk_bf16_f32 v114, v114, v115
	v_cvt_pk_bf16_f32 v115, v116, v117
	ds_write_b128 v200, v[78:81]
	ds_write_b128 v200, v[74:77] offset:64
	ds_read_b128 v[74:77], v201
	ds_read_b128 v[78:81], v201 offset:1152
	v_lshl_add_u64 v[116:117], s[48:49], 0, v[138:139]
	v_lshl_add_u64 v[124:125], s[48:49], 0, v[140:141]
	s_waitcnt lgkmcnt(1)
	v_pk_fma_f32 v[74:75], v[50:51], v[74:75], v[110:111]
	v_pk_fma_f32 v[76:77], v[52:53], v[76:77], v[112:113]
	v_pk_mul_f32 v[112:113], v[176:177], v[74:75]
	global_store_dwordx4 v[116:117], v[74:77], off nt
	v_pk_mul_f32 v[110:111], v[174:175], v[76:77]
	v_cvt_pk_bf16_f32 v112, v112, v113
	s_waitcnt vmcnt(13) lgkmcnt(0)
	v_pk_fma_f32 v[78:79], v[50:51], v[78:79], v[106:107]
	v_cvt_pk_bf16_f32 v113, v110, v111
	ds_bpermute_b32 v106, v203, v112
	ds_bpermute_b32 v107, v203, v113
	v_pk_fma_f32 v[80:81], v[52:53], v[80:81], v[108:109]
	v_pk_mul_f32 v[108:109], v[176:177], v[78:79]
	v_pk_mul_f32 v[110:111], v[174:175], v[80:81]
	global_store_dwordx4 v[124:125], v[78:81], off nt
	v_cvt_pk_bf16_f32 v108, v108, v109
	v_cvt_pk_bf16_f32 v109, v110, v111
	v_lshlrev_b32_e32 v110, 1, v120
	s_waitcnt lgkmcnt(0)
	v_add_u32_e32 v250, 0xfffff040, v110
	v_cndmask_b32_e64 v250, v110, v250, s[40:41]
	v_cndmask_b32_e64 v248, v118, v106, s[40:41]
	v_cndmask_b32_e64 v249, v119, v107, s[40:41]
	global_store_dwordx2 v250, v[248:249], s[46:47]
	v_cndmask_b32_e64 v246, v106, v118, s[40:41]
	v_cndmask_b32_e64 v247, v107, v119, s[40:41]
	s_waitcnt lgkmcnt(1)
	v_add_u32_e32 v106, 0x1040, v110
	v_cndmask_b32_e64 v106, v110, v106, s[38:39]
	global_store_dwordx2 v106, v[246:247], s[46:47]
	ds_bpermute_b32 v106, v203, v108
	s_waitcnt lgkmcnt(1)
	ds_bpermute_b32 v107, v203, v109
	v_add_u32_e32 v109, 0x1c000, v202
	v_lshlrev_b32_e32 v108, 1, v109
	s_waitcnt lgkmcnt(0)
	v_add_u32_e32 v250, 0xfffff040, v108
	v_cndmask_b32_e64 v250, v108, v250, s[40:41]
	v_cndmask_b32_e64 v248, v114, v106, s[40:41]
	v_cndmask_b32_e64 v249, v115, v107, s[40:41]
	global_store_dwordx2 v250, v[248:249], s[46:47]
	v_cndmask_b32_e64 v246, v106, v114, s[40:41]
	v_cndmask_b32_e64 v247, v107, v115, s[40:41]
	v_mul_f32_e32 v75, v75, v75
	v_fmac_f32_e32 v75, v74, v74
	v_mul_f32_e32 v74, v77, v77
	v_mul_f32_e32 v85, v85, v85
	v_fmac_f32_e32 v74, v76, v76
	v_mul_f32_e32 v83, v83, v83
	v_fmac_f32_e32 v85, v84, v84
	v_mul_f32_e32 v84, v87, v87
	v_mul_f32_e32 v87, v89, v89
	v_add_f32_e32 v74, v75, v74
	v_mul_f32_e32 v75, v79, v79
	v_mul_f32_e32 v76, v81, v81
	v_fmac_f32_e32 v87, v88, v88
	v_fmac_f32_e32 v75, v78, v78
	v_fmac_f32_e32 v76, v80, v80
	v_fmac_f32_e32 v83, v82, v82
	v_fmac_f32_e32 v84, v86, v86
	v_add_f32_e32 v75, v75, v76
	v_add_f32_e32 v76, v83, v85
	v_add_f32_e32 v77, v84, v87
	v_add_f32_e32 v74, v76, v74
	v_add_f32_e32 v75, v77, v75
	s_nop 1
	v_mov_b32_dpp v76, v74 quad_perm:[1,0,3,2] row_mask:0xf bank_mask:0xf
	s_nop 1
	v_mov_b32_dpp v77, v75 quad_perm:[1,0,3,2] row_mask:0xf bank_mask:0xf
	s_waitcnt lgkmcnt(1)
	v_add_f32_e32 v74, v74, v76
	s_waitcnt lgkmcnt(0)
	v_add_f32_e32 v77, v75, v77
	s_nop 1
	v_mov_b32_dpp v76, v74 quad_perm:[2,3,0,1] row_mask:0xf bank_mask:0xf
	s_nop 1
	v_mov_b32_dpp v78, v77 quad_perm:[2,3,0,1] row_mask:0xf bank_mask:0xf
	s_waitcnt lgkmcnt(1)
	v_add_f32_e32 v74, v74, v76
	s_waitcnt lgkmcnt(0)
	v_add_f32_e32 v76, v77, v78
	s_nop 1
	v_mov_b32_dpp v75, v74 row_half_mirror row_mask:0xf bank_mask:0xf
	s_nop 1
	v_mov_b32_dpp v77, v76 row_half_mirror row_mask:0xf bank_mask:0xf
	v_add_u32_e32 v78, 0x1040, v108
	v_cndmask_b32_e64 v78, v108, v78, s[38:39]
	global_store_dwordx2 v78, v[246:247], s[46:47]
	s_and_saveexec_b64 s[16:17], s[42:43]
	s_cbranch_execz .LBB0_1293
; #define LAS __attribute__((address_space(3)))
; __device__ __forceinline__ unsigned cvt_pk_bf16(float lo, float hi) { unsigned r; asm volatile("v_cvt_pk_bf16_f32 %0, %1, %2" : "=v"(r) : "v"(lo), "v"(hi)); return r; }
;     __device__ __forceinline__ void operator()(const f32x4 (&acc)[2][2][4][2], const Unit& u, int wr, int wc, int fr, int fq) const {
;     ...
;             if (g + 1 < 8) ERN_LOADX(g + 1);
;             float sq0 = 0.f, sq1 = 0.f; u32x2 hw[2][2];
; #pragma unroll
;             for (int bj = 0; bj < 2; ++bj) {
;                 *(LAS f32x4*)(st + wr_off) = acc[ai][bj][m][0]; *(LAS f32x4*)(st + wr_off + 64) = acc[ai][bj][m][1];
;                 const f32x4 a0 = *(const LAS f32x4*)(st + rd_off), a1 = *(const LAS f32x4*)(st + rd_off + 8 * 144);
;                 { const f32x4 xv = xb[g & 1][bj][0] + gv[bj] * a0; __builtin_nontemporal_store(xv, (f32x4*)((char*)xo + 4u * ERN_EOFF(g, bj, 0)));
;                   sq0 += (xv.x * xv.x + xv.y * xv.y) + (xv.z * xv.z + xv.w * xv.w);
;                   const f32x4 hv = xv * gsn[bj]; hw[bj][0].x = cvt_pk_bf16(hv.x, hv.y); hw[bj][0].y = cvt_pk_bf16(hv.z, hv.w); }
;                 { const f32x4 xv = xb[g & 1][bj][1] + gv[bj] * a1; __builtin_nontemporal_store(xv, (f32x4*)((char*)xo + 4u * ERN_EOFF(g, bj, 1)));
;                   sq1 += (xv.x * xv.x + xv.y * xv.y) + (xv.z * xv.z + xv.w * xv.w);
;                   const f32x4 hv = xv * gsn[bj]; hw[bj][1].x = cvt_pk_bf16(hv.x, hv.y); hw[bj][1].y = cvt_pk_bf16(hv.z, hv.w); }
;             }
;             if (!NOH && !PLAIN) {
; #pragma unroll
;                 for (int rh = 0; rh < 2; ++rh) { u32x2 rv; rv.x = __shfl_xor(hw[1][rh].x, 8); rv.y = __shfl_xor(hw[1][rh].y, 8);
;                     const unsigned e0 = ERN_EOFF(g, 0, rh);
;                     const unsigned ee = odd ? (e0 - DM + 32) : e0, eo2 = odd ? e0 : (e0 + DM + 32);
;                     *(u32x2*)((char*)ho + 2u * ee) = odd ? rv : hw[0][rh];
;                     *(u32x2*)((char*)ho + 2u * eo2) = odd ? hw[0][rh] : rv; }
;             }
;             if (!PLAIN) { sq0 += __shfl_xor(sq0, 1); sq0 += __shfl_xor(sq0, 2); sq0 += __shfl_xor(sq0, 4);
;             sq1 += __shfl_xor(sq1, 1); sq1 += __shfl_xor(sq1, 2); sq1 += __shfl_xor(sq1, 4); }
;             if (!PLAIN && pc == 0) { sst[g * 16 + rr] = sq0; sst[g * 16 + 8 + rr] = sq1; }
	s_waitcnt lgkmcnt(1)
	v_add_f32_e32 v74, v74, v75
	s_waitcnt lgkmcnt(0)
	v_add_f32_e32 v75, v76, v77
	ds_write2_b32 v194, v74, v75 offset0:48 offset1:56
.LBB0_1293:
	s_or_b64 exec, exec, s[16:17]
	v_lshl_add_u64 v[112:113], s[48:49], 0, v[162:163]
	v_add_u32_e32 v162, 0x120000, v205
	v_add_u32_e32 v108, 0x120080, v205
	v_add_u32_e32 v110, 0x130000, v205
	global_load_dwordx4 v[86:89], v162, s[48:49]
	global_load_dwordx4 v[82:85], v110, s[48:49]
	v_add_u32_e32 v106, 0x130080, v205
	global_load_dwordx4 v[78:81], v108, s[48:49]
	s_waitcnt lgkmcnt(0)
	global_load_dwordx4 v[74:77], v106, s[48:49]
	ds_write_b128 v200, v[70:73]
	ds_write_b128 v200, v[66:69] offset:64
	ds_read_b128 v[66:69], v201
	ds_read_b128 v[70:73], v201 offset:1152
	v_mov_b32_e32 v123, v163
	s_waitcnt vmcnt(13) lgkmcnt(1)
	v_pk_fma_f32 v[68:69], v[56:57], v[68:69], v[104:105]
	v_add_u32_e32 v104, 0x40000, v202
	v_pk_fma_f32 v[66:67], v[54:55], v[66:67], v[102:103]
	v_lshlrev_b32_e32 v102, 2, v104
	s_waitcnt vmcnt(12) lgkmcnt(0)
	v_pk_fma_f32 v[72:73], v[56:57], v[72:73], v[100:101]
	v_add_u32_e32 v100, 0x44000, v202
	global_store_dwordx4 v102, v[66:69], s[48:49] nt
	v_pk_mul_f32 v[102:103], v[180:181], v[66:67]
	v_pk_fma_f32 v[70:71], v[54:55], v[70:71], v[98:99]
	v_lshlrev_b32_e32 v98, 2, v100
	v_pk_mul_f32 v[114:115], v[178:179], v[68:69]
	v_cvt_pk_bf16_f32 v102, v102, v103
	s_nop 0
	v_cvt_pk_bf16_f32 v103, v114, v115
	global_store_dwordx4 v98, v[70:73], s[48:49] nt
	v_pk_mul_f32 v[98:99], v[180:181], v[70:71]
	v_pk_mul_f32 v[114:115], v[178:179], v[72:73]
	v_cvt_pk_bf16_f32 v98, v98, v99
	s_nop 0
	v_cvt_pk_bf16_f32 v99, v114, v115
	ds_write_b128 v200, v[62:65]
	ds_write_b128 v200, v[58:61] offset:64
	ds_read_b128 v[58:61], v201
	ds_read_b128 v[62:65], v201 offset:1152
	v_lshl_add_u64 v[114:115], s[48:49], 0, v[122:123]
	s_waitcnt vmcnt(13) lgkmcnt(1)
	v_pk_fma_f32 v[58:59], v[50:51], v[58:59], v[94:95]
	v_pk_fma_f32 v[60:61], v[52:53], v[60:61], v[96:97]
	v_pk_mul_f32 v[96:97], v[176:177], v[58:59]
	global_store_dwordx4 v[112:113], v[58:61], off nt
	v_pk_mul_f32 v[94:95], v[174:175], v[60:61]
	v_cvt_pk_bf16_f32 v96, v96, v97
	s_waitcnt vmcnt(13) lgkmcnt(0)
	v_pk_fma_f32 v[62:63], v[50:51], v[62:63], v[90:91]
	v_cvt_pk_bf16_f32 v97, v94, v95
	ds_bpermute_b32 v90, v203, v96
	ds_bpermute_b32 v91, v203, v97
	v_pk_fma_f32 v[64:65], v[52:53], v[64:65], v[92:93]
	v_pk_mul_f32 v[92:93], v[176:177], v[62:63]
	v_pk_mul_f32 v[94:95], v[174:175], v[64:65]
	global_store_dwordx4 v[114:115], v[62:65], off nt
	v_cvt_pk_bf16_f32 v92, v92, v93
	v_cvt_pk_bf16_f32 v93, v94, v95
	v_lshlrev_b32_e32 v94, 1, v104
	s_waitcnt lgkmcnt(0)
	v_add_u32_e32 v250, 0xfffff040, v94
	v_cndmask_b32_e64 v250, v94, v250, s[40:41]
	v_cndmask_b32_e64 v248, v102, v90, s[40:41]
	v_cndmask_b32_e64 v249, v103, v91, s[40:41]
	global_store_dwordx2 v250, v[248:249], s[46:47]
	v_cndmask_b32_e64 v246, v90, v102, s[40:41]
	v_cndmask_b32_e64 v247, v91, v103, s[40:41]
	s_waitcnt lgkmcnt(1)
	v_add_u32_e32 v90, 0x1040, v94
	v_cndmask_b32_e64 v90, v94, v90, s[38:39]
	global_store_dwordx2 v90, v[246:247], s[46:47]
	ds_bpermute_b32 v90, v203, v92
	s_waitcnt lgkmcnt(1)
	ds_bpermute_b32 v91, v203, v93
	v_lshlrev_b32_e32 v92, 1, v100
	s_waitcnt lgkmcnt(0)
	v_add_u32_e32 v250, 0xfffff040, v92
	v_cndmask_b32_e64 v250, v92, v250, s[40:41]
	v_cndmask_b32_e64 v248, v98, v90, s[40:41]
	v_cndmask_b32_e64 v249, v99, v91, s[40:41]
	global_store_dwordx2 v250, v[248:249], s[46:47]
	v_cndmask_b32_e64 v246, v90, v98, s[40:41]
	v_cndmask_b32_e64 v247, v91, v99, s[40:41]
	v_mul_f32_e32 v59, v59, v59
	v_fmac_f32_e32 v59, v58, v58
	v_mul_f32_e32 v58, v61, v61
	v_mul_f32_e32 v69, v69, v69
	v_fmac_f32_e32 v58, v60, v60
	v_mul_f32_e32 v67, v67, v67
	v_fmac_f32_e32 v69, v68, v68
	v_mul_f32_e32 v68, v71, v71
	v_mul_f32_e32 v71, v73, v73
	v_add_f32_e32 v58, v59, v58
	v_mul_f32_e32 v59, v63, v63
	v_mul_f32_e32 v60, v65, v65
	v_fmac_f32_e32 v71, v72, v72
	v_fmac_f32_e32 v59, v62, v62
	v_fmac_f32_e32 v60, v64, v64
	v_fmac_f32_e32 v67, v66, v66
	v_fmac_f32_e32 v68, v70, v70
	v_add_f32_e32 v59, v59, v60
	v_add_f32_e32 v60, v67, v69
	v_add_f32_e32 v61, v68, v71
	v_add_f32_e32 v58, v60, v58
	v_add_f32_e32 v59, v61, v59
	s_nop 1
	v_mov_b32_dpp v60, v58 quad_perm:[1,0,3,2] row_mask:0xf bank_mask:0xf
	s_nop 1
	v_mov_b32_dpp v61, v59 quad_perm:[1,0,3,2] row_mask:0xf bank_mask:0xf
	s_waitcnt lgkmcnt(1)
	v_add_f32_e32 v58, v58, v60
	s_waitcnt lgkmcnt(0)
	v_add_f32_e32 v61, v59, v61
	s_nop 1
	v_mov_b32_dpp v60, v58 quad_perm:[2,3,0,1] row_mask:0xf bank_mask:0xf
	s_nop 1
	v_mov_b32_dpp v62, v61 quad_perm:[2,3,0,1] row_mask:0xf bank_mask:0xf
	s_waitcnt lgkmcnt(1)
	v_add_f32_e32 v58, v58, v60
	s_waitcnt lgkmcnt(0)
	v_add_f32_e32 v60, v61, v62
	s_nop 1
	v_mov_b32_dpp v59, v58 row_half_mirror row_mask:0xf bank_mask:0xf
	s_nop 1
	v_mov_b32_dpp v61, v60 row_half_mirror row_mask:0xf bank_mask:0xf
	v_add_u32_e32 v62, 0x1040, v92
	v_cndmask_b32_e64 v62, v92, v62, s[38:39]
	global_store_dwordx2 v62, v[246:247], s[46:47]
	s_and_saveexec_b64 s[16:17], s[42:43]
	s_cbranch_execz .LBB0_1303
	s_waitcnt lgkmcnt(1)
	v_add_f32_e32 v58, v58, v59
	s_waitcnt lgkmcnt(0)
	v_add_f32_e32 v59, v60, v61
	ds_write2_b32 v194, v58, v59 offset0:64 offset1:72
; #define LAS __attribute__((address_space(3)))
; __device__ __forceinline__ unsigned cvt_pk_bf16(float lo, float hi) { unsigned r; asm volatile("v_cvt_pk_bf16_f32 %0, %1, %2" : "=v"(r) : "v"(lo), "v"(hi)); return r; }
;     __device__ __forceinline__ void operator()(const f32x4 (&acc)[2][2][4][2], const Unit& u, int wr, int wc, int fr, int fq) const {
;     ...
;             if (g + 1 < 8) ERN_LOADX(g + 1);
;             float sq0 = 0.f, sq1 = 0.f; u32x2 hw[2][2];
; #pragma unroll
;             for (int bj = 0; bj < 2; ++bj) {
;                 *(LAS f32x4*)(st + wr_off) = acc[ai][bj][m][0]; *(LAS f32x4*)(st + wr_off + 64) = acc[ai][bj][m][1];
;                 const f32x4 a0 = *(const LAS f32x4*)(st + rd_off), a1 = *(const LAS f32x4*)(st + rd_off + 8 * 144);
;                 { const f32x4 xv = xb[g & 1][bj][0] + gv[bj] * a0; __builtin_nontemporal_store(xv, (f32x4*)((char*)xo + 4u * ERN_EOFF(g, bj, 0)));
;                   sq0 += (xv.x * xv.x + xv.y * xv.y) + (xv.z * xv.z + xv.w * xv.w);
;                   const f32x4 hv = xv * gsn[bj]; hw[bj][0].x = cvt_pk_bf16(hv.x, hv.y); hw[bj][0].y = cvt_pk_bf16(hv.z, hv.w); }
;                 { const f32x4 xv = xb[g & 1][bj][1] + gv[bj] * a1; __builtin_nontemporal_store(xv, (f32x4*)((char*)xo + 4u * ERN_EOFF(g, bj, 1)));
;                   sq1 += (xv.x * xv.x + xv.y * xv.y) + (xv.z * xv.z + xv.w * xv.w);
;                   const f32x4 hv = xv * gsn[bj]; hw[bj][1].x = cvt_pk_bf16(hv.x, hv.y); hw[bj][1].y = cvt_pk_bf16(hv.z, hv.w); }
;             }
;             if (!NOH && !PLAIN) {
; #pragma unroll
;                 for (int rh = 0; rh < 2; ++rh) { u32x2 rv; rv.x = __shfl_xor(hw[1][rh].x, 8); rv.y = __shfl_xor(hw[1][rh].y, 8);
;                     const unsigned e0 = ERN_EOFF(g, 0, rh);
;                     const unsigned ee = odd ? (e0 - DM + 32) : e0, eo2 = odd ? e0 : (e0 + DM + 32);
;                     *(u32x2*)((char*)ho + 2u * ee) = odd ? rv : hw[0][rh];
;                     *(u32x2*)((char*)ho + 2u * eo2) = odd ? hw[0][rh] : rv; }
;             }
;             if (!PLAIN) { sq0 += __shfl_xor(sq0, 1); sq0 += __shfl_xor(sq0, 2); sq0 += __shfl_xor(sq0, 4);
;             sq1 += __shfl_xor(sq1, 1); sq1 += __shfl_xor(sq1, 2); sq1 += __shfl_xor(sq1, 4); }
;             if (!PLAIN && pc == 0) { sst[g * 16 + rr] = sq0; sst[g * 16 + 8 + rr] = sq1; }
.LBB0_1303:
	s_or_b64 exec, exec, s[16:17]
	v_lshl_add_u64 v[96:97], s[48:49], 0, v[162:163]
	v_add_u32_e32 v162, 0x140000, v205
	v_add_u32_e32 v92, 0x140080, v205
	v_add_u32_e32 v94, 0x150000, v205
	global_load_dwordx4 v[70:73], v162, s[48:49]
	global_load_dwordx4 v[66:69], v94, s[48:49]
	v_add_u32_e32 v90, 0x150080, v205
	global_load_dwordx4 v[62:65], v92, s[48:49]
	s_waitcnt lgkmcnt(0)
	global_load_dwordx4 v[58:61], v90, s[48:49]
	ds_write_b128 v200, v[46:49]
	ds_write_b128 v200, v[42:45] offset:64
	ds_read_b128 v[42:45], v201
	ds_read_b128 v[46:49], v201 offset:1152
	v_mov_b32_e32 v111, v163
	v_lshl_add_u64 v[98:99], s[48:49], 0, v[110:111]
	v_mov_b32_e32 v109, v163
	s_waitcnt vmcnt(13) lgkmcnt(1)
	v_pk_fma_f32 v[42:43], v[54:55], v[42:43], v[86:87]
	s_waitcnt vmcnt(12) lgkmcnt(0)
	v_pk_fma_f32 v[46:47], v[54:55], v[46:47], v[82:83]
	v_pk_fma_f32 v[44:45], v[56:57], v[44:45], v[88:89]
	v_pk_mul_f32 v[86:87], v[180:181], v[42:43]
	v_pk_fma_f32 v[48:49], v[56:57], v[48:49], v[84:85]
	v_pk_mul_f32 v[82:83], v[180:181], v[46:47]
	global_store_dwordx4 v[96:97], v[42:45], off nt
	v_pk_mul_f32 v[88:89], v[178:179], v[44:45]
	v_cvt_pk_bf16_f32 v86, v86, v87
	v_pk_mul_f32 v[84:85], v[178:179], v[48:49]
	v_cvt_pk_bf16_f32 v87, v88, v89
	global_store_dwordx4 v[98:99], v[46:49], off nt
	v_cvt_pk_bf16_f32 v82, v82, v83
	v_cvt_pk_bf16_f32 v83, v84, v85
	ds_write_b128 v200, v[38:41]
	ds_write_b128 v200, v[34:37] offset:64
	ds_read_b128 v[34:37], v201
	ds_read_b128 v[38:41], v201 offset:1152
	v_lshl_add_u64 v[84:85], s[48:49], 0, v[108:109]
	v_mov_b32_e32 v107, v163
	v_lshl_add_u64 v[88:89], s[48:49], 0, v[106:107]
	s_waitcnt vmcnt(13) lgkmcnt(1)
	v_pk_fma_f32 v[34:35], v[50:51], v[34:35], v[78:79]
	v_pk_fma_f32 v[36:37], v[52:53], v[36:37], v[80:81]
	v_pk_mul_f32 v[80:81], v[176:177], v[34:35]
	global_store_dwordx4 v[84:85], v[34:37], off nt
	v_pk_mul_f32 v[78:79], v[174:175], v[36:37]
	v_cvt_pk_bf16_f32 v80, v80, v81
	s_waitcnt vmcnt(13) lgkmcnt(0)
	v_pk_fma_f32 v[38:39], v[50:51], v[38:39], v[74:75]
	v_cvt_pk_bf16_f32 v81, v78, v79
	ds_bpermute_b32 v74, v203, v80
	ds_bpermute_b32 v75, v203, v81
	v_pk_fma_f32 v[40:41], v[52:53], v[40:41], v[76:77]
	v_pk_mul_f32 v[76:77], v[176:177], v[38:39]
	v_pk_mul_f32 v[78:79], v[174:175], v[40:41]
	global_store_dwordx4 v[88:89], v[38:41], off nt
	v_cvt_pk_bf16_f32 v76, v76, v77
	v_cvt_pk_bf16_f32 v77, v78, v79
	v_add_u32_e32 v79, 0x48000, v202
	v_lshlrev_b32_e32 v78, 1, v79
	s_waitcnt lgkmcnt(0)
	v_add_u32_e32 v250, 0xfffff040, v78
	v_cndmask_b32_e64 v250, v78, v250, s[40:41]
	v_cndmask_b32_e64 v248, v86, v74, s[40:41]
	v_cndmask_b32_e64 v249, v87, v75, s[40:41]
	global_store_dwordx2 v250, v[248:249], s[46:47]
	v_cndmask_b32_e64 v246, v74, v86, s[40:41]
	v_cndmask_b32_e64 v247, v75, v87, s[40:41]
	s_waitcnt lgkmcnt(1)
	v_add_u32_e32 v74, 0x1040, v78
	v_cndmask_b32_e64 v74, v78, v74, s[38:39]
	global_store_dwordx2 v74, v[246:247], s[46:47]
	ds_bpermute_b32 v74, v203, v76
	s_waitcnt lgkmcnt(1)
	ds_bpermute_b32 v75, v203, v77
	v_add_u32_e32 v77, 0x4c000, v202
	v_lshlrev_b32_e32 v76, 1, v77
	s_waitcnt lgkmcnt(0)
	v_add_u32_e32 v250, 0xfffff040, v76
	v_cndmask_b32_e64 v250, v76, v250, s[40:41]
	v_cndmask_b32_e64 v248, v82, v74, s[40:41]
	v_cndmask_b32_e64 v249, v83, v75, s[40:41]
	global_store_dwordx2 v250, v[248:249], s[46:47]
	v_cndmask_b32_e64 v246, v74, v82, s[40:41]
	v_cndmask_b32_e64 v247, v75, v83, s[40:41]
	v_mul_f32_e32 v35, v35, v35
	v_fmac_f32_e32 v35, v34, v34
	v_mul_f32_e32 v34, v37, v37
	v_mul_f32_e32 v45, v45, v45
	v_fmac_f32_e32 v34, v36, v36
	v_mul_f32_e32 v43, v43, v43
	v_fmac_f32_e32 v45, v44, v44
	v_mul_f32_e32 v44, v47, v47
	v_mul_f32_e32 v47, v49, v49
	v_add_f32_e32 v34, v35, v34
	v_mul_f32_e32 v35, v39, v39
	v_mul_f32_e32 v36, v41, v41
	v_fmac_f32_e32 v47, v48, v48
	v_fmac_f32_e32 v35, v38, v38
	v_fmac_f32_e32 v36, v40, v40
	v_fmac_f32_e32 v43, v42, v42
	v_fmac_f32_e32 v44, v46, v46
	v_add_f32_e32 v35, v35, v36
	v_add_f32_e32 v36, v43, v45
	v_add_f32_e32 v37, v44, v47
	v_add_f32_e32 v34, v36, v34
	v_add_f32_e32 v35, v37, v35
	s_nop 1
	v_mov_b32_dpp v36, v34 quad_perm:[1,0,3,2] row_mask:0xf bank_mask:0xf
	s_nop 1
	v_mov_b32_dpp v37, v35 quad_perm:[1,0,3,2] row_mask:0xf bank_mask:0xf
	s_waitcnt lgkmcnt(1)
	v_add_f32_e32 v34, v34, v36
	s_waitcnt lgkmcnt(0)
	v_add_f32_e32 v37, v35, v37
	s_nop 1
	v_mov_b32_dpp v36, v34 quad_perm:[2,3,0,1] row_mask:0xf bank_mask:0xf
	s_nop 1
	v_mov_b32_dpp v38, v37 quad_perm:[2,3,0,1] row_mask:0xf bank_mask:0xf
	s_waitcnt lgkmcnt(1)
	v_add_f32_e32 v34, v34, v36
	s_waitcnt lgkmcnt(0)
	v_add_f32_e32 v36, v37, v38
	s_nop 1
	v_mov_b32_dpp v35, v34 row_half_mirror row_mask:0xf bank_mask:0xf
	s_nop 1
	v_mov_b32_dpp v37, v36 row_half_mirror row_mask:0xf bank_mask:0xf
	v_add_u32_e32 v38, 0x1040, v76
	v_cndmask_b32_e64 v38, v76, v38, s[38:39]
	global_store_dwordx2 v38, v[246:247], s[46:47]
	s_and_saveexec_b64 s[16:17], s[42:43]
	s_cbranch_execz .LBB0_1313
	s_waitcnt lgkmcnt(1)
	v_add_f32_e32 v34, v34, v35
	s_waitcnt lgkmcnt(0)
	v_add_f32_e32 v35, v36, v37
	ds_write2_b32 v194, v34, v35 offset0:80 offset1:88
; #define LAS __attribute__((address_space(3)))
; __device__ __forceinline__ unsigned cvt_pk_bf16(float lo, float hi) { unsigned r; asm volatile("v_cvt_pk_bf16_f32 %0, %1, %2" : "=v"(r) : "v"(lo), "v"(hi)); return r; }
;     __device__ __forceinline__ void operator()(const f32x4 (&acc)[2][2][4][2], const Unit& u, int wr, int wc, int fr, int fq) const {
;     ...
;             if (g + 1 < 8) ERN_LOADX(g + 1);
;             float sq0 = 0.f, sq1 = 0.f; u32x2 hw[2][2];
; #pragma unroll
;             for (int bj = 0; bj < 2; ++bj) {
;                 *(LAS f32x4*)(st + wr_off) = acc[ai][bj][m][0]; *(LAS f32x4*)(st + wr_off + 64) = acc[ai][bj][m][1];
;                 const f32x4 a0 = *(const LAS f32x4*)(st + rd_off), a1 = *(const LAS f32x4*)(st + rd_off + 8 * 144);
;                 { const f32x4 xv = xb[g & 1][bj][0] + gv[bj] * a0; __builtin_nontemporal_store(xv, (f32x4*)((char*)xo + 4u * ERN_EOFF(g, bj, 0)));
;                   sq0 += (xv.x * xv.x + xv.y * xv.y) + (xv.z * xv.z + xv.w * xv.w);
;                   const f32x4 hv = xv * gsn[bj]; hw[bj][0].x = cvt_pk_bf16(hv.x, hv.y); hw[bj][0].y = cvt_pk_bf16(hv.z, hv.w); }
;                 { const f32x4 xv = xb[g & 1][bj][1] + gv[bj] * a1; __builtin_nontemporal_store(xv, (f32x4*)((char*)xo + 4u * ERN_EOFF(g, bj, 1)));
;                   sq1 += (xv.x * xv.x + xv.y * xv.y) + (xv.z * xv.z + xv.w * xv.w);
;                   const f32x4 hv = xv * gsn[bj]; hw[bj][1].x = cvt_pk_bf16(hv.x, hv.y); hw[bj][1].y = cvt_pk_bf16(hv.z, hv.w); }
;             }
;             if (!NOH && !PLAIN) {
; #pragma unroll
;                 for (int rh = 0; rh < 2; ++rh) { u32x2 rv; rv.x = __shfl_xor(hw[1][rh].x, 8); rv.y = __shfl_xor(hw[1][rh].y, 8);
;                     const unsigned e0 = ERN_EOFF(g, 0, rh);
;                     const unsigned ee = odd ? (e0 - DM + 32) : e0, eo2 = odd ? e0 : (e0 + DM + 32);
;                     *(u32x2*)((char*)ho + 2u * ee) = odd ? rv : hw[0][rh];
;                     *(u32x2*)((char*)ho + 2u * eo2) = odd ? hw[0][rh] : rv; }
;             }
;             if (!PLAIN) { sq0 += __shfl_xor(sq0, 1); sq0 += __shfl_xor(sq0, 2); sq0 += __shfl_xor(sq0, 4);
;             sq1 += __shfl_xor(sq1, 1); sq1 += __shfl_xor(sq1, 2); sq1 += __shfl_xor(sq1, 4); }
;             if (!PLAIN && pc == 0) { sst[g * 16 + rr] = sq0; sst[g * 16 + 8 + rr] = sq1; }
.LBB0_1313:
	s_or_b64 exec, exec, s[16:17]
	v_lshl_add_u64 v[80:81], s[48:49], 0, v[162:163]
	v_add_u32_e32 v162, 0x160000, v205
	v_add_u32_e32 v76, 0x160080, v205
	v_add_u32_e32 v78, 0x170000, v205
	global_load_dwordx4 v[46:49], v162, s[48:49]
	global_load_dwordx4 v[42:45], v78, s[48:49]
	v_add_u32_e32 v74, 0x170080, v205
	global_load_dwordx4 v[38:41], v76, s[48:49]
	s_waitcnt lgkmcnt(0)
	global_load_dwordx4 v[34:37], v74, s[48:49]
	ds_write_b128 v200, v[30:33]
	ds_write_b128 v200, v[26:29] offset:64
	ds_read_b128 v[26:29], v201
	ds_read_b128 v[30:33], v201 offset:1152
	v_mov_b32_e32 v95, v163
	v_lshl_add_u64 v[82:83], s[48:49], 0, v[94:95]
	v_mov_b32_e32 v93, v163
	s_waitcnt vmcnt(13) lgkmcnt(1)
	v_pk_fma_f32 v[26:27], v[54:55], v[26:27], v[70:71]
	s_waitcnt vmcnt(12) lgkmcnt(0)
	v_pk_fma_f32 v[30:31], v[54:55], v[30:31], v[66:67]
	v_pk_fma_f32 v[28:29], v[56:57], v[28:29], v[72:73]
	v_pk_mul_f32 v[70:71], v[180:181], v[26:27]
	v_pk_fma_f32 v[32:33], v[56:57], v[32:33], v[68:69]
	v_pk_mul_f32 v[66:67], v[180:181], v[30:31]
	global_store_dwordx4 v[80:81], v[26:29], off nt
	v_pk_mul_f32 v[72:73], v[178:179], v[28:29]
	v_cvt_pk_bf16_f32 v70, v70, v71
	v_pk_mul_f32 v[68:69], v[178:179], v[32:33]
	v_cvt_pk_bf16_f32 v71, v72, v73
	global_store_dwordx4 v[82:83], v[30:33], off nt
	v_cvt_pk_bf16_f32 v66, v66, v67
	v_cvt_pk_bf16_f32 v67, v68, v69
	ds_write_b128 v200, v[22:25]
	ds_write_b128 v200, v[18:21] offset:64
	ds_read_b128 v[18:21], v201
	ds_read_b128 v[22:25], v201 offset:1152
	v_lshl_add_u64 v[68:69], s[48:49], 0, v[92:93]
	v_mov_b32_e32 v91, v163
	v_lshl_add_u64 v[72:73], s[48:49], 0, v[90:91]
	s_waitcnt vmcnt(13) lgkmcnt(1)
	v_pk_fma_f32 v[18:19], v[50:51], v[18:19], v[62:63]
	v_pk_fma_f32 v[20:21], v[52:53], v[20:21], v[64:65]
	v_pk_mul_f32 v[64:65], v[176:177], v[18:19]
	global_store_dwordx4 v[68:69], v[18:21], off nt
	v_pk_mul_f32 v[62:63], v[174:175], v[20:21]
	v_cvt_pk_bf16_f32 v64, v64, v65
	s_waitcnt vmcnt(13) lgkmcnt(0)
	v_pk_fma_f32 v[22:23], v[50:51], v[22:23], v[58:59]
	v_cvt_pk_bf16_f32 v65, v62, v63
	ds_bpermute_b32 v58, v203, v64
	ds_bpermute_b32 v59, v203, v65
	v_pk_fma_f32 v[24:25], v[52:53], v[24:25], v[60:61]
	v_pk_mul_f32 v[60:61], v[176:177], v[22:23]
	v_pk_mul_f32 v[62:63], v[174:175], v[24:25]
	global_store_dwordx4 v[72:73], v[22:25], off nt
	v_cvt_pk_bf16_f32 v60, v60, v61
	v_cvt_pk_bf16_f32 v61, v62, v63
	v_add_u32_e32 v63, 0x50000, v202
	v_lshlrev_b32_e32 v62, 1, v63
	s_waitcnt lgkmcnt(0)
	v_add_u32_e32 v250, 0xfffff040, v62
	v_cndmask_b32_e64 v250, v62, v250, s[40:41]
	v_cndmask_b32_e64 v248, v70, v58, s[40:41]
	v_cndmask_b32_e64 v249, v71, v59, s[40:41]
	global_store_dwordx2 v250, v[248:249], s[46:47]
	v_cndmask_b32_e64 v246, v58, v70, s[40:41]
	v_cndmask_b32_e64 v247, v59, v71, s[40:41]
	s_waitcnt lgkmcnt(1)
	v_add_u32_e32 v58, 0x1040, v62
	v_cndmask_b32_e64 v58, v62, v58, s[38:39]
	global_store_dwordx2 v58, v[246:247], s[46:47]
	ds_bpermute_b32 v58, v203, v60
	s_waitcnt lgkmcnt(1)
	ds_bpermute_b32 v59, v203, v61
	v_add_u32_e32 v61, 0x54000, v202
	v_lshlrev_b32_e32 v60, 1, v61
	s_waitcnt lgkmcnt(0)
	v_add_u32_e32 v250, 0xfffff040, v60
	v_cndmask_b32_e64 v250, v60, v250, s[40:41]
	v_cndmask_b32_e64 v248, v66, v58, s[40:41]
	v_cndmask_b32_e64 v249, v67, v59, s[40:41]
	global_store_dwordx2 v250, v[248:249], s[46:47]
	v_cndmask_b32_e64 v246, v58, v66, s[40:41]
	v_cndmask_b32_e64 v247, v59, v67, s[40:41]
	v_mul_f32_e32 v19, v19, v19
	v_fmac_f32_e32 v19, v18, v18
	v_mul_f32_e32 v18, v21, v21
	v_mul_f32_e32 v29, v29, v29
	v_fmac_f32_e32 v18, v20, v20
	v_mul_f32_e32 v27, v27, v27
	v_fmac_f32_e32 v29, v28, v28
	v_mul_f32_e32 v28, v31, v31
	v_mul_f32_e32 v31, v33, v33
	v_add_f32_e32 v18, v19, v18
	v_mul_f32_e32 v19, v23, v23
	v_mul_f32_e32 v20, v25, v25
	v_fmac_f32_e32 v31, v32, v32
	v_fmac_f32_e32 v19, v22, v22
	v_fmac_f32_e32 v20, v24, v24
	v_fmac_f32_e32 v27, v26, v26
	v_fmac_f32_e32 v28, v30, v30
	v_add_f32_e32 v19, v19, v20
	v_add_f32_e32 v20, v27, v29
	v_add_f32_e32 v21, v28, v31
	v_add_f32_e32 v18, v20, v18
	v_add_f32_e32 v19, v21, v19
	s_nop 1
	v_mov_b32_dpp v20, v18 quad_perm:[1,0,3,2] row_mask:0xf bank_mask:0xf
	s_nop 1
	v_mov_b32_dpp v21, v19 quad_perm:[1,0,3,2] row_mask:0xf bank_mask:0xf
	s_waitcnt lgkmcnt(1)
	v_add_f32_e32 v18, v18, v20
	s_waitcnt lgkmcnt(0)
	v_add_f32_e32 v21, v19, v21
	s_nop 1
	v_mov_b32_dpp v20, v18 quad_perm:[2,3,0,1] row_mask:0xf bank_mask:0xf
	s_nop 1
	v_mov_b32_dpp v22, v21 quad_perm:[2,3,0,1] row_mask:0xf bank_mask:0xf
	s_waitcnt lgkmcnt(1)
	v_add_f32_e32 v18, v18, v20
	s_waitcnt lgkmcnt(0)
	v_add_f32_e32 v20, v21, v22
	s_nop 1
	v_mov_b32_dpp v19, v18 row_half_mirror row_mask:0xf bank_mask:0xf
	s_nop 1
	v_mov_b32_dpp v21, v20 row_half_mirror row_mask:0xf bank_mask:0xf
	v_add_u32_e32 v22, 0x1040, v60
	v_cndmask_b32_e64 v22, v60, v22, s[38:39]
	global_store_dwordx2 v22, v[246:247], s[46:47]
	s_and_saveexec_b64 s[16:17], s[42:43]
	s_cbranch_execz .LBB0_1323
	s_waitcnt lgkmcnt(1)
	v_add_f32_e32 v18, v18, v19
	s_waitcnt lgkmcnt(0)
	v_add_f32_e32 v19, v20, v21
	ds_write2_b32 v194, v18, v19 offset0:96 offset1:104
; #define LAS __attribute__((address_space(3)))
; __device__ __forceinline__ unsigned cvt_pk_bf16(float lo, float hi) { unsigned r; asm volatile("v_cvt_pk_bf16_f32 %0, %1, %2" : "=v"(r) : "v"(lo), "v"(hi)); return r; }
;     __device__ __forceinline__ void operator()(const f32x4 (&acc)[2][2][4][2], const Unit& u, int wr, int wc, int fr, int fq) const {
;     ...
;             if (g + 1 < 8) ERN_LOADX(g + 1);
;             float sq0 = 0.f, sq1 = 0.f; u32x2 hw[2][2];
; #pragma unroll
;             for (int bj = 0; bj < 2; ++bj) {
;                 *(LAS f32x4*)(st + wr_off) = acc[ai][bj][m][0]; *(LAS f32x4*)(st + wr_off + 64) = acc[ai][bj][m][1];
;                 const f32x4 a0 = *(const LAS f32x4*)(st + rd_off), a1 = *(const LAS f32x4*)(st + rd_off + 8 * 144);
;                 { const f32x4 xv = xb[g & 1][bj][0] + gv[bj] * a0; __builtin_nontemporal_store(xv, (f32x4*)((char*)xo + 4u * ERN_EOFF(g, bj, 0)));
;                   sq0 += (xv.x * xv.x + xv.y * xv.y) + (xv.z * xv.z + xv.w * xv.w);
;                   const f32x4 hv = xv * gsn[bj]; hw[bj][0].x = cvt_pk_bf16(hv.x, hv.y); hw[bj][0].y = cvt_pk_bf16(hv.z, hv.w); }
;                 { const f32x4 xv = xb[g & 1][bj][1] + gv[bj] * a1; __builtin_nontemporal_store(xv, (f32x4*)((char*)xo + 4u * ERN_EOFF(g, bj, 1)));
;                   sq1 += (xv.x * xv.x + xv.y * xv.y) + (xv.z * xv.z + xv.w * xv.w);
;                   const f32x4 hv = xv * gsn[bj]; hw[bj][1].x = cvt_pk_bf16(hv.x, hv.y); hw[bj][1].y = cvt_pk_bf16(hv.z, hv.w); }
;             }
;             if (!NOH && !PLAIN) {
; #pragma unroll
;                 for (int rh = 0; rh < 2; ++rh) { u32x2 rv; rv.x = __shfl_xor(hw[1][rh].x, 8); rv.y = __shfl_xor(hw[1][rh].y, 8);
;                     const unsigned e0 = ERN_EOFF(g, 0, rh);
;                     const unsigned ee = odd ? (e0 - DM + 32) : e0, eo2 = odd ? e0 : (e0 + DM + 32);
;                     *(u32x2*)((char*)ho + 2u * ee) = odd ? rv : hw[0][rh];
;                     *(u32x2*)((char*)ho + 2u * eo2) = odd ? hw[0][rh] : rv; }
;             }
;             if (!PLAIN) { sq0 += __shfl_xor(sq0, 1); sq0 += __shfl_xor(sq0, 2); sq0 += __shfl_xor(sq0, 4);
;             sq1 += __shfl_xor(sq1, 1); sq1 += __shfl_xor(sq1, 2); sq1 += __shfl_xor(sq1, 4); }
;             if (!PLAIN && pc == 0) { sst[g * 16 + rr] = sq0; sst[g * 16 + 8 + rr] = sq1; }
.LBB0_1323:
	s_or_b64 exec, exec, s[16:17]
	ds_write_b128 v200, v[14:17]
	ds_write_b128 v200, v[10:13] offset:64
	ds_read_b128 v[10:13], v201
	ds_read_b128 v[14:17], v201 offset:1152
	s_waitcnt lgkmcnt(5)
	v_lshl_add_u64 v[18:19], s[48:49], 0, v[162:163]
	v_mov_b32_e32 v79, v163
	v_lshl_add_u64 v[22:23], s[48:49], 0, v[78:79]
	s_waitcnt vmcnt(9) lgkmcnt(1)
	v_pk_fma_f32 v[12:13], v[56:57], v[12:13], v[48:49]
	v_pk_fma_f32 v[10:11], v[54:55], v[10:11], v[46:47]
	global_store_dwordx4 v[18:19], v[10:13], off nt
	v_pk_mul_f32 v[18:19], v[178:179], v[12:13]
	v_pk_mul_f32 v[20:21], v[180:181], v[10:11]
	s_waitcnt vmcnt(9) lgkmcnt(0)
	v_pk_fma_f32 v[14:15], v[54:55], v[14:15], v[42:43]
	v_cvt_pk_bf16_f32 v20, v20, v21
	v_cvt_pk_bf16_f32 v21, v18, v19
	v_pk_fma_f32 v[16:17], v[56:57], v[16:17], v[44:45]
	v_pk_mul_f32 v[18:19], v[180:181], v[14:15]
	global_store_dwordx4 v[22:23], v[14:17], off nt
	v_pk_mul_f32 v[22:23], v[178:179], v[16:17]
	v_cvt_pk_bf16_f32 v18, v18, v19
	v_mov_b32_e32 v77, v163
	v_cvt_pk_bf16_f32 v19, v22, v23
	ds_write_b128 v200, v[6:9]
	ds_write_b128 v200, v[2:5] offset:64
	ds_read_b128 v[2:5], v201
	ds_read_b128 v[6:9], v201 offset:1152
	v_lshl_add_u64 v[22:23], s[48:49], 0, v[76:77]
	v_mov_b32_e32 v75, v163
	v_lshl_add_u64 v[24:25], s[48:49], 0, v[74:75]
	s_waitcnt vmcnt(9) lgkmcnt(1)
	v_pk_fma_f32 v[4:5], v[52:53], v[4:5], v[40:41]
	v_pk_fma_f32 v[2:3], v[50:51], v[2:3], v[38:39]
	global_store_dwordx4 v[22:23], v[2:5], off nt
	v_pk_mul_f32 v[22:23], v[174:175], v[4:5]
	v_pk_mul_f32 v[26:27], v[176:177], v[2:3]
	s_waitcnt vmcnt(9) lgkmcnt(0)
	v_pk_fma_f32 v[8:9], v[52:53], v[8:9], v[36:37]
	v_cvt_pk_bf16_f32 v28, v26, v27
	v_cvt_pk_bf16_f32 v23, v22, v23
	ds_bpermute_b32 v22, v203, v28
	ds_bpermute_b32 v23, v203, v23
	v_pk_fma_f32 v[6:7], v[50:51], v[6:7], v[34:35]
	global_store_dwordx4 v[24:25], v[6:9], off nt
	v_pk_mul_f32 v[26:27], v[174:175], v[8:9]
	v_pk_mul_f32 v[24:25], v[176:177], v[6:7]
	s_nop 0
	v_cvt_pk_bf16_f32 v24, v24, v25
	v_cvt_pk_bf16_f32 v25, v26, v27
	v_add_u32_e32 v27, 0x58000, v202
	v_lshlrev_b32_e32 v26, 1, v27
	s_waitcnt lgkmcnt(0)
	v_add_u32_e32 v250, 0xfffff040, v26
	v_cndmask_b32_e64 v250, v26, v250, s[40:41]
	v_cndmask_b32_e64 v248, v20, v22, s[40:41]
	v_cndmask_b32_e64 v249, v21, v23, s[40:41]
	global_store_dwordx2 v250, v[248:249], s[46:47]
	v_cndmask_b32_e64 v246, v22, v20, s[40:41]
	v_cndmask_b32_e64 v247, v23, v21, s[40:41]
	s_waitcnt lgkmcnt(1)
	v_add_u32_e32 v22, 0x1040, v26
	v_cndmask_b32_e64 v22, v26, v22, s[38:39]
	global_store_dwordx2 v22, v[246:247], s[46:47]
	ds_bpermute_b32 v20, v203, v24
	ds_bpermute_b32 v21, v203, v25
	s_waitcnt lgkmcnt(2)
	v_add_u32_e32 v23, 0x5c000, v202
	v_lshlrev_b32_e32 v22, 1, v23
	s_waitcnt lgkmcnt(0)
	v_add_u32_e32 v250, 0xfffff040, v22
	v_cndmask_b32_e64 v250, v22, v250, s[40:41]
	v_cndmask_b32_e64 v248, v18, v20, s[40:41]
	v_cndmask_b32_e64 v249, v19, v21, s[40:41]
	global_store_dwordx2 v250, v[248:249], s[46:47]
	v_cndmask_b32_e64 v246, v20, v18, s[40:41]
	v_cndmask_b32_e64 v247, v21, v19, s[40:41]
	v_mul_f32_e32 v3, v3, v3
	v_fmac_f32_e32 v3, v2, v2
	v_mul_f32_e32 v2, v5, v5
	v_mul_f32_e32 v13, v13, v13
	v_fmac_f32_e32 v2, v4, v4
	v_mul_f32_e32 v11, v11, v11
	v_fmac_f32_e32 v13, v12, v12
	v_mul_f32_e32 v12, v15, v15
	v_mul_f32_e32 v15, v17, v17
	v_add_f32_e32 v2, v3, v2
	v_mul_f32_e32 v3, v7, v7
	v_mul_f32_e32 v4, v9, v9
	v_fmac_f32_e32 v15, v16, v16
	v_fmac_f32_e32 v3, v6, v6
	v_fmac_f32_e32 v4, v8, v8
	v_fmac_f32_e32 v11, v10, v10
	v_fmac_f32_e32 v12, v14, v14
	v_add_f32_e32 v3, v3, v4
	v_add_f32_e32 v4, v11, v13
	v_add_f32_e32 v5, v12, v15
	v_add_f32_e32 v2, v4, v2
	v_add_f32_e32 v3, v5, v3
	s_nop 1
	v_mov_b32_dpp v4, v2 quad_perm:[1,0,3,2] row_mask:0xf bank_mask:0xf
	s_nop 1
	v_mov_b32_dpp v5, v3 quad_perm:[1,0,3,2] row_mask:0xf bank_mask:0xf
	s_waitcnt lgkmcnt(1)
	v_add_f32_e32 v2, v2, v4
	s_waitcnt lgkmcnt(0)
	v_add_f32_e32 v5, v3, v5
	s_nop 1
	v_mov_b32_dpp v4, v2 quad_perm:[2,3,0,1] row_mask:0xf bank_mask:0xf
	s_nop 1
	v_mov_b32_dpp v6, v5 quad_perm:[2,3,0,1] row_mask:0xf bank_mask:0xf
	s_waitcnt lgkmcnt(1)
	v_add_f32_e32 v2, v2, v4
	s_waitcnt lgkmcnt(0)
	v_add_f32_e32 v4, v5, v6
	s_nop 1
	v_mov_b32_dpp v3, v2 row_half_mirror row_mask:0xf bank_mask:0xf
	s_nop 1
	v_mov_b32_dpp v5, v4 row_half_mirror row_mask:0xf bank_mask:0xf
	v_add_u32_e32 v6, 0x1040, v22
	v_cndmask_b32_e64 v6, v22, v6, s[38:39]
	global_store_dwordx2 v6, v[246:247], s[46:47]
	s_and_saveexec_b64 s[16:17], s[42:43]
	s_cbranch_execz .LBB0_1333
	s_waitcnt lgkmcnt(1)
	v_add_f32_e32 v2, v2, v3
	s_waitcnt lgkmcnt(0)
	v_add_f32_e32 v3, v4, v5
	ds_write2_b32 v194, v2, v3 offset0:112 offset1:120

; #define LAS __attribute__((address_space(3)))
;     __device__ __forceinline__ void operator()(const f32x4 (&acc)[2][2][4][2], const Unit& u, int wr, int wc, int fr, int fq) const {
;         const int s = u.pm >> 5, lane = fq * 16 + fr, rr = lane >> 3, pc = lane & 7;
;         const float* __restrict__ xi = xin + (size_t)u.pm * BM * DM; float* __restrict__ xo = xout + (size_t)u.pm * BM * DM; bf16_t* __restrict__ ho = Hn + (size_t)u.pm * BM * DM;
;         LAS unsigned char* st = lds_epi + (wr * 4 + wc) * 2304;
;         LAS float* sst = (LAS float*)(lds_epi + 18432 + (wr * 4 + wc) * 512);
;         const int colr = u.pn * BM + wc * 64 + 4 * pc;
;         const unsigned eb = (unsigned)((wr * 64 + rr) * DM + colr);
;         f32x4 gv[2], gsn[2];
; #pragma unroll
;         for (int bj = 0; bj < 2; ++bj) { gv[bj] = *(const f32x4*)(gate + (size_t)s * MODW + colr + bj * 32) * (0.5f * GS2);
;             if (!PLAIN) gsn[bj] = *(const f32x4*)(gnext + colr + bj * 32) * (*(const f32x4*)(scnext + (size_t)s * MODW + colr + bj * 32) + 1.0f); else gsn[bj] = gv[bj]; }
;         const unsigned wr_off = (unsigned)(fr * 144 + 16 * fq), rd_off = (unsigned)(rr * 144 + pc * 16);
;         const bool odd = (rr & 1) != 0;
;         f32x4 xb[2][2][2];
;     ...
;         ERN_LOADX(0);
; #pragma unroll
;         for (int g = 0; g < 8; ++g) { const int ai = g >> 2, m = g & 3;
;             if (g + 1 < 8) ERN_LOADX(g + 1);
;             float sq0 = 0.f, sq1 = 0.f; u32x2 hw[2][2];
; #pragma unroll
;             for (int bj = 0; bj < 2; ++bj) {
;                 *(LAS f32x4*)(st + wr_off) = acc[ai][bj][m][0]; *(LAS f32x4*)(st + wr_off + 64) = acc[ai][bj][m][1];
;                 const f32x4 a0 = *(const LAS f32x4*)(st + rd_off), a1 = *(const LAS f32x4*)(st + rd_off + 8 * 144);
;                 { const f32x4 xv = xb[g & 1][bj][0] + gv[bj] * a0; __builtin_nontemporal_store(xv, (f32x4*)((char*)xo + 4u * ERN_EOFF(g, bj, 0)));
;                   sq0 += (xv.x * xv.x + xv.y * xv.y) + (xv.z * xv.z + xv.w * xv.w);
;                   const f32x4 hv = xv * gsn[bj]; hw[bj][0].x = cvt_pk_bf16(hv.x, hv.y); hw[bj][0].y = cvt_pk_bf16(hv.z, hv.w); }
;                 { const f32x4 xv = xb[g & 1][bj][1] + gv[bj] * a1; __builtin_nontemporal_store(xv, (f32x4*)((char*)xo + 4u * ERN_EOFF(g, bj, 1)));
;                   sq1 += (xv.x * xv.x + xv.y * xv.y) + (xv.z * xv.z + xv.w * xv.w);
.LBB0_1598:
	s_ashr_i32 s16, s8, 5
	s_ashr_i32 s9, s8, 31
	v_lshl_or_b32 v130, s0, 8, v192
	s_mul_i32 s20, s16, 0x12000
	s_mul_hi_i32 s0, s16, 0x12000
	s_add_u32 s16, s37, s20
	v_ashrrev_i32_e32 v131, 31, v130
	s_addc_u32 s17, s48, s0
	v_lshlrev_b64 v[132:133], 2, v[130:131]
	v_lshl_add_u64 v[134:135], s[16:17], 0, v[132:133]
	s_add_u32 s16, s26, s20
	s_addc_u32 s17, s27, s0
	v_lshl_add_u64 v[136:137], s[4:5], 0, v[132:133]
	v_lshl_add_u64 v[132:133], s[16:17], 0, v[132:133]
	s_lshl_b64 s[16:17], s[8:9], 21
	s_add_u32 s22, s90, s16
	v_add_u32_e32 v202, v130, v193
	s_addc_u32 s23, s91, s17
	v_lshlrev_b32_e32 v205, 2, v202
	global_load_dwordx4 v[170:173], v[136:137], off
	global_load_dwordx4 v[166:169], v[134:135], off
	global_load_dwordx4 v[186:189], v[134:135], off offset:128
	global_load_dwordx4 v[206:209], v[132:133], off
	global_load_dwordx4 v[210:213], v[132:133], off offset:128
	global_load_dwordx4 v[214:217], v205, s[22:23]
	v_add_u32_e32 v130, 0x10000, v205
	global_load_dwordx4 v[218:221], v130, s[22:23]
	global_load_dwordx4 v[222:225], v[136:137], off offset:128
	global_load_dwordx4 v[226:229], v205, s[22:23] offset:128
	v_add_u32_e32 v204, 0x10080, v205
	global_load_dwordx4 v[230:233], v204, s[22:23]
	v_add_u32_e32 v130, 0x20000, v205
	v_add_u32_e32 v154, 0x30000, v205
	v_add_u32_e32 v184, 0x20080, v205
	v_add_u32_e32 v182, 0x30080, v205
	global_load_dwordx4 v[142:145], v130, s[22:23]
	global_load_dwordx4 v[138:141], v154, s[22:23]
	global_load_dwordx4 v[134:137], v184, s[22:23]
	s_nop 0
	global_load_dwordx4 v[130:133], v182, s[22:23]
	ds_write_b128 v200, v[126:129]
	ds_write_b128 v200, v[122:125] offset:64
	v_and_b32_e32 v127, 64, v199
	ds_read_b128 v[122:125], v201
	ds_read_b128 v[234:237], v201 offset:1152
	v_xor_b32_e32 v126, 8, v199
	v_add_u32_e32 v183, 64, v127
	v_cmp_lt_i32_e32 vcc, v126, v183
	v_add_u32_e32 v185, 0x4000, v202
	v_lshlrev_b32_e32 v238, 2, v185
	v_cndmask_b32_e32 v126, v199, v126, vcc
	v_lshlrev_b32_e32 v203, 2, v126
	s_lshl_b64 s[16:17], s[8:9], 20
	s_add_u32 s20, s93, s16
	s_addc_u32 s21, s92, s17
	s_waitcnt vmcnt(0)
	v_pk_mul_f32 v[180:181], v[166:167], 0.5 op_sel_hi:[1,0]
	v_pk_mul_f32 v[176:177], v[168:169], 0.5 op_sel_hi:[1,0]
	v_pk_add_f32 v[126:127], v[208:209], 1.0 op_sel_hi:[1,0]
	v_pk_add_f32 v[128:129], v[206:207], 1.0 op_sel_hi:[1,0]
	v_pk_mul_f32 v[174:175], v[172:173], v[126:127]
	v_pk_mul_f32 v[178:179], v[170:171], v[128:129]
	s_waitcnt lgkmcnt(1)
	v_pk_fma_f32 v[126:127], v[180:181], v[122:123], v[214:215]
	s_waitcnt lgkmcnt(0)
	v_pk_fma_f32 v[122:123], v[180:181], v[234:235], v[218:219]
	v_pk_mul_f32 v[168:169], v[186:187], 0.5 op_sel_hi:[1,0]
	v_pk_fma_f32 v[128:129], v[176:177], v[124:125], v[216:217]
	v_pk_fma_f32 v[124:125], v[176:177], v[236:237], v[220:221]
	v_pk_mul_f32 v[186:187], v[178:179], v[122:123]
	v_pk_mul_f32 v[166:167], v[188:189], 0.5 op_sel_hi:[1,0]
	global_store_dwordx4 v205, v[126:129], s[22:23] nt
	v_pk_mul_f32 v[170:171], v[174:175], v[128:129]
	v_pk_mul_f32 v[172:173], v[178:179], v[126:127]
	v_pk_mul_f32 v[206:207], v[174:175], v[124:125]
	v_cvt_pk_bf16_f32 v188, v172, v173
	v_cvt_pk_bf16_f32 v189, v170, v171
	global_store_dwordx4 v238, v[122:125], s[22:23] nt
	v_cvt_pk_bf16_f32 v186, v186, v187
	v_cvt_pk_bf16_f32 v187, v206, v207
	ds_write_b128 v200, v[118:121]
	ds_write_b128 v200, v[114:117] offset:64
	ds_read_b128 v[114:117], v201
	ds_read_b128 v[206:209], v201 offset:1152
	v_pk_add_f32 v[190:191], v[212:213], 1.0 op_sel_hi:[1,0]
	v_pk_add_f32 v[118:119], v[210:211], 1.0 op_sel_hi:[1,0]
	v_pk_mul_f32 v[170:171], v[224:225], v[190:191]
	v_pk_mul_f32 v[172:173], v[222:223], v[118:119]
	s_waitcnt lgkmcnt(1)
	v_pk_fma_f32 v[120:121], v[166:167], v[116:117], v[228:229]
	v_pk_fma_f32 v[118:119], v[168:169], v[114:115], v[226:227]
	s_waitcnt lgkmcnt(0)
	v_pk_fma_f32 v[114:115], v[168:169], v[206:207], v[230:231]
	v_pk_mul_f32 v[190:191], v[170:171], v[120:121]
	v_pk_mul_f32 v[206:207], v[172:173], v[118:119]
	global_store_dwordx4 v205, v[118:121], s[22:23] offset:128 nt
	v_cvt_pk_bf16_f32 v206, v206, v207
	v_cvt_pk_bf16_f32 v191, v190, v191
	ds_bpermute_b32 v190, v203, v206
	ds_bpermute_b32 v191, v203, v191
	v_pk_fma_f32 v[116:117], v[166:167], v[208:209], v[232:233]
	v_pk_mul_f32 v[206:207], v[172:173], v[114:115]
	global_store_dwordx4 v204, v[114:117], s[22:23] nt
	v_cvt_pk_bf16_f32 v204, v206, v207
	v_lshlrev_b32_e32 v207, 1, v202
	v_pk_mul_f32 v[208:209], v[170:171], v[116:117]
	s_nop 0
	v_cvt_pk_bf16_f32 v206, v208, v209
	s_waitcnt lgkmcnt(0)
	v_add_u32_e32 v250, 0xfffff040, v207
	v_cndmask_b32_e64 v250, v207, v250, s[40:41]
	v_cndmask_b32_e64 v248, v188, v190, s[40:41]
	v_cndmask_b32_e64 v249, v189, v191, s[40:41]
	global_store_dwordx2 v250, v[248:249], s[20:21]
	v_cndmask_b32_e64 v246, v190, v188, s[40:41]
	v_cndmask_b32_e64 v247, v191, v189, s[40:41]
	s_waitcnt lgkmcnt(1)
	v_add_u32_e32 v190, 0x1040, v207
	v_cndmask_b32_e64 v190, v207, v190, s[38:39]
	global_store_dwordx2 v190, v[246:247], s[20:21]
	ds_bpermute_b32 v188, v203, v204
	ds_bpermute_b32 v189, v203, v206
	v_lshlrev_b32_e32 v206, 1, v185
	s_waitcnt lgkmcnt(0)
; #define LAS __attribute__((address_space(3)))
; __device__ __forceinline__ unsigned cvt_pk_bf16(float lo, float hi) { unsigned r; asm volatile("v_cvt_pk_bf16_f32 %0, %1, %2" : "=v"(r) : "v"(lo), "v"(hi)); return r; }
;     __device__ __forceinline__ void operator()(const f32x4 (&acc)[2][2][4][2], const Unit& u, int wr, int wc, int fr, int fq) const {
;     ...
;             if (g + 1 < 8) ERN_LOADX(g + 1);
;             float sq0 = 0.f, sq1 = 0.f; u32x2 hw[2][2];
; #pragma unroll
;             for (int bj = 0; bj < 2; ++bj) {
;                 *(LAS f32x4*)(st + wr_off) = acc[ai][bj][m][0]; *(LAS f32x4*)(st + wr_off + 64) = acc[ai][bj][m][1];
;                 const f32x4 a0 = *(const LAS f32x4*)(st + rd_off), a1 = *(const LAS f32x4*)(st + rd_off + 8 * 144);
;                 { const f32x4 xv = xb[g & 1][bj][0] + gv[bj] * a0; __builtin_nontemporal_store(xv, (f32x4*)((char*)xo + 4u * ERN_EOFF(g, bj, 0)));
;                   sq0 += (xv.x * xv.x + xv.y * xv.y) + (xv.z * xv.z + xv.w * xv.w);
;                   const f32x4 hv = xv * gsn[bj]; hw[bj][0].x = cvt_pk_bf16(hv.x, hv.y); hw[bj][0].y = cvt_pk_bf16(hv.z, hv.w); }
;                 { const f32x4 xv = xb[g & 1][bj][1] + gv[bj] * a1; __builtin_nontemporal_store(xv, (f32x4*)((char*)xo + 4u * ERN_EOFF(g, bj, 1)));
;                   sq1 += (xv.x * xv.x + xv.y * xv.y) + (xv.z * xv.z + xv.w * xv.w);
;                   const f32x4 hv = xv * gsn[bj]; hw[bj][1].x = cvt_pk_bf16(hv.x, hv.y); hw[bj][1].y = cvt_pk_bf16(hv.z, hv.w); }
;             }
;             if (!NOH && !PLAIN) {
; #pragma unroll
;                 for (int rh = 0; rh < 2; ++rh) { u32x2 rv; rv.x = __shfl_xor(hw[1][rh].x, 8); rv.y = __shfl_xor(hw[1][rh].y, 8);
;                     const unsigned e0 = ERN_EOFF(g, 0, rh);
;                     const unsigned ee = odd ? (e0 - DM + 32) : e0, eo2 = odd ? e0 : (e0 + DM + 32);
;                     *(u32x2*)((char*)ho + 2u * ee) = odd ? rv : hw[0][rh];
;                     *(u32x2*)((char*)ho + 2u * eo2) = odd ? hw[0][rh] : rv; }
;             }
;             if (!PLAIN) { sq0 += __shfl_xor(sq0, 1); sq0 += __shfl_xor(sq0, 2); sq0 += __shfl_xor(sq0, 4);
;             sq1 += __shfl_xor(sq1, 1); sq1 += __shfl_xor(sq1, 2); sq1 += __shfl_xor(sq1, 4); }
;             if (!PLAIN && pc == 0) { sst[g * 16 + rr] = sq0; sst[g * 16 + 8 + rr] = sq1; }
	v_add_u32_e32 v250, 0xfffff040, v206
	v_cndmask_b32_e64 v250, v206, v250, s[40:41]
	v_cndmask_b32_e64 v248, v186, v188, s[40:41]
	v_cndmask_b32_e64 v249, v187, v189, s[40:41]
	global_store_dwordx2 v250, v[248:249], s[20:21]
	v_cndmask_b32_e64 v246, v188, v186, s[40:41]
	v_cndmask_b32_e64 v247, v189, v187, s[40:41]
	v_mul_f32_e32 v119, v119, v119
	v_mul_f32_e32 v127, v127, v127
	v_mul_f32_e32 v129, v129, v129
	v_fmac_f32_e32 v119, v118, v118
	v_mul_f32_e32 v118, v121, v121
	v_fmac_f32_e32 v129, v128, v128
	v_fmac_f32_e32 v118, v120, v120
	v_mul_f32_e32 v115, v115, v115
	v_fmac_f32_e32 v127, v126, v126
	v_add_f32_e32 v118, v119, v118
	v_fmac_f32_e32 v115, v114, v114
	v_mul_f32_e32 v114, v117, v117
	v_add_f32_e32 v117, v127, v129
	v_add_f32_e32 v117, v117, v118
	v_xor_b32_e32 v118, 1, v199
	v_cmp_lt_i32_e32 vcc, v118, v183
	v_mul_f32_e32 v123, v123, v123
	v_mul_f32_e32 v125, v125, v125
	v_cndmask_b32_e32 v118, v199, v118, vcc
	v_lshlrev_b32_e32 v190, 2, v118
	s_nop 1
	v_mov_b32_dpp v118, v117 quad_perm:[1,0,3,2] row_mask:0xf bank_mask:0xf
	v_fmac_f32_e32 v114, v116, v116
	v_fmac_f32_e32 v125, v124, v124
	v_fmac_f32_e32 v123, v122, v122
	v_add_f32_e32 v114, v115, v114
	s_waitcnt lgkmcnt(0)
	v_add_f32_e32 v116, v117, v118
	v_xor_b32_e32 v117, 2, v199
	v_cmp_lt_i32_e32 vcc, v117, v183
	v_add_f32_e32 v115, v123, v125
	v_add_f32_e32 v115, v115, v114
	v_cndmask_b32_e32 v117, v199, v117, vcc
	v_lshlrev_b32_e32 v191, 2, v117
	s_nop 1
	v_mov_b32_dpp v117, v116 quad_perm:[2,3,0,1] row_mask:0xf bank_mask:0xf
	s_nop 1
	v_mov_b32_dpp v118, v115 quad_perm:[1,0,3,2] row_mask:0xf bank_mask:0xf
	s_waitcnt lgkmcnt(1)
	v_add_f32_e32 v114, v116, v117
	s_waitcnt lgkmcnt(0)
	v_add_f32_e32 v117, v115, v118
	s_nop 1
	v_mov_b32_dpp v118, v117 quad_perm:[2,3,0,1] row_mask:0xf bank_mask:0xf
	v_xor_b32_e32 v116, 4, v199
	v_cmp_lt_i32_e32 vcc, v116, v183
	s_nop 1
	v_cndmask_b32_e32 v115, v199, v116, vcc
	v_lshlrev_b32_e32 v204, 2, v115
	s_waitcnt lgkmcnt(0)
	v_add_f32_e32 v116, v117, v118
	s_nop 1
	v_mov_b32_dpp v115, v114 row_half_mirror row_mask:0xf bank_mask:0xf
	s_nop 1
	v_mov_b32_dpp v117, v116 row_half_mirror row_mask:0xf bank_mask:0xf
	v_add_u32_e32 v118, 0x1040, v206
	v_cndmask_b32_e64 v118, v206, v118, s[38:39]
	global_store_dwordx2 v118, v[246:247], s[20:21]
	s_and_saveexec_b64 s[16:17], s[42:43]
	s_cbranch_execz .LBB0_1608
	s_waitcnt lgkmcnt(1)
	v_add_f32_e32 v114, v114, v115
	s_waitcnt lgkmcnt(0)
	v_add_f32_e32 v115, v116, v117
	ds_write2_b32 v194, v114, v115 offset1:8
.LBB0_1608:
	s_or_b64 exec, exec, s[16:17]
	v_lshl_add_u64 v[206:207], s[22:23], 0, v[154:155]
	v_add_u32_e32 v114, 0x40000, v205
	v_add_u32_e32 v154, 0x50000, v205
	v_add_u32_e32 v186, 0x40080, v205
	global_load_dwordx4 v[122:125], v154, s[22:23]
	global_load_dwordx4 v[118:121], v186, s[22:23]
	v_add_u32_e32 v188, 0x50080, v205
	global_load_dwordx4 v[126:129], v114, s[22:23]
	s_waitcnt lgkmcnt(0)
	global_load_dwordx4 v[114:117], v188, s[22:23]
	ds_write_b128 v200, v[110:113]
	ds_write_b128 v200, v[106:109] offset:64
	ds_read_b128 v[106:109], v201
	ds_read_b128 v[110:113], v201 offset:1152
	v_mov_b32_e32 v185, v155
	v_mov_b32_e32 v183, v155
	v_lshl_add_u64 v[182:183], s[22:23], 0, v[182:183]
	s_waitcnt lgkmcnt(1)
	v_pk_fma_f32 v[108:109], v[176:177], v[108:109], v[144:145]
	v_add_u32_e32 v144, 0x8000, v202
	v_pk_fma_f32 v[106:107], v[180:181], v[106:107], v[142:143]
	v_lshlrev_b32_e32 v142, 2, v144
	s_waitcnt lgkmcnt(0)
	v_pk_fma_f32 v[110:111], v[180:181], v[110:111], v[138:139]
	global_store_dwordx4 v142, v[106:109], s[22:23] nt
	v_pk_mul_f32 v[142:143], v[178:179], v[106:107]
	v_pk_fma_f32 v[112:113], v[176:177], v[112:113], v[140:141]
	v_pk_mul_f32 v[138:139], v[178:179], v[110:111]
	v_pk_mul_f32 v[208:209], v[174:175], v[108:109]
	v_cvt_pk_bf16_f32 v142, v142, v143
	v_pk_mul_f32 v[140:141], v[174:175], v[112:113]
	v_cvt_pk_bf16_f32 v143, v208, v209
	global_store_dwordx4 v[206:207], v[110:113], off nt
	v_cvt_pk_bf16_f32 v138, v138, v139
	v_cvt_pk_bf16_f32 v139, v140, v141
	ds_write_b128 v200, v[102:105]
	ds_write_b128 v200, v[98:101] offset:64
	ds_read_b128 v[98:101], v201
	ds_read_b128 v[102:105], v201 offset:1152
	v_lshl_add_u64 v[140:141], s[22:23], 0, v[184:185]
	s_waitcnt lgkmcnt(1)
	v_pk_fma_f32 v[98:99], v[168:169], v[98:99], v[134:135]
	v_pk_fma_f32 v[100:101], v[166:167], v[100:101], v[136:137]
	v_pk_mul_f32 v[136:137], v[172:173], v[98:99]
	global_store_dwordx4 v[140:141], v[98:101], off nt
	v_pk_mul_f32 v[134:135], v[170:171], v[100:101]
	v_cvt_pk_bf16_f32 v136, v136, v137
	s_waitcnt lgkmcnt(0)
	v_pk_fma_f32 v[102:103], v[168:169], v[102:103], v[130:131]
	v_cvt_pk_bf16_f32 v137, v134, v135
	ds_bpermute_b32 v130, v203, v136
	ds_bpermute_b32 v131, v203, v137
	v_pk_fma_f32 v[104:105], v[166:167], v[104:105], v[132:133]
	v_pk_mul_f32 v[132:133], v[172:173], v[102:103]
	v_pk_mul_f32 v[134:135], v[170:171], v[104:105]
	global_store_dwordx4 v[182:183], v[102:105], off nt
	v_cvt_pk_bf16_f32 v132, v132, v133
	v_cvt_pk_bf16_f32 v133, v134, v135
	v_lshlrev_b32_e32 v134, 1, v144
	s_waitcnt lgkmcnt(0)
	v_add_u32_e32 v250, 0xfffff040, v134
	v_cndmask_b32_e64 v250, v134, v250, s[40:41]
	v_cndmask_b32_e64 v248, v142, v130, s[40:41]
	v_cndmask_b32_e64 v249, v143, v131, s[40:41]
	global_store_dwordx2 v250, v[248:249], s[20:21]
	v_cndmask_b32_e64 v246, v130, v142, s[40:41]
	v_cndmask_b32_e64 v247, v131, v143, s[40:41]
	s_waitcnt lgkmcnt(1)
	v_add_u32_e32 v130, 0x1040, v134
	v_cndmask_b32_e64 v130, v134, v130, s[38:39]
	global_store_dwordx2 v130, v[246:247], s[20:21]
	ds_bpermute_b32 v130, v203, v132
	s_waitcnt lgkmcnt(1)
	ds_bpermute_b32 v131, v203, v133
	v_add_u32_e32 v133, 0xc000, v202
	v_lshlrev_b32_e32 v132, 1, v133
	s_waitcnt lgkmcnt(0)
; #define LAS __attribute__((address_space(3)))
; __device__ __forceinline__ unsigned cvt_pk_bf16(float lo, float hi) { unsigned r; asm volatile("v_cvt_pk_bf16_f32 %0, %1, %2" : "=v"(r) : "v"(lo), "v"(hi)); return r; }
;     __device__ __forceinline__ void operator()(const f32x4 (&acc)[2][2][4][2], const Unit& u, int wr, int wc, int fr, int fq) const {
;     ...
;             if (g + 1 < 8) ERN_LOADX(g + 1);
;             float sq0 = 0.f, sq1 = 0.f; u32x2 hw[2][2];
; #pragma unroll
;             for (int bj = 0; bj < 2; ++bj) {
;                 *(LAS f32x4*)(st + wr_off) = acc[ai][bj][m][0]; *(LAS f32x4*)(st + wr_off + 64) = acc[ai][bj][m][1];
;                 const f32x4 a0 = *(const LAS f32x4*)(st + rd_off), a1 = *(const LAS f32x4*)(st + rd_off + 8 * 144);
;                 { const f32x4 xv = xb[g & 1][bj][0] + gv[bj] * a0; __builtin_nontemporal_store(xv, (f32x4*)((char*)xo + 4u * ERN_EOFF(g, bj, 0)));
;                   sq0 += (xv.x * xv.x + xv.y * xv.y) + (xv.z * xv.z + xv.w * xv.w);
;                   const f32x4 hv = xv * gsn[bj]; hw[bj][0].x = cvt_pk_bf16(hv.x, hv.y); hw[bj][0].y = cvt_pk_bf16(hv.z, hv.w); }
;                 { const f32x4 xv = xb[g & 1][bj][1] + gv[bj] * a1; __builtin_nontemporal_store(xv, (f32x4*)((char*)xo + 4u * ERN_EOFF(g, bj, 1)));
;                   sq1 += (xv.x * xv.x + xv.y * xv.y) + (xv.z * xv.z + xv.w * xv.w);
;                   const f32x4 hv = xv * gsn[bj]; hw[bj][1].x = cvt_pk_bf16(hv.x, hv.y); hw[bj][1].y = cvt_pk_bf16(hv.z, hv.w); }
;             }
;             if (!NOH && !PLAIN) {
; #pragma unroll
;                 for (int rh = 0; rh < 2; ++rh) { u32x2 rv; rv.x = __shfl_xor(hw[1][rh].x, 8); rv.y = __shfl_xor(hw[1][rh].y, 8);
;                     const unsigned e0 = ERN_EOFF(g, 0, rh);
;                     const unsigned ee = odd ? (e0 - DM + 32) : e0, eo2 = odd ? e0 : (e0 + DM + 32);
;                     *(u32x2*)((char*)ho + 2u * ee) = odd ? rv : hw[0][rh];
;                     *(u32x2*)((char*)ho + 2u * eo2) = odd ? hw[0][rh] : rv; }
;             }
;             if (!PLAIN) { sq0 += __shfl_xor(sq0, 1); sq0 += __shfl_xor(sq0, 2); sq0 += __shfl_xor(sq0, 4);
;             sq1 += __shfl_xor(sq1, 1); sq1 += __shfl_xor(sq1, 2); sq1 += __shfl_xor(sq1, 4); }
;             if (!PLAIN && pc == 0) { sst[g * 16 + rr] = sq0; sst[g * 16 + 8 + rr] = sq1; }
	v_add_u32_e32 v250, 0xfffff040, v132
	v_cndmask_b32_e64 v250, v132, v250, s[40:41]
	v_cndmask_b32_e64 v248, v138, v130, s[40:41]
	v_cndmask_b32_e64 v249, v139, v131, s[40:41]
	global_store_dwordx2 v250, v[248:249], s[20:21]
	v_cndmask_b32_e64 v246, v130, v138, s[40:41]
	v_cndmask_b32_e64 v247, v131, v139, s[40:41]
	v_mul_f32_e32 v99, v99, v99
	v_fmac_f32_e32 v99, v98, v98
	v_mul_f32_e32 v98, v101, v101
	v_mul_f32_e32 v109, v109, v109
	v_fmac_f32_e32 v98, v100, v100
	v_mul_f32_e32 v107, v107, v107
	v_fmac_f32_e32 v109, v108, v108
	v_mul_f32_e32 v108, v111, v111
	v_mul_f32_e32 v111, v113, v113
	v_add_f32_e32 v98, v99, v98
	v_mul_f32_e32 v99, v103, v103
	v_mul_f32_e32 v100, v105, v105
	v_fmac_f32_e32 v111, v112, v112
	v_fmac_f32_e32 v99, v102, v102
	v_fmac_f32_e32 v100, v104, v104
	v_fmac_f32_e32 v107, v106, v106
	v_fmac_f32_e32 v108, v110, v110
	v_add_f32_e32 v99, v99, v100
	v_add_f32_e32 v100, v107, v109
	v_add_f32_e32 v101, v108, v111
	v_add_f32_e32 v98, v100, v98
	v_add_f32_e32 v99, v101, v99
	s_nop 1
	v_mov_b32_dpp v100, v98 quad_perm:[1,0,3,2] row_mask:0xf bank_mask:0xf
	s_nop 1
	v_mov_b32_dpp v101, v99 quad_perm:[1,0,3,2] row_mask:0xf bank_mask:0xf
	s_waitcnt lgkmcnt(1)
	v_add_f32_e32 v98, v98, v100
	s_waitcnt lgkmcnt(0)
	v_add_f32_e32 v101, v99, v101
	s_nop 1
	v_mov_b32_dpp v100, v98 quad_perm:[2,3,0,1] row_mask:0xf bank_mask:0xf
	s_nop 1
	v_mov_b32_dpp v102, v101 quad_perm:[2,3,0,1] row_mask:0xf bank_mask:0xf
	s_waitcnt lgkmcnt(1)
	v_add_f32_e32 v98, v98, v100
	s_waitcnt lgkmcnt(0)
	v_add_f32_e32 v100, v101, v102
	s_nop 1
	v_mov_b32_dpp v99, v98 row_half_mirror row_mask:0xf bank_mask:0xf
	s_nop 1
	v_mov_b32_dpp v101, v100 row_half_mirror row_mask:0xf bank_mask:0xf
	v_add_u32_e32 v102, 0x1040, v132
	v_cndmask_b32_e64 v102, v132, v102, s[38:39]
	global_store_dwordx2 v102, v[246:247], s[20:21]
	s_and_saveexec_b64 s[16:17], s[42:43]
	s_cbranch_execz .LBB0_1618
	s_waitcnt lgkmcnt(1)
	v_add_f32_e32 v98, v98, v99
	s_waitcnt lgkmcnt(0)
	v_add_f32_e32 v99, v100, v101
	ds_write2_b32 v194, v98, v99 offset0:16 offset1:24
.LBB0_1618:
	s_or_b64 exec, exec, s[16:17]
	v_lshl_add_u64 v[134:135], s[22:23], 0, v[154:155]
	v_add_u32_e32 v98, 0x60000, v205
	v_add_u32_e32 v154, 0x70000, v205
	v_add_u32_e32 v130, 0x60080, v205
	global_load_dwordx4 v[106:109], v154, s[22:23]
	global_load_dwordx4 v[102:105], v130, s[22:23]
	v_add_u32_e32 v132, 0x70080, v205
	global_load_dwordx4 v[110:113], v98, s[22:23]
	s_waitcnt lgkmcnt(0)
	global_load_dwordx4 v[98:101], v132, s[22:23]
	ds_write_b128 v200, v[94:97]
	ds_write_b128 v200, v[90:93] offset:64
	ds_read_b128 v[90:93], v201
	ds_read_b128 v[94:97], v201 offset:1152
	v_mov_b32_e32 v187, v155
	v_mov_b32_e32 v189, v155
	s_waitcnt vmcnt(11) lgkmcnt(1)
	v_pk_fma_f32 v[92:93], v[176:177], v[92:93], v[128:129]
	v_add_u32_e32 v128, 0x10000, v202
	v_pk_fma_f32 v[90:91], v[180:181], v[90:91], v[126:127]
	v_lshlrev_b32_e32 v126, 2, v128
	s_waitcnt lgkmcnt(0)
	v_pk_fma_f32 v[94:95], v[180:181], v[94:95], v[122:123]
	global_store_dwordx4 v126, v[90:93], s[22:23] nt
	v_pk_mul_f32 v[126:127], v[178:179], v[90:91]
	v_pk_fma_f32 v[96:97], v[176:177], v[96:97], v[124:125]
	v_pk_mul_f32 v[122:123], v[178:179], v[94:95]
	v_pk_mul_f32 v[136:137], v[174:175], v[92:93]
	v_cvt_pk_bf16_f32 v126, v126, v127
	v_pk_mul_f32 v[124:125], v[174:175], v[96:97]
	v_cvt_pk_bf16_f32 v127, v136, v137
	global_store_dwordx4 v[134:135], v[94:97], off nt
	v_cvt_pk_bf16_f32 v122, v122, v123
	v_cvt_pk_bf16_f32 v123, v124, v125
	ds_write_b128 v200, v[86:89]
	ds_write_b128 v200, v[82:85] offset:64
	ds_read_b128 v[82:85], v201
	ds_read_b128 v[86:89], v201 offset:1152
	v_lshl_add_u64 v[124:125], s[22:23], 0, v[186:187]
	v_lshl_add_u64 v[134:135], s[22:23], 0, v[188:189]
	s_waitcnt lgkmcnt(1)
	v_pk_fma_f32 v[82:83], v[168:169], v[82:83], v[118:119]
	v_pk_fma_f32 v[84:85], v[166:167], v[84:85], v[120:121]
	v_pk_mul_f32 v[120:121], v[172:173], v[82:83]
	global_store_dwordx4 v[124:125], v[82:85], off nt
	v_pk_mul_f32 v[118:119], v[170:171], v[84:85]
	v_cvt_pk_bf16_f32 v120, v120, v121
	s_waitcnt vmcnt(13) lgkmcnt(0)
	v_pk_fma_f32 v[86:87], v[168:169], v[86:87], v[114:115]
	v_cvt_pk_bf16_f32 v121, v118, v119
	ds_bpermute_b32 v114, v203, v120
	ds_bpermute_b32 v115, v203, v121
	v_pk_fma_f32 v[88:89], v[166:167], v[88:89], v[116:117]
	v_pk_mul_f32 v[116:117], v[172:173], v[86:87]
	v_pk_mul_f32 v[118:119], v[170:171], v[88:89]
	global_store_dwordx4 v[134:135], v[86:89], off nt
	v_cvt_pk_bf16_f32 v116, v116, v117
	v_cvt_pk_bf16_f32 v117, v118, v119
	v_lshlrev_b32_e32 v118, 1, v128
	s_waitcnt lgkmcnt(0)
	v_add_u32_e32 v250, 0xfffff040, v118
	v_cndmask_b32_e64 v250, v118, v250, s[40:41]
	v_cndmask_b32_e64 v248, v126, v114, s[40:41]
	v_cndmask_b32_e64 v249, v127, v115, s[40:41]
	global_store_dwordx2 v250, v[248:249], s[20:21]
	v_cndmask_b32_e64 v246, v114, v126, s[40:41]
	v_cndmask_b32_e64 v247, v115, v127, s[40:41]
	s_waitcnt lgkmcnt(1)
	v_add_u32_e32 v114, 0x1040, v118
	v_cndmask_b32_e64 v114, v118, v114, s[38:39]
	global_store_dwordx2 v114, v[246:247], s[20:21]
	ds_bpermute_b32 v114, v203, v116
	s_waitcnt lgkmcnt(1)
	ds_bpermute_b32 v115, v203, v117
	v_add_u32_e32 v117, 0x14000, v202
	v_lshlrev_b32_e32 v116, 1, v117
	s_waitcnt lgkmcnt(0)
	v_add_u32_e32 v250, 0xfffff040, v116
	v_cndmask_b32_e64 v250, v116, v250, s[40:41]
	v_cndmask_b32_e64 v248, v122, v114, s[40:41]
	v_cndmask_b32_e64 v249, v123, v115, s[40:41]
	global_store_dwordx2 v250, v[248:249], s[20:21]
	v_cndmask_b32_e64 v246, v114, v122, s[40:41]
	v_cndmask_b32_e64 v247, v115, v123, s[40:41]
	v_mul_f32_e32 v83, v83, v83
	v_fmac_f32_e32 v83, v82, v82
	v_mul_f32_e32 v82, v85, v85
	v_mul_f32_e32 v93, v93, v93
	v_fmac_f32_e32 v82, v84, v84
	v_mul_f32_e32 v91, v91, v91
	v_fmac_f32_e32 v93, v92, v92
	v_mul_f32_e32 v92, v95, v95
	v_mul_f32_e32 v95, v97, v97
	v_add_f32_e32 v82, v83, v82
	v_mul_f32_e32 v83, v87, v87
	v_mul_f32_e32 v84, v89, v89
	v_fmac_f32_e32 v95, v96, v96
	v_fmac_f32_e32 v83, v86, v86
	v_fmac_f32_e32 v84, v88, v88
	v_fmac_f32_e32 v91, v90, v90
	v_fmac_f32_e32 v92, v94, v94
	v_add_f32_e32 v83, v83, v84
	v_add_f32_e32 v84, v91, v93
	v_add_f32_e32 v85, v92, v95
	v_add_f32_e32 v82, v84, v82
	v_add_f32_e32 v83, v85, v83
	s_nop 1
	v_mov_b32_dpp v84, v82 quad_perm:[1,0,3,2] row_mask:0xf bank_mask:0xf
	s_nop 1
	v_mov_b32_dpp v85, v83 quad_perm:[1,0,3,2] row_mask:0xf bank_mask:0xf
	s_waitcnt lgkmcnt(1)
	v_add_f32_e32 v82, v82, v84
	s_waitcnt lgkmcnt(0)
	v_add_f32_e32 v85, v83, v85
	s_nop 1
	v_mov_b32_dpp v84, v82 quad_perm:[2,3,0,1] row_mask:0xf bank_mask:0xf
	s_nop 1
	v_mov_b32_dpp v86, v85 quad_perm:[2,3,0,1] row_mask:0xf bank_mask:0xf
	s_waitcnt lgkmcnt(1)
	v_add_f32_e32 v82, v82, v84
	s_waitcnt lgkmcnt(0)
	v_add_f32_e32 v84, v85, v86
	s_nop 1
	v_mov_b32_dpp v83, v82 row_half_mirror row_mask:0xf bank_mask:0xf
	s_nop 1
	v_mov_b32_dpp v85, v84 row_half_mirror row_mask:0xf bank_mask:0xf
	v_add_u32_e32 v86, 0x1040, v116
	v_cndmask_b32_e64 v86, v116, v86, s[38:39]
	global_store_dwordx2 v86, v[246:247], s[20:21]
	s_and_saveexec_b64 s[16:17], s[42:43]
	s_cbranch_execz .LBB0_1628
; #define LAS __attribute__((address_space(3)))
; __device__ __forceinline__ unsigned cvt_pk_bf16(float lo, float hi) { unsigned r; asm volatile("v_cvt_pk_bf16_f32 %0, %1, %2" : "=v"(r) : "v"(lo), "v"(hi)); return r; }
;     __device__ __forceinline__ void operator()(const f32x4 (&acc)[2][2][4][2], const Unit& u, int wr, int wc, int fr, int fq) const {
;     ...
;             if (g + 1 < 8) ERN_LOADX(g + 1);
;             float sq0 = 0.f, sq1 = 0.f; u32x2 hw[2][2];
; #pragma unroll
;             for (int bj = 0; bj < 2; ++bj) {
;                 *(LAS f32x4*)(st + wr_off) = acc[ai][bj][m][0]; *(LAS f32x4*)(st + wr_off + 64) = acc[ai][bj][m][1];
;                 const f32x4 a0 = *(const LAS f32x4*)(st + rd_off), a1 = *(const LAS f32x4*)(st + rd_off + 8 * 144);
;                 { const f32x4 xv = xb[g & 1][bj][0] + gv[bj] * a0; __builtin_nontemporal_store(xv, (f32x4*)((char*)xo + 4u * ERN_EOFF(g, bj, 0)));
;                   sq0 += (xv.x * xv.x + xv.y * xv.y) + (xv.z * xv.z + xv.w * xv.w);
;                   const f32x4 hv = xv * gsn[bj]; hw[bj][0].x = cvt_pk_bf16(hv.x, hv.y); hw[bj][0].y = cvt_pk_bf16(hv.z, hv.w); }
;                 { const f32x4 xv = xb[g & 1][bj][1] + gv[bj] * a1; __builtin_nontemporal_store(xv, (f32x4*)((char*)xo + 4u * ERN_EOFF(g, bj, 1)));
;                   sq1 += (xv.x * xv.x + xv.y * xv.y) + (xv.z * xv.z + xv.w * xv.w);
;                   const f32x4 hv = xv * gsn[bj]; hw[bj][1].x = cvt_pk_bf16(hv.x, hv.y); hw[bj][1].y = cvt_pk_bf16(hv.z, hv.w); }
;             }
;             if (!NOH && !PLAIN) {
; #pragma unroll
;                 for (int rh = 0; rh < 2; ++rh) { u32x2 rv; rv.x = __shfl_xor(hw[1][rh].x, 8); rv.y = __shfl_xor(hw[1][rh].y, 8);
;                     const unsigned e0 = ERN_EOFF(g, 0, rh);
;                     const unsigned ee = odd ? (e0 - DM + 32) : e0, eo2 = odd ? e0 : (e0 + DM + 32);
;                     *(u32x2*)((char*)ho + 2u * ee) = odd ? rv : hw[0][rh];
;                     *(u32x2*)((char*)ho + 2u * eo2) = odd ? hw[0][rh] : rv; }
;             }
;             if (!PLAIN) { sq0 += __shfl_xor(sq0, 1); sq0 += __shfl_xor(sq0, 2); sq0 += __shfl_xor(sq0, 4);
;             sq1 += __shfl_xor(sq1, 1); sq1 += __shfl_xor(sq1, 2); sq1 += __shfl_xor(sq1, 4); }
;             if (!PLAIN && pc == 0) { sst[g * 16 + rr] = sq0; sst[g * 16 + 8 + rr] = sq1; }
	s_waitcnt lgkmcnt(1)
	v_add_f32_e32 v82, v82, v83
	s_waitcnt lgkmcnt(0)
	v_add_f32_e32 v83, v84, v85
	ds_write2_b32 v194, v82, v83 offset0:32 offset1:40
.LBB0_1628:
	s_or_b64 exec, exec, s[16:17]
	v_lshl_add_u64 v[116:117], s[22:23], 0, v[154:155]
	v_add_u32_e32 v82, 0x100000, v205
	s_waitcnt lgkmcnt(1)
	v_add_u32_e32 v83, 0x110000, v205
	v_add_u32_e32 v154, 0x100080, v205
	global_load_dwordx4 v[94:97], v82, s[22:23]
	global_load_dwordx4 v[90:93], v83, s[22:23]
	v_add_u32_e32 v114, 0x110080, v205
	global_load_dwordx4 v[86:89], v154, s[22:23]
	s_waitcnt lgkmcnt(0)
	global_load_dwordx4 v[82:85], v114, s[22:23]
	ds_write_b128 v200, v[78:81]
	ds_write_b128 v200, v[74:77] offset:64
	ds_read_b128 v[74:77], v201
	ds_read_b128 v[78:81], v201 offset:1152
	v_mov_b32_e32 v131, v155
	v_mov_b32_e32 v133, v155
	s_waitcnt vmcnt(11) lgkmcnt(1)
	v_pk_fma_f32 v[76:77], v[176:177], v[76:77], v[112:113]
	v_add_u32_e32 v112, 0x18000, v202
	v_pk_fma_f32 v[74:75], v[180:181], v[74:75], v[110:111]
	v_lshlrev_b32_e32 v110, 2, v112
	s_waitcnt lgkmcnt(0)
	v_pk_fma_f32 v[78:79], v[180:181], v[78:79], v[106:107]
	global_store_dwordx4 v110, v[74:77], s[22:23] nt
	v_pk_mul_f32 v[110:111], v[178:179], v[74:75]
	v_pk_fma_f32 v[80:81], v[176:177], v[80:81], v[108:109]
	v_pk_mul_f32 v[106:107], v[178:179], v[78:79]
	v_pk_mul_f32 v[118:119], v[174:175], v[76:77]
	v_cvt_pk_bf16_f32 v110, v110, v111
	v_pk_mul_f32 v[108:109], v[174:175], v[80:81]
	v_cvt_pk_bf16_f32 v111, v118, v119
	global_store_dwordx4 v[116:117], v[78:81], off nt
	v_cvt_pk_bf16_f32 v106, v106, v107
	v_cvt_pk_bf16_f32 v107, v108, v109
	ds_write_b128 v200, v[70:73]
	ds_write_b128 v200, v[66:69] offset:64
	ds_read_b128 v[66:69], v201
	ds_read_b128 v[70:73], v201 offset:1152
	v_lshl_add_u64 v[108:109], s[22:23], 0, v[130:131]
	v_lshl_add_u64 v[116:117], s[22:23], 0, v[132:133]
	s_waitcnt lgkmcnt(1)
	v_pk_fma_f32 v[66:67], v[168:169], v[66:67], v[102:103]
	v_pk_fma_f32 v[68:69], v[166:167], v[68:69], v[104:105]
	v_pk_mul_f32 v[104:105], v[172:173], v[66:67]
	global_store_dwordx4 v[108:109], v[66:69], off nt
	v_pk_mul_f32 v[102:103], v[170:171], v[68:69]
	v_cvt_pk_bf16_f32 v104, v104, v105
	s_waitcnt vmcnt(13) lgkmcnt(0)
	v_pk_fma_f32 v[70:71], v[168:169], v[70:71], v[98:99]
	v_cvt_pk_bf16_f32 v105, v102, v103
	ds_bpermute_b32 v98, v203, v104
	ds_bpermute_b32 v99, v203, v105
	v_pk_fma_f32 v[72:73], v[166:167], v[72:73], v[100:101]
	v_pk_mul_f32 v[100:101], v[172:173], v[70:71]
	v_pk_mul_f32 v[102:103], v[170:171], v[72:73]
	global_store_dwordx4 v[116:117], v[70:73], off nt
	v_cvt_pk_bf16_f32 v100, v100, v101
	v_cvt_pk_bf16_f32 v101, v102, v103
	v_lshlrev_b32_e32 v102, 1, v112
	s_waitcnt lgkmcnt(0)
	v_add_u32_e32 v250, 0xfffff040, v102
	v_cndmask_b32_e64 v250, v102, v250, s[40:41]
	v_cndmask_b32_e64 v248, v110, v98, s[40:41]
	v_cndmask_b32_e64 v249, v111, v99, s[40:41]
	global_store_dwordx2 v250, v[248:249], s[20:21]
	v_cndmask_b32_e64 v246, v98, v110, s[40:41]
	v_cndmask_b32_e64 v247, v99, v111, s[40:41]
	s_waitcnt lgkmcnt(1)
	v_add_u32_e32 v98, 0x1040, v102
	v_cndmask_b32_e64 v98, v102, v98, s[38:39]
	global_store_dwordx2 v98, v[246:247], s[20:21]
	ds_bpermute_b32 v98, v203, v100
	s_waitcnt lgkmcnt(1)
	ds_bpermute_b32 v99, v203, v101
	v_add_u32_e32 v101, 0x1c000, v202
	v_lshlrev_b32_e32 v100, 1, v101
	s_waitcnt lgkmcnt(0)
	v_add_u32_e32 v250, 0xfffff040, v100
	v_cndmask_b32_e64 v250, v100, v250, s[40:41]
	v_cndmask_b32_e64 v248, v106, v98, s[40:41]
	v_cndmask_b32_e64 v249, v107, v99, s[40:41]
	global_store_dwordx2 v250, v[248:249], s[20:21]
	v_cndmask_b32_e64 v246, v98, v106, s[40:41]
	v_cndmask_b32_e64 v247, v99, v107, s[40:41]
	v_mul_f32_e32 v67, v67, v67
	v_fmac_f32_e32 v67, v66, v66
	v_mul_f32_e32 v66, v69, v69
	v_mul_f32_e32 v77, v77, v77
	v_fmac_f32_e32 v66, v68, v68
	v_mul_f32_e32 v75, v75, v75
	v_fmac_f32_e32 v77, v76, v76
	v_mul_f32_e32 v76, v79, v79
	v_mul_f32_e32 v79, v81, v81
	v_add_f32_e32 v66, v67, v66
	v_mul_f32_e32 v67, v71, v71
	v_mul_f32_e32 v68, v73, v73
	v_fmac_f32_e32 v79, v80, v80
	v_fmac_f32_e32 v67, v70, v70
	v_fmac_f32_e32 v68, v72, v72
	v_fmac_f32_e32 v75, v74, v74
	v_fmac_f32_e32 v76, v78, v78
	v_add_f32_e32 v67, v67, v68
	v_add_f32_e32 v68, v75, v77
	v_add_f32_e32 v69, v76, v79
	v_add_f32_e32 v66, v68, v66
	v_add_f32_e32 v67, v69, v67
	s_nop 1
	v_mov_b32_dpp v68, v66 quad_perm:[1,0,3,2] row_mask:0xf bank_mask:0xf
	s_nop 1
	v_mov_b32_dpp v69, v67 quad_perm:[1,0,3,2] row_mask:0xf bank_mask:0xf
	s_waitcnt lgkmcnt(1)
	v_add_f32_e32 v66, v66, v68
	s_waitcnt lgkmcnt(0)
	v_add_f32_e32 v69, v67, v69
	s_nop 1
	v_mov_b32_dpp v68, v66 quad_perm:[2,3,0,1] row_mask:0xf bank_mask:0xf
	s_nop 1
	v_mov_b32_dpp v70, v69 quad_perm:[2,3,0,1] row_mask:0xf bank_mask:0xf
	s_waitcnt lgkmcnt(1)
	v_add_f32_e32 v66, v66, v68
	s_waitcnt lgkmcnt(0)
	v_add_f32_e32 v68, v69, v70
	s_nop 1
	v_mov_b32_dpp v67, v66 row_half_mirror row_mask:0xf bank_mask:0xf
	s_nop 1
	v_mov_b32_dpp v69, v68 row_half_mirror row_mask:0xf bank_mask:0xf
	v_add_u32_e32 v70, 0x1040, v100
	v_cndmask_b32_e64 v70, v100, v70, s[38:39]
	global_store_dwordx2 v70, v[246:247], s[20:21]
	s_and_saveexec_b64 s[16:17], s[42:43]
	s_cbranch_execz .LBB0_1638
	s_waitcnt lgkmcnt(1)
	v_add_f32_e32 v66, v66, v67
	s_waitcnt lgkmcnt(0)
	v_add_f32_e32 v67, v68, v69
	ds_write2_b32 v194, v66, v67 offset0:48 offset1:56
; #define LAS __attribute__((address_space(3)))
; __device__ __forceinline__ unsigned cvt_pk_bf16(float lo, float hi) { unsigned r; asm volatile("v_cvt_pk_bf16_f32 %0, %1, %2" : "=v"(r) : "v"(lo), "v"(hi)); return r; }
;     __device__ __forceinline__ void operator()(const f32x4 (&acc)[2][2][4][2], const Unit& u, int wr, int wc, int fr, int fq) const {
;     ...
;             if (g + 1 < 8) ERN_LOADX(g + 1);
;             float sq0 = 0.f, sq1 = 0.f; u32x2 hw[2][2];
; #pragma unroll
;             for (int bj = 0; bj < 2; ++bj) {
;                 *(LAS f32x4*)(st + wr_off) = acc[ai][bj][m][0]; *(LAS f32x4*)(st + wr_off + 64) = acc[ai][bj][m][1];
;                 const f32x4 a0 = *(const LAS f32x4*)(st + rd_off), a1 = *(const LAS f32x4*)(st + rd_off + 8 * 144);
;                 { const f32x4 xv = xb[g & 1][bj][0] + gv[bj] * a0; __builtin_nontemporal_store(xv, (f32x4*)((char*)xo + 4u * ERN_EOFF(g, bj, 0)));
;                   sq0 += (xv.x * xv.x + xv.y * xv.y) + (xv.z * xv.z + xv.w * xv.w);
;                   const f32x4 hv = xv * gsn[bj]; hw[bj][0].x = cvt_pk_bf16(hv.x, hv.y); hw[bj][0].y = cvt_pk_bf16(hv.z, hv.w); }
;                 { const f32x4 xv = xb[g & 1][bj][1] + gv[bj] * a1; __builtin_nontemporal_store(xv, (f32x4*)((char*)xo + 4u * ERN_EOFF(g, bj, 1)));
;                   sq1 += (xv.x * xv.x + xv.y * xv.y) + (xv.z * xv.z + xv.w * xv.w);
;                   const f32x4 hv = xv * gsn[bj]; hw[bj][1].x = cvt_pk_bf16(hv.x, hv.y); hw[bj][1].y = cvt_pk_bf16(hv.z, hv.w); }
;             }
;             if (!NOH && !PLAIN) {
; #pragma unroll
;                 for (int rh = 0; rh < 2; ++rh) { u32x2 rv; rv.x = __shfl_xor(hw[1][rh].x, 8); rv.y = __shfl_xor(hw[1][rh].y, 8);
;                     const unsigned e0 = ERN_EOFF(g, 0, rh);
;                     const unsigned ee = odd ? (e0 - DM + 32) : e0, eo2 = odd ? e0 : (e0 + DM + 32);
;                     *(u32x2*)((char*)ho + 2u * ee) = odd ? rv : hw[0][rh];
;                     *(u32x2*)((char*)ho + 2u * eo2) = odd ? hw[0][rh] : rv; }
;             }
;             if (!PLAIN) { sq0 += __shfl_xor(sq0, 1); sq0 += __shfl_xor(sq0, 2); sq0 += __shfl_xor(sq0, 4);
;             sq1 += __shfl_xor(sq1, 1); sq1 += __shfl_xor(sq1, 2); sq1 += __shfl_xor(sq1, 4); }
;             if (!PLAIN && pc == 0) { sst[g * 16 + rr] = sq0; sst[g * 16 + 8 + rr] = sq1; }
.LBB0_1638:
	s_or_b64 exec, exec, s[16:17]
	v_lshl_add_u64 v[104:105], s[22:23], 0, v[154:155]
	v_add_u32_e32 v154, 0x120000, v205
	v_add_u32_e32 v100, 0x120080, v205
	v_add_u32_e32 v102, 0x130000, v205
	global_load_dwordx4 v[78:81], v154, s[22:23]
	global_load_dwordx4 v[74:77], v102, s[22:23]
	v_add_u32_e32 v98, 0x130080, v205
	global_load_dwordx4 v[70:73], v100, s[22:23]
	s_waitcnt lgkmcnt(0)
	global_load_dwordx4 v[66:69], v98, s[22:23]
	ds_write_b128 v200, v[62:65]
	ds_write_b128 v200, v[58:61] offset:64
	ds_read_b128 v[58:61], v201
	ds_read_b128 v[62:65], v201 offset:1152
	v_mov_b32_e32 v115, v155
	s_waitcnt vmcnt(13) lgkmcnt(1)
	v_pk_fma_f32 v[60:61], v[176:177], v[60:61], v[96:97]
	v_add_u32_e32 v96, 0x40000, v202
	v_pk_fma_f32 v[58:59], v[180:181], v[58:59], v[94:95]
	v_lshlrev_b32_e32 v94, 2, v96
	s_waitcnt vmcnt(12) lgkmcnt(0)
	v_pk_fma_f32 v[64:65], v[176:177], v[64:65], v[92:93]
	v_add_u32_e32 v92, 0x44000, v202
	global_store_dwordx4 v94, v[58:61], s[22:23] nt
	v_pk_mul_f32 v[94:95], v[178:179], v[58:59]
	v_pk_fma_f32 v[62:63], v[180:181], v[62:63], v[90:91]
	v_lshlrev_b32_e32 v90, 2, v92
	v_pk_mul_f32 v[106:107], v[174:175], v[60:61]
	v_cvt_pk_bf16_f32 v94, v94, v95
	s_nop 0
	v_cvt_pk_bf16_f32 v95, v106, v107
	global_store_dwordx4 v90, v[62:65], s[22:23] nt
	v_pk_mul_f32 v[90:91], v[178:179], v[62:63]
	v_pk_mul_f32 v[106:107], v[174:175], v[64:65]
	v_cvt_pk_bf16_f32 v90, v90, v91
	s_nop 0
	v_cvt_pk_bf16_f32 v91, v106, v107
	ds_write_b128 v200, v[54:57]
	ds_write_b128 v200, v[50:53] offset:64
	ds_read_b128 v[50:53], v201
	ds_read_b128 v[54:57], v201 offset:1152
	v_lshl_add_u64 v[106:107], s[22:23], 0, v[114:115]
	s_waitcnt vmcnt(13) lgkmcnt(1)
	v_pk_fma_f32 v[50:51], v[168:169], v[50:51], v[86:87]
	v_pk_fma_f32 v[52:53], v[166:167], v[52:53], v[88:89]
	v_pk_mul_f32 v[88:89], v[172:173], v[50:51]
	global_store_dwordx4 v[104:105], v[50:53], off nt
	v_pk_mul_f32 v[86:87], v[170:171], v[52:53]
	v_cvt_pk_bf16_f32 v88, v88, v89
	s_waitcnt vmcnt(13) lgkmcnt(0)
	v_pk_fma_f32 v[54:55], v[168:169], v[54:55], v[82:83]
	v_cvt_pk_bf16_f32 v89, v86, v87
	ds_bpermute_b32 v82, v203, v88
	ds_bpermute_b32 v83, v203, v89
	v_pk_fma_f32 v[56:57], v[166:167], v[56:57], v[84:85]
	v_pk_mul_f32 v[84:85], v[172:173], v[54:55]
	v_pk_mul_f32 v[86:87], v[170:171], v[56:57]
	global_store_dwordx4 v[106:107], v[54:57], off nt
	v_cvt_pk_bf16_f32 v84, v84, v85
	v_cvt_pk_bf16_f32 v85, v86, v87
	v_lshlrev_b32_e32 v86, 1, v96
	s_waitcnt lgkmcnt(0)
	v_add_u32_e32 v250, 0xfffff040, v86
	v_cndmask_b32_e64 v250, v86, v250, s[40:41]
	v_cndmask_b32_e64 v248, v94, v82, s[40:41]
	v_cndmask_b32_e64 v249, v95, v83, s[40:41]
	global_store_dwordx2 v250, v[248:249], s[20:21]
	v_cndmask_b32_e64 v246, v82, v94, s[40:41]
	v_cndmask_b32_e64 v247, v83, v95, s[40:41]
	s_waitcnt lgkmcnt(1)
	v_add_u32_e32 v82, 0x1040, v86
	v_cndmask_b32_e64 v82, v86, v82, s[38:39]
	global_store_dwordx2 v82, v[246:247], s[20:21]
	ds_bpermute_b32 v82, v203, v84
	s_waitcnt lgkmcnt(1)
	ds_bpermute_b32 v83, v203, v85
	v_lshlrev_b32_e32 v84, 1, v92
	s_waitcnt lgkmcnt(0)
	v_add_u32_e32 v250, 0xfffff040, v84
	v_cndmask_b32_e64 v250, v84, v250, s[40:41]
	v_cndmask_b32_e64 v248, v90, v82, s[40:41]
	v_cndmask_b32_e64 v249, v91, v83, s[40:41]
	global_store_dwordx2 v250, v[248:249], s[20:21]
	v_cndmask_b32_e64 v246, v82, v90, s[40:41]
	v_cndmask_b32_e64 v247, v83, v91, s[40:41]
	v_mul_f32_e32 v51, v51, v51
	v_fmac_f32_e32 v51, v50, v50
	v_mul_f32_e32 v50, v53, v53
	v_mul_f32_e32 v61, v61, v61
	v_fmac_f32_e32 v50, v52, v52
	v_mul_f32_e32 v59, v59, v59
	v_fmac_f32_e32 v61, v60, v60
	v_mul_f32_e32 v60, v63, v63
	v_mul_f32_e32 v63, v65, v65
	v_add_f32_e32 v50, v51, v50
	v_mul_f32_e32 v51, v55, v55
	v_mul_f32_e32 v52, v57, v57
	v_fmac_f32_e32 v63, v64, v64
	v_fmac_f32_e32 v51, v54, v54
	v_fmac_f32_e32 v52, v56, v56
	v_fmac_f32_e32 v59, v58, v58
	v_fmac_f32_e32 v60, v62, v62
	v_add_f32_e32 v51, v51, v52
	v_add_f32_e32 v52, v59, v61
	v_add_f32_e32 v53, v60, v63
	v_add_f32_e32 v50, v52, v50
	v_add_f32_e32 v51, v53, v51
	s_nop 1
	v_mov_b32_dpp v52, v50 quad_perm:[1,0,3,2] row_mask:0xf bank_mask:0xf
	s_nop 1
	v_mov_b32_dpp v53, v51 quad_perm:[1,0,3,2] row_mask:0xf bank_mask:0xf
	s_waitcnt lgkmcnt(1)
	v_add_f32_e32 v50, v50, v52
	s_waitcnt lgkmcnt(0)
	v_add_f32_e32 v53, v51, v53
	s_nop 1
	v_mov_b32_dpp v52, v50 quad_perm:[2,3,0,1] row_mask:0xf bank_mask:0xf
	s_nop 1
	v_mov_b32_dpp v54, v53 quad_perm:[2,3,0,1] row_mask:0xf bank_mask:0xf
	s_waitcnt lgkmcnt(1)
	v_add_f32_e32 v50, v50, v52
	s_waitcnt lgkmcnt(0)
	v_add_f32_e32 v52, v53, v54
	s_nop 1
	v_mov_b32_dpp v51, v50 row_half_mirror row_mask:0xf bank_mask:0xf
	s_nop 1
	v_mov_b32_dpp v53, v52 row_half_mirror row_mask:0xf bank_mask:0xf
	v_add_u32_e32 v54, 0x1040, v84
	v_cndmask_b32_e64 v54, v84, v54, s[38:39]
	global_store_dwordx2 v54, v[246:247], s[20:21]
	s_and_saveexec_b64 s[16:17], s[42:43]
	s_cbranch_execz .LBB0_1648
	s_waitcnt lgkmcnt(1)
	v_add_f32_e32 v50, v50, v51
	s_waitcnt lgkmcnt(0)
	v_add_f32_e32 v51, v52, v53
	ds_write2_b32 v194, v50, v51 offset0:64 offset1:72
; #define LAS __attribute__((address_space(3)))
; __device__ __forceinline__ unsigned cvt_pk_bf16(float lo, float hi) { unsigned r; asm volatile("v_cvt_pk_bf16_f32 %0, %1, %2" : "=v"(r) : "v"(lo), "v"(hi)); return r; }
;     __device__ __forceinline__ void operator()(const f32x4 (&acc)[2][2][4][2], const Unit& u, int wr, int wc, int fr, int fq) const {
;     ...
;             if (g + 1 < 8) ERN_LOADX(g + 1);
;             float sq0 = 0.f, sq1 = 0.f; u32x2 hw[2][2];
; #pragma unroll
;             for (int bj = 0; bj < 2; ++bj) {
;                 *(LAS f32x4*)(st + wr_off) = acc[ai][bj][m][0]; *(LAS f32x4*)(st + wr_off + 64) = acc[ai][bj][m][1];
;                 const f32x4 a0 = *(const LAS f32x4*)(st + rd_off), a1 = *(const LAS f32x4*)(st + rd_off + 8 * 144);
;                 { const f32x4 xv = xb[g & 1][bj][0] + gv[bj] * a0; __builtin_nontemporal_store(xv, (f32x4*)((char*)xo + 4u * ERN_EOFF(g, bj, 0)));
;                   sq0 += (xv.x * xv.x + xv.y * xv.y) + (xv.z * xv.z + xv.w * xv.w);
;                   const f32x4 hv = xv * gsn[bj]; hw[bj][0].x = cvt_pk_bf16(hv.x, hv.y); hw[bj][0].y = cvt_pk_bf16(hv.z, hv.w); }
;                 { const f32x4 xv = xb[g & 1][bj][1] + gv[bj] * a1; __builtin_nontemporal_store(xv, (f32x4*)((char*)xo + 4u * ERN_EOFF(g, bj, 1)));
;                   sq1 += (xv.x * xv.x + xv.y * xv.y) + (xv.z * xv.z + xv.w * xv.w);
;                   const f32x4 hv = xv * gsn[bj]; hw[bj][1].x = cvt_pk_bf16(hv.x, hv.y); hw[bj][1].y = cvt_pk_bf16(hv.z, hv.w); }
;             }
;             if (!NOH && !PLAIN) {
; #pragma unroll
;                 for (int rh = 0; rh < 2; ++rh) { u32x2 rv; rv.x = __shfl_xor(hw[1][rh].x, 8); rv.y = __shfl_xor(hw[1][rh].y, 8);
;                     const unsigned e0 = ERN_EOFF(g, 0, rh);
;                     const unsigned ee = odd ? (e0 - DM + 32) : e0, eo2 = odd ? e0 : (e0 + DM + 32);
;                     *(u32x2*)((char*)ho + 2u * ee) = odd ? rv : hw[0][rh];
;                     *(u32x2*)((char*)ho + 2u * eo2) = odd ? hw[0][rh] : rv; }
;             }
;             if (!PLAIN) { sq0 += __shfl_xor(sq0, 1); sq0 += __shfl_xor(sq0, 2); sq0 += __shfl_xor(sq0, 4);
;             sq1 += __shfl_xor(sq1, 1); sq1 += __shfl_xor(sq1, 2); sq1 += __shfl_xor(sq1, 4); }
;             if (!PLAIN && pc == 0) { sst[g * 16 + rr] = sq0; sst[g * 16 + 8 + rr] = sq1; }
.LBB0_1648:
	s_or_b64 exec, exec, s[16:17]
	v_lshl_add_u64 v[88:89], s[22:23], 0, v[154:155]
	v_add_u32_e32 v154, 0x140000, v205
	v_add_u32_e32 v84, 0x140080, v205
	v_add_u32_e32 v86, 0x150000, v205
	global_load_dwordx4 v[62:65], v154, s[22:23]
	global_load_dwordx4 v[58:61], v86, s[22:23]
	v_add_u32_e32 v82, 0x150080, v205
	global_load_dwordx4 v[54:57], v84, s[22:23]
	s_waitcnt lgkmcnt(0)
	global_load_dwordx4 v[50:53], v82, s[22:23]
	ds_write_b128 v200, v[46:49]
	ds_write_b128 v200, v[42:45] offset:64
	ds_read_b128 v[42:45], v201
	ds_read_b128 v[46:49], v201 offset:1152
	v_mov_b32_e32 v103, v155
	v_lshl_add_u64 v[90:91], s[22:23], 0, v[102:103]
	v_mov_b32_e32 v101, v155
	s_waitcnt vmcnt(13) lgkmcnt(1)
	v_pk_fma_f32 v[42:43], v[180:181], v[42:43], v[78:79]
	s_waitcnt vmcnt(12) lgkmcnt(0)
	v_pk_fma_f32 v[46:47], v[180:181], v[46:47], v[74:75]
	v_pk_fma_f32 v[44:45], v[176:177], v[44:45], v[80:81]
	v_pk_mul_f32 v[78:79], v[178:179], v[42:43]
	v_pk_fma_f32 v[48:49], v[176:177], v[48:49], v[76:77]
	v_pk_mul_f32 v[74:75], v[178:179], v[46:47]
	global_store_dwordx4 v[88:89], v[42:45], off nt
	v_pk_mul_f32 v[80:81], v[174:175], v[44:45]
	v_cvt_pk_bf16_f32 v78, v78, v79
	v_pk_mul_f32 v[76:77], v[174:175], v[48:49]
	v_cvt_pk_bf16_f32 v79, v80, v81
	global_store_dwordx4 v[90:91], v[46:49], off nt
	v_cvt_pk_bf16_f32 v74, v74, v75
	v_cvt_pk_bf16_f32 v75, v76, v77
	ds_write_b128 v200, v[38:41]
	ds_write_b128 v200, v[34:37] offset:64
	ds_read_b128 v[34:37], v201
	ds_read_b128 v[38:41], v201 offset:1152
	v_lshl_add_u64 v[76:77], s[22:23], 0, v[100:101]
	v_mov_b32_e32 v99, v155
	v_lshl_add_u64 v[80:81], s[22:23], 0, v[98:99]
	s_waitcnt vmcnt(13) lgkmcnt(1)
	v_pk_fma_f32 v[34:35], v[168:169], v[34:35], v[70:71]
	v_pk_fma_f32 v[36:37], v[166:167], v[36:37], v[72:73]
	v_pk_mul_f32 v[72:73], v[172:173], v[34:35]
	global_store_dwordx4 v[76:77], v[34:37], off nt
	v_pk_mul_f32 v[70:71], v[170:171], v[36:37]
	v_cvt_pk_bf16_f32 v72, v72, v73
	s_waitcnt vmcnt(13) lgkmcnt(0)
	v_pk_fma_f32 v[38:39], v[168:169], v[38:39], v[66:67]
	v_cvt_pk_bf16_f32 v73, v70, v71
	ds_bpermute_b32 v66, v203, v72
	ds_bpermute_b32 v67, v203, v73
	v_pk_fma_f32 v[40:41], v[166:167], v[40:41], v[68:69]
	v_pk_mul_f32 v[68:69], v[172:173], v[38:39]
	v_pk_mul_f32 v[70:71], v[170:171], v[40:41]
	global_store_dwordx4 v[80:81], v[38:41], off nt
	v_cvt_pk_bf16_f32 v68, v68, v69
	v_cvt_pk_bf16_f32 v69, v70, v71
	v_add_u32_e32 v71, 0x48000, v202
	v_lshlrev_b32_e32 v70, 1, v71
	s_waitcnt lgkmcnt(0)
	v_add_u32_e32 v250, 0xfffff040, v70
	v_cndmask_b32_e64 v250, v70, v250, s[40:41]
	v_cndmask_b32_e64 v248, v78, v66, s[40:41]
	v_cndmask_b32_e64 v249, v79, v67, s[40:41]
	global_store_dwordx2 v250, v[248:249], s[20:21]
	v_cndmask_b32_e64 v246, v66, v78, s[40:41]
	v_cndmask_b32_e64 v247, v67, v79, s[40:41]
	s_waitcnt lgkmcnt(1)
	v_add_u32_e32 v66, 0x1040, v70
	v_cndmask_b32_e64 v66, v70, v66, s[38:39]
	global_store_dwordx2 v66, v[246:247], s[20:21]
	ds_bpermute_b32 v66, v203, v68
	s_waitcnt lgkmcnt(1)
	ds_bpermute_b32 v67, v203, v69
	v_add_u32_e32 v69, 0x4c000, v202
	v_lshlrev_b32_e32 v68, 1, v69
	s_waitcnt lgkmcnt(0)
	v_add_u32_e32 v250, 0xfffff040, v68
	v_cndmask_b32_e64 v250, v68, v250, s[40:41]
	v_cndmask_b32_e64 v248, v74, v66, s[40:41]
	v_cndmask_b32_e64 v249, v75, v67, s[40:41]
	global_store_dwordx2 v250, v[248:249], s[20:21]
	v_cndmask_b32_e64 v246, v66, v74, s[40:41]
	v_cndmask_b32_e64 v247, v67, v75, s[40:41]
	v_mul_f32_e32 v35, v35, v35
	v_fmac_f32_e32 v35, v34, v34
	v_mul_f32_e32 v34, v37, v37
	v_mul_f32_e32 v45, v45, v45
	v_fmac_f32_e32 v34, v36, v36
	v_mul_f32_e32 v43, v43, v43
	v_fmac_f32_e32 v45, v44, v44
	v_mul_f32_e32 v44, v47, v47
	v_mul_f32_e32 v47, v49, v49
	v_add_f32_e32 v34, v35, v34
	v_mul_f32_e32 v35, v39, v39
	v_mul_f32_e32 v36, v41, v41
	v_fmac_f32_e32 v47, v48, v48
	v_fmac_f32_e32 v35, v38, v38
	v_fmac_f32_e32 v36, v40, v40
	v_fmac_f32_e32 v43, v42, v42
	v_fmac_f32_e32 v44, v46, v46
	v_add_f32_e32 v35, v35, v36
	v_add_f32_e32 v36, v43, v45
	v_add_f32_e32 v37, v44, v47
	v_add_f32_e32 v34, v36, v34
	v_add_f32_e32 v35, v37, v35
	s_nop 1
	v_mov_b32_dpp v36, v34 quad_perm:[1,0,3,2] row_mask:0xf bank_mask:0xf
	s_nop 1
	v_mov_b32_dpp v37, v35 quad_perm:[1,0,3,2] row_mask:0xf bank_mask:0xf
	s_waitcnt lgkmcnt(1)
	v_add_f32_e32 v34, v34, v36
	s_waitcnt lgkmcnt(0)
	v_add_f32_e32 v37, v35, v37
	s_nop 1
	v_mov_b32_dpp v36, v34 quad_perm:[2,3,0,1] row_mask:0xf bank_mask:0xf
	s_nop 1
	v_mov_b32_dpp v38, v37 quad_perm:[2,3,0,1] row_mask:0xf bank_mask:0xf
	s_waitcnt lgkmcnt(1)
	v_add_f32_e32 v34, v34, v36
	s_waitcnt lgkmcnt(0)
	v_add_f32_e32 v36, v37, v38
	s_nop 1
	v_mov_b32_dpp v35, v34 row_half_mirror row_mask:0xf bank_mask:0xf
	s_nop 1
	v_mov_b32_dpp v37, v36 row_half_mirror row_mask:0xf bank_mask:0xf
	v_add_u32_e32 v38, 0x1040, v68
	v_cndmask_b32_e64 v38, v68, v38, s[38:39]
	global_store_dwordx2 v38, v[246:247], s[20:21]
	s_and_saveexec_b64 s[16:17], s[42:43]
	s_cbranch_execz .LBB0_1658
	s_waitcnt lgkmcnt(1)
	v_add_f32_e32 v34, v34, v35
	s_waitcnt lgkmcnt(0)
	v_add_f32_e32 v35, v36, v37
	ds_write2_b32 v194, v34, v35 offset0:80 offset1:88
; #define LAS __attribute__((address_space(3)))
; __device__ __forceinline__ unsigned cvt_pk_bf16(float lo, float hi) { unsigned r; asm volatile("v_cvt_pk_bf16_f32 %0, %1, %2" : "=v"(r) : "v"(lo), "v"(hi)); return r; }
;     __device__ __forceinline__ void operator()(const f32x4 (&acc)[2][2][4][2], const Unit& u, int wr, int wc, int fr, int fq) const {
;     ...
;             if (g + 1 < 8) ERN_LOADX(g + 1);
;             float sq0 = 0.f, sq1 = 0.f; u32x2 hw[2][2];
; #pragma unroll
;             for (int bj = 0; bj < 2; ++bj) {
;                 *(LAS f32x4*)(st + wr_off) = acc[ai][bj][m][0]; *(LAS f32x4*)(st + wr_off + 64) = acc[ai][bj][m][1];
;                 const f32x4 a0 = *(const LAS f32x4*)(st + rd_off), a1 = *(const LAS f32x4*)(st + rd_off + 8 * 144);
;                 { const f32x4 xv = xb[g & 1][bj][0] + gv[bj] * a0; __builtin_nontemporal_store(xv, (f32x4*)((char*)xo + 4u * ERN_EOFF(g, bj, 0)));
;                   sq0 += (xv.x * xv.x + xv.y * xv.y) + (xv.z * xv.z + xv.w * xv.w);
;                   const f32x4 hv = xv * gsn[bj]; hw[bj][0].x = cvt_pk_bf16(hv.x, hv.y); hw[bj][0].y = cvt_pk_bf16(hv.z, hv.w); }
;                 { const f32x4 xv = xb[g & 1][bj][1] + gv[bj] * a1; __builtin_nontemporal_store(xv, (f32x4*)((char*)xo + 4u * ERN_EOFF(g, bj, 1)));
;                   sq1 += (xv.x * xv.x + xv.y * xv.y) + (xv.z * xv.z + xv.w * xv.w);
;                   const f32x4 hv = xv * gsn[bj]; hw[bj][1].x = cvt_pk_bf16(hv.x, hv.y); hw[bj][1].y = cvt_pk_bf16(hv.z, hv.w); }
;             }
;             if (!NOH && !PLAIN) {
; #pragma unroll
;                 for (int rh = 0; rh < 2; ++rh) { u32x2 rv; rv.x = __shfl_xor(hw[1][rh].x, 8); rv.y = __shfl_xor(hw[1][rh].y, 8);
;                     const unsigned e0 = ERN_EOFF(g, 0, rh);
;                     const unsigned ee = odd ? (e0 - DM + 32) : e0, eo2 = odd ? e0 : (e0 + DM + 32);
;                     *(u32x2*)((char*)ho + 2u * ee) = odd ? rv : hw[0][rh];
;                     *(u32x2*)((char*)ho + 2u * eo2) = odd ? hw[0][rh] : rv; }
;             }
;             if (!PLAIN) { sq0 += __shfl_xor(sq0, 1); sq0 += __shfl_xor(sq0, 2); sq0 += __shfl_xor(sq0, 4);
;             sq1 += __shfl_xor(sq1, 1); sq1 += __shfl_xor(sq1, 2); sq1 += __shfl_xor(sq1, 4); }
;             if (!PLAIN && pc == 0) { sst[g * 16 + rr] = sq0; sst[g * 16 + 8 + rr] = sq1; }
.LBB0_1658:
	s_or_b64 exec, exec, s[16:17]
	v_lshl_add_u64 v[72:73], s[22:23], 0, v[154:155]
	v_add_u32_e32 v154, 0x160000, v205
	v_add_u32_e32 v68, 0x160080, v205
	v_add_u32_e32 v70, 0x170000, v205
	global_load_dwordx4 v[46:49], v154, s[22:23]
	global_load_dwordx4 v[42:45], v70, s[22:23]
	v_add_u32_e32 v66, 0x170080, v205
	global_load_dwordx4 v[38:41], v68, s[22:23]
	s_waitcnt lgkmcnt(0)
	global_load_dwordx4 v[34:37], v66, s[22:23]
	ds_write_b128 v200, v[30:33]
	ds_write_b128 v200, v[26:29] offset:64
	ds_read_b128 v[26:29], v201
	ds_read_b128 v[30:33], v201 offset:1152
	v_mov_b32_e32 v87, v155
	v_lshl_add_u64 v[74:75], s[22:23], 0, v[86:87]
	v_mov_b32_e32 v85, v155
	s_waitcnt vmcnt(13) lgkmcnt(1)
	v_pk_fma_f32 v[26:27], v[180:181], v[26:27], v[62:63]
	s_waitcnt vmcnt(12) lgkmcnt(0)
	v_pk_fma_f32 v[30:31], v[180:181], v[30:31], v[58:59]
	v_pk_fma_f32 v[28:29], v[176:177], v[28:29], v[64:65]
	v_pk_mul_f32 v[62:63], v[178:179], v[26:27]
	v_pk_fma_f32 v[32:33], v[176:177], v[32:33], v[60:61]
	v_pk_mul_f32 v[58:59], v[178:179], v[30:31]
	global_store_dwordx4 v[72:73], v[26:29], off nt
	v_pk_mul_f32 v[64:65], v[174:175], v[28:29]
	v_cvt_pk_bf16_f32 v62, v62, v63
	v_pk_mul_f32 v[60:61], v[174:175], v[32:33]
	v_cvt_pk_bf16_f32 v63, v64, v65
	global_store_dwordx4 v[74:75], v[30:33], off nt
	v_cvt_pk_bf16_f32 v58, v58, v59
	v_cvt_pk_bf16_f32 v59, v60, v61
	ds_write_b128 v200, v[22:25]
	ds_write_b128 v200, v[18:21] offset:64
	ds_read_b128 v[18:21], v201
	ds_read_b128 v[22:25], v201 offset:1152
	v_lshl_add_u64 v[60:61], s[22:23], 0, v[84:85]
	v_mov_b32_e32 v83, v155
	v_lshl_add_u64 v[64:65], s[22:23], 0, v[82:83]
	s_waitcnt vmcnt(13) lgkmcnt(1)
	v_pk_fma_f32 v[18:19], v[168:169], v[18:19], v[54:55]
	v_pk_fma_f32 v[20:21], v[166:167], v[20:21], v[56:57]
	v_pk_mul_f32 v[56:57], v[172:173], v[18:19]
	global_store_dwordx4 v[60:61], v[18:21], off nt
	v_pk_mul_f32 v[54:55], v[170:171], v[20:21]
	v_cvt_pk_bf16_f32 v56, v56, v57
	s_waitcnt vmcnt(13) lgkmcnt(0)
	v_pk_fma_f32 v[22:23], v[168:169], v[22:23], v[50:51]
	v_cvt_pk_bf16_f32 v57, v54, v55
	ds_bpermute_b32 v50, v203, v56
	ds_bpermute_b32 v51, v203, v57
	v_pk_fma_f32 v[24:25], v[166:167], v[24:25], v[52:53]
	v_pk_mul_f32 v[52:53], v[172:173], v[22:23]
	v_pk_mul_f32 v[54:55], v[170:171], v[24:25]
	global_store_dwordx4 v[64:65], v[22:25], off nt
	v_cvt_pk_bf16_f32 v52, v52, v53
	v_cvt_pk_bf16_f32 v53, v54, v55
	v_add_u32_e32 v55, 0x50000, v202
	v_lshlrev_b32_e32 v54, 1, v55
	s_waitcnt lgkmcnt(0)
	v_add_u32_e32 v250, 0xfffff040, v54
	v_cndmask_b32_e64 v250, v54, v250, s[40:41]
	v_cndmask_b32_e64 v248, v62, v50, s[40:41]
	v_cndmask_b32_e64 v249, v63, v51, s[40:41]
	global_store_dwordx2 v250, v[248:249], s[20:21]
	v_cndmask_b32_e64 v246, v50, v62, s[40:41]
	v_cndmask_b32_e64 v247, v51, v63, s[40:41]
	s_waitcnt lgkmcnt(1)
	v_add_u32_e32 v50, 0x1040, v54
	v_cndmask_b32_e64 v50, v54, v50, s[38:39]
	global_store_dwordx2 v50, v[246:247], s[20:21]
	ds_bpermute_b32 v50, v203, v52
	s_waitcnt lgkmcnt(1)
	ds_bpermute_b32 v51, v203, v53
	v_add_u32_e32 v53, 0x54000, v202
	v_lshlrev_b32_e32 v52, 1, v53
	s_waitcnt lgkmcnt(0)
	v_add_u32_e32 v250, 0xfffff040, v52
	v_cndmask_b32_e64 v250, v52, v250, s[40:41]
	v_cndmask_b32_e64 v248, v58, v50, s[40:41]
	v_cndmask_b32_e64 v249, v59, v51, s[40:41]
	global_store_dwordx2 v250, v[248:249], s[20:21]
	v_cndmask_b32_e64 v246, v50, v58, s[40:41]
	v_cndmask_b32_e64 v247, v51, v59, s[40:41]
	v_mul_f32_e32 v19, v19, v19
	v_fmac_f32_e32 v19, v18, v18
	v_mul_f32_e32 v18, v21, v21
	v_mul_f32_e32 v29, v29, v29
	v_fmac_f32_e32 v18, v20, v20
	v_mul_f32_e32 v27, v27, v27
	v_fmac_f32_e32 v29, v28, v28
	v_mul_f32_e32 v28, v31, v31
	v_mul_f32_e32 v31, v33, v33
	v_add_f32_e32 v18, v19, v18
	v_mul_f32_e32 v19, v23, v23
	v_mul_f32_e32 v20, v25, v25
	v_fmac_f32_e32 v31, v32, v32
	v_fmac_f32_e32 v19, v22, v22
	v_fmac_f32_e32 v20, v24, v24
	v_fmac_f32_e32 v27, v26, v26
	v_fmac_f32_e32 v28, v30, v30
	v_add_f32_e32 v19, v19, v20
	v_add_f32_e32 v20, v27, v29
	v_add_f32_e32 v21, v28, v31
	v_add_f32_e32 v18, v20, v18
	v_add_f32_e32 v19, v21, v19
	s_nop 1
	v_mov_b32_dpp v20, v18 quad_perm:[1,0,3,2] row_mask:0xf bank_mask:0xf
	s_nop 1
	v_mov_b32_dpp v21, v19 quad_perm:[1,0,3,2] row_mask:0xf bank_mask:0xf
	s_waitcnt lgkmcnt(1)
	v_add_f32_e32 v18, v18, v20
	s_waitcnt lgkmcnt(0)
	v_add_f32_e32 v21, v19, v21
	s_nop 1
	v_mov_b32_dpp v20, v18 quad_perm:[2,3,0,1] row_mask:0xf bank_mask:0xf
	s_nop 1
	v_mov_b32_dpp v22, v21 quad_perm:[2,3,0,1] row_mask:0xf bank_mask:0xf
	s_waitcnt lgkmcnt(1)
	v_add_f32_e32 v18, v18, v20
	s_waitcnt lgkmcnt(0)
	v_add_f32_e32 v20, v21, v22
	s_nop 1
	v_mov_b32_dpp v19, v18 row_half_mirror row_mask:0xf bank_mask:0xf
	s_nop 1
	v_mov_b32_dpp v21, v20 row_half_mirror row_mask:0xf bank_mask:0xf
	v_add_u32_e32 v22, 0x1040, v52
	v_cndmask_b32_e64 v22, v52, v22, s[38:39]
	global_store_dwordx2 v22, v[246:247], s[20:21]
	s_and_saveexec_b64 s[16:17], s[42:43]
	s_cbranch_execz .LBB0_1668
	s_waitcnt lgkmcnt(1)
	v_add_f32_e32 v18, v18, v19
	s_waitcnt lgkmcnt(0)
	v_add_f32_e32 v19, v20, v21
	ds_write2_b32 v194, v18, v19 offset0:96 offset1:104
; #define LAS __attribute__((address_space(3)))
; __device__ __forceinline__ unsigned cvt_pk_bf16(float lo, float hi) { unsigned r; asm volatile("v_cvt_pk_bf16_f32 %0, %1, %2" : "=v"(r) : "v"(lo), "v"(hi)); return r; }
;     __device__ __forceinline__ void operator()(const f32x4 (&acc)[2][2][4][2], const Unit& u, int wr, int wc, int fr, int fq) const {
;     ...
;             if (g + 1 < 8) ERN_LOADX(g + 1);
;             float sq0 = 0.f, sq1 = 0.f; u32x2 hw[2][2];
; #pragma unroll
;             for (int bj = 0; bj < 2; ++bj) {
;                 *(LAS f32x4*)(st + wr_off) = acc[ai][bj][m][0]; *(LAS f32x4*)(st + wr_off + 64) = acc[ai][bj][m][1];
;                 const f32x4 a0 = *(const LAS f32x4*)(st + rd_off), a1 = *(const LAS f32x4*)(st + rd_off + 8 * 144);
;                 { const f32x4 xv = xb[g & 1][bj][0] + gv[bj] * a0; __builtin_nontemporal_store(xv, (f32x4*)((char*)xo + 4u * ERN_EOFF(g, bj, 0)));
;                   sq0 += (xv.x * xv.x + xv.y * xv.y) + (xv.z * xv.z + xv.w * xv.w);
;                   const f32x4 hv = xv * gsn[bj]; hw[bj][0].x = cvt_pk_bf16(hv.x, hv.y); hw[bj][0].y = cvt_pk_bf16(hv.z, hv.w); }
;                 { const f32x4 xv = xb[g & 1][bj][1] + gv[bj] * a1; __builtin_nontemporal_store(xv, (f32x4*)((char*)xo + 4u * ERN_EOFF(g, bj, 1)));
;                   sq1 += (xv.x * xv.x + xv.y * xv.y) + (xv.z * xv.z + xv.w * xv.w);
;                   const f32x4 hv = xv * gsn[bj]; hw[bj][1].x = cvt_pk_bf16(hv.x, hv.y); hw[bj][1].y = cvt_pk_bf16(hv.z, hv.w); }
;             }
;             if (!NOH && !PLAIN) {
; #pragma unroll
;                 for (int rh = 0; rh < 2; ++rh) { u32x2 rv; rv.x = __shfl_xor(hw[1][rh].x, 8); rv.y = __shfl_xor(hw[1][rh].y, 8);
;                     const unsigned e0 = ERN_EOFF(g, 0, rh);
;                     const unsigned ee = odd ? (e0 - DM + 32) : e0, eo2 = odd ? e0 : (e0 + DM + 32);
;                     *(u32x2*)((char*)ho + 2u * ee) = odd ? rv : hw[0][rh];
;                     *(u32x2*)((char*)ho + 2u * eo2) = odd ? hw[0][rh] : rv; }
;             }
;             if (!PLAIN) { sq0 += __shfl_xor(sq0, 1); sq0 += __shfl_xor(sq0, 2); sq0 += __shfl_xor(sq0, 4);
;             sq1 += __shfl_xor(sq1, 1); sq1 += __shfl_xor(sq1, 2); sq1 += __shfl_xor(sq1, 4); }
;             if (!PLAIN && pc == 0) { sst[g * 16 + rr] = sq0; sst[g * 16 + 8 + rr] = sq1; }
.LBB0_1668:
	s_or_b64 exec, exec, s[16:17]
	ds_write_b128 v200, v[14:17]
	ds_write_b128 v200, v[10:13] offset:64
	ds_read_b128 v[10:13], v201
	ds_read_b128 v[14:17], v201 offset:1152
	s_waitcnt lgkmcnt(5)
	v_lshl_add_u64 v[18:19], s[22:23], 0, v[154:155]
	v_mov_b32_e32 v71, v155
	v_lshl_add_u64 v[22:23], s[22:23], 0, v[70:71]
	s_waitcnt vmcnt(9) lgkmcnt(1)
	v_pk_fma_f32 v[12:13], v[176:177], v[12:13], v[48:49]
	v_pk_fma_f32 v[10:11], v[180:181], v[10:11], v[46:47]
	global_store_dwordx4 v[18:19], v[10:13], off nt
	v_pk_mul_f32 v[18:19], v[174:175], v[12:13]
	v_pk_mul_f32 v[20:21], v[178:179], v[10:11]
	s_waitcnt vmcnt(9) lgkmcnt(0)
	v_pk_fma_f32 v[14:15], v[180:181], v[14:15], v[42:43]
	v_cvt_pk_bf16_f32 v20, v20, v21
	v_cvt_pk_bf16_f32 v21, v18, v19
	v_pk_fma_f32 v[16:17], v[176:177], v[16:17], v[44:45]
	v_pk_mul_f32 v[18:19], v[178:179], v[14:15]
	global_store_dwordx4 v[22:23], v[14:17], off nt
	v_pk_mul_f32 v[22:23], v[174:175], v[16:17]
	v_cvt_pk_bf16_f32 v18, v18, v19
	v_mov_b32_e32 v69, v155
	v_cvt_pk_bf16_f32 v19, v22, v23
	ds_write_b128 v200, v[6:9]
	ds_write_b128 v200, v[2:5] offset:64
	ds_read_b128 v[2:5], v201
	ds_read_b128 v[6:9], v201 offset:1152
	v_lshl_add_u64 v[22:23], s[22:23], 0, v[68:69]
	v_mov_b32_e32 v67, v155
	v_lshl_add_u64 v[24:25], s[22:23], 0, v[66:67]
	s_waitcnt vmcnt(9) lgkmcnt(1)
	v_pk_fma_f32 v[4:5], v[166:167], v[4:5], v[40:41]
	v_pk_fma_f32 v[2:3], v[168:169], v[2:3], v[38:39]
	global_store_dwordx4 v[22:23], v[2:5], off nt
	v_pk_mul_f32 v[22:23], v[170:171], v[4:5]
	v_pk_mul_f32 v[26:27], v[172:173], v[2:3]
	s_waitcnt vmcnt(9) lgkmcnt(0)
	v_pk_fma_f32 v[8:9], v[166:167], v[8:9], v[36:37]
	v_cvt_pk_bf16_f32 v28, v26, v27
	v_cvt_pk_bf16_f32 v23, v22, v23
	ds_bpermute_b32 v22, v203, v28
	ds_bpermute_b32 v23, v203, v23
	v_pk_fma_f32 v[6:7], v[168:169], v[6:7], v[34:35]
	global_store_dwordx4 v[24:25], v[6:9], off nt
	v_pk_mul_f32 v[26:27], v[170:171], v[8:9]
	v_pk_mul_f32 v[24:25], v[172:173], v[6:7]
	s_nop 0
	v_cvt_pk_bf16_f32 v24, v24, v25
	v_cvt_pk_bf16_f32 v25, v26, v27
	v_add_u32_e32 v27, 0x58000, v202
	v_lshlrev_b32_e32 v26, 1, v27
	s_waitcnt lgkmcnt(0)
	v_add_u32_e32 v250, 0xfffff040, v26
	v_cndmask_b32_e64 v250, v26, v250, s[40:41]
	v_cndmask_b32_e64 v248, v20, v22, s[40:41]
	v_cndmask_b32_e64 v249, v21, v23, s[40:41]
	global_store_dwordx2 v250, v[248:249], s[20:21]
	v_cndmask_b32_e64 v246, v22, v20, s[40:41]
	v_cndmask_b32_e64 v247, v23, v21, s[40:41]
	s_waitcnt lgkmcnt(1)
	v_add_u32_e32 v22, 0x1040, v26
	v_cndmask_b32_e64 v22, v26, v22, s[38:39]
	global_store_dwordx2 v22, v[246:247], s[20:21]
	ds_bpermute_b32 v20, v203, v24
	ds_bpermute_b32 v21, v203, v25
	s_waitcnt lgkmcnt(2)
	v_add_u32_e32 v23, 0x5c000, v202
	v_lshlrev_b32_e32 v22, 1, v23
	s_waitcnt lgkmcnt(0)
	v_add_u32_e32 v250, 0xfffff040, v22
	v_cndmask_b32_e64 v250, v22, v250, s[40:41]
	v_cndmask_b32_e64 v248, v18, v20, s[40:41]
	v_cndmask_b32_e64 v249, v19, v21, s[40:41]
	global_store_dwordx2 v250, v[248:249], s[20:21]
	v_cndmask_b32_e64 v246, v20, v18, s[40:41]
	v_cndmask_b32_e64 v247, v21, v19, s[40:41]
	v_mul_f32_e32 v3, v3, v3
	v_fmac_f32_e32 v3, v2, v2
	v_mul_f32_e32 v2, v5, v5
	v_mul_f32_e32 v13, v13, v13
	v_fmac_f32_e32 v2, v4, v4
	v_mul_f32_e32 v11, v11, v11
	v_fmac_f32_e32 v13, v12, v12
	v_mul_f32_e32 v12, v15, v15
	v_mul_f32_e32 v15, v17, v17
	v_add_f32_e32 v2, v3, v2
	v_mul_f32_e32 v3, v7, v7
	v_mul_f32_e32 v4, v9, v9
	v_fmac_f32_e32 v15, v16, v16
	v_fmac_f32_e32 v3, v6, v6
	v_fmac_f32_e32 v4, v8, v8
	v_fmac_f32_e32 v11, v10, v10
	v_fmac_f32_e32 v12, v14, v14
	v_add_f32_e32 v3, v3, v4
	v_add_f32_e32 v4, v11, v13
	v_add_f32_e32 v5, v12, v15
	v_add_f32_e32 v2, v4, v2
	v_add_f32_e32 v3, v5, v3
	s_nop 1
	v_mov_b32_dpp v4, v2 quad_perm:[1,0,3,2] row_mask:0xf bank_mask:0xf
	s_nop 1
	v_mov_b32_dpp v5, v3 quad_perm:[1,0,3,2] row_mask:0xf bank_mask:0xf
	s_waitcnt lgkmcnt(1)
	v_add_f32_e32 v2, v2, v4
	s_waitcnt lgkmcnt(0)
	v_add_f32_e32 v5, v3, v5
	s_nop 1
	v_mov_b32_dpp v4, v2 quad_perm:[2,3,0,1] row_mask:0xf bank_mask:0xf
	s_nop 1
	v_mov_b32_dpp v6, v5 quad_perm:[2,3,0,1] row_mask:0xf bank_mask:0xf
	s_waitcnt lgkmcnt(1)
	v_add_f32_e32 v2, v2, v4
	s_waitcnt lgkmcnt(0)
	v_add_f32_e32 v4, v5, v6
	s_nop 1
	v_mov_b32_dpp v3, v2 row_half_mirror row_mask:0xf bank_mask:0xf
	s_nop 1
	v_mov_b32_dpp v5, v4 row_half_mirror row_mask:0xf bank_mask:0xf
	v_add_u32_e32 v6, 0x1040, v22
	v_cndmask_b32_e64 v6, v22, v6, s[38:39]
	global_store_dwordx2 v6, v[246:247], s[20:21]
	s_and_saveexec_b64 s[16:17], s[42:43]
	s_cbranch_execz .LBB0_1678
	s_waitcnt lgkmcnt(1)
	v_add_f32_e32 v2, v2, v3
	s_waitcnt lgkmcnt(0)
	v_add_f32_e32 v3, v4, v5
	ds_write2_b32 v194, v2, v3 offset0:112 offset1:120

; #define LAS __attribute__((address_space(3)))
;     __device__ __forceinline__ void operator()(const f32x4 (&acc)[2][2][4][2], const Unit& u, int wr, int wc, int fr, int fq) const {
;         const int s = u.pm >> 5, lane = fq * 16 + fr, rr = lane >> 3, pc = lane & 7;
;         const float* __restrict__ xi = xin + (size_t)u.pm * BM * DM; float* __restrict__ xo = xout + (size_t)u.pm * BM * DM; bf16_t* __restrict__ ho = Hn + (size_t)u.pm * BM * DM;
;         LAS unsigned char* st = lds_epi + (wr * 4 + wc) * 2304;
;         LAS float* sst = (LAS float*)(lds_epi + 18432 + (wr * 4 + wc) * 512);
;         const int colr = u.pn * BM + wc * 64 + 4 * pc;
;         const unsigned eb = (unsigned)((wr * 64 + rr) * DM + colr);
;         f32x4 gv[2], gsn[2];
; #pragma unroll
;         for (int bj = 0; bj < 2; ++bj) { gv[bj] = *(const f32x4*)(gate + (size_t)s * MODW + colr + bj * 32) * (0.5f * GS2);
;             if (!PLAIN) gsn[bj] = *(const f32x4*)(gnext + colr + bj * 32) * (*(const f32x4*)(scnext + (size_t)s * MODW + colr + bj * 32) + 1.0f); else gsn[bj] = gv[bj]; }
;         const unsigned wr_off = (unsigned)(fr * 144 + 16 * fq), rd_off = (unsigned)(rr * 144 + pc * 16);
;         const bool odd = (rr & 1) != 0;
;         f32x4 xb[2][2][2];
;     ...
;         ERN_LOADX(0);
; #pragma unroll
;         for (int g = 0; g < 8; ++g) { const int ai = g >> 2, m = g & 3;
;             if (g + 1 < 8) ERN_LOADX(g + 1);
;             float sq0 = 0.f, sq1 = 0.f; u32x2 hw[2][2];
; #pragma unroll
;             for (int bj = 0; bj < 2; ++bj) {
;                 *(LAS f32x4*)(st + wr_off) = acc[ai][bj][m][0]; *(LAS f32x4*)(st + wr_off + 64) = acc[ai][bj][m][1];
;                 const f32x4 a0 = *(const LAS f32x4*)(st + rd_off), a1 = *(const LAS f32x4*)(st + rd_off + 8 * 144);
;                 { const f32x4 xv = xb[g & 1][bj][0] + gv[bj] * a0; __builtin_nontemporal_store(xv, (f32x4*)((char*)xo + 4u * ERN_EOFF(g, bj, 0)));
;                   sq0 += (xv.x * xv.x + xv.y * xv.y) + (xv.z * xv.z + xv.w * xv.w);
;                   const f32x4 hv = xv * gsn[bj]; hw[bj][0].x = cvt_pk_bf16(hv.x, hv.y); hw[bj][0].y = cvt_pk_bf16(hv.z, hv.w); }
;                 { const f32x4 xv = xb[g & 1][bj][1] + gv[bj] * a1; __builtin_nontemporal_store(xv, (f32x4*)((char*)xo + 4u * ERN_EOFF(g, bj, 1)));
;                   sq1 += (xv.x * xv.x + xv.y * xv.y) + (xv.z * xv.z + xv.w * xv.w);
.LBB0_1929:
	s_ashr_i32 s18, s4, 5
	s_ashr_i32 s5, s4, 31
	v_lshl_or_b32 v130, s0, 8, v192
	s_mul_i32 s20, s18, 0x12000
	s_mul_hi_i32 s0, s18, 0x12000
	s_add_u32 s18, s33, s20
	v_ashrrev_i32_e32 v131, 31, v130
	s_addc_u32 s19, s34, s0
	v_lshlrev_b64 v[132:133], 2, v[130:131]
	v_lshl_add_u64 v[134:135], s[18:19], 0, v[132:133]
	s_add_u32 s18, s35, s20
	s_addc_u32 s19, s36, s0
	v_lshl_add_u64 v[136:137], s[10:11], 0, v[132:133]
	v_lshl_add_u64 v[132:133], s[18:19], 0, v[132:133]
	s_lshl_b64 s[18:19], s[4:5], 21
	s_add_u32 s20, s90, s18
	v_add_u32_e32 v202, v130, v193
	s_addc_u32 s21, s91, s19
	v_lshlrev_b32_e32 v205, 2, v202
	global_load_dwordx4 v[170:173], v[136:137], off
	global_load_dwordx4 v[166:169], v[134:135], off
	global_load_dwordx4 v[186:189], v[134:135], off offset:128
	global_load_dwordx4 v[206:209], v[132:133], off
	global_load_dwordx4 v[210:213], v[132:133], off offset:128
	global_load_dwordx4 v[214:217], v205, s[20:21]
	v_add_u32_e32 v130, 0x10000, v205
	global_load_dwordx4 v[218:221], v130, s[20:21]
	global_load_dwordx4 v[222:225], v[136:137], off offset:128
	global_load_dwordx4 v[226:229], v205, s[20:21] offset:128
	v_add_u32_e32 v204, 0x10080, v205
	global_load_dwordx4 v[230:233], v204, s[20:21]
	v_add_u32_e32 v130, 0x20000, v205
	v_add_u32_e32 v154, 0x30000, v205
	v_add_u32_e32 v184, 0x20080, v205
	v_add_u32_e32 v182, 0x30080, v205
	global_load_dwordx4 v[142:145], v130, s[20:21]
	global_load_dwordx4 v[138:141], v154, s[20:21]
	global_load_dwordx4 v[134:137], v184, s[20:21]
	s_nop 0
	global_load_dwordx4 v[130:133], v182, s[20:21]
	ds_write_b128 v200, v[126:129]
	ds_write_b128 v200, v[122:125] offset:64
	v_and_b32_e32 v127, 64, v199
	ds_read_b128 v[122:125], v201
	ds_read_b128 v[234:237], v201 offset:1152
	v_xor_b32_e32 v126, 8, v199
	v_add_u32_e32 v183, 64, v127
	v_cmp_lt_i32_e32 vcc, v126, v183
	v_add_u32_e32 v185, 0x4000, v202
	v_lshlrev_b32_e32 v238, 2, v185
	v_cndmask_b32_e32 v126, v199, v126, vcc
	v_lshlrev_b32_e32 v203, 2, v126
	s_lshl_b64 s[18:19], s[4:5], 20
	s_add_u32 s18, s93, s18
	s_addc_u32 s19, s92, s19
	s_waitcnt vmcnt(0)
	v_pk_mul_f32 v[180:181], v[166:167], 0.5 op_sel_hi:[1,0]
	v_pk_mul_f32 v[176:177], v[168:169], 0.5 op_sel_hi:[1,0]
	v_pk_add_f32 v[126:127], v[208:209], 1.0 op_sel_hi:[1,0]
	v_pk_add_f32 v[128:129], v[206:207], 1.0 op_sel_hi:[1,0]
	v_pk_mul_f32 v[174:175], v[172:173], v[126:127]
	v_pk_mul_f32 v[178:179], v[170:171], v[128:129]
	s_waitcnt lgkmcnt(1)
	v_pk_fma_f32 v[126:127], v[180:181], v[122:123], v[214:215]
	s_waitcnt lgkmcnt(0)
	v_pk_fma_f32 v[122:123], v[180:181], v[234:235], v[218:219]
	v_pk_mul_f32 v[168:169], v[186:187], 0.5 op_sel_hi:[1,0]
	v_pk_fma_f32 v[128:129], v[176:177], v[124:125], v[216:217]
	v_pk_fma_f32 v[124:125], v[176:177], v[236:237], v[220:221]
	v_pk_mul_f32 v[186:187], v[178:179], v[122:123]
	v_pk_mul_f32 v[166:167], v[188:189], 0.5 op_sel_hi:[1,0]
	global_store_dwordx4 v205, v[126:129], s[20:21] nt
	v_pk_mul_f32 v[170:171], v[174:175], v[128:129]
	v_pk_mul_f32 v[172:173], v[178:179], v[126:127]
	v_pk_mul_f32 v[206:207], v[174:175], v[124:125]
	v_cvt_pk_bf16_f32 v188, v172, v173
	v_cvt_pk_bf16_f32 v189, v170, v171
	global_store_dwordx4 v238, v[122:125], s[20:21] nt
	v_cvt_pk_bf16_f32 v186, v186, v187
	v_cvt_pk_bf16_f32 v187, v206, v207
	ds_write_b128 v200, v[118:121]
	ds_write_b128 v200, v[114:117] offset:64
	ds_read_b128 v[114:117], v201
	ds_read_b128 v[206:209], v201 offset:1152
	v_pk_add_f32 v[190:191], v[212:213], 1.0 op_sel_hi:[1,0]
	v_pk_add_f32 v[118:119], v[210:211], 1.0 op_sel_hi:[1,0]
	v_pk_mul_f32 v[170:171], v[224:225], v[190:191]
	v_pk_mul_f32 v[172:173], v[222:223], v[118:119]
	s_waitcnt lgkmcnt(1)
	v_pk_fma_f32 v[120:121], v[166:167], v[116:117], v[228:229]
	v_pk_fma_f32 v[118:119], v[168:169], v[114:115], v[226:227]
	s_waitcnt lgkmcnt(0)
	v_pk_fma_f32 v[114:115], v[168:169], v[206:207], v[230:231]
	v_pk_mul_f32 v[190:191], v[170:171], v[120:121]
	v_pk_mul_f32 v[206:207], v[172:173], v[118:119]
	global_store_dwordx4 v205, v[118:121], s[20:21] offset:128 nt
	v_cvt_pk_bf16_f32 v206, v206, v207
	v_cvt_pk_bf16_f32 v191, v190, v191
	ds_bpermute_b32 v190, v203, v206
	ds_bpermute_b32 v191, v203, v191
	v_pk_fma_f32 v[116:117], v[166:167], v[208:209], v[232:233]
	v_pk_mul_f32 v[206:207], v[172:173], v[114:115]
	global_store_dwordx4 v204, v[114:117], s[20:21] nt
	v_cvt_pk_bf16_f32 v204, v206, v207
	v_lshlrev_b32_e32 v207, 1, v202
	v_pk_mul_f32 v[208:209], v[170:171], v[116:117]
	s_nop 0
	v_cvt_pk_bf16_f32 v206, v208, v209
	s_waitcnt lgkmcnt(0)
	v_add_u32_e32 v250, 0xfffff040, v207
	v_cndmask_b32_e64 v250, v207, v250, s[40:41]
	v_cndmask_b32_e64 v248, v188, v190, s[40:41]
	v_cndmask_b32_e64 v249, v189, v191, s[40:41]
	global_store_dwordx2 v250, v[248:249], s[18:19]
	v_cndmask_b32_e64 v246, v190, v188, s[40:41]
	v_cndmask_b32_e64 v247, v191, v189, s[40:41]
	s_waitcnt lgkmcnt(1)
	v_add_u32_e32 v190, 0x1040, v207
	v_cndmask_b32_e64 v190, v207, v190, s[38:39]
	global_store_dwordx2 v190, v[246:247], s[18:19]
	ds_bpermute_b32 v188, v203, v204
	ds_bpermute_b32 v189, v203, v206
	v_lshlrev_b32_e32 v206, 1, v185
	s_waitcnt lgkmcnt(0)
; #define LAS __attribute__((address_space(3)))
; __device__ __forceinline__ unsigned cvt_pk_bf16(float lo, float hi) { unsigned r; asm volatile("v_cvt_pk_bf16_f32 %0, %1, %2" : "=v"(r) : "v"(lo), "v"(hi)); return r; }
;     __device__ __forceinline__ void operator()(const f32x4 (&acc)[2][2][4][2], const Unit& u, int wr, int wc, int fr, int fq) const {
;     ...
;             if (g + 1 < 8) ERN_LOADX(g + 1);
;             float sq0 = 0.f, sq1 = 0.f; u32x2 hw[2][2];
; #pragma unroll
;             for (int bj = 0; bj < 2; ++bj) {
;                 *(LAS f32x4*)(st + wr_off) = acc[ai][bj][m][0]; *(LAS f32x4*)(st + wr_off + 64) = acc[ai][bj][m][1];
;                 const f32x4 a0 = *(const LAS f32x4*)(st + rd_off), a1 = *(const LAS f32x4*)(st + rd_off + 8 * 144);
;                 { const f32x4 xv = xb[g & 1][bj][0] + gv[bj] * a0; __builtin_nontemporal_store(xv, (f32x4*)((char*)xo + 4u * ERN_EOFF(g, bj, 0)));
;                   sq0 += (xv.x * xv.x + xv.y * xv.y) + (xv.z * xv.z + xv.w * xv.w);
;                   const f32x4 hv = xv * gsn[bj]; hw[bj][0].x = cvt_pk_bf16(hv.x, hv.y); hw[bj][0].y = cvt_pk_bf16(hv.z, hv.w); }
;                 { const f32x4 xv = xb[g & 1][bj][1] + gv[bj] * a1; __builtin_nontemporal_store(xv, (f32x4*)((char*)xo + 4u * ERN_EOFF(g, bj, 1)));
;                   sq1 += (xv.x * xv.x + xv.y * xv.y) + (xv.z * xv.z + xv.w * xv.w);
;                   const f32x4 hv = xv * gsn[bj]; hw[bj][1].x = cvt_pk_bf16(hv.x, hv.y); hw[bj][1].y = cvt_pk_bf16(hv.z, hv.w); }
;             }
;             if (!NOH && !PLAIN) {
; #pragma unroll
;                 for (int rh = 0; rh < 2; ++rh) { u32x2 rv; rv.x = __shfl_xor(hw[1][rh].x, 8); rv.y = __shfl_xor(hw[1][rh].y, 8);
;                     const unsigned e0 = ERN_EOFF(g, 0, rh);
;                     const unsigned ee = odd ? (e0 - DM + 32) : e0, eo2 = odd ? e0 : (e0 + DM + 32);
;                     *(u32x2*)((char*)ho + 2u * ee) = odd ? rv : hw[0][rh];
;                     *(u32x2*)((char*)ho + 2u * eo2) = odd ? hw[0][rh] : rv; }
;             }
;             if (!PLAIN) { sq0 += __shfl_xor(sq0, 1); sq0 += __shfl_xor(sq0, 2); sq0 += __shfl_xor(sq0, 4);
;             sq1 += __shfl_xor(sq1, 1); sq1 += __shfl_xor(sq1, 2); sq1 += __shfl_xor(sq1, 4); }
;             if (!PLAIN && pc == 0) { sst[g * 16 + rr] = sq0; sst[g * 16 + 8 + rr] = sq1; }
	v_add_u32_e32 v250, 0xfffff040, v206
	v_cndmask_b32_e64 v250, v206, v250, s[40:41]
	v_cndmask_b32_e64 v248, v186, v188, s[40:41]
	v_cndmask_b32_e64 v249, v187, v189, s[40:41]
	global_store_dwordx2 v250, v[248:249], s[18:19]
	v_cndmask_b32_e64 v246, v188, v186, s[40:41]
	v_cndmask_b32_e64 v247, v189, v187, s[40:41]
	v_mul_f32_e32 v119, v119, v119
	v_mul_f32_e32 v127, v127, v127
	v_mul_f32_e32 v129, v129, v129
	v_fmac_f32_e32 v119, v118, v118
	v_mul_f32_e32 v118, v121, v121
	v_fmac_f32_e32 v129, v128, v128
	v_fmac_f32_e32 v118, v120, v120
	v_mul_f32_e32 v115, v115, v115
	v_fmac_f32_e32 v127, v126, v126
	v_add_f32_e32 v118, v119, v118
	v_fmac_f32_e32 v115, v114, v114
	v_mul_f32_e32 v114, v117, v117
	v_add_f32_e32 v117, v127, v129
	v_add_f32_e32 v117, v117, v118
	v_xor_b32_e32 v118, 1, v199
	v_cmp_lt_i32_e32 vcc, v118, v183
	v_mul_f32_e32 v123, v123, v123
	v_mul_f32_e32 v125, v125, v125
	v_cndmask_b32_e32 v118, v199, v118, vcc
	v_lshlrev_b32_e32 v190, 2, v118
	s_nop 1
	v_mov_b32_dpp v118, v117 quad_perm:[1,0,3,2] row_mask:0xf bank_mask:0xf
	v_fmac_f32_e32 v114, v116, v116
	v_fmac_f32_e32 v125, v124, v124
	v_fmac_f32_e32 v123, v122, v122
	v_add_f32_e32 v114, v115, v114
	s_waitcnt lgkmcnt(0)
	v_add_f32_e32 v116, v117, v118
	v_xor_b32_e32 v117, 2, v199
	v_cmp_lt_i32_e32 vcc, v117, v183
	v_add_f32_e32 v115, v123, v125
	v_add_f32_e32 v115, v115, v114
	v_cndmask_b32_e32 v117, v199, v117, vcc
	v_lshlrev_b32_e32 v191, 2, v117
	s_nop 1
	v_mov_b32_dpp v117, v116 quad_perm:[2,3,0,1] row_mask:0xf bank_mask:0xf
	s_nop 1
	v_mov_b32_dpp v118, v115 quad_perm:[1,0,3,2] row_mask:0xf bank_mask:0xf
	s_waitcnt lgkmcnt(1)
	v_add_f32_e32 v114, v116, v117
	s_waitcnt lgkmcnt(0)
	v_add_f32_e32 v117, v115, v118
	s_nop 1
	v_mov_b32_dpp v118, v117 quad_perm:[2,3,0,1] row_mask:0xf bank_mask:0xf
	v_xor_b32_e32 v116, 4, v199
	v_cmp_lt_i32_e32 vcc, v116, v183
	s_nop 1
	v_cndmask_b32_e32 v115, v199, v116, vcc
	v_lshlrev_b32_e32 v204, 2, v115
	s_waitcnt lgkmcnt(0)
	v_add_f32_e32 v116, v117, v118
	s_nop 1
	v_mov_b32_dpp v115, v114 row_half_mirror row_mask:0xf bank_mask:0xf
	s_nop 1
	v_mov_b32_dpp v117, v116 row_half_mirror row_mask:0xf bank_mask:0xf
	v_add_u32_e32 v118, 0x1040, v206
	v_cndmask_b32_e64 v118, v206, v118, s[38:39]
	global_store_dwordx2 v118, v[246:247], s[18:19]
	s_and_saveexec_b64 s[22:23], s[42:43]
	s_cbranch_execz .LBB0_1939
	s_waitcnt lgkmcnt(1)
	v_add_f32_e32 v114, v114, v115
	s_waitcnt lgkmcnt(0)
	v_add_f32_e32 v115, v116, v117
	ds_write2_b32 v194, v114, v115 offset1:8
.LBB0_1939:
	s_or_b64 exec, exec, s[22:23]
	v_lshl_add_u64 v[206:207], s[20:21], 0, v[154:155]
	v_add_u32_e32 v114, 0x40000, v205
	v_add_u32_e32 v154, 0x50000, v205
	v_add_u32_e32 v186, 0x40080, v205
	global_load_dwordx4 v[122:125], v154, s[20:21]
	global_load_dwordx4 v[118:121], v186, s[20:21]
	v_add_u32_e32 v188, 0x50080, v205
	global_load_dwordx4 v[126:129], v114, s[20:21]
	s_waitcnt lgkmcnt(0)
	global_load_dwordx4 v[114:117], v188, s[20:21]
	ds_write_b128 v200, v[110:113]
	ds_write_b128 v200, v[106:109] offset:64
	ds_read_b128 v[106:109], v201
	ds_read_b128 v[110:113], v201 offset:1152
	v_mov_b32_e32 v185, v155
	v_mov_b32_e32 v183, v155
	v_lshl_add_u64 v[182:183], s[20:21], 0, v[182:183]
	s_waitcnt lgkmcnt(1)
	v_pk_fma_f32 v[108:109], v[176:177], v[108:109], v[144:145]
	v_add_u32_e32 v144, 0x8000, v202
	v_pk_fma_f32 v[106:107], v[180:181], v[106:107], v[142:143]
	v_lshlrev_b32_e32 v142, 2, v144
	s_waitcnt lgkmcnt(0)
	v_pk_fma_f32 v[110:111], v[180:181], v[110:111], v[138:139]
	global_store_dwordx4 v142, v[106:109], s[20:21] nt
	v_pk_mul_f32 v[142:143], v[178:179], v[106:107]
	v_pk_fma_f32 v[112:113], v[176:177], v[112:113], v[140:141]
	v_pk_mul_f32 v[138:139], v[178:179], v[110:111]
	v_pk_mul_f32 v[208:209], v[174:175], v[108:109]
	v_cvt_pk_bf16_f32 v142, v142, v143
	v_pk_mul_f32 v[140:141], v[174:175], v[112:113]
	v_cvt_pk_bf16_f32 v143, v208, v209
	global_store_dwordx4 v[206:207], v[110:113], off nt
	v_cvt_pk_bf16_f32 v138, v138, v139
	v_cvt_pk_bf16_f32 v139, v140, v141
	ds_write_b128 v200, v[102:105]
	ds_write_b128 v200, v[98:101] offset:64
	ds_read_b128 v[98:101], v201
	ds_read_b128 v[102:105], v201 offset:1152
	v_lshl_add_u64 v[140:141], s[20:21], 0, v[184:185]
	s_waitcnt lgkmcnt(1)
	v_pk_fma_f32 v[98:99], v[168:169], v[98:99], v[134:135]
	v_pk_fma_f32 v[100:101], v[166:167], v[100:101], v[136:137]
	v_pk_mul_f32 v[136:137], v[172:173], v[98:99]
	global_store_dwordx4 v[140:141], v[98:101], off nt
	v_pk_mul_f32 v[134:135], v[170:171], v[100:101]
	v_cvt_pk_bf16_f32 v136, v136, v137
	s_waitcnt lgkmcnt(0)
	v_pk_fma_f32 v[102:103], v[168:169], v[102:103], v[130:131]
	v_cvt_pk_bf16_f32 v137, v134, v135
	ds_bpermute_b32 v130, v203, v136
	ds_bpermute_b32 v131, v203, v137
	v_pk_fma_f32 v[104:105], v[166:167], v[104:105], v[132:133]
	v_pk_mul_f32 v[132:133], v[172:173], v[102:103]
	v_pk_mul_f32 v[134:135], v[170:171], v[104:105]
	global_store_dwordx4 v[182:183], v[102:105], off nt
	v_cvt_pk_bf16_f32 v132, v132, v133
	v_cvt_pk_bf16_f32 v133, v134, v135
	v_lshlrev_b32_e32 v134, 1, v144
	s_waitcnt lgkmcnt(0)
	v_add_u32_e32 v250, 0xfffff040, v134
	v_cndmask_b32_e64 v250, v134, v250, s[40:41]
	v_cndmask_b32_e64 v248, v142, v130, s[40:41]
	v_cndmask_b32_e64 v249, v143, v131, s[40:41]
	global_store_dwordx2 v250, v[248:249], s[18:19]
	v_cndmask_b32_e64 v246, v130, v142, s[40:41]
	v_cndmask_b32_e64 v247, v131, v143, s[40:41]
	s_waitcnt lgkmcnt(1)
	v_add_u32_e32 v130, 0x1040, v134
	v_cndmask_b32_e64 v130, v134, v130, s[38:39]
	global_store_dwordx2 v130, v[246:247], s[18:19]
	ds_bpermute_b32 v130, v203, v132
	s_waitcnt lgkmcnt(1)
	ds_bpermute_b32 v131, v203, v133
	v_add_u32_e32 v133, 0xc000, v202
	v_lshlrev_b32_e32 v132, 1, v133
	s_waitcnt lgkmcnt(0)
; #define LAS __attribute__((address_space(3)))
; __device__ __forceinline__ unsigned cvt_pk_bf16(float lo, float hi) { unsigned r; asm volatile("v_cvt_pk_bf16_f32 %0, %1, %2" : "=v"(r) : "v"(lo), "v"(hi)); return r; }
;     __device__ __forceinline__ void operator()(const f32x4 (&acc)[2][2][4][2], const Unit& u, int wr, int wc, int fr, int fq) const {
;     ...
;             if (g + 1 < 8) ERN_LOADX(g + 1);
;             float sq0 = 0.f, sq1 = 0.f; u32x2 hw[2][2];
; #pragma unroll
;             for (int bj = 0; bj < 2; ++bj) {
;                 *(LAS f32x4*)(st + wr_off) = acc[ai][bj][m][0]; *(LAS f32x4*)(st + wr_off + 64) = acc[ai][bj][m][1];
;                 const f32x4 a0 = *(const LAS f32x4*)(st + rd_off), a1 = *(const LAS f32x4*)(st + rd_off + 8 * 144);
;                 { const f32x4 xv = xb[g & 1][bj][0] + gv[bj] * a0; __builtin_nontemporal_store(xv, (f32x4*)((char*)xo + 4u * ERN_EOFF(g, bj, 0)));
;                   sq0 += (xv.x * xv.x + xv.y * xv.y) + (xv.z * xv.z + xv.w * xv.w);
;                   const f32x4 hv = xv * gsn[bj]; hw[bj][0].x = cvt_pk_bf16(hv.x, hv.y); hw[bj][0].y = cvt_pk_bf16(hv.z, hv.w); }
;                 { const f32x4 xv = xb[g & 1][bj][1] + gv[bj] * a1; __builtin_nontemporal_store(xv, (f32x4*)((char*)xo + 4u * ERN_EOFF(g, bj, 1)));
;                   sq1 += (xv.x * xv.x + xv.y * xv.y) + (xv.z * xv.z + xv.w * xv.w);
;                   const f32x4 hv = xv * gsn[bj]; hw[bj][1].x = cvt_pk_bf16(hv.x, hv.y); hw[bj][1].y = cvt_pk_bf16(hv.z, hv.w); }
;             }
;             if (!NOH && !PLAIN) {
; #pragma unroll
;                 for (int rh = 0; rh < 2; ++rh) { u32x2 rv; rv.x = __shfl_xor(hw[1][rh].x, 8); rv.y = __shfl_xor(hw[1][rh].y, 8);
;                     const unsigned e0 = ERN_EOFF(g, 0, rh);
;                     const unsigned ee = odd ? (e0 - DM + 32) : e0, eo2 = odd ? e0 : (e0 + DM + 32);
;                     *(u32x2*)((char*)ho + 2u * ee) = odd ? rv : hw[0][rh];
;                     *(u32x2*)((char*)ho + 2u * eo2) = odd ? hw[0][rh] : rv; }
;             }
;             if (!PLAIN) { sq0 += __shfl_xor(sq0, 1); sq0 += __shfl_xor(sq0, 2); sq0 += __shfl_xor(sq0, 4);
;             sq1 += __shfl_xor(sq1, 1); sq1 += __shfl_xor(sq1, 2); sq1 += __shfl_xor(sq1, 4); }
;             if (!PLAIN && pc == 0) { sst[g * 16 + rr] = sq0; sst[g * 16 + 8 + rr] = sq1; }
	v_add_u32_e32 v250, 0xfffff040, v132
	v_cndmask_b32_e64 v250, v132, v250, s[40:41]
	v_cndmask_b32_e64 v248, v138, v130, s[40:41]
	v_cndmask_b32_e64 v249, v139, v131, s[40:41]
	global_store_dwordx2 v250, v[248:249], s[18:19]
	v_cndmask_b32_e64 v246, v130, v138, s[40:41]
	v_cndmask_b32_e64 v247, v131, v139, s[40:41]
	v_mul_f32_e32 v99, v99, v99
	v_fmac_f32_e32 v99, v98, v98
	v_mul_f32_e32 v98, v101, v101
	v_mul_f32_e32 v109, v109, v109
	v_fmac_f32_e32 v98, v100, v100
	v_mul_f32_e32 v107, v107, v107
	v_fmac_f32_e32 v109, v108, v108
	v_mul_f32_e32 v108, v111, v111
	v_mul_f32_e32 v111, v113, v113
	v_add_f32_e32 v98, v99, v98
	v_mul_f32_e32 v99, v103, v103
	v_mul_f32_e32 v100, v105, v105
	v_fmac_f32_e32 v111, v112, v112
	v_fmac_f32_e32 v99, v102, v102
	v_fmac_f32_e32 v100, v104, v104
	v_fmac_f32_e32 v107, v106, v106
	v_fmac_f32_e32 v108, v110, v110
	v_add_f32_e32 v99, v99, v100
	v_add_f32_e32 v100, v107, v109
	v_add_f32_e32 v101, v108, v111
	v_add_f32_e32 v98, v100, v98
	v_add_f32_e32 v99, v101, v99
	s_nop 1
	v_mov_b32_dpp v100, v98 quad_perm:[1,0,3,2] row_mask:0xf bank_mask:0xf
	s_nop 1
	v_mov_b32_dpp v101, v99 quad_perm:[1,0,3,2] row_mask:0xf bank_mask:0xf
	s_waitcnt lgkmcnt(1)
	v_add_f32_e32 v98, v98, v100
	s_waitcnt lgkmcnt(0)
	v_add_f32_e32 v101, v99, v101
	s_nop 1
	v_mov_b32_dpp v100, v98 quad_perm:[2,3,0,1] row_mask:0xf bank_mask:0xf
	s_nop 1
	v_mov_b32_dpp v102, v101 quad_perm:[2,3,0,1] row_mask:0xf bank_mask:0xf
	s_waitcnt lgkmcnt(1)
	v_add_f32_e32 v98, v98, v100
	s_waitcnt lgkmcnt(0)
	v_add_f32_e32 v100, v101, v102
	s_nop 1
	v_mov_b32_dpp v99, v98 row_half_mirror row_mask:0xf bank_mask:0xf
	s_nop 1
	v_mov_b32_dpp v101, v100 row_half_mirror row_mask:0xf bank_mask:0xf
	v_add_u32_e32 v102, 0x1040, v132
	v_cndmask_b32_e64 v102, v132, v102, s[38:39]
	global_store_dwordx2 v102, v[246:247], s[18:19]
	s_and_saveexec_b64 s[22:23], s[42:43]
	s_cbranch_execz .LBB0_1949
	s_waitcnt lgkmcnt(1)
	v_add_f32_e32 v98, v98, v99
	s_waitcnt lgkmcnt(0)
	v_add_f32_e32 v99, v100, v101
	ds_write2_b32 v194, v98, v99 offset0:16 offset1:24
.LBB0_1949:
	s_or_b64 exec, exec, s[22:23]
	v_lshl_add_u64 v[134:135], s[20:21], 0, v[154:155]
	v_add_u32_e32 v98, 0x60000, v205
	v_add_u32_e32 v154, 0x70000, v205
	v_add_u32_e32 v130, 0x60080, v205
	global_load_dwordx4 v[106:109], v154, s[20:21]
	global_load_dwordx4 v[102:105], v130, s[20:21]
	v_add_u32_e32 v132, 0x70080, v205
	global_load_dwordx4 v[110:113], v98, s[20:21]
	s_waitcnt lgkmcnt(0)
	global_load_dwordx4 v[98:101], v132, s[20:21]
	ds_write_b128 v200, v[94:97]
	ds_write_b128 v200, v[90:93] offset:64
	ds_read_b128 v[90:93], v201
	ds_read_b128 v[94:97], v201 offset:1152
	v_mov_b32_e32 v187, v155
	v_mov_b32_e32 v189, v155
	s_waitcnt vmcnt(11) lgkmcnt(1)
	v_pk_fma_f32 v[92:93], v[176:177], v[92:93], v[128:129]
	v_add_u32_e32 v128, 0x10000, v202
	v_pk_fma_f32 v[90:91], v[180:181], v[90:91], v[126:127]
	v_lshlrev_b32_e32 v126, 2, v128
	s_waitcnt lgkmcnt(0)
	v_pk_fma_f32 v[94:95], v[180:181], v[94:95], v[122:123]
	global_store_dwordx4 v126, v[90:93], s[20:21] nt
	v_pk_mul_f32 v[126:127], v[178:179], v[90:91]
	v_pk_fma_f32 v[96:97], v[176:177], v[96:97], v[124:125]
	v_pk_mul_f32 v[122:123], v[178:179], v[94:95]
	v_pk_mul_f32 v[136:137], v[174:175], v[92:93]
	v_cvt_pk_bf16_f32 v126, v126, v127
	v_pk_mul_f32 v[124:125], v[174:175], v[96:97]
	v_cvt_pk_bf16_f32 v127, v136, v137
	global_store_dwordx4 v[134:135], v[94:97], off nt
	v_cvt_pk_bf16_f32 v122, v122, v123
	v_cvt_pk_bf16_f32 v123, v124, v125
	ds_write_b128 v200, v[86:89]
	ds_write_b128 v200, v[82:85] offset:64
	ds_read_b128 v[82:85], v201
	ds_read_b128 v[86:89], v201 offset:1152
	v_lshl_add_u64 v[124:125], s[20:21], 0, v[186:187]
	v_lshl_add_u64 v[134:135], s[20:21], 0, v[188:189]
	s_waitcnt lgkmcnt(1)
	v_pk_fma_f32 v[82:83], v[168:169], v[82:83], v[118:119]
	v_pk_fma_f32 v[84:85], v[166:167], v[84:85], v[120:121]
	v_pk_mul_f32 v[120:121], v[172:173], v[82:83]
	global_store_dwordx4 v[124:125], v[82:85], off nt
	v_pk_mul_f32 v[118:119], v[170:171], v[84:85]
	v_cvt_pk_bf16_f32 v120, v120, v121
	s_waitcnt vmcnt(13) lgkmcnt(0)
	v_pk_fma_f32 v[86:87], v[168:169], v[86:87], v[114:115]
	v_cvt_pk_bf16_f32 v121, v118, v119
	ds_bpermute_b32 v114, v203, v120
	ds_bpermute_b32 v115, v203, v121
	v_pk_fma_f32 v[88:89], v[166:167], v[88:89], v[116:117]
	v_pk_mul_f32 v[116:117], v[172:173], v[86:87]
	v_pk_mul_f32 v[118:119], v[170:171], v[88:89]
	global_store_dwordx4 v[134:135], v[86:89], off nt
	v_cvt_pk_bf16_f32 v116, v116, v117
	v_cvt_pk_bf16_f32 v117, v118, v119
	v_lshlrev_b32_e32 v118, 1, v128
	s_waitcnt lgkmcnt(0)
	v_add_u32_e32 v250, 0xfffff040, v118
	v_cndmask_b32_e64 v250, v118, v250, s[40:41]
	v_cndmask_b32_e64 v248, v126, v114, s[40:41]
	v_cndmask_b32_e64 v249, v127, v115, s[40:41]
	global_store_dwordx2 v250, v[248:249], s[18:19]
	v_cndmask_b32_e64 v246, v114, v126, s[40:41]
	v_cndmask_b32_e64 v247, v115, v127, s[40:41]
	s_waitcnt lgkmcnt(1)
	v_add_u32_e32 v114, 0x1040, v118
	v_cndmask_b32_e64 v114, v118, v114, s[38:39]
	global_store_dwordx2 v114, v[246:247], s[18:19]
	ds_bpermute_b32 v114, v203, v116
	s_waitcnt lgkmcnt(1)
	ds_bpermute_b32 v115, v203, v117
	v_add_u32_e32 v117, 0x14000, v202
	v_lshlrev_b32_e32 v116, 1, v117
	s_waitcnt lgkmcnt(0)
	v_add_u32_e32 v250, 0xfffff040, v116
	v_cndmask_b32_e64 v250, v116, v250, s[40:41]
	v_cndmask_b32_e64 v248, v122, v114, s[40:41]
	v_cndmask_b32_e64 v249, v123, v115, s[40:41]
	global_store_dwordx2 v250, v[248:249], s[18:19]
	v_cndmask_b32_e64 v246, v114, v122, s[40:41]
	v_cndmask_b32_e64 v247, v115, v123, s[40:41]
	v_mul_f32_e32 v83, v83, v83
	v_fmac_f32_e32 v83, v82, v82
	v_mul_f32_e32 v82, v85, v85
	v_mul_f32_e32 v93, v93, v93
	v_fmac_f32_e32 v82, v84, v84
	v_mul_f32_e32 v91, v91, v91
	v_fmac_f32_e32 v93, v92, v92
	v_mul_f32_e32 v92, v95, v95
	v_mul_f32_e32 v95, v97, v97
	v_add_f32_e32 v82, v83, v82
	v_mul_f32_e32 v83, v87, v87
	v_mul_f32_e32 v84, v89, v89
	v_fmac_f32_e32 v95, v96, v96
	v_fmac_f32_e32 v83, v86, v86
	v_fmac_f32_e32 v84, v88, v88
	v_fmac_f32_e32 v91, v90, v90
	v_fmac_f32_e32 v92, v94, v94
	v_add_f32_e32 v83, v83, v84
	v_add_f32_e32 v84, v91, v93
	v_add_f32_e32 v85, v92, v95
	v_add_f32_e32 v82, v84, v82
	v_add_f32_e32 v83, v85, v83
	s_nop 1
	v_mov_b32_dpp v84, v82 quad_perm:[1,0,3,2] row_mask:0xf bank_mask:0xf
	s_nop 1
	v_mov_b32_dpp v85, v83 quad_perm:[1,0,3,2] row_mask:0xf bank_mask:0xf
	s_waitcnt lgkmcnt(1)
	v_add_f32_e32 v82, v82, v84
	s_waitcnt lgkmcnt(0)
	v_add_f32_e32 v85, v83, v85
	s_nop 1
	v_mov_b32_dpp v84, v82 quad_perm:[2,3,0,1] row_mask:0xf bank_mask:0xf
	s_nop 1
	v_mov_b32_dpp v86, v85 quad_perm:[2,3,0,1] row_mask:0xf bank_mask:0xf
	s_waitcnt lgkmcnt(1)
	v_add_f32_e32 v82, v82, v84
	s_waitcnt lgkmcnt(0)
	v_add_f32_e32 v84, v85, v86
	s_nop 1
	v_mov_b32_dpp v83, v82 row_half_mirror row_mask:0xf bank_mask:0xf
	s_nop 1
	v_mov_b32_dpp v85, v84 row_half_mirror row_mask:0xf bank_mask:0xf
	v_add_u32_e32 v86, 0x1040, v116
	v_cndmask_b32_e64 v86, v116, v86, s[38:39]
	global_store_dwordx2 v86, v[246:247], s[18:19]
	s_and_saveexec_b64 s[22:23], s[42:43]
	s_cbranch_execz .LBB0_1959
; #define LAS __attribute__((address_space(3)))
; __device__ __forceinline__ unsigned cvt_pk_bf16(float lo, float hi) { unsigned r; asm volatile("v_cvt_pk_bf16_f32 %0, %1, %2" : "=v"(r) : "v"(lo), "v"(hi)); return r; }
;     __device__ __forceinline__ void operator()(const f32x4 (&acc)[2][2][4][2], const Unit& u, int wr, int wc, int fr, int fq) const {
;     ...
;             if (g + 1 < 8) ERN_LOADX(g + 1);
;             float sq0 = 0.f, sq1 = 0.f; u32x2 hw[2][2];
; #pragma unroll
;             for (int bj = 0; bj < 2; ++bj) {
;                 *(LAS f32x4*)(st + wr_off) = acc[ai][bj][m][0]; *(LAS f32x4*)(st + wr_off + 64) = acc[ai][bj][m][1];
;                 const f32x4 a0 = *(const LAS f32x4*)(st + rd_off), a1 = *(const LAS f32x4*)(st + rd_off + 8 * 144);
;                 { const f32x4 xv = xb[g & 1][bj][0] + gv[bj] * a0; __builtin_nontemporal_store(xv, (f32x4*)((char*)xo + 4u * ERN_EOFF(g, bj, 0)));
;                   sq0 += (xv.x * xv.x + xv.y * xv.y) + (xv.z * xv.z + xv.w * xv.w);
;                   const f32x4 hv = xv * gsn[bj]; hw[bj][0].x = cvt_pk_bf16(hv.x, hv.y); hw[bj][0].y = cvt_pk_bf16(hv.z, hv.w); }
;                 { const f32x4 xv = xb[g & 1][bj][1] + gv[bj] * a1; __builtin_nontemporal_store(xv, (f32x4*)((char*)xo + 4u * ERN_EOFF(g, bj, 1)));
;                   sq1 += (xv.x * xv.x + xv.y * xv.y) + (xv.z * xv.z + xv.w * xv.w);
;                   const f32x4 hv = xv * gsn[bj]; hw[bj][1].x = cvt_pk_bf16(hv.x, hv.y); hw[bj][1].y = cvt_pk_bf16(hv.z, hv.w); }
;             }
;             if (!NOH && !PLAIN) {
; #pragma unroll
;                 for (int rh = 0; rh < 2; ++rh) { u32x2 rv; rv.x = __shfl_xor(hw[1][rh].x, 8); rv.y = __shfl_xor(hw[1][rh].y, 8);
;                     const unsigned e0 = ERN_EOFF(g, 0, rh);
;                     const unsigned ee = odd ? (e0 - DM + 32) : e0, eo2 = odd ? e0 : (e0 + DM + 32);
;                     *(u32x2*)((char*)ho + 2u * ee) = odd ? rv : hw[0][rh];
;                     *(u32x2*)((char*)ho + 2u * eo2) = odd ? hw[0][rh] : rv; }
;             }
;             if (!PLAIN) { sq0 += __shfl_xor(sq0, 1); sq0 += __shfl_xor(sq0, 2); sq0 += __shfl_xor(sq0, 4);
;             sq1 += __shfl_xor(sq1, 1); sq1 += __shfl_xor(sq1, 2); sq1 += __shfl_xor(sq1, 4); }
;             if (!PLAIN && pc == 0) { sst[g * 16 + rr] = sq0; sst[g * 16 + 8 + rr] = sq1; }
	s_waitcnt lgkmcnt(1)
	v_add_f32_e32 v82, v82, v83
	s_waitcnt lgkmcnt(0)
	v_add_f32_e32 v83, v84, v85
	ds_write2_b32 v194, v82, v83 offset0:32 offset1:40
.LBB0_1959:
	s_or_b64 exec, exec, s[22:23]
	v_lshl_add_u64 v[116:117], s[20:21], 0, v[154:155]
	v_add_u32_e32 v82, 0x100000, v205
	s_waitcnt lgkmcnt(1)
	v_add_u32_e32 v83, 0x110000, v205
	v_add_u32_e32 v154, 0x100080, v205
	global_load_dwordx4 v[94:97], v82, s[20:21]
	global_load_dwordx4 v[90:93], v83, s[20:21]
	v_add_u32_e32 v114, 0x110080, v205
	global_load_dwordx4 v[86:89], v154, s[20:21]
	s_waitcnt lgkmcnt(0)
	global_load_dwordx4 v[82:85], v114, s[20:21]
	ds_write_b128 v200, v[78:81]
	ds_write_b128 v200, v[74:77] offset:64
	ds_read_b128 v[74:77], v201
	ds_read_b128 v[78:81], v201 offset:1152
	v_mov_b32_e32 v131, v155
	v_mov_b32_e32 v133, v155
	s_waitcnt vmcnt(11) lgkmcnt(1)
	v_pk_fma_f32 v[76:77], v[176:177], v[76:77], v[112:113]
	v_add_u32_e32 v112, 0x18000, v202
	v_pk_fma_f32 v[74:75], v[180:181], v[74:75], v[110:111]
	v_lshlrev_b32_e32 v110, 2, v112
	s_waitcnt lgkmcnt(0)
	v_pk_fma_f32 v[78:79], v[180:181], v[78:79], v[106:107]
	global_store_dwordx4 v110, v[74:77], s[20:21] nt
	v_pk_mul_f32 v[110:111], v[178:179], v[74:75]
	v_pk_fma_f32 v[80:81], v[176:177], v[80:81], v[108:109]
	v_pk_mul_f32 v[106:107], v[178:179], v[78:79]
	v_pk_mul_f32 v[118:119], v[174:175], v[76:77]
	v_cvt_pk_bf16_f32 v110, v110, v111
	v_pk_mul_f32 v[108:109], v[174:175], v[80:81]
	v_cvt_pk_bf16_f32 v111, v118, v119
	global_store_dwordx4 v[116:117], v[78:81], off nt
	v_cvt_pk_bf16_f32 v106, v106, v107
	v_cvt_pk_bf16_f32 v107, v108, v109
	ds_write_b128 v200, v[70:73]
	ds_write_b128 v200, v[66:69] offset:64
	ds_read_b128 v[66:69], v201
	ds_read_b128 v[70:73], v201 offset:1152
	v_lshl_add_u64 v[108:109], s[20:21], 0, v[130:131]
	v_lshl_add_u64 v[116:117], s[20:21], 0, v[132:133]
	s_waitcnt lgkmcnt(1)
	v_pk_fma_f32 v[66:67], v[168:169], v[66:67], v[102:103]
	v_pk_fma_f32 v[68:69], v[166:167], v[68:69], v[104:105]
	v_pk_mul_f32 v[104:105], v[172:173], v[66:67]
	global_store_dwordx4 v[108:109], v[66:69], off nt
	v_pk_mul_f32 v[102:103], v[170:171], v[68:69]
	v_cvt_pk_bf16_f32 v104, v104, v105
	s_waitcnt vmcnt(13) lgkmcnt(0)
	v_pk_fma_f32 v[70:71], v[168:169], v[70:71], v[98:99]
	v_cvt_pk_bf16_f32 v105, v102, v103
	ds_bpermute_b32 v98, v203, v104
	ds_bpermute_b32 v99, v203, v105
	v_pk_fma_f32 v[72:73], v[166:167], v[72:73], v[100:101]
	v_pk_mul_f32 v[100:101], v[172:173], v[70:71]
	v_pk_mul_f32 v[102:103], v[170:171], v[72:73]
	global_store_dwordx4 v[116:117], v[70:73], off nt
	v_cvt_pk_bf16_f32 v100, v100, v101
	v_cvt_pk_bf16_f32 v101, v102, v103
	v_lshlrev_b32_e32 v102, 1, v112
	s_waitcnt lgkmcnt(0)
	v_add_u32_e32 v250, 0xfffff040, v102
	v_cndmask_b32_e64 v250, v102, v250, s[40:41]
	v_cndmask_b32_e64 v248, v110, v98, s[40:41]
	v_cndmask_b32_e64 v249, v111, v99, s[40:41]
	global_store_dwordx2 v250, v[248:249], s[18:19]
	v_cndmask_b32_e64 v246, v98, v110, s[40:41]
	v_cndmask_b32_e64 v247, v99, v111, s[40:41]
	s_waitcnt lgkmcnt(1)
	v_add_u32_e32 v98, 0x1040, v102
	v_cndmask_b32_e64 v98, v102, v98, s[38:39]
	global_store_dwordx2 v98, v[246:247], s[18:19]
	ds_bpermute_b32 v98, v203, v100
	s_waitcnt lgkmcnt(1)
	ds_bpermute_b32 v99, v203, v101
	v_add_u32_e32 v101, 0x1c000, v202
	v_lshlrev_b32_e32 v100, 1, v101
	s_waitcnt lgkmcnt(0)
	v_add_u32_e32 v250, 0xfffff040, v100
	v_cndmask_b32_e64 v250, v100, v250, s[40:41]
	v_cndmask_b32_e64 v248, v106, v98, s[40:41]
	v_cndmask_b32_e64 v249, v107, v99, s[40:41]
	global_store_dwordx2 v250, v[248:249], s[18:19]
	v_cndmask_b32_e64 v246, v98, v106, s[40:41]
	v_cndmask_b32_e64 v247, v99, v107, s[40:41]
	v_mul_f32_e32 v67, v67, v67
	v_fmac_f32_e32 v67, v66, v66
	v_mul_f32_e32 v66, v69, v69
	v_mul_f32_e32 v77, v77, v77
	v_fmac_f32_e32 v66, v68, v68
	v_mul_f32_e32 v75, v75, v75
	v_fmac_f32_e32 v77, v76, v76
	v_mul_f32_e32 v76, v79, v79
	v_mul_f32_e32 v79, v81, v81
	v_add_f32_e32 v66, v67, v66
	v_mul_f32_e32 v67, v71, v71
	v_mul_f32_e32 v68, v73, v73
	v_fmac_f32_e32 v79, v80, v80
	v_fmac_f32_e32 v67, v70, v70
	v_fmac_f32_e32 v68, v72, v72
	v_fmac_f32_e32 v75, v74, v74
	v_fmac_f32_e32 v76, v78, v78
	v_add_f32_e32 v67, v67, v68
	v_add_f32_e32 v68, v75, v77
	v_add_f32_e32 v69, v76, v79
	v_add_f32_e32 v66, v68, v66
	v_add_f32_e32 v67, v69, v67
	s_nop 1
	v_mov_b32_dpp v68, v66 quad_perm:[1,0,3,2] row_mask:0xf bank_mask:0xf
	s_nop 1
	v_mov_b32_dpp v69, v67 quad_perm:[1,0,3,2] row_mask:0xf bank_mask:0xf
	s_waitcnt lgkmcnt(1)
	v_add_f32_e32 v66, v66, v68
	s_waitcnt lgkmcnt(0)
	v_add_f32_e32 v69, v67, v69
	s_nop 1
	v_mov_b32_dpp v68, v66 quad_perm:[2,3,0,1] row_mask:0xf bank_mask:0xf
	s_nop 1
	v_mov_b32_dpp v70, v69 quad_perm:[2,3,0,1] row_mask:0xf bank_mask:0xf
	s_waitcnt lgkmcnt(1)
	v_add_f32_e32 v66, v66, v68
	s_waitcnt lgkmcnt(0)
	v_add_f32_e32 v68, v69, v70
	s_nop 1
	v_mov_b32_dpp v67, v66 row_half_mirror row_mask:0xf bank_mask:0xf
	s_nop 1
	v_mov_b32_dpp v69, v68 row_half_mirror row_mask:0xf bank_mask:0xf
	v_add_u32_e32 v70, 0x1040, v100
	v_cndmask_b32_e64 v70, v100, v70, s[38:39]
	global_store_dwordx2 v70, v[246:247], s[18:19]
	s_and_saveexec_b64 s[22:23], s[42:43]
	s_cbranch_execz .LBB0_1969
	s_waitcnt lgkmcnt(1)
	v_add_f32_e32 v66, v66, v67
	s_waitcnt lgkmcnt(0)
	v_add_f32_e32 v67, v68, v69
	ds_write2_b32 v194, v66, v67 offset0:48 offset1:56
; #define LAS __attribute__((address_space(3)))
; __device__ __forceinline__ unsigned cvt_pk_bf16(float lo, float hi) { unsigned r; asm volatile("v_cvt_pk_bf16_f32 %0, %1, %2" : "=v"(r) : "v"(lo), "v"(hi)); return r; }
;     __device__ __forceinline__ void operator()(const f32x4 (&acc)[2][2][4][2], const Unit& u, int wr, int wc, int fr, int fq) const {
;     ...
;             if (g + 1 < 8) ERN_LOADX(g + 1);
;             float sq0 = 0.f, sq1 = 0.f; u32x2 hw[2][2];
; #pragma unroll
;             for (int bj = 0; bj < 2; ++bj) {
;                 *(LAS f32x4*)(st + wr_off) = acc[ai][bj][m][0]; *(LAS f32x4*)(st + wr_off + 64) = acc[ai][bj][m][1];
;                 const f32x4 a0 = *(const LAS f32x4*)(st + rd_off), a1 = *(const LAS f32x4*)(st + rd_off + 8 * 144);
;                 { const f32x4 xv = xb[g & 1][bj][0] + gv[bj] * a0; __builtin_nontemporal_store(xv, (f32x4*)((char*)xo + 4u * ERN_EOFF(g, bj, 0)));
;                   sq0 += (xv.x * xv.x + xv.y * xv.y) + (xv.z * xv.z + xv.w * xv.w);
;                   const f32x4 hv = xv * gsn[bj]; hw[bj][0].x = cvt_pk_bf16(hv.x, hv.y); hw[bj][0].y = cvt_pk_bf16(hv.z, hv.w); }
;                 { const f32x4 xv = xb[g & 1][bj][1] + gv[bj] * a1; __builtin_nontemporal_store(xv, (f32x4*)((char*)xo + 4u * ERN_EOFF(g, bj, 1)));
;                   sq1 += (xv.x * xv.x + xv.y * xv.y) + (xv.z * xv.z + xv.w * xv.w);
;                   const f32x4 hv = xv * gsn[bj]; hw[bj][1].x = cvt_pk_bf16(hv.x, hv.y); hw[bj][1].y = cvt_pk_bf16(hv.z, hv.w); }
;             }
;             if (!NOH && !PLAIN) {
; #pragma unroll
;                 for (int rh = 0; rh < 2; ++rh) { u32x2 rv; rv.x = __shfl_xor(hw[1][rh].x, 8); rv.y = __shfl_xor(hw[1][rh].y, 8);
;                     const unsigned e0 = ERN_EOFF(g, 0, rh);
;                     const unsigned ee = odd ? (e0 - DM + 32) : e0, eo2 = odd ? e0 : (e0 + DM + 32);
;                     *(u32x2*)((char*)ho + 2u * ee) = odd ? rv : hw[0][rh];
;                     *(u32x2*)((char*)ho + 2u * eo2) = odd ? hw[0][rh] : rv; }
;             }
;             if (!PLAIN) { sq0 += __shfl_xor(sq0, 1); sq0 += __shfl_xor(sq0, 2); sq0 += __shfl_xor(sq0, 4);
;             sq1 += __shfl_xor(sq1, 1); sq1 += __shfl_xor(sq1, 2); sq1 += __shfl_xor(sq1, 4); }
;             if (!PLAIN && pc == 0) { sst[g * 16 + rr] = sq0; sst[g * 16 + 8 + rr] = sq1; }
.LBB0_1969:
	s_or_b64 exec, exec, s[22:23]
	v_lshl_add_u64 v[104:105], s[20:21], 0, v[154:155]
	v_add_u32_e32 v154, 0x120000, v205
	v_add_u32_e32 v100, 0x120080, v205
	v_add_u32_e32 v102, 0x130000, v205
	global_load_dwordx4 v[78:81], v154, s[20:21]
	global_load_dwordx4 v[74:77], v102, s[20:21]
	v_add_u32_e32 v98, 0x130080, v205
	global_load_dwordx4 v[70:73], v100, s[20:21]
	s_waitcnt lgkmcnt(0)
	global_load_dwordx4 v[66:69], v98, s[20:21]
	ds_write_b128 v200, v[62:65]
	ds_write_b128 v200, v[58:61] offset:64
	ds_read_b128 v[58:61], v201
	ds_read_b128 v[62:65], v201 offset:1152
	v_mov_b32_e32 v115, v155
	s_waitcnt vmcnt(13) lgkmcnt(1)
	v_pk_fma_f32 v[60:61], v[176:177], v[60:61], v[96:97]
	v_add_u32_e32 v96, 0x40000, v202
	v_pk_fma_f32 v[58:59], v[180:181], v[58:59], v[94:95]
	v_lshlrev_b32_e32 v94, 2, v96
	s_waitcnt vmcnt(12) lgkmcnt(0)
	v_pk_fma_f32 v[64:65], v[176:177], v[64:65], v[92:93]
	v_add_u32_e32 v92, 0x44000, v202
	global_store_dwordx4 v94, v[58:61], s[20:21] nt
	v_pk_mul_f32 v[94:95], v[178:179], v[58:59]
	v_pk_fma_f32 v[62:63], v[180:181], v[62:63], v[90:91]
	v_lshlrev_b32_e32 v90, 2, v92
	v_pk_mul_f32 v[106:107], v[174:175], v[60:61]
	v_cvt_pk_bf16_f32 v94, v94, v95
	s_nop 0
	v_cvt_pk_bf16_f32 v95, v106, v107
	global_store_dwordx4 v90, v[62:65], s[20:21] nt
	v_pk_mul_f32 v[90:91], v[178:179], v[62:63]
	v_pk_mul_f32 v[106:107], v[174:175], v[64:65]
	v_cvt_pk_bf16_f32 v90, v90, v91
	s_nop 0
	v_cvt_pk_bf16_f32 v91, v106, v107
	ds_write_b128 v200, v[54:57]
	ds_write_b128 v200, v[50:53] offset:64
	ds_read_b128 v[50:53], v201
	ds_read_b128 v[54:57], v201 offset:1152
	v_lshl_add_u64 v[106:107], s[20:21], 0, v[114:115]
	s_waitcnt vmcnt(13) lgkmcnt(1)
	v_pk_fma_f32 v[50:51], v[168:169], v[50:51], v[86:87]
	v_pk_fma_f32 v[52:53], v[166:167], v[52:53], v[88:89]
	v_pk_mul_f32 v[88:89], v[172:173], v[50:51]
	global_store_dwordx4 v[104:105], v[50:53], off nt
	v_pk_mul_f32 v[86:87], v[170:171], v[52:53]
	v_cvt_pk_bf16_f32 v88, v88, v89
	s_waitcnt vmcnt(13) lgkmcnt(0)
	v_pk_fma_f32 v[54:55], v[168:169], v[54:55], v[82:83]
	v_cvt_pk_bf16_f32 v89, v86, v87
	ds_bpermute_b32 v82, v203, v88
	ds_bpermute_b32 v83, v203, v89
	v_pk_fma_f32 v[56:57], v[166:167], v[56:57], v[84:85]
	v_pk_mul_f32 v[84:85], v[172:173], v[54:55]
	v_pk_mul_f32 v[86:87], v[170:171], v[56:57]
	global_store_dwordx4 v[106:107], v[54:57], off nt
	v_cvt_pk_bf16_f32 v84, v84, v85
	v_cvt_pk_bf16_f32 v85, v86, v87
	v_lshlrev_b32_e32 v86, 1, v96
	s_waitcnt lgkmcnt(0)
	v_add_u32_e32 v250, 0xfffff040, v86
	v_cndmask_b32_e64 v250, v86, v250, s[40:41]
	v_cndmask_b32_e64 v248, v94, v82, s[40:41]
	v_cndmask_b32_e64 v249, v95, v83, s[40:41]
	global_store_dwordx2 v250, v[248:249], s[18:19]
	v_cndmask_b32_e64 v246, v82, v94, s[40:41]
	v_cndmask_b32_e64 v247, v83, v95, s[40:41]
	s_waitcnt lgkmcnt(1)
	v_add_u32_e32 v82, 0x1040, v86
	v_cndmask_b32_e64 v82, v86, v82, s[38:39]
	global_store_dwordx2 v82, v[246:247], s[18:19]
	ds_bpermute_b32 v82, v203, v84
	s_waitcnt lgkmcnt(1)
	ds_bpermute_b32 v83, v203, v85
	v_lshlrev_b32_e32 v84, 1, v92
	s_waitcnt lgkmcnt(0)
	v_add_u32_e32 v250, 0xfffff040, v84
	v_cndmask_b32_e64 v250, v84, v250, s[40:41]
	v_cndmask_b32_e64 v248, v90, v82, s[40:41]
	v_cndmask_b32_e64 v249, v91, v83, s[40:41]
	global_store_dwordx2 v250, v[248:249], s[18:19]
	v_cndmask_b32_e64 v246, v82, v90, s[40:41]
	v_cndmask_b32_e64 v247, v83, v91, s[40:41]
	v_mul_f32_e32 v51, v51, v51
	v_fmac_f32_e32 v51, v50, v50
	v_mul_f32_e32 v50, v53, v53
	v_mul_f32_e32 v61, v61, v61
	v_fmac_f32_e32 v50, v52, v52
	v_mul_f32_e32 v59, v59, v59
	v_fmac_f32_e32 v61, v60, v60
	v_mul_f32_e32 v60, v63, v63
	v_mul_f32_e32 v63, v65, v65
	v_add_f32_e32 v50, v51, v50
	v_mul_f32_e32 v51, v55, v55
	v_mul_f32_e32 v52, v57, v57
	v_fmac_f32_e32 v63, v64, v64
	v_fmac_f32_e32 v51, v54, v54
	v_fmac_f32_e32 v52, v56, v56
	v_fmac_f32_e32 v59, v58, v58
	v_fmac_f32_e32 v60, v62, v62
	v_add_f32_e32 v51, v51, v52
	v_add_f32_e32 v52, v59, v61
	v_add_f32_e32 v53, v60, v63
	v_add_f32_e32 v50, v52, v50
	v_add_f32_e32 v51, v53, v51
	s_nop 1
	v_mov_b32_dpp v52, v50 quad_perm:[1,0,3,2] row_mask:0xf bank_mask:0xf
	s_nop 1
	v_mov_b32_dpp v53, v51 quad_perm:[1,0,3,2] row_mask:0xf bank_mask:0xf
	s_waitcnt lgkmcnt(1)
	v_add_f32_e32 v50, v50, v52
	s_waitcnt lgkmcnt(0)
	v_add_f32_e32 v53, v51, v53
	s_nop 1
	v_mov_b32_dpp v52, v50 quad_perm:[2,3,0,1] row_mask:0xf bank_mask:0xf
	s_nop 1
	v_mov_b32_dpp v54, v53 quad_perm:[2,3,0,1] row_mask:0xf bank_mask:0xf
	s_waitcnt lgkmcnt(1)
	v_add_f32_e32 v50, v50, v52
	s_waitcnt lgkmcnt(0)
	v_add_f32_e32 v52, v53, v54
	s_nop 1
	v_mov_b32_dpp v51, v50 row_half_mirror row_mask:0xf bank_mask:0xf
	s_nop 1
	v_mov_b32_dpp v53, v52 row_half_mirror row_mask:0xf bank_mask:0xf
	v_add_u32_e32 v54, 0x1040, v84
	v_cndmask_b32_e64 v54, v84, v54, s[38:39]
	global_store_dwordx2 v54, v[246:247], s[18:19]
	s_and_saveexec_b64 s[22:23], s[42:43]
	s_cbranch_execz .LBB0_1979
	s_waitcnt lgkmcnt(1)
	v_add_f32_e32 v50, v50, v51
	s_waitcnt lgkmcnt(0)
	v_add_f32_e32 v51, v52, v53
	ds_write2_b32 v194, v50, v51 offset0:64 offset1:72
; #define LAS __attribute__((address_space(3)))
; __device__ __forceinline__ unsigned cvt_pk_bf16(float lo, float hi) { unsigned r; asm volatile("v_cvt_pk_bf16_f32 %0, %1, %2" : "=v"(r) : "v"(lo), "v"(hi)); return r; }
;     __device__ __forceinline__ void operator()(const f32x4 (&acc)[2][2][4][2], const Unit& u, int wr, int wc, int fr, int fq) const {
;     ...
;             if (g + 1 < 8) ERN_LOADX(g + 1);
;             float sq0 = 0.f, sq1 = 0.f; u32x2 hw[2][2];
; #pragma unroll
;             for (int bj = 0; bj < 2; ++bj) {
;                 *(LAS f32x4*)(st + wr_off) = acc[ai][bj][m][0]; *(LAS f32x4*)(st + wr_off + 64) = acc[ai][bj][m][1];
;                 const f32x4 a0 = *(const LAS f32x4*)(st + rd_off), a1 = *(const LAS f32x4*)(st + rd_off + 8 * 144);
;                 { const f32x4 xv = xb[g & 1][bj][0] + gv[bj] * a0; __builtin_nontemporal_store(xv, (f32x4*)((char*)xo + 4u * ERN_EOFF(g, bj, 0)));
;                   sq0 += (xv.x * xv.x + xv.y * xv.y) + (xv.z * xv.z + xv.w * xv.w);
;                   const f32x4 hv = xv * gsn[bj]; hw[bj][0].x = cvt_pk_bf16(hv.x, hv.y); hw[bj][0].y = cvt_pk_bf16(hv.z, hv.w); }
;                 { const f32x4 xv = xb[g & 1][bj][1] + gv[bj] * a1; __builtin_nontemporal_store(xv, (f32x4*)((char*)xo + 4u * ERN_EOFF(g, bj, 1)));
;                   sq1 += (xv.x * xv.x + xv.y * xv.y) + (xv.z * xv.z + xv.w * xv.w);
;                   const f32x4 hv = xv * gsn[bj]; hw[bj][1].x = cvt_pk_bf16(hv.x, hv.y); hw[bj][1].y = cvt_pk_bf16(hv.z, hv.w); }
;             }
;             if (!NOH && !PLAIN) {
; #pragma unroll
;                 for (int rh = 0; rh < 2; ++rh) { u32x2 rv; rv.x = __shfl_xor(hw[1][rh].x, 8); rv.y = __shfl_xor(hw[1][rh].y, 8);
;                     const unsigned e0 = ERN_EOFF(g, 0, rh);
;                     const unsigned ee = odd ? (e0 - DM + 32) : e0, eo2 = odd ? e0 : (e0 + DM + 32);
;                     *(u32x2*)((char*)ho + 2u * ee) = odd ? rv : hw[0][rh];
;                     *(u32x2*)((char*)ho + 2u * eo2) = odd ? hw[0][rh] : rv; }
;             }
;             if (!PLAIN) { sq0 += __shfl_xor(sq0, 1); sq0 += __shfl_xor(sq0, 2); sq0 += __shfl_xor(sq0, 4);
;             sq1 += __shfl_xor(sq1, 1); sq1 += __shfl_xor(sq1, 2); sq1 += __shfl_xor(sq1, 4); }
;             if (!PLAIN && pc == 0) { sst[g * 16 + rr] = sq0; sst[g * 16 + 8 + rr] = sq1; }
.LBB0_1979:
	s_or_b64 exec, exec, s[22:23]
	v_lshl_add_u64 v[88:89], s[20:21], 0, v[154:155]
	v_add_u32_e32 v154, 0x140000, v205
	v_add_u32_e32 v84, 0x140080, v205
	v_add_u32_e32 v86, 0x150000, v205
	global_load_dwordx4 v[62:65], v154, s[20:21]
	global_load_dwordx4 v[58:61], v86, s[20:21]
	v_add_u32_e32 v82, 0x150080, v205
	global_load_dwordx4 v[54:57], v84, s[20:21]
	s_waitcnt lgkmcnt(0)
	global_load_dwordx4 v[50:53], v82, s[20:21]
	ds_write_b128 v200, v[46:49]
	ds_write_b128 v200, v[42:45] offset:64
	ds_read_b128 v[42:45], v201
	ds_read_b128 v[46:49], v201 offset:1152
	v_mov_b32_e32 v103, v155
	v_lshl_add_u64 v[90:91], s[20:21], 0, v[102:103]
	v_mov_b32_e32 v101, v155
	s_waitcnt vmcnt(13) lgkmcnt(1)
	v_pk_fma_f32 v[42:43], v[180:181], v[42:43], v[78:79]
	s_waitcnt vmcnt(12) lgkmcnt(0)
	v_pk_fma_f32 v[46:47], v[180:181], v[46:47], v[74:75]
	v_pk_fma_f32 v[44:45], v[176:177], v[44:45], v[80:81]
	v_pk_mul_f32 v[78:79], v[178:179], v[42:43]
	v_pk_fma_f32 v[48:49], v[176:177], v[48:49], v[76:77]
	v_pk_mul_f32 v[74:75], v[178:179], v[46:47]
	global_store_dwordx4 v[88:89], v[42:45], off nt
	v_pk_mul_f32 v[80:81], v[174:175], v[44:45]
	v_cvt_pk_bf16_f32 v78, v78, v79
	v_pk_mul_f32 v[76:77], v[174:175], v[48:49]
	v_cvt_pk_bf16_f32 v79, v80, v81
	global_store_dwordx4 v[90:91], v[46:49], off nt
	v_cvt_pk_bf16_f32 v74, v74, v75
	v_cvt_pk_bf16_f32 v75, v76, v77
	ds_write_b128 v200, v[38:41]
	ds_write_b128 v200, v[34:37] offset:64
	ds_read_b128 v[34:37], v201
	ds_read_b128 v[38:41], v201 offset:1152
	v_lshl_add_u64 v[76:77], s[20:21], 0, v[100:101]
	v_mov_b32_e32 v99, v155
	v_lshl_add_u64 v[80:81], s[20:21], 0, v[98:99]
	s_waitcnt vmcnt(13) lgkmcnt(1)
	v_pk_fma_f32 v[34:35], v[168:169], v[34:35], v[70:71]
	v_pk_fma_f32 v[36:37], v[166:167], v[36:37], v[72:73]
	v_pk_mul_f32 v[72:73], v[172:173], v[34:35]
	global_store_dwordx4 v[76:77], v[34:37], off nt
	v_pk_mul_f32 v[70:71], v[170:171], v[36:37]
	v_cvt_pk_bf16_f32 v72, v72, v73
	s_waitcnt vmcnt(13) lgkmcnt(0)
	v_pk_fma_f32 v[38:39], v[168:169], v[38:39], v[66:67]
	v_cvt_pk_bf16_f32 v73, v70, v71
	ds_bpermute_b32 v66, v203, v72
	ds_bpermute_b32 v67, v203, v73
	v_pk_fma_f32 v[40:41], v[166:167], v[40:41], v[68:69]
	v_pk_mul_f32 v[68:69], v[172:173], v[38:39]
	v_pk_mul_f32 v[70:71], v[170:171], v[40:41]
	global_store_dwordx4 v[80:81], v[38:41], off nt
	v_cvt_pk_bf16_f32 v68, v68, v69
	v_cvt_pk_bf16_f32 v69, v70, v71
	v_add_u32_e32 v71, 0x48000, v202
	v_lshlrev_b32_e32 v70, 1, v71
	s_waitcnt lgkmcnt(0)
	v_add_u32_e32 v250, 0xfffff040, v70
	v_cndmask_b32_e64 v250, v70, v250, s[40:41]
	v_cndmask_b32_e64 v248, v78, v66, s[40:41]
	v_cndmask_b32_e64 v249, v79, v67, s[40:41]
	global_store_dwordx2 v250, v[248:249], s[18:19]
	v_cndmask_b32_e64 v246, v66, v78, s[40:41]
	v_cndmask_b32_e64 v247, v67, v79, s[40:41]
	s_waitcnt lgkmcnt(1)
	v_add_u32_e32 v66, 0x1040, v70
	v_cndmask_b32_e64 v66, v70, v66, s[38:39]
	global_store_dwordx2 v66, v[246:247], s[18:19]
	ds_bpermute_b32 v66, v203, v68
	s_waitcnt lgkmcnt(1)
	ds_bpermute_b32 v67, v203, v69
	v_add_u32_e32 v69, 0x4c000, v202
	v_lshlrev_b32_e32 v68, 1, v69
	s_waitcnt lgkmcnt(0)
	v_add_u32_e32 v250, 0xfffff040, v68
	v_cndmask_b32_e64 v250, v68, v250, s[40:41]
	v_cndmask_b32_e64 v248, v74, v66, s[40:41]
	v_cndmask_b32_e64 v249, v75, v67, s[40:41]
	global_store_dwordx2 v250, v[248:249], s[18:19]
	v_cndmask_b32_e64 v246, v66, v74, s[40:41]
	v_cndmask_b32_e64 v247, v67, v75, s[40:41]
	v_mul_f32_e32 v35, v35, v35
	v_fmac_f32_e32 v35, v34, v34
	v_mul_f32_e32 v34, v37, v37
	v_mul_f32_e32 v45, v45, v45
	v_fmac_f32_e32 v34, v36, v36
	v_mul_f32_e32 v43, v43, v43
	v_fmac_f32_e32 v45, v44, v44
	v_mul_f32_e32 v44, v47, v47
	v_mul_f32_e32 v47, v49, v49
	v_add_f32_e32 v34, v35, v34
	v_mul_f32_e32 v35, v39, v39
	v_mul_f32_e32 v36, v41, v41
	v_fmac_f32_e32 v47, v48, v48
	v_fmac_f32_e32 v35, v38, v38
	v_fmac_f32_e32 v36, v40, v40
	v_fmac_f32_e32 v43, v42, v42
	v_fmac_f32_e32 v44, v46, v46
	v_add_f32_e32 v35, v35, v36
	v_add_f32_e32 v36, v43, v45
	v_add_f32_e32 v37, v44, v47
	v_add_f32_e32 v34, v36, v34
	v_add_f32_e32 v35, v37, v35
	s_nop 1
	v_mov_b32_dpp v36, v34 quad_perm:[1,0,3,2] row_mask:0xf bank_mask:0xf
	s_nop 1
	v_mov_b32_dpp v37, v35 quad_perm:[1,0,3,2] row_mask:0xf bank_mask:0xf
	s_waitcnt lgkmcnt(1)
	v_add_f32_e32 v34, v34, v36
	s_waitcnt lgkmcnt(0)
	v_add_f32_e32 v37, v35, v37
	s_nop 1
	v_mov_b32_dpp v36, v34 quad_perm:[2,3,0,1] row_mask:0xf bank_mask:0xf
	s_nop 1
	v_mov_b32_dpp v38, v37 quad_perm:[2,3,0,1] row_mask:0xf bank_mask:0xf
	s_waitcnt lgkmcnt(1)
	v_add_f32_e32 v34, v34, v36
	s_waitcnt lgkmcnt(0)
	v_add_f32_e32 v36, v37, v38
	s_nop 1
	v_mov_b32_dpp v35, v34 row_half_mirror row_mask:0xf bank_mask:0xf
	s_nop 1
	v_mov_b32_dpp v37, v36 row_half_mirror row_mask:0xf bank_mask:0xf
	v_add_u32_e32 v38, 0x1040, v68
	v_cndmask_b32_e64 v38, v68, v38, s[38:39]
	global_store_dwordx2 v38, v[246:247], s[18:19]
	s_and_saveexec_b64 s[22:23], s[42:43]
	s_cbranch_execz .LBB0_1989
	s_waitcnt lgkmcnt(1)
	v_add_f32_e32 v34, v34, v35
	s_waitcnt lgkmcnt(0)
	v_add_f32_e32 v35, v36, v37
	ds_write2_b32 v194, v34, v35 offset0:80 offset1:88
; #define LAS __attribute__((address_space(3)))
; __device__ __forceinline__ unsigned cvt_pk_bf16(float lo, float hi) { unsigned r; asm volatile("v_cvt_pk_bf16_f32 %0, %1, %2" : "=v"(r) : "v"(lo), "v"(hi)); return r; }
;     __device__ __forceinline__ void operator()(const f32x4 (&acc)[2][2][4][2], const Unit& u, int wr, int wc, int fr, int fq) const {
;     ...
;             if (g + 1 < 8) ERN_LOADX(g + 1);
;             float sq0 = 0.f, sq1 = 0.f; u32x2 hw[2][2];
; #pragma unroll
;             for (int bj = 0; bj < 2; ++bj) {
;                 *(LAS f32x4*)(st + wr_off) = acc[ai][bj][m][0]; *(LAS f32x4*)(st + wr_off + 64) = acc[ai][bj][m][1];
;                 const f32x4 a0 = *(const LAS f32x4*)(st + rd_off), a1 = *(const LAS f32x4*)(st + rd_off + 8 * 144);
;                 { const f32x4 xv = xb[g & 1][bj][0] + gv[bj] * a0; __builtin_nontemporal_store(xv, (f32x4*)((char*)xo + 4u * ERN_EOFF(g, bj, 0)));
;                   sq0 += (xv.x * xv.x + xv.y * xv.y) + (xv.z * xv.z + xv.w * xv.w);
;                   const f32x4 hv = xv * gsn[bj]; hw[bj][0].x = cvt_pk_bf16(hv.x, hv.y); hw[bj][0].y = cvt_pk_bf16(hv.z, hv.w); }
;                 { const f32x4 xv = xb[g & 1][bj][1] + gv[bj] * a1; __builtin_nontemporal_store(xv, (f32x4*)((char*)xo + 4u * ERN_EOFF(g, bj, 1)));
;                   sq1 += (xv.x * xv.x + xv.y * xv.y) + (xv.z * xv.z + xv.w * xv.w);
;                   const f32x4 hv = xv * gsn[bj]; hw[bj][1].x = cvt_pk_bf16(hv.x, hv.y); hw[bj][1].y = cvt_pk_bf16(hv.z, hv.w); }
;             }
;             if (!NOH && !PLAIN) {
; #pragma unroll
;                 for (int rh = 0; rh < 2; ++rh) { u32x2 rv; rv.x = __shfl_xor(hw[1][rh].x, 8); rv.y = __shfl_xor(hw[1][rh].y, 8);
;                     const unsigned e0 = ERN_EOFF(g, 0, rh);
;                     const unsigned ee = odd ? (e0 - DM + 32) : e0, eo2 = odd ? e0 : (e0 + DM + 32);
;                     *(u32x2*)((char*)ho + 2u * ee) = odd ? rv : hw[0][rh];
;                     *(u32x2*)((char*)ho + 2u * eo2) = odd ? hw[0][rh] : rv; }
;             }
;             if (!PLAIN) { sq0 += __shfl_xor(sq0, 1); sq0 += __shfl_xor(sq0, 2); sq0 += __shfl_xor(sq0, 4);
;             sq1 += __shfl_xor(sq1, 1); sq1 += __shfl_xor(sq1, 2); sq1 += __shfl_xor(sq1, 4); }
;             if (!PLAIN && pc == 0) { sst[g * 16 + rr] = sq0; sst[g * 16 + 8 + rr] = sq1; }
.LBB0_1989:
	s_or_b64 exec, exec, s[22:23]
	v_lshl_add_u64 v[72:73], s[20:21], 0, v[154:155]
	v_add_u32_e32 v154, 0x160000, v205
	v_add_u32_e32 v68, 0x160080, v205
	v_add_u32_e32 v70, 0x170000, v205
	global_load_dwordx4 v[46:49], v154, s[20:21]
	global_load_dwordx4 v[42:45], v70, s[20:21]
	v_add_u32_e32 v66, 0x170080, v205
	global_load_dwordx4 v[38:41], v68, s[20:21]
	s_waitcnt lgkmcnt(0)
	global_load_dwordx4 v[34:37], v66, s[20:21]
	ds_write_b128 v200, v[30:33]
	ds_write_b128 v200, v[26:29] offset:64
	ds_read_b128 v[26:29], v201
	ds_read_b128 v[30:33], v201 offset:1152
	v_mov_b32_e32 v87, v155
	v_lshl_add_u64 v[74:75], s[20:21], 0, v[86:87]
	v_mov_b32_e32 v85, v155
	s_waitcnt vmcnt(13) lgkmcnt(1)
	v_pk_fma_f32 v[26:27], v[180:181], v[26:27], v[62:63]
	s_waitcnt vmcnt(12) lgkmcnt(0)
	v_pk_fma_f32 v[30:31], v[180:181], v[30:31], v[58:59]
	v_pk_fma_f32 v[28:29], v[176:177], v[28:29], v[64:65]
	v_pk_mul_f32 v[62:63], v[178:179], v[26:27]
	v_pk_fma_f32 v[32:33], v[176:177], v[32:33], v[60:61]
	v_pk_mul_f32 v[58:59], v[178:179], v[30:31]
	global_store_dwordx4 v[72:73], v[26:29], off nt
	v_pk_mul_f32 v[64:65], v[174:175], v[28:29]
	v_cvt_pk_bf16_f32 v62, v62, v63
	v_pk_mul_f32 v[60:61], v[174:175], v[32:33]
	v_cvt_pk_bf16_f32 v63, v64, v65
	global_store_dwordx4 v[74:75], v[30:33], off nt
	v_cvt_pk_bf16_f32 v58, v58, v59
	v_cvt_pk_bf16_f32 v59, v60, v61
	ds_write_b128 v200, v[22:25]
	ds_write_b128 v200, v[18:21] offset:64
	ds_read_b128 v[18:21], v201
	ds_read_b128 v[22:25], v201 offset:1152
	v_lshl_add_u64 v[60:61], s[20:21], 0, v[84:85]
	v_mov_b32_e32 v83, v155
	v_lshl_add_u64 v[64:65], s[20:21], 0, v[82:83]
	s_waitcnt vmcnt(13) lgkmcnt(1)
	v_pk_fma_f32 v[18:19], v[168:169], v[18:19], v[54:55]
	v_pk_fma_f32 v[20:21], v[166:167], v[20:21], v[56:57]
	v_pk_mul_f32 v[56:57], v[172:173], v[18:19]
	global_store_dwordx4 v[60:61], v[18:21], off nt
	v_pk_mul_f32 v[54:55], v[170:171], v[20:21]
	v_cvt_pk_bf16_f32 v56, v56, v57
	s_waitcnt vmcnt(13) lgkmcnt(0)
	v_pk_fma_f32 v[22:23], v[168:169], v[22:23], v[50:51]
	v_cvt_pk_bf16_f32 v57, v54, v55
	ds_bpermute_b32 v50, v203, v56
	ds_bpermute_b32 v51, v203, v57
	v_pk_fma_f32 v[24:25], v[166:167], v[24:25], v[52:53]
	v_pk_mul_f32 v[52:53], v[172:173], v[22:23]
	v_pk_mul_f32 v[54:55], v[170:171], v[24:25]
	global_store_dwordx4 v[64:65], v[22:25], off nt
	v_cvt_pk_bf16_f32 v52, v52, v53
	v_cvt_pk_bf16_f32 v53, v54, v55
	v_add_u32_e32 v55, 0x50000, v202
	v_lshlrev_b32_e32 v54, 1, v55
	s_waitcnt lgkmcnt(0)
	v_add_u32_e32 v250, 0xfffff040, v54
	v_cndmask_b32_e64 v250, v54, v250, s[40:41]
	v_cndmask_b32_e64 v248, v62, v50, s[40:41]
	v_cndmask_b32_e64 v249, v63, v51, s[40:41]
	global_store_dwordx2 v250, v[248:249], s[18:19]
	v_cndmask_b32_e64 v246, v50, v62, s[40:41]
	v_cndmask_b32_e64 v247, v51, v63, s[40:41]
	s_waitcnt lgkmcnt(1)
	v_add_u32_e32 v50, 0x1040, v54
	v_cndmask_b32_e64 v50, v54, v50, s[38:39]
	global_store_dwordx2 v50, v[246:247], s[18:19]
	ds_bpermute_b32 v50, v203, v52
	s_waitcnt lgkmcnt(1)
	ds_bpermute_b32 v51, v203, v53
	v_add_u32_e32 v53, 0x54000, v202
	v_lshlrev_b32_e32 v52, 1, v53
	s_waitcnt lgkmcnt(0)
	v_add_u32_e32 v250, 0xfffff040, v52
	v_cndmask_b32_e64 v250, v52, v250, s[40:41]
	v_cndmask_b32_e64 v248, v58, v50, s[40:41]
	v_cndmask_b32_e64 v249, v59, v51, s[40:41]
	global_store_dwordx2 v250, v[248:249], s[18:19]
	v_cndmask_b32_e64 v246, v50, v58, s[40:41]
	v_cndmask_b32_e64 v247, v51, v59, s[40:41]
	v_mul_f32_e32 v19, v19, v19
	v_fmac_f32_e32 v19, v18, v18
	v_mul_f32_e32 v18, v21, v21
	v_mul_f32_e32 v29, v29, v29
	v_fmac_f32_e32 v18, v20, v20
	v_mul_f32_e32 v27, v27, v27
	v_fmac_f32_e32 v29, v28, v28
	v_mul_f32_e32 v28, v31, v31
	v_mul_f32_e32 v31, v33, v33
	v_add_f32_e32 v18, v19, v18
	v_mul_f32_e32 v19, v23, v23
	v_mul_f32_e32 v20, v25, v25
	v_fmac_f32_e32 v31, v32, v32
	v_fmac_f32_e32 v19, v22, v22
	v_fmac_f32_e32 v20, v24, v24
	v_fmac_f32_e32 v27, v26, v26
	v_fmac_f32_e32 v28, v30, v30
	v_add_f32_e32 v19, v19, v20
	v_add_f32_e32 v20, v27, v29
	v_add_f32_e32 v21, v28, v31
	v_add_f32_e32 v18, v20, v18
	v_add_f32_e32 v19, v21, v19
	s_nop 1
	v_mov_b32_dpp v20, v18 quad_perm:[1,0,3,2] row_mask:0xf bank_mask:0xf
	s_nop 1
	v_mov_b32_dpp v21, v19 quad_perm:[1,0,3,2] row_mask:0xf bank_mask:0xf
	s_waitcnt lgkmcnt(1)
	v_add_f32_e32 v18, v18, v20
	s_waitcnt lgkmcnt(0)
	v_add_f32_e32 v21, v19, v21
	s_nop 1
	v_mov_b32_dpp v20, v18 quad_perm:[2,3,0,1] row_mask:0xf bank_mask:0xf
	s_nop 1
	v_mov_b32_dpp v22, v21 quad_perm:[2,3,0,1] row_mask:0xf bank_mask:0xf
	s_waitcnt lgkmcnt(1)
	v_add_f32_e32 v18, v18, v20
	s_waitcnt lgkmcnt(0)
	v_add_f32_e32 v20, v21, v22
	s_nop 1
	v_mov_b32_dpp v19, v18 row_half_mirror row_mask:0xf bank_mask:0xf
	s_nop 1
	v_mov_b32_dpp v21, v20 row_half_mirror row_mask:0xf bank_mask:0xf
	v_add_u32_e32 v22, 0x1040, v52
	v_cndmask_b32_e64 v22, v52, v22, s[38:39]
	global_store_dwordx2 v22, v[246:247], s[18:19]
	s_and_saveexec_b64 s[22:23], s[42:43]
	s_cbranch_execz .LBB0_1999
	s_waitcnt lgkmcnt(1)
	v_add_f32_e32 v18, v18, v19
	s_waitcnt lgkmcnt(0)
	v_add_f32_e32 v19, v20, v21
	ds_write2_b32 v194, v18, v19 offset0:96 offset1:104
; #define LAS __attribute__((address_space(3)))
; #define ERN_EOFF(q, m) (eb + (unsigned)((((q) & 1) * HALF + (m) * 16) * DM + ERN_COL((q) >> 1)))
;     __device__ __forceinline__ void operator()(const f32x4 (&acc)[2][2][4][2], const Unit& u, int wr, int wc, int fr, int fq) const {
;     ...
;         for (int g = 0; g < 8; ++g) { const int ai = g >> 2, m = g & 3;
;             if (g + 1 < 8) ERN_LOADX(g + 1);
;             float sq0 = 0.f, sq1 = 0.f; u32x2 hw[2][2];
; #pragma unroll
;             for (int bj = 0; bj < 2; ++bj) {
;                 *(LAS f32x4*)(st + wr_off) = acc[ai][bj][m][0]; *(LAS f32x4*)(st + wr_off + 64) = acc[ai][bj][m][1];
;                 const f32x4 a0 = *(const LAS f32x4*)(st + rd_off), a1 = *(const LAS f32x4*)(st + rd_off + 8 * 144);
;                 { const f32x4 xv = xb[g & 1][bj][0] + gv[bj] * a0; __builtin_nontemporal_store(xv, (f32x4*)((char*)xo + 4u * ERN_EOFF(g, bj, 0)));
;                   sq0 += (xv.x * xv.x + xv.y * xv.y) + (xv.z * xv.z + xv.w * xv.w);
;                   const f32x4 hv = xv * gsn[bj]; hw[bj][0].x = cvt_pk_bf16(hv.x, hv.y); hw[bj][0].y = cvt_pk_bf16(hv.z, hv.w); }
;                 { const f32x4 xv = xb[g & 1][bj][1] + gv[bj] * a1; __builtin_nontemporal_store(xv, (f32x4*)((char*)xo + 4u * ERN_EOFF(g, bj, 1)));
;                   sq1 += (xv.x * xv.x + xv.y * xv.y) + (xv.z * xv.z + xv.w * xv.w);
;                   const f32x4 hv = xv * gsn[bj]; hw[bj][1].x = cvt_pk_bf16(hv.x, hv.y); hw[bj][1].y = cvt_pk_bf16(hv.z, hv.w); }
;             }
;             if (!NOH && !PLAIN) {
; #pragma unroll
;                 for (int rh = 0; rh < 2; ++rh) { u32x2 rv; rv.x = __shfl_xor(hw[1][rh].x, 8); rv.y = __shfl_xor(hw[1][rh].y, 8);
;                     const unsigned e0 = ERN_EOFF(g, 0, rh);
;                     const unsigned ee = odd ? (e0 - DM + 32) : e0, eo2 = odd ? e0 : (e0 + DM + 32);
;                     *(u32x2*)((char*)ho + 2u * ee) = odd ? rv : hw[0][rh];
;                     *(u32x2*)((char*)ho + 2u * eo2) = odd ? hw[0][rh] : rv; }
;             }
;             if (!PLAIN) { sq0 += __shfl_xor(sq0, 1); sq0 += __shfl_xor(sq0, 2); sq0 += __shfl_xor(sq0, 4);
;             sq1 += __shfl_xor(sq1, 1); sq1 += __shfl_xor(sq1, 2); sq1 += __shfl_xor(sq1, 4); }
;             if (!PLAIN && pc == 0) { sst[g * 16 + rr] = sq0; sst[g * 16 + 8 + rr] = sq1; }
.LBB0_1999:
	s_or_b64 exec, exec, s[22:23]
	ds_write_b128 v200, v[14:17]
	ds_write_b128 v200, v[10:13] offset:64
	ds_read_b128 v[10:13], v201
	ds_read_b128 v[14:17], v201 offset:1152
	s_waitcnt lgkmcnt(5)
	v_lshl_add_u64 v[18:19], s[20:21], 0, v[154:155]
	v_mov_b32_e32 v71, v155
	v_lshl_add_u64 v[22:23], s[20:21], 0, v[70:71]
	s_waitcnt vmcnt(9) lgkmcnt(1)
	v_pk_fma_f32 v[12:13], v[176:177], v[12:13], v[48:49]
	v_pk_fma_f32 v[10:11], v[180:181], v[10:11], v[46:47]
	global_store_dwordx4 v[18:19], v[10:13], off nt
	v_pk_mul_f32 v[18:19], v[174:175], v[12:13]
	v_pk_mul_f32 v[20:21], v[178:179], v[10:11]
	s_waitcnt vmcnt(9) lgkmcnt(0)
	v_pk_fma_f32 v[14:15], v[180:181], v[14:15], v[42:43]
	v_cvt_pk_bf16_f32 v20, v20, v21
	v_cvt_pk_bf16_f32 v21, v18, v19
	v_pk_fma_f32 v[16:17], v[176:177], v[16:17], v[44:45]
	v_pk_mul_f32 v[18:19], v[178:179], v[14:15]
	global_store_dwordx4 v[22:23], v[14:17], off nt
	v_pk_mul_f32 v[22:23], v[174:175], v[16:17]
	v_cvt_pk_bf16_f32 v18, v18, v19
	v_mov_b32_e32 v69, v155
	v_cvt_pk_bf16_f32 v19, v22, v23
	ds_write_b128 v200, v[6:9]
	ds_write_b128 v200, v[2:5] offset:64
	ds_read_b128 v[2:5], v201
	ds_read_b128 v[6:9], v201 offset:1152
	v_lshl_add_u64 v[22:23], s[20:21], 0, v[68:69]
	v_mov_b32_e32 v67, v155
	v_lshl_add_u64 v[24:25], s[20:21], 0, v[66:67]
	s_waitcnt vmcnt(9) lgkmcnt(1)
	v_pk_fma_f32 v[4:5], v[166:167], v[4:5], v[40:41]
	v_pk_fma_f32 v[2:3], v[168:169], v[2:3], v[38:39]
	global_store_dwordx4 v[22:23], v[2:5], off nt
	v_pk_mul_f32 v[22:23], v[170:171], v[4:5]
	v_pk_mul_f32 v[26:27], v[172:173], v[2:3]
	s_waitcnt vmcnt(9) lgkmcnt(0)
	v_pk_fma_f32 v[8:9], v[166:167], v[8:9], v[36:37]
	v_cvt_pk_bf16_f32 v28, v26, v27
	v_cvt_pk_bf16_f32 v23, v22, v23
	ds_bpermute_b32 v22, v203, v28
	ds_bpermute_b32 v23, v203, v23
	v_pk_fma_f32 v[6:7], v[168:169], v[6:7], v[34:35]
	global_store_dwordx4 v[24:25], v[6:9], off nt
	v_pk_mul_f32 v[26:27], v[170:171], v[8:9]
	v_pk_mul_f32 v[24:25], v[172:173], v[6:7]
	s_nop 0
	v_cvt_pk_bf16_f32 v24, v24, v25
	v_cvt_pk_bf16_f32 v25, v26, v27
	v_add_u32_e32 v27, 0x58000, v202
	v_lshlrev_b32_e32 v26, 1, v27
	s_waitcnt lgkmcnt(0)
	v_add_u32_e32 v250, 0xfffff040, v26
	v_cndmask_b32_e64 v250, v26, v250, s[40:41]
	v_cndmask_b32_e64 v248, v20, v22, s[40:41]
	v_cndmask_b32_e64 v249, v21, v23, s[40:41]
	global_store_dwordx2 v250, v[248:249], s[18:19]
	v_cndmask_b32_e64 v246, v22, v20, s[40:41]
	v_cndmask_b32_e64 v247, v23, v21, s[40:41]
	s_waitcnt lgkmcnt(1)
	v_add_u32_e32 v22, 0x1040, v26
	v_cndmask_b32_e64 v22, v26, v22, s[38:39]
	global_store_dwordx2 v22, v[246:247], s[18:19]
	ds_bpermute_b32 v20, v203, v24
	ds_bpermute_b32 v21, v203, v25
	s_waitcnt lgkmcnt(2)
	v_add_u32_e32 v23, 0x5c000, v202
	v_lshlrev_b32_e32 v22, 1, v23
	s_waitcnt lgkmcnt(0)
	v_add_u32_e32 v250, 0xfffff040, v22
	v_cndmask_b32_e64 v250, v22, v250, s[40:41]
	v_cndmask_b32_e64 v248, v18, v20, s[40:41]
	v_cndmask_b32_e64 v249, v19, v21, s[40:41]
	global_store_dwordx2 v250, v[248:249], s[18:19]
	v_cndmask_b32_e64 v246, v20, v18, s[40:41]
	v_cndmask_b32_e64 v247, v21, v19, s[40:41]
	v_mul_f32_e32 v3, v3, v3
	v_fmac_f32_e32 v3, v2, v2
	v_mul_f32_e32 v2, v5, v5
	v_mul_f32_e32 v13, v13, v13
	v_fmac_f32_e32 v2, v4, v4
	v_mul_f32_e32 v11, v11, v11
	v_fmac_f32_e32 v13, v12, v12
	v_mul_f32_e32 v12, v15, v15
	v_mul_f32_e32 v15, v17, v17
	v_add_f32_e32 v2, v3, v2
	v_mul_f32_e32 v3, v7, v7
	v_mul_f32_e32 v4, v9, v9
	v_fmac_f32_e32 v15, v16, v16
	v_fmac_f32_e32 v3, v6, v6
	v_fmac_f32_e32 v4, v8, v8
	v_fmac_f32_e32 v11, v10, v10
	v_fmac_f32_e32 v12, v14, v14
	v_add_f32_e32 v3, v3, v4
	v_add_f32_e32 v4, v11, v13
	v_add_f32_e32 v5, v12, v15
	v_add_f32_e32 v2, v4, v2
	v_add_f32_e32 v3, v5, v3
	s_nop 1
	v_mov_b32_dpp v4, v2 quad_perm:[1,0,3,2] row_mask:0xf bank_mask:0xf
	s_nop 1
	v_mov_b32_dpp v5, v3 quad_perm:[1,0,3,2] row_mask:0xf bank_mask:0xf
	s_waitcnt lgkmcnt(1)
	v_add_f32_e32 v2, v2, v4
	s_waitcnt lgkmcnt(0)
	v_add_f32_e32 v5, v3, v5
	s_nop 1
	v_mov_b32_dpp v4, v2 quad_perm:[2,3,0,1] row_mask:0xf bank_mask:0xf
	s_nop 1
	v_mov_b32_dpp v6, v5 quad_perm:[2,3,0,1] row_mask:0xf bank_mask:0xf
	s_waitcnt lgkmcnt(1)
	v_add_f32_e32 v2, v2, v4
	s_waitcnt lgkmcnt(0)
	v_add_f32_e32 v4, v5, v6
	s_nop 1
	v_mov_b32_dpp v3, v2 row_half_mirror row_mask:0xf bank_mask:0xf
	s_nop 1
	v_mov_b32_dpp v5, v4 row_half_mirror row_mask:0xf bank_mask:0xf
	v_add_u32_e32 v6, 0x1040, v22
	v_cndmask_b32_e64 v6, v22, v6, s[38:39]
	global_store_dwordx2 v6, v[246:247], s[18:19]
	s_and_saveexec_b64 s[18:19], s[42:43]
	s_cbranch_execz .LBB0_2009
	s_waitcnt lgkmcnt(1)
	v_add_f32_e32 v2, v2, v3
	s_waitcnt lgkmcnt(0)
	v_add_f32_e32 v3, v4, v5
	ds_write2_b32 v194, v2, v3 offset0:112 offset1:120

; #define LAS __attribute__((address_space(3)))
; #define ERN_EOFF(q, m) (eb + (unsigned)((((q) & 1) * HALF + (m) * 16) * DM + ERN_COL((q) >> 1)))
;     __device__ __forceinline__ void operator()(const f32x4 (&acc)[2][2][4][2], const Unit& u, int wr, int wc, int fr, int fq) const {
;     ...
;         for (int g = 0; g < 8; ++g) { const int ai = g >> 2, m = g & 3;
;             if (g + 1 < 8) ERN_LOADX(g + 1);
;             float sq0 = 0.f, sq1 = 0.f; u32x2 hw[2][2];
; #pragma unroll
;             for (int bj = 0; bj < 2; ++bj) {
;                 *(LAS f32x4*)(st + wr_off) = acc[ai][bj][m][0]; *(LAS f32x4*)(st + wr_off + 64) = acc[ai][bj][m][1];
;                 const f32x4 a0 = *(const LAS f32x4*)(st + rd_off), a1 = *(const LAS f32x4*)(st + rd_off + 8 * 144);
;                 { const f32x4 xv = xb[g & 1][bj][0] + gv[bj] * a0; __builtin_nontemporal_store(xv, (f32x4*)((char*)xo + 4u * ERN_EOFF(g, bj, 0)));
;                   sq0 += (xv.x * xv.x + xv.y * xv.y) + (xv.z * xv.z + xv.w * xv.w);
;                   const f32x4 hv = xv * gsn[bj]; hw[bj][0].x = cvt_pk_bf16(hv.x, hv.y); hw[bj][0].y = cvt_pk_bf16(hv.z, hv.w); }
;                 { const f32x4 xv = xb[g & 1][bj][1] + gv[bj] * a1; __builtin_nontemporal_store(xv, (f32x4*)((char*)xo + 4u * ERN_EOFF(g, bj, 1)));
;                   sq1 += (xv.x * xv.x + xv.y * xv.y) + (xv.z * xv.z + xv.w * xv.w);
;                   const f32x4 hv = xv * gsn[bj]; hw[bj][1].x = cvt_pk_bf16(hv.x, hv.y); hw[bj][1].y = cvt_pk_bf16(hv.z, hv.w); }
;             }
;             if (!NOH && !PLAIN) {
; #pragma unroll
;                 for (int rh = 0; rh < 2; ++rh) { u32x2 rv; rv.x = __shfl_xor(hw[1][rh].x, 8); rv.y = __shfl_xor(hw[1][rh].y, 8);
;                     const unsigned e0 = ERN_EOFF(g, 0, rh);
;                     const unsigned ee = odd ? (e0 - DM + 32) : e0, eo2 = odd ? e0 : (e0 + DM + 32);
;                     *(u32x2*)((char*)ho + 2u * ee) = odd ? rv : hw[0][rh];
;                     *(u32x2*)((char*)ho + 2u * eo2) = odd ? hw[0][rh] : rv; }
;             }
;             if (!PLAIN) { sq0 += __shfl_xor(sq0, 1); sq0 += __shfl_xor(sq0, 2); sq0 += __shfl_xor(sq0, 4);
;             sq1 += __shfl_xor(sq1, 1); sq1 += __shfl_xor(sq1, 2); sq1 += __shfl_xor(sq1, 4); }
;             if (!PLAIN && pc == 0) { sst[g * 16 + rr] = sq0; sst[g * 16 + 8 + rr] = sq1; }
.LBB0_2777:
	s_or_b64 exec, exec, s[24:25]
	v_mul_f32_e32 v127, v127, v127
	v_mul_f32_e32 v135, v135, v135
	v_mul_f32_e32 v137, v137, v137
	v_fmac_f32_e32 v127, v126, v126
	v_mul_f32_e32 v126, v129, v129
	v_fmac_f32_e32 v137, v136, v136
	v_fmac_f32_e32 v126, v128, v128
	v_mul_f32_e32 v123, v123, v123
	v_fmac_f32_e32 v135, v134, v134
	v_add_f32_e32 v126, v127, v126
	v_fmac_f32_e32 v123, v122, v122
	v_mul_f32_e32 v122, v125, v125
	v_add_f32_e32 v125, v135, v137
	v_add_f32_e32 v125, v125, v126
	v_xor_b32_e32 v126, 1, v199
	v_cmp_lt_i32_e32 vcc, v126, v183
	v_mul_f32_e32 v131, v131, v131
	v_mul_f32_e32 v133, v133, v133
	v_cndmask_b32_e32 v126, v199, v126, vcc
	v_lshlrev_b32_e32 v190, 2, v126
	s_nop 1
	v_mov_b32_dpp v126, v125 quad_perm:[1,0,3,2] row_mask:0xf bank_mask:0xf
	v_fmac_f32_e32 v122, v124, v124
	v_fmac_f32_e32 v133, v132, v132
	v_fmac_f32_e32 v131, v130, v130
	v_add_f32_e32 v122, v123, v122
	s_waitcnt lgkmcnt(0)
	v_add_f32_e32 v124, v125, v126
	v_xor_b32_e32 v125, 2, v199
	v_cmp_lt_i32_e32 vcc, v125, v183
	v_add_f32_e32 v123, v131, v133
	v_add_f32_e32 v123, v123, v122
	v_cndmask_b32_e32 v125, v199, v125, vcc
	v_lshlrev_b32_e32 v191, 2, v125
	s_nop 1
	v_mov_b32_dpp v125, v124 quad_perm:[2,3,0,1] row_mask:0xf bank_mask:0xf
	s_nop 1
	v_mov_b32_dpp v126, v123 quad_perm:[1,0,3,2] row_mask:0xf bank_mask:0xf
	s_waitcnt lgkmcnt(1)
	v_add_f32_e32 v122, v124, v125
	s_waitcnt lgkmcnt(0)
	v_add_f32_e32 v125, v123, v126
	s_nop 1
	v_mov_b32_dpp v126, v125 quad_perm:[2,3,0,1] row_mask:0xf bank_mask:0xf
	v_xor_b32_e32 v124, 4, v199
	v_cmp_lt_i32_e32 vcc, v124, v183
	s_nop 1
	v_cndmask_b32_e32 v123, v199, v124, vcc
	v_lshlrev_b32_e32 v204, 2, v123
	s_waitcnt lgkmcnt(0)
	v_add_f32_e32 v124, v125, v126
	s_nop 1
	v_mov_b32_dpp v123, v122 row_half_mirror row_mask:0xf bank_mask:0xf
	s_nop 1
	v_mov_b32_dpp v125, v124 row_half_mirror row_mask:0xf bank_mask:0xf
	v_add_u32_e32 v126, 0x1040, v206
	v_cndmask_b32_e64 v126, v206, v126, s[36:37]
	global_store_dwordx2 v126, v[186:187], s[20:21]
	s_and_saveexec_b64 s[24:25], s[40:41]
	s_cbranch_execz .LBB0_2779
	s_waitcnt lgkmcnt(1)
	v_add_f32_e32 v122, v122, v123
	s_waitcnt lgkmcnt(0)
	v_add_f32_e32 v123, v124, v125
	ds_write2_b32 v194, v122, v123 offset1:8
.LBB0_2779:
	s_or_b64 exec, exec, s[24:25]
	v_lshl_add_u64 v[206:207], s[22:23], 0, v[162:163]
	v_add_u32_e32 v122, 0x40000, v205
	v_add_u32_e32 v162, 0x50000, v205
	v_add_u32_e32 v186, 0x40080, v205
	global_load_dwordx4 v[130:133], v162, s[22:23]
	global_load_dwordx4 v[126:129], v186, s[22:23]
	v_add_u32_e32 v188, 0x50080, v205
	global_load_dwordx4 v[134:137], v122, s[22:23]
	s_waitcnt lgkmcnt(0)
	global_load_dwordx4 v[122:125], v188, s[22:23]
	ds_write_b128 v200, v[118:121]
	ds_write_b128 v200, v[114:117] offset:64
	ds_read_b128 v[114:117], v201
	ds_read_b128 v[118:121], v201 offset:1152
	v_mov_b32_e32 v185, v163
	v_mov_b32_e32 v183, v163
	v_lshl_add_u64 v[182:183], s[22:23], 0, v[182:183]
	s_waitcnt lgkmcnt(1)
	v_pk_fma_f32 v[116:117], v[56:57], v[116:117], v[152:153]
	v_add_u32_e32 v152, 0x8000, v202
	v_pk_fma_f32 v[114:115], v[54:55], v[114:115], v[150:151]
	v_lshlrev_b32_e32 v150, 2, v152
	s_waitcnt lgkmcnt(0)
	v_pk_fma_f32 v[118:119], v[54:55], v[118:119], v[146:147]
	global_store_dwordx4 v150, v[114:117], s[22:23] nt
	v_pk_mul_f32 v[150:151], v[180:181], v[114:115]
	v_pk_fma_f32 v[120:121], v[56:57], v[120:121], v[148:149]
	v_pk_mul_f32 v[146:147], v[180:181], v[118:119]
	v_pk_mul_f32 v[208:209], v[178:179], v[116:117]
	v_cvt_pk_bf16_f32 v150, v150, v151
	v_pk_mul_f32 v[148:149], v[178:179], v[120:121]
	v_cvt_pk_bf16_f32 v151, v208, v209
	global_store_dwordx4 v[206:207], v[118:121], off nt
	v_cvt_pk_bf16_f32 v146, v146, v147
	v_cvt_pk_bf16_f32 v147, v148, v149
	ds_write_b128 v200, v[110:113]
	ds_write_b128 v200, v[106:109] offset:64
	ds_read_b128 v[106:109], v201
	ds_read_b128 v[110:113], v201 offset:1152
	v_lshl_add_u64 v[148:149], s[22:23], 0, v[184:185]
	s_waitcnt lgkmcnt(1)
	v_pk_fma_f32 v[106:107], v[50:51], v[106:107], v[142:143]
	v_pk_fma_f32 v[108:109], v[52:53], v[108:109], v[144:145]
	v_pk_mul_f32 v[144:145], v[176:177], v[106:107]
	global_store_dwordx4 v[148:149], v[106:109], off nt
	v_pk_mul_f32 v[142:143], v[174:175], v[108:109]
	v_cvt_pk_bf16_f32 v144, v144, v145
	s_waitcnt lgkmcnt(0)
	v_pk_fma_f32 v[110:111], v[50:51], v[110:111], v[138:139]
	v_cvt_pk_bf16_f32 v145, v142, v143
	ds_bpermute_b32 v138, v203, v144
	ds_bpermute_b32 v139, v203, v145
	v_pk_fma_f32 v[112:113], v[52:53], v[112:113], v[140:141]
	v_pk_mul_f32 v[140:141], v[176:177], v[110:111]
	v_pk_mul_f32 v[142:143], v[174:175], v[112:113]
	global_store_dwordx4 v[182:183], v[110:113], off nt
	v_cvt_pk_bf16_f32 v140, v140, v141
	v_cvt_pk_bf16_f32 v141, v142, v143
	v_lshlrev_b32_e32 v142, 1, v152
	s_waitcnt lgkmcnt(0)
	v_add_u32_e32 v250, 0xfffff040, v142
	v_cndmask_b32_e64 v250, v142, v250, s[38:39]
	v_cndmask_b32_e64 v248, v150, v138, s[38:39]
	v_cndmask_b32_e64 v249, v151, v139, s[38:39]
	global_store_dwordx2 v250, v[248:249], s[20:21]
	v_cndmask_b32_e64 v246, v138, v150, s[38:39]
	v_cndmask_b32_e64 v247, v139, v151, s[38:39]
	s_waitcnt lgkmcnt(1)
	v_add_u32_e32 v138, 0x1040, v142
	v_cndmask_b32_e64 v138, v142, v138, s[36:37]
	global_store_dwordx2 v138, v[246:247], s[20:21]
	ds_bpermute_b32 v138, v203, v140
	s_waitcnt lgkmcnt(1)
	ds_bpermute_b32 v139, v203, v141
	v_add_u32_e32 v141, 0xc000, v202
	v_lshlrev_b32_e32 v140, 1, v141
	s_waitcnt lgkmcnt(0)
; #define LAS __attribute__((address_space(3)))
; #define ERN_EOFF(q, m) (eb + (unsigned)((((q) & 1) * HALF + (m) * 16) * DM + ERN_COL((q) >> 1)))
;     __device__ __forceinline__ void operator()(const f32x4 (&acc)[2][2][4][2], const Unit& u, int wr, int wc, int fr, int fq) const {
;     ...
;         for (int g = 0; g < 8; ++g) { const int ai = g >> 2, m = g & 3;
;             if (g + 1 < 8) ERN_LOADX(g + 1);
;             float sq0 = 0.f, sq1 = 0.f; u32x2 hw[2][2];
; #pragma unroll
;             for (int bj = 0; bj < 2; ++bj) {
;                 *(LAS f32x4*)(st + wr_off) = acc[ai][bj][m][0]; *(LAS f32x4*)(st + wr_off + 64) = acc[ai][bj][m][1];
;                 const f32x4 a0 = *(const LAS f32x4*)(st + rd_off), a1 = *(const LAS f32x4*)(st + rd_off + 8 * 144);
;                 { const f32x4 xv = xb[g & 1][bj][0] + gv[bj] * a0; __builtin_nontemporal_store(xv, (f32x4*)((char*)xo + 4u * ERN_EOFF(g, bj, 0)));
;                   sq0 += (xv.x * xv.x + xv.y * xv.y) + (xv.z * xv.z + xv.w * xv.w);
;                   const f32x4 hv = xv * gsn[bj]; hw[bj][0].x = cvt_pk_bf16(hv.x, hv.y); hw[bj][0].y = cvt_pk_bf16(hv.z, hv.w); }
;                 { const f32x4 xv = xb[g & 1][bj][1] + gv[bj] * a1; __builtin_nontemporal_store(xv, (f32x4*)((char*)xo + 4u * ERN_EOFF(g, bj, 1)));
;                   sq1 += (xv.x * xv.x + xv.y * xv.y) + (xv.z * xv.z + xv.w * xv.w);
;                   const f32x4 hv = xv * gsn[bj]; hw[bj][1].x = cvt_pk_bf16(hv.x, hv.y); hw[bj][1].y = cvt_pk_bf16(hv.z, hv.w); }
;             }
;             if (!NOH && !PLAIN) {
; #pragma unroll
;                 for (int rh = 0; rh < 2; ++rh) { u32x2 rv; rv.x = __shfl_xor(hw[1][rh].x, 8); rv.y = __shfl_xor(hw[1][rh].y, 8);
;                     const unsigned e0 = ERN_EOFF(g, 0, rh);
;                     const unsigned ee = odd ? (e0 - DM + 32) : e0, eo2 = odd ? e0 : (e0 + DM + 32);
;                     *(u32x2*)((char*)ho + 2u * ee) = odd ? rv : hw[0][rh];
;                     *(u32x2*)((char*)ho + 2u * eo2) = odd ? hw[0][rh] : rv; }
;             }
;             if (!PLAIN) { sq0 += __shfl_xor(sq0, 1); sq0 += __shfl_xor(sq0, 2); sq0 += __shfl_xor(sq0, 4);
;             sq1 += __shfl_xor(sq1, 1); sq1 += __shfl_xor(sq1, 2); sq1 += __shfl_xor(sq1, 4); }
;             if (!PLAIN && pc == 0) { sst[g * 16 + rr] = sq0; sst[g * 16 + 8 + rr] = sq1; }
	v_add_u32_e32 v250, 0xfffff040, v140
	v_cndmask_b32_e64 v250, v140, v250, s[38:39]
	v_cndmask_b32_e64 v248, v146, v138, s[38:39]
	v_cndmask_b32_e64 v249, v147, v139, s[38:39]
	global_store_dwordx2 v250, v[248:249], s[20:21]
	v_cndmask_b32_e64 v246, v138, v146, s[38:39]
	v_cndmask_b32_e64 v247, v139, v147, s[38:39]
	v_mul_f32_e32 v107, v107, v107
	v_fmac_f32_e32 v107, v106, v106
	v_mul_f32_e32 v106, v109, v109
	v_mul_f32_e32 v117, v117, v117
	v_fmac_f32_e32 v106, v108, v108
	v_mul_f32_e32 v115, v115, v115
	v_fmac_f32_e32 v117, v116, v116
	v_mul_f32_e32 v116, v119, v119
	v_mul_f32_e32 v119, v121, v121
	v_add_f32_e32 v106, v107, v106
	v_mul_f32_e32 v107, v111, v111
	v_mul_f32_e32 v108, v113, v113
	v_fmac_f32_e32 v119, v120, v120
	v_fmac_f32_e32 v107, v110, v110
	v_fmac_f32_e32 v108, v112, v112
	v_fmac_f32_e32 v115, v114, v114
	v_fmac_f32_e32 v116, v118, v118
	v_add_f32_e32 v107, v107, v108
	v_add_f32_e32 v108, v115, v117
	v_add_f32_e32 v109, v116, v119
	v_add_f32_e32 v106, v108, v106
	v_add_f32_e32 v107, v109, v107
	s_nop 1
	v_mov_b32_dpp v108, v106 quad_perm:[1,0,3,2] row_mask:0xf bank_mask:0xf
	s_nop 1
	v_mov_b32_dpp v109, v107 quad_perm:[1,0,3,2] row_mask:0xf bank_mask:0xf
	s_waitcnt lgkmcnt(1)
	v_add_f32_e32 v106, v106, v108
	s_waitcnt lgkmcnt(0)
	v_add_f32_e32 v109, v107, v109
	s_nop 1
	v_mov_b32_dpp v108, v106 quad_perm:[2,3,0,1] row_mask:0xf bank_mask:0xf
	s_nop 1
	v_mov_b32_dpp v110, v109 quad_perm:[2,3,0,1] row_mask:0xf bank_mask:0xf
	s_waitcnt lgkmcnt(1)
	v_add_f32_e32 v106, v106, v108
	s_waitcnt lgkmcnt(0)
	v_add_f32_e32 v108, v109, v110
	s_nop 1
	v_mov_b32_dpp v107, v106 row_half_mirror row_mask:0xf bank_mask:0xf
	s_nop 1
	v_mov_b32_dpp v109, v108 row_half_mirror row_mask:0xf bank_mask:0xf
	v_add_u32_e32 v110, 0x1040, v140
	v_cndmask_b32_e64 v110, v140, v110, s[36:37]
	global_store_dwordx2 v110, v[246:247], s[20:21]
	s_and_saveexec_b64 s[24:25], s[40:41]
	s_cbranch_execz .LBB0_2789
	s_waitcnt lgkmcnt(1)
	v_add_f32_e32 v106, v106, v107
	s_waitcnt lgkmcnt(0)
	v_add_f32_e32 v107, v108, v109
	ds_write2_b32 v194, v106, v107 offset0:16 offset1:24
.LBB0_2789:
	s_or_b64 exec, exec, s[24:25]
	v_lshl_add_u64 v[142:143], s[22:23], 0, v[162:163]
	v_add_u32_e32 v106, 0x60000, v205
	v_add_u32_e32 v162, 0x70000, v205
	v_add_u32_e32 v138, 0x60080, v205
	global_load_dwordx4 v[114:117], v162, s[22:23]
	global_load_dwordx4 v[110:113], v138, s[22:23]
	v_add_u32_e32 v140, 0x70080, v205
	global_load_dwordx4 v[118:121], v106, s[22:23]
	s_waitcnt lgkmcnt(0)
	global_load_dwordx4 v[106:109], v140, s[22:23]
	ds_write_b128 v200, v[102:105]
	ds_write_b128 v200, v[98:101] offset:64
	ds_read_b128 v[98:101], v201
	ds_read_b128 v[102:105], v201 offset:1152
	v_mov_b32_e32 v187, v163
	v_mov_b32_e32 v189, v163
	s_waitcnt vmcnt(11) lgkmcnt(1)
	v_pk_fma_f32 v[100:101], v[56:57], v[100:101], v[136:137]
	v_add_u32_e32 v136, 0x10000, v202
	v_pk_fma_f32 v[98:99], v[54:55], v[98:99], v[134:135]
	v_lshlrev_b32_e32 v134, 2, v136
	s_waitcnt lgkmcnt(0)
	v_pk_fma_f32 v[102:103], v[54:55], v[102:103], v[130:131]
	global_store_dwordx4 v134, v[98:101], s[22:23] nt
	v_pk_mul_f32 v[134:135], v[180:181], v[98:99]
	v_pk_fma_f32 v[104:105], v[56:57], v[104:105], v[132:133]
	v_pk_mul_f32 v[130:131], v[180:181], v[102:103]
	v_pk_mul_f32 v[144:145], v[178:179], v[100:101]
	v_cvt_pk_bf16_f32 v134, v134, v135
	v_pk_mul_f32 v[132:133], v[178:179], v[104:105]
	v_cvt_pk_bf16_f32 v135, v144, v145
	global_store_dwordx4 v[142:143], v[102:105], off nt
	v_cvt_pk_bf16_f32 v130, v130, v131
	v_cvt_pk_bf16_f32 v131, v132, v133
	ds_write_b128 v200, v[94:97]
	ds_write_b128 v200, v[90:93] offset:64
	ds_read_b128 v[90:93], v201
	ds_read_b128 v[94:97], v201 offset:1152
	v_lshl_add_u64 v[132:133], s[22:23], 0, v[186:187]
	v_lshl_add_u64 v[142:143], s[22:23], 0, v[188:189]
	s_waitcnt lgkmcnt(1)
	v_pk_fma_f32 v[90:91], v[50:51], v[90:91], v[126:127]
	v_pk_fma_f32 v[92:93], v[52:53], v[92:93], v[128:129]
	v_pk_mul_f32 v[128:129], v[176:177], v[90:91]
	global_store_dwordx4 v[132:133], v[90:93], off nt
	v_pk_mul_f32 v[126:127], v[174:175], v[92:93]
	v_cvt_pk_bf16_f32 v128, v128, v129
	s_waitcnt vmcnt(13) lgkmcnt(0)
	v_pk_fma_f32 v[94:95], v[50:51], v[94:95], v[122:123]
	v_cvt_pk_bf16_f32 v129, v126, v127
	ds_bpermute_b32 v122, v203, v128
	ds_bpermute_b32 v123, v203, v129
	v_pk_fma_f32 v[96:97], v[52:53], v[96:97], v[124:125]
	v_pk_mul_f32 v[124:125], v[176:177], v[94:95]
	v_pk_mul_f32 v[126:127], v[174:175], v[96:97]
	global_store_dwordx4 v[142:143], v[94:97], off nt
	v_cvt_pk_bf16_f32 v124, v124, v125
	v_cvt_pk_bf16_f32 v125, v126, v127
	v_lshlrev_b32_e32 v126, 1, v136
	s_waitcnt lgkmcnt(0)
	v_add_u32_e32 v250, 0xfffff040, v126
	v_cndmask_b32_e64 v250, v126, v250, s[38:39]
	v_cndmask_b32_e64 v248, v134, v122, s[38:39]
	v_cndmask_b32_e64 v249, v135, v123, s[38:39]
	global_store_dwordx2 v250, v[248:249], s[20:21]
	v_cndmask_b32_e64 v246, v122, v134, s[38:39]
	v_cndmask_b32_e64 v247, v123, v135, s[38:39]
	s_waitcnt lgkmcnt(1)
	v_add_u32_e32 v122, 0x1040, v126
	v_cndmask_b32_e64 v122, v126, v122, s[36:37]
	global_store_dwordx2 v122, v[246:247], s[20:21]
	ds_bpermute_b32 v122, v203, v124
	s_waitcnt lgkmcnt(1)
	ds_bpermute_b32 v123, v203, v125
	v_add_u32_e32 v125, 0x14000, v202
	v_lshlrev_b32_e32 v124, 1, v125
	s_waitcnt lgkmcnt(0)
; #define LAS __attribute__((address_space(3)))
; #define ERN_EOFF(q, m) (eb + (unsigned)((((q) & 1) * HALF + (m) * 16) * DM + ERN_COL((q) >> 1)))
;     __device__ __forceinline__ void operator()(const f32x4 (&acc)[2][2][4][2], const Unit& u, int wr, int wc, int fr, int fq) const {
;     ...
;         for (int g = 0; g < 8; ++g) { const int ai = g >> 2, m = g & 3;
;             if (g + 1 < 8) ERN_LOADX(g + 1);
;             float sq0 = 0.f, sq1 = 0.f; u32x2 hw[2][2];
; #pragma unroll
;             for (int bj = 0; bj < 2; ++bj) {
;                 *(LAS f32x4*)(st + wr_off) = acc[ai][bj][m][0]; *(LAS f32x4*)(st + wr_off + 64) = acc[ai][bj][m][1];
;                 const f32x4 a0 = *(const LAS f32x4*)(st + rd_off), a1 = *(const LAS f32x4*)(st + rd_off + 8 * 144);
;                 { const f32x4 xv = xb[g & 1][bj][0] + gv[bj] * a0; __builtin_nontemporal_store(xv, (f32x4*)((char*)xo + 4u * ERN_EOFF(g, bj, 0)));
;                   sq0 += (xv.x * xv.x + xv.y * xv.y) + (xv.z * xv.z + xv.w * xv.w);
;                   const f32x4 hv = xv * gsn[bj]; hw[bj][0].x = cvt_pk_bf16(hv.x, hv.y); hw[bj][0].y = cvt_pk_bf16(hv.z, hv.w); }
;                 { const f32x4 xv = xb[g & 1][bj][1] + gv[bj] * a1; __builtin_nontemporal_store(xv, (f32x4*)((char*)xo + 4u * ERN_EOFF(g, bj, 1)));
;                   sq1 += (xv.x * xv.x + xv.y * xv.y) + (xv.z * xv.z + xv.w * xv.w);
;                   const f32x4 hv = xv * gsn[bj]; hw[bj][1].x = cvt_pk_bf16(hv.x, hv.y); hw[bj][1].y = cvt_pk_bf16(hv.z, hv.w); }
;             }
;             if (!NOH && !PLAIN) {
; #pragma unroll
;                 for (int rh = 0; rh < 2; ++rh) { u32x2 rv; rv.x = __shfl_xor(hw[1][rh].x, 8); rv.y = __shfl_xor(hw[1][rh].y, 8);
;                     const unsigned e0 = ERN_EOFF(g, 0, rh);
;                     const unsigned ee = odd ? (e0 - DM + 32) : e0, eo2 = odd ? e0 : (e0 + DM + 32);
;                     *(u32x2*)((char*)ho + 2u * ee) = odd ? rv : hw[0][rh];
;                     *(u32x2*)((char*)ho + 2u * eo2) = odd ? hw[0][rh] : rv; }
;             }
;             if (!PLAIN) { sq0 += __shfl_xor(sq0, 1); sq0 += __shfl_xor(sq0, 2); sq0 += __shfl_xor(sq0, 4);
;             sq1 += __shfl_xor(sq1, 1); sq1 += __shfl_xor(sq1, 2); sq1 += __shfl_xor(sq1, 4); }
;             if (!PLAIN && pc == 0) { sst[g * 16 + rr] = sq0; sst[g * 16 + 8 + rr] = sq1; }
	v_add_u32_e32 v250, 0xfffff040, v124
	v_cndmask_b32_e64 v250, v124, v250, s[38:39]
	v_cndmask_b32_e64 v248, v130, v122, s[38:39]
	v_cndmask_b32_e64 v249, v131, v123, s[38:39]
	global_store_dwordx2 v250, v[248:249], s[20:21]
	v_cndmask_b32_e64 v246, v122, v130, s[38:39]
	v_cndmask_b32_e64 v247, v123, v131, s[38:39]
	v_mul_f32_e32 v91, v91, v91
	v_fmac_f32_e32 v91, v90, v90
	v_mul_f32_e32 v90, v93, v93
	v_mul_f32_e32 v101, v101, v101
	v_fmac_f32_e32 v90, v92, v92
	v_mul_f32_e32 v99, v99, v99
	v_fmac_f32_e32 v101, v100, v100
	v_mul_f32_e32 v100, v103, v103
	v_mul_f32_e32 v103, v105, v105
	v_add_f32_e32 v90, v91, v90
	v_mul_f32_e32 v91, v95, v95
	v_mul_f32_e32 v92, v97, v97
	v_fmac_f32_e32 v103, v104, v104
	v_fmac_f32_e32 v91, v94, v94
	v_fmac_f32_e32 v92, v96, v96
	v_fmac_f32_e32 v99, v98, v98
	v_fmac_f32_e32 v100, v102, v102
	v_add_f32_e32 v91, v91, v92
	v_add_f32_e32 v92, v99, v101
	v_add_f32_e32 v93, v100, v103
	v_add_f32_e32 v90, v92, v90
	v_add_f32_e32 v91, v93, v91
	s_nop 1
	v_mov_b32_dpp v92, v90 quad_perm:[1,0,3,2] row_mask:0xf bank_mask:0xf
	s_nop 1
	v_mov_b32_dpp v93, v91 quad_perm:[1,0,3,2] row_mask:0xf bank_mask:0xf
	s_waitcnt lgkmcnt(1)
	v_add_f32_e32 v90, v90, v92
	s_waitcnt lgkmcnt(0)
	v_add_f32_e32 v93, v91, v93
	s_nop 1
	v_mov_b32_dpp v92, v90 quad_perm:[2,3,0,1] row_mask:0xf bank_mask:0xf
	s_nop 1
	v_mov_b32_dpp v94, v93 quad_perm:[2,3,0,1] row_mask:0xf bank_mask:0xf
	s_waitcnt lgkmcnt(1)
	v_add_f32_e32 v90, v90, v92
	s_waitcnt lgkmcnt(0)
	v_add_f32_e32 v92, v93, v94
	s_nop 1
	v_mov_b32_dpp v91, v90 row_half_mirror row_mask:0xf bank_mask:0xf
	s_nop 1
	v_mov_b32_dpp v93, v92 row_half_mirror row_mask:0xf bank_mask:0xf
	v_add_u32_e32 v94, 0x1040, v124
	v_cndmask_b32_e64 v94, v124, v94, s[36:37]
	global_store_dwordx2 v94, v[246:247], s[20:21]
	s_and_saveexec_b64 s[24:25], s[40:41]
	s_cbranch_execz .LBB0_2799
	s_waitcnt lgkmcnt(1)
	v_add_f32_e32 v90, v90, v91
	s_waitcnt lgkmcnt(0)
	v_add_f32_e32 v91, v92, v93
	ds_write2_b32 v194, v90, v91 offset0:32 offset1:40
.LBB0_2799:
	s_or_b64 exec, exec, s[24:25]
	v_lshl_add_u64 v[124:125], s[22:23], 0, v[162:163]
	v_add_u32_e32 v90, 0x100000, v205
	s_waitcnt lgkmcnt(1)
	v_add_u32_e32 v91, 0x110000, v205
	v_add_u32_e32 v162, 0x100080, v205
	global_load_dwordx4 v[102:105], v90, s[22:23]
	global_load_dwordx4 v[98:101], v91, s[22:23]
	v_add_u32_e32 v122, 0x110080, v205
	global_load_dwordx4 v[94:97], v162, s[22:23]
	s_waitcnt lgkmcnt(0)
	global_load_dwordx4 v[90:93], v122, s[22:23]
	ds_write_b128 v200, v[86:89]
	ds_write_b128 v200, v[82:85] offset:64
	ds_read_b128 v[82:85], v201
	ds_read_b128 v[86:89], v201 offset:1152
	v_mov_b32_e32 v139, v163
	v_mov_b32_e32 v141, v163
	s_waitcnt vmcnt(11) lgkmcnt(1)
	v_pk_fma_f32 v[84:85], v[56:57], v[84:85], v[120:121]
	v_add_u32_e32 v120, 0x18000, v202
	v_pk_fma_f32 v[82:83], v[54:55], v[82:83], v[118:119]
	v_lshlrev_b32_e32 v118, 2, v120
	s_waitcnt lgkmcnt(0)
	v_pk_fma_f32 v[86:87], v[54:55], v[86:87], v[114:115]
	global_store_dwordx4 v118, v[82:85], s[22:23] nt
	v_pk_mul_f32 v[118:119], v[180:181], v[82:83]
	v_pk_fma_f32 v[88:89], v[56:57], v[88:89], v[116:117]
	v_pk_mul_f32 v[114:115], v[180:181], v[86:87]
	v_pk_mul_f32 v[126:127], v[178:179], v[84:85]
	v_cvt_pk_bf16_f32 v118, v118, v119
	v_pk_mul_f32 v[116:117], v[178:179], v[88:89]
	v_cvt_pk_bf16_f32 v119, v126, v127
	global_store_dwordx4 v[124:125], v[86:89], off nt
	v_cvt_pk_bf16_f32 v114, v114, v115
	v_cvt_pk_bf16_f32 v115, v116, v117
	ds_write_b128 v200, v[78:81]
	ds_write_b128 v200, v[74:77] offset:64
	ds_read_b128 v[74:77], v201
	ds_read_b128 v[78:81], v201 offset:1152
	v_lshl_add_u64 v[116:117], s[22:23], 0, v[138:139]
	v_lshl_add_u64 v[124:125], s[22:23], 0, v[140:141]
	s_waitcnt lgkmcnt(1)
	v_pk_fma_f32 v[74:75], v[50:51], v[74:75], v[110:111]
	v_pk_fma_f32 v[76:77], v[52:53], v[76:77], v[112:113]
	v_pk_mul_f32 v[112:113], v[176:177], v[74:75]
	global_store_dwordx4 v[116:117], v[74:77], off nt
	v_pk_mul_f32 v[110:111], v[174:175], v[76:77]
	v_cvt_pk_bf16_f32 v112, v112, v113
	s_waitcnt vmcnt(13) lgkmcnt(0)
	v_pk_fma_f32 v[78:79], v[50:51], v[78:79], v[106:107]
	v_cvt_pk_bf16_f32 v113, v110, v111
	ds_bpermute_b32 v106, v203, v112
	ds_bpermute_b32 v107, v203, v113
	v_pk_fma_f32 v[80:81], v[52:53], v[80:81], v[108:109]
	v_pk_mul_f32 v[108:109], v[176:177], v[78:79]
	v_pk_mul_f32 v[110:111], v[174:175], v[80:81]
	global_store_dwordx4 v[124:125], v[78:81], off nt
	v_cvt_pk_bf16_f32 v108, v108, v109
	v_cvt_pk_bf16_f32 v109, v110, v111
	v_lshlrev_b32_e32 v110, 1, v120
	s_waitcnt lgkmcnt(0)
	v_add_u32_e32 v250, 0xfffff040, v110
	v_cndmask_b32_e64 v250, v110, v250, s[38:39]
	v_cndmask_b32_e64 v248, v118, v106, s[38:39]
	v_cndmask_b32_e64 v249, v119, v107, s[38:39]
	global_store_dwordx2 v250, v[248:249], s[20:21]
	v_cndmask_b32_e64 v246, v106, v118, s[38:39]
	v_cndmask_b32_e64 v247, v107, v119, s[38:39]
	s_waitcnt lgkmcnt(1)
	v_add_u32_e32 v106, 0x1040, v110
	v_cndmask_b32_e64 v106, v110, v106, s[36:37]
	global_store_dwordx2 v106, v[246:247], s[20:21]
	ds_bpermute_b32 v106, v203, v108
	s_waitcnt lgkmcnt(1)
	ds_bpermute_b32 v107, v203, v109
	v_add_u32_e32 v109, 0x1c000, v202
	v_lshlrev_b32_e32 v108, 1, v109
	s_waitcnt lgkmcnt(0)
	v_add_u32_e32 v250, 0xfffff040, v108
	v_cndmask_b32_e64 v250, v108, v250, s[38:39]
	v_cndmask_b32_e64 v248, v114, v106, s[38:39]
	v_cndmask_b32_e64 v249, v115, v107, s[38:39]
	global_store_dwordx2 v250, v[248:249], s[20:21]
	v_cndmask_b32_e64 v246, v106, v114, s[38:39]
	v_cndmask_b32_e64 v247, v107, v115, s[38:39]
	v_mul_f32_e32 v75, v75, v75
	v_fmac_f32_e32 v75, v74, v74
	v_mul_f32_e32 v74, v77, v77
	v_mul_f32_e32 v85, v85, v85
	v_fmac_f32_e32 v74, v76, v76
	v_mul_f32_e32 v83, v83, v83
	v_fmac_f32_e32 v85, v84, v84
	v_mul_f32_e32 v84, v87, v87
	v_mul_f32_e32 v87, v89, v89
	v_add_f32_e32 v74, v75, v74
	v_mul_f32_e32 v75, v79, v79
	v_mul_f32_e32 v76, v81, v81
	v_fmac_f32_e32 v87, v88, v88
	v_fmac_f32_e32 v75, v78, v78
	v_fmac_f32_e32 v76, v80, v80
	v_fmac_f32_e32 v83, v82, v82
	v_fmac_f32_e32 v84, v86, v86
	v_add_f32_e32 v75, v75, v76
	v_add_f32_e32 v76, v83, v85
	v_add_f32_e32 v77, v84, v87
	v_add_f32_e32 v74, v76, v74
	v_add_f32_e32 v75, v77, v75
	s_nop 1
	v_mov_b32_dpp v76, v74 quad_perm:[1,0,3,2] row_mask:0xf bank_mask:0xf
	s_nop 1
	v_mov_b32_dpp v77, v75 quad_perm:[1,0,3,2] row_mask:0xf bank_mask:0xf
	s_waitcnt lgkmcnt(1)
	v_add_f32_e32 v74, v74, v76
	s_waitcnt lgkmcnt(0)
	v_add_f32_e32 v77, v75, v77
	s_nop 1
	v_mov_b32_dpp v76, v74 quad_perm:[2,3,0,1] row_mask:0xf bank_mask:0xf
	s_nop 1
	v_mov_b32_dpp v78, v77 quad_perm:[2,3,0,1] row_mask:0xf bank_mask:0xf
	s_waitcnt lgkmcnt(1)
	v_add_f32_e32 v74, v74, v76
	s_waitcnt lgkmcnt(0)
	v_add_f32_e32 v76, v77, v78
	s_nop 1
	v_mov_b32_dpp v75, v74 row_half_mirror row_mask:0xf bank_mask:0xf
	s_nop 1
	v_mov_b32_dpp v77, v76 row_half_mirror row_mask:0xf bank_mask:0xf
	v_add_u32_e32 v78, 0x1040, v108
	v_cndmask_b32_e64 v78, v108, v78, s[36:37]
	global_store_dwordx2 v78, v[246:247], s[20:21]
	s_and_saveexec_b64 s[24:25], s[40:41]
	s_cbranch_execz .LBB0_2809
; #define LAS __attribute__((address_space(3)))
; #define ERN_EOFF(q, m) (eb + (unsigned)((((q) & 1) * HALF + (m) * 16) * DM + ERN_COL((q) >> 1)))
;     __device__ __forceinline__ void operator()(const f32x4 (&acc)[2][2][4][2], const Unit& u, int wr, int wc, int fr, int fq) const {
;     ...
;         for (int g = 0; g < 8; ++g) { const int ai = g >> 2, m = g & 3;
;             if (g + 1 < 8) ERN_LOADX(g + 1);
;             float sq0 = 0.f, sq1 = 0.f; u32x2 hw[2][2];
; #pragma unroll
;             for (int bj = 0; bj < 2; ++bj) {
;                 *(LAS f32x4*)(st + wr_off) = acc[ai][bj][m][0]; *(LAS f32x4*)(st + wr_off + 64) = acc[ai][bj][m][1];
;                 const f32x4 a0 = *(const LAS f32x4*)(st + rd_off), a1 = *(const LAS f32x4*)(st + rd_off + 8 * 144);
;                 { const f32x4 xv = xb[g & 1][bj][0] + gv[bj] * a0; __builtin_nontemporal_store(xv, (f32x4*)((char*)xo + 4u * ERN_EOFF(g, bj, 0)));
;                   sq0 += (xv.x * xv.x + xv.y * xv.y) + (xv.z * xv.z + xv.w * xv.w);
;                   const f32x4 hv = xv * gsn[bj]; hw[bj][0].x = cvt_pk_bf16(hv.x, hv.y); hw[bj][0].y = cvt_pk_bf16(hv.z, hv.w); }
;                 { const f32x4 xv = xb[g & 1][bj][1] + gv[bj] * a1; __builtin_nontemporal_store(xv, (f32x4*)((char*)xo + 4u * ERN_EOFF(g, bj, 1)));
;                   sq1 += (xv.x * xv.x + xv.y * xv.y) + (xv.z * xv.z + xv.w * xv.w);
;                   const f32x4 hv = xv * gsn[bj]; hw[bj][1].x = cvt_pk_bf16(hv.x, hv.y); hw[bj][1].y = cvt_pk_bf16(hv.z, hv.w); }
;             }
;             if (!NOH && !PLAIN) {
; #pragma unroll
;                 for (int rh = 0; rh < 2; ++rh) { u32x2 rv; rv.x = __shfl_xor(hw[1][rh].x, 8); rv.y = __shfl_xor(hw[1][rh].y, 8);
;                     const unsigned e0 = ERN_EOFF(g, 0, rh);
;                     const unsigned ee = odd ? (e0 - DM + 32) : e0, eo2 = odd ? e0 : (e0 + DM + 32);
;                     *(u32x2*)((char*)ho + 2u * ee) = odd ? rv : hw[0][rh];
;                     *(u32x2*)((char*)ho + 2u * eo2) = odd ? hw[0][rh] : rv; }
;             }
;             if (!PLAIN) { sq0 += __shfl_xor(sq0, 1); sq0 += __shfl_xor(sq0, 2); sq0 += __shfl_xor(sq0, 4);
;             sq1 += __shfl_xor(sq1, 1); sq1 += __shfl_xor(sq1, 2); sq1 += __shfl_xor(sq1, 4); }
;             if (!PLAIN && pc == 0) { sst[g * 16 + rr] = sq0; sst[g * 16 + 8 + rr] = sq1; }
	s_waitcnt lgkmcnt(1)
	v_add_f32_e32 v74, v74, v75
	s_waitcnt lgkmcnt(0)
	v_add_f32_e32 v75, v76, v77
	ds_write2_b32 v194, v74, v75 offset0:48 offset1:56
.LBB0_2809:
	s_or_b64 exec, exec, s[24:25]
	v_lshl_add_u64 v[112:113], s[22:23], 0, v[162:163]
	v_add_u32_e32 v162, 0x120000, v205
	v_add_u32_e32 v108, 0x120080, v205
	v_add_u32_e32 v110, 0x130000, v205
	global_load_dwordx4 v[86:89], v162, s[22:23]
	global_load_dwordx4 v[82:85], v110, s[22:23]
	v_add_u32_e32 v106, 0x130080, v205
	global_load_dwordx4 v[78:81], v108, s[22:23]
	s_waitcnt lgkmcnt(0)
	global_load_dwordx4 v[74:77], v106, s[22:23]
	ds_write_b128 v200, v[70:73]
	ds_write_b128 v200, v[66:69] offset:64
	ds_read_b128 v[66:69], v201
	ds_read_b128 v[70:73], v201 offset:1152
	v_mov_b32_e32 v123, v163
	s_waitcnt vmcnt(13) lgkmcnt(1)
	v_pk_fma_f32 v[68:69], v[56:57], v[68:69], v[104:105]
	v_add_u32_e32 v104, 0x40000, v202
	v_pk_fma_f32 v[66:67], v[54:55], v[66:67], v[102:103]
	v_lshlrev_b32_e32 v102, 2, v104
	s_waitcnt vmcnt(12) lgkmcnt(0)
	v_pk_fma_f32 v[72:73], v[56:57], v[72:73], v[100:101]
	v_add_u32_e32 v100, 0x44000, v202
	global_store_dwordx4 v102, v[66:69], s[22:23] nt
	v_pk_mul_f32 v[102:103], v[180:181], v[66:67]
	v_pk_fma_f32 v[70:71], v[54:55], v[70:71], v[98:99]
	v_lshlrev_b32_e32 v98, 2, v100
	v_pk_mul_f32 v[114:115], v[178:179], v[68:69]
	v_cvt_pk_bf16_f32 v102, v102, v103
	s_nop 0
	v_cvt_pk_bf16_f32 v103, v114, v115
	global_store_dwordx4 v98, v[70:73], s[22:23] nt
	v_pk_mul_f32 v[98:99], v[180:181], v[70:71]
	v_pk_mul_f32 v[114:115], v[178:179], v[72:73]
	v_cvt_pk_bf16_f32 v98, v98, v99
	s_nop 0
	v_cvt_pk_bf16_f32 v99, v114, v115
	ds_write_b128 v200, v[62:65]
	ds_write_b128 v200, v[58:61] offset:64
	ds_read_b128 v[58:61], v201
	ds_read_b128 v[62:65], v201 offset:1152
	v_lshl_add_u64 v[114:115], s[22:23], 0, v[122:123]
	s_waitcnt vmcnt(13) lgkmcnt(1)
	v_pk_fma_f32 v[58:59], v[50:51], v[58:59], v[94:95]
	v_pk_fma_f32 v[60:61], v[52:53], v[60:61], v[96:97]
	v_pk_mul_f32 v[96:97], v[176:177], v[58:59]
	global_store_dwordx4 v[112:113], v[58:61], off nt
	v_pk_mul_f32 v[94:95], v[174:175], v[60:61]
	v_cvt_pk_bf16_f32 v96, v96, v97
	s_waitcnt vmcnt(13) lgkmcnt(0)
	v_pk_fma_f32 v[62:63], v[50:51], v[62:63], v[90:91]
	v_cvt_pk_bf16_f32 v97, v94, v95
	ds_bpermute_b32 v90, v203, v96
	ds_bpermute_b32 v91, v203, v97
	v_pk_fma_f32 v[64:65], v[52:53], v[64:65], v[92:93]
	v_pk_mul_f32 v[92:93], v[176:177], v[62:63]
	v_pk_mul_f32 v[94:95], v[174:175], v[64:65]
	global_store_dwordx4 v[114:115], v[62:65], off nt
	v_cvt_pk_bf16_f32 v92, v92, v93
	v_cvt_pk_bf16_f32 v93, v94, v95
	v_lshlrev_b32_e32 v94, 1, v104
	s_waitcnt lgkmcnt(0)
	v_add_u32_e32 v250, 0xfffff040, v94
	v_cndmask_b32_e64 v250, v94, v250, s[38:39]
	v_cndmask_b32_e64 v248, v102, v90, s[38:39]
	v_cndmask_b32_e64 v249, v103, v91, s[38:39]
	global_store_dwordx2 v250, v[248:249], s[20:21]
	v_cndmask_b32_e64 v246, v90, v102, s[38:39]
	v_cndmask_b32_e64 v247, v91, v103, s[38:39]
	s_waitcnt lgkmcnt(1)
	v_add_u32_e32 v90, 0x1040, v94
	v_cndmask_b32_e64 v90, v94, v90, s[36:37]
	global_store_dwordx2 v90, v[246:247], s[20:21]
	ds_bpermute_b32 v90, v203, v92
	s_waitcnt lgkmcnt(1)
	ds_bpermute_b32 v91, v203, v93
	v_lshlrev_b32_e32 v92, 1, v100
	s_waitcnt lgkmcnt(0)
	v_add_u32_e32 v250, 0xfffff040, v92
	v_cndmask_b32_e64 v250, v92, v250, s[38:39]
	v_cndmask_b32_e64 v248, v98, v90, s[38:39]
	v_cndmask_b32_e64 v249, v99, v91, s[38:39]
	global_store_dwordx2 v250, v[248:249], s[20:21]
	v_cndmask_b32_e64 v246, v90, v98, s[38:39]
	v_cndmask_b32_e64 v247, v91, v99, s[38:39]
	v_mul_f32_e32 v59, v59, v59
	v_fmac_f32_e32 v59, v58, v58
	v_mul_f32_e32 v58, v61, v61
	v_mul_f32_e32 v69, v69, v69
	v_fmac_f32_e32 v58, v60, v60
	v_mul_f32_e32 v67, v67, v67
	v_fmac_f32_e32 v69, v68, v68
	v_mul_f32_e32 v68, v71, v71
	v_mul_f32_e32 v71, v73, v73
	v_add_f32_e32 v58, v59, v58
	v_mul_f32_e32 v59, v63, v63
	v_mul_f32_e32 v60, v65, v65
	v_fmac_f32_e32 v71, v72, v72
	v_fmac_f32_e32 v59, v62, v62
	v_fmac_f32_e32 v60, v64, v64
	v_fmac_f32_e32 v67, v66, v66
	v_fmac_f32_e32 v68, v70, v70
	v_add_f32_e32 v59, v59, v60
	v_add_f32_e32 v60, v67, v69
	v_add_f32_e32 v61, v68, v71
	v_add_f32_e32 v58, v60, v58
	v_add_f32_e32 v59, v61, v59
	s_nop 1
	v_mov_b32_dpp v60, v58 quad_perm:[1,0,3,2] row_mask:0xf bank_mask:0xf
	s_nop 1
	v_mov_b32_dpp v61, v59 quad_perm:[1,0,3,2] row_mask:0xf bank_mask:0xf
	s_waitcnt lgkmcnt(1)
	v_add_f32_e32 v58, v58, v60
	s_waitcnt lgkmcnt(0)
	v_add_f32_e32 v61, v59, v61
	s_nop 1
	v_mov_b32_dpp v60, v58 quad_perm:[2,3,0,1] row_mask:0xf bank_mask:0xf
	s_nop 1
	v_mov_b32_dpp v62, v61 quad_perm:[2,3,0,1] row_mask:0xf bank_mask:0xf
	s_waitcnt lgkmcnt(1)
	v_add_f32_e32 v58, v58, v60
	s_waitcnt lgkmcnt(0)
	v_add_f32_e32 v60, v61, v62
	s_nop 1
	v_mov_b32_dpp v59, v58 row_half_mirror row_mask:0xf bank_mask:0xf
	s_nop 1
	v_mov_b32_dpp v61, v60 row_half_mirror row_mask:0xf bank_mask:0xf
	v_add_u32_e32 v62, 0x1040, v92
	v_cndmask_b32_e64 v62, v92, v62, s[36:37]
	global_store_dwordx2 v62, v[246:247], s[20:21]
	s_and_saveexec_b64 s[24:25], s[40:41]
	s_cbranch_execz .LBB0_2819
	s_waitcnt lgkmcnt(1)
	v_add_f32_e32 v58, v58, v59
	s_waitcnt lgkmcnt(0)
	v_add_f32_e32 v59, v60, v61
	ds_write2_b32 v194, v58, v59 offset0:64 offset1:72
; #define LAS __attribute__((address_space(3)))
; #define ERN_EOFF(q, m) (eb + (unsigned)((((q) & 1) * HALF + (m) * 16) * DM + ERN_COL((q) >> 1)))
;     __device__ __forceinline__ void operator()(const f32x4 (&acc)[2][2][4][2], const Unit& u, int wr, int wc, int fr, int fq) const {
;     ...
;         for (int g = 0; g < 8; ++g) { const int ai = g >> 2, m = g & 3;
;             if (g + 1 < 8) ERN_LOADX(g + 1);
;             float sq0 = 0.f, sq1 = 0.f; u32x2 hw[2][2];
; #pragma unroll
;             for (int bj = 0; bj < 2; ++bj) {
;                 *(LAS f32x4*)(st + wr_off) = acc[ai][bj][m][0]; *(LAS f32x4*)(st + wr_off + 64) = acc[ai][bj][m][1];
;                 const f32x4 a0 = *(const LAS f32x4*)(st + rd_off), a1 = *(const LAS f32x4*)(st + rd_off + 8 * 144);
;                 { const f32x4 xv = xb[g & 1][bj][0] + gv[bj] * a0; __builtin_nontemporal_store(xv, (f32x4*)((char*)xo + 4u * ERN_EOFF(g, bj, 0)));
;                   sq0 += (xv.x * xv.x + xv.y * xv.y) + (xv.z * xv.z + xv.w * xv.w);
;                   const f32x4 hv = xv * gsn[bj]; hw[bj][0].x = cvt_pk_bf16(hv.x, hv.y); hw[bj][0].y = cvt_pk_bf16(hv.z, hv.w); }
;                 { const f32x4 xv = xb[g & 1][bj][1] + gv[bj] * a1; __builtin_nontemporal_store(xv, (f32x4*)((char*)xo + 4u * ERN_EOFF(g, bj, 1)));
;                   sq1 += (xv.x * xv.x + xv.y * xv.y) + (xv.z * xv.z + xv.w * xv.w);
;                   const f32x4 hv = xv * gsn[bj]; hw[bj][1].x = cvt_pk_bf16(hv.x, hv.y); hw[bj][1].y = cvt_pk_bf16(hv.z, hv.w); }
;             }
;             if (!NOH && !PLAIN) {
; #pragma unroll
;                 for (int rh = 0; rh < 2; ++rh) { u32x2 rv; rv.x = __shfl_xor(hw[1][rh].x, 8); rv.y = __shfl_xor(hw[1][rh].y, 8);
;                     const unsigned e0 = ERN_EOFF(g, 0, rh);
;                     const unsigned ee = odd ? (e0 - DM + 32) : e0, eo2 = odd ? e0 : (e0 + DM + 32);
;                     *(u32x2*)((char*)ho + 2u * ee) = odd ? rv : hw[0][rh];
;                     *(u32x2*)((char*)ho + 2u * eo2) = odd ? hw[0][rh] : rv; }
;             }
;             if (!PLAIN) { sq0 += __shfl_xor(sq0, 1); sq0 += __shfl_xor(sq0, 2); sq0 += __shfl_xor(sq0, 4);
;             sq1 += __shfl_xor(sq1, 1); sq1 += __shfl_xor(sq1, 2); sq1 += __shfl_xor(sq1, 4); }
;             if (!PLAIN && pc == 0) { sst[g * 16 + rr] = sq0; sst[g * 16 + 8 + rr] = sq1; }
.LBB0_2819:
	s_or_b64 exec, exec, s[24:25]
	v_lshl_add_u64 v[96:97], s[22:23], 0, v[162:163]
	v_add_u32_e32 v162, 0x140000, v205
	v_add_u32_e32 v92, 0x140080, v205
	v_add_u32_e32 v94, 0x150000, v205
	global_load_dwordx4 v[70:73], v162, s[22:23]
	global_load_dwordx4 v[66:69], v94, s[22:23]
	v_add_u32_e32 v90, 0x150080, v205
	global_load_dwordx4 v[62:65], v92, s[22:23]
	s_waitcnt lgkmcnt(0)
	global_load_dwordx4 v[58:61], v90, s[22:23]
	ds_write_b128 v200, v[46:49]
	ds_write_b128 v200, v[42:45] offset:64
	ds_read_b128 v[42:45], v201
	ds_read_b128 v[46:49], v201 offset:1152
	v_mov_b32_e32 v111, v163
	v_lshl_add_u64 v[98:99], s[22:23], 0, v[110:111]
	v_mov_b32_e32 v109, v163
	s_waitcnt vmcnt(13) lgkmcnt(1)
	v_pk_fma_f32 v[42:43], v[54:55], v[42:43], v[86:87]
	s_waitcnt vmcnt(12) lgkmcnt(0)
	v_pk_fma_f32 v[46:47], v[54:55], v[46:47], v[82:83]
	v_pk_fma_f32 v[44:45], v[56:57], v[44:45], v[88:89]
	v_pk_mul_f32 v[86:87], v[180:181], v[42:43]
	v_pk_fma_f32 v[48:49], v[56:57], v[48:49], v[84:85]
	v_pk_mul_f32 v[82:83], v[180:181], v[46:47]
	global_store_dwordx4 v[96:97], v[42:45], off nt
	v_pk_mul_f32 v[88:89], v[178:179], v[44:45]
	v_cvt_pk_bf16_f32 v86, v86, v87
	v_pk_mul_f32 v[84:85], v[178:179], v[48:49]
	v_cvt_pk_bf16_f32 v87, v88, v89
	global_store_dwordx4 v[98:99], v[46:49], off nt
	v_cvt_pk_bf16_f32 v82, v82, v83
	v_cvt_pk_bf16_f32 v83, v84, v85
	ds_write_b128 v200, v[38:41]
	ds_write_b128 v200, v[34:37] offset:64
	ds_read_b128 v[34:37], v201
	ds_read_b128 v[38:41], v201 offset:1152
	v_lshl_add_u64 v[84:85], s[22:23], 0, v[108:109]
	v_mov_b32_e32 v107, v163
	v_lshl_add_u64 v[88:89], s[22:23], 0, v[106:107]
	s_waitcnt vmcnt(13) lgkmcnt(1)
	v_pk_fma_f32 v[34:35], v[50:51], v[34:35], v[78:79]
	v_pk_fma_f32 v[36:37], v[52:53], v[36:37], v[80:81]
	v_pk_mul_f32 v[80:81], v[176:177], v[34:35]
	global_store_dwordx4 v[84:85], v[34:37], off nt
	v_pk_mul_f32 v[78:79], v[174:175], v[36:37]
	v_cvt_pk_bf16_f32 v80, v80, v81
	s_waitcnt vmcnt(13) lgkmcnt(0)
	v_pk_fma_f32 v[38:39], v[50:51], v[38:39], v[74:75]
	v_cvt_pk_bf16_f32 v81, v78, v79
	ds_bpermute_b32 v74, v203, v80
	ds_bpermute_b32 v75, v203, v81
	v_pk_fma_f32 v[40:41], v[52:53], v[40:41], v[76:77]
	v_pk_mul_f32 v[76:77], v[176:177], v[38:39]
	v_pk_mul_f32 v[78:79], v[174:175], v[40:41]
	global_store_dwordx4 v[88:89], v[38:41], off nt
	v_cvt_pk_bf16_f32 v76, v76, v77
	v_cvt_pk_bf16_f32 v77, v78, v79
	v_add_u32_e32 v79, 0x48000, v202
	v_lshlrev_b32_e32 v78, 1, v79
	s_waitcnt lgkmcnt(0)
	v_add_u32_e32 v250, 0xfffff040, v78
	v_cndmask_b32_e64 v250, v78, v250, s[38:39]
	v_cndmask_b32_e64 v248, v86, v74, s[38:39]
	v_cndmask_b32_e64 v249, v87, v75, s[38:39]
	global_store_dwordx2 v250, v[248:249], s[20:21]
	v_cndmask_b32_e64 v246, v74, v86, s[38:39]
	v_cndmask_b32_e64 v247, v75, v87, s[38:39]
	s_waitcnt lgkmcnt(1)
	v_add_u32_e32 v74, 0x1040, v78
	v_cndmask_b32_e64 v74, v78, v74, s[36:37]
	global_store_dwordx2 v74, v[246:247], s[20:21]
	ds_bpermute_b32 v74, v203, v76
	s_waitcnt lgkmcnt(1)
	ds_bpermute_b32 v75, v203, v77
	v_add_u32_e32 v77, 0x4c000, v202
	v_lshlrev_b32_e32 v76, 1, v77
	s_waitcnt lgkmcnt(0)
	v_add_u32_e32 v250, 0xfffff040, v76
	v_cndmask_b32_e64 v250, v76, v250, s[38:39]
	v_cndmask_b32_e64 v248, v82, v74, s[38:39]
	v_cndmask_b32_e64 v249, v83, v75, s[38:39]
	global_store_dwordx2 v250, v[248:249], s[20:21]
	v_cndmask_b32_e64 v246, v74, v82, s[38:39]
	v_cndmask_b32_e64 v247, v75, v83, s[38:39]
	v_mul_f32_e32 v35, v35, v35
	v_fmac_f32_e32 v35, v34, v34
	v_mul_f32_e32 v34, v37, v37
	v_mul_f32_e32 v45, v45, v45
	v_fmac_f32_e32 v34, v36, v36
	v_mul_f32_e32 v43, v43, v43
	v_fmac_f32_e32 v45, v44, v44
	v_mul_f32_e32 v44, v47, v47
	v_mul_f32_e32 v47, v49, v49
	v_add_f32_e32 v34, v35, v34
	v_mul_f32_e32 v35, v39, v39
	v_mul_f32_e32 v36, v41, v41
	v_fmac_f32_e32 v47, v48, v48
	v_fmac_f32_e32 v35, v38, v38
	v_fmac_f32_e32 v36, v40, v40
	v_fmac_f32_e32 v43, v42, v42
	v_fmac_f32_e32 v44, v46, v46
	v_add_f32_e32 v35, v35, v36
	v_add_f32_e32 v36, v43, v45
	v_add_f32_e32 v37, v44, v47
	v_add_f32_e32 v34, v36, v34
	v_add_f32_e32 v35, v37, v35
	s_nop 1
	v_mov_b32_dpp v36, v34 quad_perm:[1,0,3,2] row_mask:0xf bank_mask:0xf
	s_nop 1
	v_mov_b32_dpp v37, v35 quad_perm:[1,0,3,2] row_mask:0xf bank_mask:0xf
	s_waitcnt lgkmcnt(1)
	v_add_f32_e32 v34, v34, v36
	s_waitcnt lgkmcnt(0)
	v_add_f32_e32 v37, v35, v37
	s_nop 1
	v_mov_b32_dpp v36, v34 quad_perm:[2,3,0,1] row_mask:0xf bank_mask:0xf
	s_nop 1
	v_mov_b32_dpp v38, v37 quad_perm:[2,3,0,1] row_mask:0xf bank_mask:0xf
	s_waitcnt lgkmcnt(1)
	v_add_f32_e32 v34, v34, v36
	s_waitcnt lgkmcnt(0)
	v_add_f32_e32 v36, v37, v38
	s_nop 1
	v_mov_b32_dpp v35, v34 row_half_mirror row_mask:0xf bank_mask:0xf
	s_nop 1
	v_mov_b32_dpp v37, v36 row_half_mirror row_mask:0xf bank_mask:0xf
	v_add_u32_e32 v38, 0x1040, v76
	v_cndmask_b32_e64 v38, v76, v38, s[36:37]
	global_store_dwordx2 v38, v[246:247], s[20:21]
	s_and_saveexec_b64 s[24:25], s[40:41]
	s_cbranch_execz .LBB0_2829
	s_waitcnt lgkmcnt(1)
	v_add_f32_e32 v34, v34, v35
	s_waitcnt lgkmcnt(0)
	v_add_f32_e32 v35, v36, v37
	ds_write2_b32 v194, v34, v35 offset0:80 offset1:88
; #define LAS __attribute__((address_space(3)))
; #define ERN_EOFF(q, m) (eb + (unsigned)((((q) & 1) * HALF + (m) * 16) * DM + ERN_COL((q) >> 1)))
;     __device__ __forceinline__ void operator()(const f32x4 (&acc)[2][2][4][2], const Unit& u, int wr, int wc, int fr, int fq) const {
;     ...
;         for (int g = 0; g < 8; ++g) { const int ai = g >> 2, m = g & 3;
;             if (g + 1 < 8) ERN_LOADX(g + 1);
;             float sq0 = 0.f, sq1 = 0.f; u32x2 hw[2][2];
; #pragma unroll
;             for (int bj = 0; bj < 2; ++bj) {
;                 *(LAS f32x4*)(st + wr_off) = acc[ai][bj][m][0]; *(LAS f32x4*)(st + wr_off + 64) = acc[ai][bj][m][1];
;                 const f32x4 a0 = *(const LAS f32x4*)(st + rd_off), a1 = *(const LAS f32x4*)(st + rd_off + 8 * 144);
;                 { const f32x4 xv = xb[g & 1][bj][0] + gv[bj] * a0; __builtin_nontemporal_store(xv, (f32x4*)((char*)xo + 4u * ERN_EOFF(g, bj, 0)));
;                   sq0 += (xv.x * xv.x + xv.y * xv.y) + (xv.z * xv.z + xv.w * xv.w);
;                   const f32x4 hv = xv * gsn[bj]; hw[bj][0].x = cvt_pk_bf16(hv.x, hv.y); hw[bj][0].y = cvt_pk_bf16(hv.z, hv.w); }
;                 { const f32x4 xv = xb[g & 1][bj][1] + gv[bj] * a1; __builtin_nontemporal_store(xv, (f32x4*)((char*)xo + 4u * ERN_EOFF(g, bj, 1)));
;                   sq1 += (xv.x * xv.x + xv.y * xv.y) + (xv.z * xv.z + xv.w * xv.w);
;                   const f32x4 hv = xv * gsn[bj]; hw[bj][1].x = cvt_pk_bf16(hv.x, hv.y); hw[bj][1].y = cvt_pk_bf16(hv.z, hv.w); }
;             }
;             if (!NOH && !PLAIN) {
; #pragma unroll
;                 for (int rh = 0; rh < 2; ++rh) { u32x2 rv; rv.x = __shfl_xor(hw[1][rh].x, 8); rv.y = __shfl_xor(hw[1][rh].y, 8);
;                     const unsigned e0 = ERN_EOFF(g, 0, rh);
;                     const unsigned ee = odd ? (e0 - DM + 32) : e0, eo2 = odd ? e0 : (e0 + DM + 32);
;                     *(u32x2*)((char*)ho + 2u * ee) = odd ? rv : hw[0][rh];
;                     *(u32x2*)((char*)ho + 2u * eo2) = odd ? hw[0][rh] : rv; }
;             }
;             if (!PLAIN) { sq0 += __shfl_xor(sq0, 1); sq0 += __shfl_xor(sq0, 2); sq0 += __shfl_xor(sq0, 4);
;             sq1 += __shfl_xor(sq1, 1); sq1 += __shfl_xor(sq1, 2); sq1 += __shfl_xor(sq1, 4); }
;             if (!PLAIN && pc == 0) { sst[g * 16 + rr] = sq0; sst[g * 16 + 8 + rr] = sq1; }
.LBB0_2829:
	s_or_b64 exec, exec, s[24:25]
	v_lshl_add_u64 v[80:81], s[22:23], 0, v[162:163]
	v_add_u32_e32 v162, 0x160000, v205
	v_add_u32_e32 v76, 0x160080, v205
	v_add_u32_e32 v78, 0x170000, v205
	global_load_dwordx4 v[46:49], v162, s[22:23]
	global_load_dwordx4 v[42:45], v78, s[22:23]
	v_add_u32_e32 v74, 0x170080, v205
	global_load_dwordx4 v[38:41], v76, s[22:23]
	s_waitcnt lgkmcnt(0)
	global_load_dwordx4 v[34:37], v74, s[22:23]
	ds_write_b128 v200, v[30:33]
	ds_write_b128 v200, v[26:29] offset:64
	ds_read_b128 v[26:29], v201
	ds_read_b128 v[30:33], v201 offset:1152
	v_mov_b32_e32 v95, v163
	v_lshl_add_u64 v[82:83], s[22:23], 0, v[94:95]
	v_mov_b32_e32 v93, v163
	s_waitcnt vmcnt(13) lgkmcnt(1)
	v_pk_fma_f32 v[26:27], v[54:55], v[26:27], v[70:71]
	s_waitcnt vmcnt(12) lgkmcnt(0)
	v_pk_fma_f32 v[30:31], v[54:55], v[30:31], v[66:67]
	v_pk_fma_f32 v[28:29], v[56:57], v[28:29], v[72:73]
	v_pk_mul_f32 v[70:71], v[180:181], v[26:27]
	v_pk_fma_f32 v[32:33], v[56:57], v[32:33], v[68:69]
	v_pk_mul_f32 v[66:67], v[180:181], v[30:31]
	global_store_dwordx4 v[80:81], v[26:29], off nt
	v_pk_mul_f32 v[72:73], v[178:179], v[28:29]
	v_cvt_pk_bf16_f32 v70, v70, v71
	v_pk_mul_f32 v[68:69], v[178:179], v[32:33]
	v_cvt_pk_bf16_f32 v71, v72, v73
	global_store_dwordx4 v[82:83], v[30:33], off nt
	v_cvt_pk_bf16_f32 v66, v66, v67
	v_cvt_pk_bf16_f32 v67, v68, v69
	ds_write_b128 v200, v[22:25]
	ds_write_b128 v200, v[18:21] offset:64
	ds_read_b128 v[18:21], v201
	ds_read_b128 v[22:25], v201 offset:1152
	v_lshl_add_u64 v[68:69], s[22:23], 0, v[92:93]
	v_mov_b32_e32 v91, v163
	v_lshl_add_u64 v[72:73], s[22:23], 0, v[90:91]
	s_waitcnt vmcnt(13) lgkmcnt(1)
	v_pk_fma_f32 v[18:19], v[50:51], v[18:19], v[62:63]
	v_pk_fma_f32 v[20:21], v[52:53], v[20:21], v[64:65]
	v_pk_mul_f32 v[64:65], v[176:177], v[18:19]
	global_store_dwordx4 v[68:69], v[18:21], off nt
	v_pk_mul_f32 v[62:63], v[174:175], v[20:21]
	v_cvt_pk_bf16_f32 v64, v64, v65
	s_waitcnt vmcnt(13) lgkmcnt(0)
	v_pk_fma_f32 v[22:23], v[50:51], v[22:23], v[58:59]
	v_cvt_pk_bf16_f32 v65, v62, v63
	ds_bpermute_b32 v58, v203, v64
	ds_bpermute_b32 v59, v203, v65
	v_pk_fma_f32 v[24:25], v[52:53], v[24:25], v[60:61]
	v_pk_mul_f32 v[60:61], v[176:177], v[22:23]
	v_pk_mul_f32 v[62:63], v[174:175], v[24:25]
	global_store_dwordx4 v[72:73], v[22:25], off nt
	v_cvt_pk_bf16_f32 v60, v60, v61
	v_cvt_pk_bf16_f32 v61, v62, v63
	v_add_u32_e32 v63, 0x50000, v202
	v_lshlrev_b32_e32 v62, 1, v63
	s_waitcnt lgkmcnt(0)
	v_add_u32_e32 v250, 0xfffff040, v62
	v_cndmask_b32_e64 v250, v62, v250, s[38:39]
	v_cndmask_b32_e64 v248, v70, v58, s[38:39]
	v_cndmask_b32_e64 v249, v71, v59, s[38:39]
	global_store_dwordx2 v250, v[248:249], s[20:21]
	v_cndmask_b32_e64 v246, v58, v70, s[38:39]
	v_cndmask_b32_e64 v247, v59, v71, s[38:39]
	s_waitcnt lgkmcnt(1)
	v_add_u32_e32 v58, 0x1040, v62
	v_cndmask_b32_e64 v58, v62, v58, s[36:37]
	global_store_dwordx2 v58, v[246:247], s[20:21]
	ds_bpermute_b32 v58, v203, v60
	s_waitcnt lgkmcnt(1)
	ds_bpermute_b32 v59, v203, v61
	v_add_u32_e32 v61, 0x54000, v202
	v_lshlrev_b32_e32 v60, 1, v61
	s_waitcnt lgkmcnt(0)
	v_add_u32_e32 v250, 0xfffff040, v60
	v_cndmask_b32_e64 v250, v60, v250, s[38:39]
	v_cndmask_b32_e64 v248, v66, v58, s[38:39]
	v_cndmask_b32_e64 v249, v67, v59, s[38:39]
	global_store_dwordx2 v250, v[248:249], s[20:21]
	v_cndmask_b32_e64 v246, v58, v66, s[38:39]
	v_cndmask_b32_e64 v247, v59, v67, s[38:39]
	v_mul_f32_e32 v19, v19, v19
	v_fmac_f32_e32 v19, v18, v18
	v_mul_f32_e32 v18, v21, v21
	v_mul_f32_e32 v29, v29, v29
	v_fmac_f32_e32 v18, v20, v20
	v_mul_f32_e32 v27, v27, v27
	v_fmac_f32_e32 v29, v28, v28
	v_mul_f32_e32 v28, v31, v31
	v_mul_f32_e32 v31, v33, v33
	v_add_f32_e32 v18, v19, v18
	v_mul_f32_e32 v19, v23, v23
	v_mul_f32_e32 v20, v25, v25
	v_fmac_f32_e32 v31, v32, v32
	v_fmac_f32_e32 v19, v22, v22
	v_fmac_f32_e32 v20, v24, v24
	v_fmac_f32_e32 v27, v26, v26
	v_fmac_f32_e32 v28, v30, v30
	v_add_f32_e32 v19, v19, v20
	v_add_f32_e32 v20, v27, v29
	v_add_f32_e32 v21, v28, v31
	v_add_f32_e32 v18, v20, v18
	v_add_f32_e32 v19, v21, v19
	s_nop 1
	v_mov_b32_dpp v20, v18 quad_perm:[1,0,3,2] row_mask:0xf bank_mask:0xf
	s_nop 1
	v_mov_b32_dpp v21, v19 quad_perm:[1,0,3,2] row_mask:0xf bank_mask:0xf
	s_waitcnt lgkmcnt(1)
	v_add_f32_e32 v18, v18, v20
	s_waitcnt lgkmcnt(0)
	v_add_f32_e32 v21, v19, v21
	s_nop 1
	v_mov_b32_dpp v20, v18 quad_perm:[2,3,0,1] row_mask:0xf bank_mask:0xf
	s_nop 1
	v_mov_b32_dpp v22, v21 quad_perm:[2,3,0,1] row_mask:0xf bank_mask:0xf
	s_waitcnt lgkmcnt(1)
	v_add_f32_e32 v18, v18, v20
	s_waitcnt lgkmcnt(0)
	v_add_f32_e32 v20, v21, v22
	s_nop 1
	v_mov_b32_dpp v19, v18 row_half_mirror row_mask:0xf bank_mask:0xf
	s_nop 1
	v_mov_b32_dpp v21, v20 row_half_mirror row_mask:0xf bank_mask:0xf
	v_add_u32_e32 v22, 0x1040, v60
	v_cndmask_b32_e64 v22, v60, v22, s[36:37]
	global_store_dwordx2 v22, v[246:247], s[20:21]
	s_and_saveexec_b64 s[24:25], s[40:41]
	s_cbranch_execz .LBB0_2839
	s_waitcnt lgkmcnt(1)
	v_add_f32_e32 v18, v18, v19
	s_waitcnt lgkmcnt(0)
	v_add_f32_e32 v19, v20, v21
	ds_write2_b32 v194, v18, v19 offset0:96 offset1:104
; #define LAS __attribute__((address_space(3)))
; #define ERN_EOFF(q, m) (eb + (unsigned)((((q) & 1) * HALF + (m) * 16) * DM + ERN_COL((q) >> 1)))
;     __device__ __forceinline__ void operator()(const f32x4 (&acc)[2][2][4][2], const Unit& u, int wr, int wc, int fr, int fq) const {
;     ...
;         for (int g = 0; g < 8; ++g) { const int ai = g >> 2, m = g & 3;
;             if (g + 1 < 8) ERN_LOADX(g + 1);
;             float sq0 = 0.f, sq1 = 0.f; u32x2 hw[2][2];
; #pragma unroll
;             for (int bj = 0; bj < 2; ++bj) {
;                 *(LAS f32x4*)(st + wr_off) = acc[ai][bj][m][0]; *(LAS f32x4*)(st + wr_off + 64) = acc[ai][bj][m][1];
;                 const f32x4 a0 = *(const LAS f32x4*)(st + rd_off), a1 = *(const LAS f32x4*)(st + rd_off + 8 * 144);
;                 { const f32x4 xv = xb[g & 1][bj][0] + gv[bj] * a0; __builtin_nontemporal_store(xv, (f32x4*)((char*)xo + 4u * ERN_EOFF(g, bj, 0)));
;                   sq0 += (xv.x * xv.x + xv.y * xv.y) + (xv.z * xv.z + xv.w * xv.w);
;                   const f32x4 hv = xv * gsn[bj]; hw[bj][0].x = cvt_pk_bf16(hv.x, hv.y); hw[bj][0].y = cvt_pk_bf16(hv.z, hv.w); }
;                 { const f32x4 xv = xb[g & 1][bj][1] + gv[bj] * a1; __builtin_nontemporal_store(xv, (f32x4*)((char*)xo + 4u * ERN_EOFF(g, bj, 1)));
;                   sq1 += (xv.x * xv.x + xv.y * xv.y) + (xv.z * xv.z + xv.w * xv.w);
;                   const f32x4 hv = xv * gsn[bj]; hw[bj][1].x = cvt_pk_bf16(hv.x, hv.y); hw[bj][1].y = cvt_pk_bf16(hv.z, hv.w); }
;             }
;             if (!NOH && !PLAIN) {
; #pragma unroll
;                 for (int rh = 0; rh < 2; ++rh) { u32x2 rv; rv.x = __shfl_xor(hw[1][rh].x, 8); rv.y = __shfl_xor(hw[1][rh].y, 8);
;                     const unsigned e0 = ERN_EOFF(g, 0, rh);
;                     const unsigned ee = odd ? (e0 - DM + 32) : e0, eo2 = odd ? e0 : (e0 + DM + 32);
;                     *(u32x2*)((char*)ho + 2u * ee) = odd ? rv : hw[0][rh];
;                     *(u32x2*)((char*)ho + 2u * eo2) = odd ? hw[0][rh] : rv; }
;             }
;             if (!PLAIN) { sq0 += __shfl_xor(sq0, 1); sq0 += __shfl_xor(sq0, 2); sq0 += __shfl_xor(sq0, 4);
;             sq1 += __shfl_xor(sq1, 1); sq1 += __shfl_xor(sq1, 2); sq1 += __shfl_xor(sq1, 4); }
;             if (!PLAIN && pc == 0) { sst[g * 16 + rr] = sq0; sst[g * 16 + 8 + rr] = sq1; }
.LBB0_2839:
	s_or_b64 exec, exec, s[24:25]
	ds_write_b128 v200, v[14:17]
	ds_write_b128 v200, v[10:13] offset:64
	ds_read_b128 v[10:13], v201
	ds_read_b128 v[14:17], v201 offset:1152
	s_waitcnt lgkmcnt(5)
	v_lshl_add_u64 v[18:19], s[22:23], 0, v[162:163]
	v_mov_b32_e32 v79, v163
	v_lshl_add_u64 v[22:23], s[22:23], 0, v[78:79]
	s_waitcnt vmcnt(9) lgkmcnt(1)
	v_pk_fma_f32 v[12:13], v[56:57], v[12:13], v[48:49]
	v_pk_fma_f32 v[10:11], v[54:55], v[10:11], v[46:47]
	global_store_dwordx4 v[18:19], v[10:13], off nt
	v_pk_mul_f32 v[18:19], v[178:179], v[12:13]
	v_pk_mul_f32 v[20:21], v[180:181], v[10:11]
	s_waitcnt vmcnt(9) lgkmcnt(0)
	v_pk_fma_f32 v[14:15], v[54:55], v[14:15], v[42:43]
	v_cvt_pk_bf16_f32 v20, v20, v21
	v_cvt_pk_bf16_f32 v21, v18, v19
	v_pk_fma_f32 v[16:17], v[56:57], v[16:17], v[44:45]
	v_pk_mul_f32 v[18:19], v[180:181], v[14:15]
	global_store_dwordx4 v[22:23], v[14:17], off nt
	v_pk_mul_f32 v[22:23], v[178:179], v[16:17]
	v_cvt_pk_bf16_f32 v18, v18, v19
	v_mov_b32_e32 v77, v163
	v_cvt_pk_bf16_f32 v19, v22, v23
	ds_write_b128 v200, v[6:9]
	ds_write_b128 v200, v[2:5] offset:64
	ds_read_b128 v[2:5], v201
	ds_read_b128 v[6:9], v201 offset:1152
	v_lshl_add_u64 v[22:23], s[22:23], 0, v[76:77]
	v_mov_b32_e32 v75, v163
	v_lshl_add_u64 v[24:25], s[22:23], 0, v[74:75]
	s_waitcnt vmcnt(9) lgkmcnt(1)
	v_pk_fma_f32 v[4:5], v[52:53], v[4:5], v[40:41]
	v_pk_fma_f32 v[2:3], v[50:51], v[2:3], v[38:39]
	global_store_dwordx4 v[22:23], v[2:5], off nt
	v_pk_mul_f32 v[22:23], v[174:175], v[4:5]
	v_pk_mul_f32 v[26:27], v[176:177], v[2:3]
	s_waitcnt vmcnt(9) lgkmcnt(0)
	v_pk_fma_f32 v[8:9], v[52:53], v[8:9], v[36:37]
	v_cvt_pk_bf16_f32 v28, v26, v27
	v_cvt_pk_bf16_f32 v23, v22, v23
	ds_bpermute_b32 v22, v203, v28
	ds_bpermute_b32 v23, v203, v23
	v_pk_fma_f32 v[6:7], v[50:51], v[6:7], v[34:35]
	global_store_dwordx4 v[24:25], v[6:9], off nt
	v_pk_mul_f32 v[26:27], v[174:175], v[8:9]
	v_pk_mul_f32 v[24:25], v[176:177], v[6:7]
	s_nop 0
	v_cvt_pk_bf16_f32 v24, v24, v25
	v_cvt_pk_bf16_f32 v25, v26, v27
	v_add_u32_e32 v27, 0x58000, v202
	v_lshlrev_b32_e32 v26, 1, v27
	s_waitcnt lgkmcnt(0)
	v_add_u32_e32 v250, 0xfffff040, v26
	v_cndmask_b32_e64 v250, v26, v250, s[38:39]
	v_cndmask_b32_e64 v248, v20, v22, s[38:39]
	v_cndmask_b32_e64 v249, v21, v23, s[38:39]
	global_store_dwordx2 v250, v[248:249], s[20:21]
	v_cndmask_b32_e64 v246, v22, v20, s[38:39]
	v_cndmask_b32_e64 v247, v23, v21, s[38:39]
	s_waitcnt lgkmcnt(1)
	v_add_u32_e32 v22, 0x1040, v26
	v_cndmask_b32_e64 v22, v26, v22, s[36:37]
	global_store_dwordx2 v22, v[246:247], s[20:21]
	ds_bpermute_b32 v20, v203, v24
	ds_bpermute_b32 v21, v203, v25
	s_waitcnt lgkmcnt(2)
	v_add_u32_e32 v23, 0x5c000, v202
	v_lshlrev_b32_e32 v22, 1, v23
	s_waitcnt lgkmcnt(0)
	v_add_u32_e32 v250, 0xfffff040, v22
	v_cndmask_b32_e64 v250, v22, v250, s[38:39]
	v_cndmask_b32_e64 v248, v18, v20, s[38:39]
	v_cndmask_b32_e64 v249, v19, v21, s[38:39]
	global_store_dwordx2 v250, v[248:249], s[20:21]
	v_cndmask_b32_e64 v246, v20, v18, s[38:39]
	v_cndmask_b32_e64 v247, v21, v19, s[38:39]
	v_mul_f32_e32 v3, v3, v3
	v_fmac_f32_e32 v3, v2, v2
	v_mul_f32_e32 v2, v5, v5
	v_mul_f32_e32 v13, v13, v13
	v_fmac_f32_e32 v2, v4, v4
	v_mul_f32_e32 v11, v11, v11
	v_fmac_f32_e32 v13, v12, v12
	v_mul_f32_e32 v12, v15, v15
	v_mul_f32_e32 v15, v17, v17
	v_add_f32_e32 v2, v3, v2
	v_mul_f32_e32 v3, v7, v7
	v_mul_f32_e32 v4, v9, v9
	v_fmac_f32_e32 v15, v16, v16
	v_fmac_f32_e32 v3, v6, v6
	v_fmac_f32_e32 v4, v8, v8
	v_fmac_f32_e32 v11, v10, v10
	v_fmac_f32_e32 v12, v14, v14
	v_add_f32_e32 v3, v3, v4
	v_add_f32_e32 v4, v11, v13
	v_add_f32_e32 v5, v12, v15
	v_add_f32_e32 v2, v4, v2
	v_add_f32_e32 v3, v5, v3
	s_nop 1
	v_mov_b32_dpp v4, v2 quad_perm:[1,0,3,2] row_mask:0xf bank_mask:0xf
	s_nop 1
	v_mov_b32_dpp v5, v3 quad_perm:[1,0,3,2] row_mask:0xf bank_mask:0xf
	s_waitcnt lgkmcnt(1)
	v_add_f32_e32 v2, v2, v4
	s_waitcnt lgkmcnt(0)
	v_add_f32_e32 v5, v3, v5
	s_nop 1
	v_mov_b32_dpp v4, v2 quad_perm:[2,3,0,1] row_mask:0xf bank_mask:0xf
	s_nop 1
	v_mov_b32_dpp v6, v5 quad_perm:[2,3,0,1] row_mask:0xf bank_mask:0xf
	s_waitcnt lgkmcnt(1)
	v_add_f32_e32 v2, v2, v4
	s_waitcnt lgkmcnt(0)
	v_add_f32_e32 v4, v5, v6
	s_nop 1
	v_mov_b32_dpp v3, v2 row_half_mirror row_mask:0xf bank_mask:0xf
	s_nop 1
	v_mov_b32_dpp v5, v4 row_half_mirror row_mask:0xf bank_mask:0xf
	v_add_u32_e32 v6, 0x1040, v22
	v_cndmask_b32_e64 v6, v22, v6, s[36:37]
	global_store_dwordx2 v6, v[246:247], s[20:21]
	s_and_saveexec_b64 s[20:21], s[40:41]
	s_cbranch_execz .LBB0_2849
	s_waitcnt lgkmcnt(1)
	v_add_f32_e32 v2, v2, v3
	s_waitcnt lgkmcnt(0)
	v_add_f32_e32 v3, v4, v5
	ds_write2_b32 v194, v2, v3 offset0:112 offset1:120
